# v37 plus: the 320 weight-conversion stores made write-through (sc1) so converted weights do not sit dirty in the L2 until the barrier's release write-back
# baseline (speedup 1.0000x reference)
; __device__ __forceinline__ unsigned cvt_pk_bf16(float lo, float hi) { unsigned r; asm volatile("v_cvt_pk_bf16_f32 %0, %1, %2" : "=v"(r) : "v"(lo), "v"(hi)); return r; }
; #define INP(i) ((const float*)(const GASP float*)kargs()[(i)])
; __device__ __forceinline__ void tr_item(const float* W, int ldw, int k0, int n0, bf16* WT, int ldk, int drow0, int lane) {
;     const int n4 = (lane & 15) * 4, kg = lane >> 4; f32x4 v[2][8];
; #pragma unroll
;     for (int kh = 0; kh < 2; ++kh) { const float* src = W + (size_t)(k0 + kh * 32 + kg * 8) * ldw + n0 + n4;
; #pragma unroll
;         for (int i = 0; i < 8; ++i) v[kh][i] = __builtin_nontemporal_load((const f32x4*)(src + (size_t)i * ldw)); }
; #pragma unroll
;     for (int kh = 0; kh < 2; ++kh)
; #pragma unroll
;         for (int e = 0; e < 4; ++e) { u32x4 o; o.x = cvt_pk_bf16(v[kh][0][e], v[kh][1][e]); o.y = cvt_pk_bf16(v[kh][2][e], v[kh][3][e]); o.z = cvt_pk_bf16(v[kh][4][e], v[kh][5][e]); o.w = cvt_pk_bf16(v[kh][6][e], v[kh][7][e]);
;             *(u32x4*)(WT + (size_t)(drow0 + n4 + e) * ldk + k0 + kh * 32 + kg * 8) = o; }
; }
; __device__ __forceinline__ void conv_item(int it, int lane) {
;     ...
;     { const int idx = r / IT_OUTC; r -= idx * IT_OUTC; const int kb = r / 32, nb = r % 32;
;       tr_item(INP(I_WOUTC) + (size_t)idx * 2560 * 2048, 2048, 64 * kb, 64 * nb, (bf16*)(ws + WS_WOUTC) + (size_t)idx * 2048 * 2560, 2560, 64 * nb, lane); }
.LBB0_208:
	s_cmpk_gt_u32 s33, 0xfbff
	s_cbranch_scc0 .LBB0_226
	s_cmp_gt_u32 s33, 0x10fff
	s_cbranch_scc0 .LBB0_223
	s_cmp_gt_u32 s33, 0x111ff
	s_cbranch_scc0 .LBB0_220
	s_cmp_gt_u32 s33, 0x119ff
	s_cbranch_scc0 .LBB0_217
	s_cmp_gt_u32 s33, 0x12dff
	s_cbranch_scc0 .LBB0_214
	s_add_i32 s6, s33, 0xfffed200
	s_mul_hi_u32 s34, s6, 0xcccccccd
	s_lshr_b32 s37, s34, 10
	s_mul_i32 s34, s37, 0xfffffb00
	s_add_i32 s6, s34, s6
	s_ashr_i32 s34, s6, 31
	s_lshr_b32 s34, s34, 27
	s_add_i32 s36, s6, s34
	s_mov_b64 s[34:35], s[0:1]
	s_load_dwordx2 s[34:35], s[34:35], 0x128
	s_and_b32 s72, s36, 0x3ffffe0
	s_sub_i32 s6, s6, s72
	s_mul_i32 s73, s37, 0x1400000
	s_mul_hi_u32 s72, s37, 0x1400000
	s_waitcnt lgkmcnt(0)
	s_add_u32 s74, s34, s73
	s_addc_u32 s35, s35, s72
	s_lshl_b32 s34, s36, 1
	s_andn2_b32 s34, s34, 63
	s_lshl_b32 s36, s6, 6
	s_mul_hi_u32 s6, s37, 0xa00000
	s_mul_i32 s37, s37, 0xa00000
	s_add_u32 s75, s30, s37
	s_addc_u32 s6, s31, s6
	s_ashr_i32 s37, s36, 31
	s_lshl_b64 s[72:73], s[36:37], 2
	v_add_u32_e32 v38, s34, v2
	s_add_u32 s72, s74, s72
	s_addc_u32 s73, s35, s73
	v_ashrrev_i32_e32 v39, 31, v38
	v_lshl_add_u64 v[40:41], s[72:73], 0, v[4:5]
	v_lshlrev_b64 v[6:7], 13, v[38:39]
	v_lshl_add_u64 v[30:31], v[40:41], 0, v[6:7]
	v_add_co_u32_e32 v10, vcc, s43, v30
	v_add_u32_e32 v38, 32, v38
	s_nop 0
	v_addc_co_u32_e32 v11, vcc, 0, v31, vcc
	v_add_co_u32_e32 v14, vcc, s44, v30
	v_ashrrev_i32_e32 v39, 31, v38
	s_nop 0
	v_addc_co_u32_e32 v15, vcc, 0, v31, vcc
	v_add_co_u32_e32 v18, vcc, s45, v30
	v_lshlrev_b64 v[38:39], 13, v[38:39]
	s_nop 0
	v_addc_co_u32_e32 v19, vcc, 0, v31, vcc
	v_add_co_u32_e32 v22, vcc, s46, v30
	v_lshl_add_u64 v[62:63], v[40:41], 0, v[38:39]
	s_nop 0
	v_addc_co_u32_e32 v23, vcc, 0, v31, vcc
	v_add_co_u32_e32 v26, vcc, s47, v30
	global_load_dwordx4 v[6:9], v[30:31], off nt
	s_nop 0
	global_load_dwordx4 v[10:13], v[10:11], off nt
	v_addc_co_u32_e32 v27, vcc, 0, v31, vcc
	v_add_co_u32_e32 v32, vcc, s48, v30
	global_load_dwordx4 v[14:17], v[14:15], off nt
	s_nop 0
	global_load_dwordx4 v[18:21], v[18:19], off nt
	v_addc_co_u32_e32 v33, vcc, 0, v31, vcc
	v_add_co_u32_e32 v34, vcc, s49, v30
	global_load_dwordx4 v[22:25], v[22:23], off nt
	s_nop 0
	global_load_dwordx4 v[26:29], v[26:27], off nt
	v_addc_co_u32_e32 v35, vcc, 0, v31, vcc
	v_add_co_u32_e32 v42, vcc, s43, v62
	global_load_dwordx4 v[30:33], v[32:33], off nt
	s_nop 0
	global_load_dwordx4 v[34:37], v[34:35], off nt
	v_addc_co_u32_e32 v43, vcc, 0, v63, vcc
	v_add_co_u32_e32 v46, vcc, s44, v62
	global_load_dwordx4 v[38:41], v[62:63], off nt
	s_nop 0
	global_load_dwordx4 v[42:45], v[42:43], off nt
	v_addc_co_u32_e32 v47, vcc, 0, v63, vcc
	v_add_co_u32_e32 v50, vcc, s45, v62
	s_ashr_i32 s35, s34, 31
	s_nop 0
	v_addc_co_u32_e32 v51, vcc, 0, v63, vcc
	v_add_co_u32_e32 v54, vcc, s46, v62
	global_load_dwordx4 v[46:49], v[46:47], off nt
	s_nop 0
	global_load_dwordx4 v[50:53], v[50:51], off nt
	v_addc_co_u32_e32 v55, vcc, 0, v63, vcc
	v_add_co_u32_e32 v58, vcc, s47, v62
	s_lshl_b64 s[34:35], s[34:35], 1
	s_nop 0
	v_addc_co_u32_e32 v59, vcc, 0, v63, vcc
	v_add_co_u32_e32 v64, vcc, s48, v62
	global_load_dwordx4 v[54:57], v[54:55], off nt
	s_nop 0
	global_load_dwordx4 v[58:61], v[58:59], off nt
	v_addc_co_u32_e32 v65, vcc, 0, v63, vcc
	v_add_co_u32_e32 v66, vcc, s49, v62
	v_or_b32_e32 v1, s36, v0
	s_nop 0
	v_addc_co_u32_e32 v67, vcc, 0, v63, vcc
	global_load_dwordx4 v[62:65], v[64:65], off nt
	s_nop 0
	global_load_dwordx4 v[66:69], v[66:67], off nt
	s_add_u32 s34, s75, s34
	s_addc_u32 s35, s6, s35
	v_mul_lo_u32 v76, v1, s41
	v_lshl_add_u64 v[74:75], v[2:3], 1, s[34:35]
	v_ashrrev_i32_e32 v77, 31, v76
	v_lshl_add_u64 v[74:75], v[76:77], 1, v[74:75]
	v_add_co_u32_e32 v78, vcc, s50, v74
	s_waitcnt vmcnt(14)
	v_cvt_pk_bf16_f32 v70, v6, v10
	s_nop 0
	v_addc_co_u32_e32 v79, vcc, 0, v75, vcc
	v_add_co_u32_e32 v10, vcc, s51, v74
	s_waitcnt vmcnt(12)
	v_cvt_pk_bf16_f32 v71, v14, v18
	s_waitcnt vmcnt(10)
	v_cvt_pk_bf16_f32 v72, v22, v26
	s_waitcnt vmcnt(8)
	v_cvt_pk_bf16_f32 v73, v30, v34
	global_store_dwordx4 v[78:79], v[70:73], off sc1
	v_lshl_add_u64 v[76:77], v[74:75], 0, s[10:11]
	s_mov_b64 s[34:35], 0
	v_cvt_pk_bf16_f32 v70, v7, v11
	v_addc_co_u32_e32 v11, vcc, 0, v75, vcc
	v_add_co_u32_e32 v14, vcc, s52, v74
	v_cvt_pk_bf16_f32 v71, v15, v19
	v_cvt_pk_bf16_f32 v72, v23, v27
	v_cvt_pk_bf16_f32 v73, v31, v35
	global_store_dwordx4 v[10:11], v[70:73], off offset:1024 sc1
	s_nop 0
	v_addc_co_u32_e32 v15, vcc, 0, v75, vcc
	v_cvt_pk_bf16_f32 v70, v8, v12
	v_add_co_u32_e32 v12, vcc, s53, v74
	v_cvt_pk_bf16_f32 v71, v16, v20
	v_cvt_pk_bf16_f32 v72, v24, v28
	v_cvt_pk_bf16_f32 v73, v32, v36
	global_store_dwordx4 v[14:15], v[70:73], off offset:2048 sc1
	v_cvt_pk_bf16_f32 v6, v9, v13
	v_cvt_pk_bf16_f32 v7, v17, v21
	v_cvt_pk_bf16_f32 v8, v25, v29
	v_cvt_pk_bf16_f32 v9, v33, v37
	s_nop 0
	v_addc_co_u32_e32 v13, vcc, 0, v75, vcc
	global_store_dwordx4 v[12:13], v[6:9], off offset:3072 sc1
	s_waitcnt vmcnt(10)
	s_nop 0
	v_cvt_pk_bf16_f32 v6, v38, v42
	s_waitcnt vmcnt(8)
	v_cvt_pk_bf16_f32 v7, v46, v50
	s_waitcnt vmcnt(6)
	v_cvt_pk_bf16_f32 v8, v54, v58
	s_waitcnt vmcnt(4)
	v_cvt_pk_bf16_f32 v9, v62, v66
	global_store_dwordx4 v[76:77], v[6:9], off offset:64 sc1
	s_nop 1
	v_cvt_pk_bf16_f32 v6, v39, v43
	v_cvt_pk_bf16_f32 v7, v47, v51
	v_cvt_pk_bf16_f32 v8, v55, v59
	v_cvt_pk_bf16_f32 v9, v63, v67
	global_store_dwordx4 v[10:11], v[6:9], off offset:1088 sc1
	s_nop 1
	v_cvt_pk_bf16_f32 v6, v40, v44
	v_cvt_pk_bf16_f32 v7, v48, v52
	v_cvt_pk_bf16_f32 v8, v56, v60
	v_cvt_pk_bf16_f32 v9, v64, v68
	global_store_dwordx4 v[14:15], v[6:9], off offset:2112 sc1
	s_nop 1
	v_cvt_pk_bf16_f32 v6, v41, v45
	v_cvt_pk_bf16_f32 v7, v49, v53
	v_cvt_pk_bf16_f32 v8, v57, v61
	v_cvt_pk_bf16_f32 v9, v65, v69
	global_store_dwordx4 v[12:13], v[6:9], off offset:3136 sc1
; __device__ __forceinline__ unsigned cvt_pk_bf16(float lo, float hi) { unsigned r; asm volatile("v_cvt_pk_bf16_f32 %0, %1, %2" : "=v"(r) : "v"(lo), "v"(hi)); return r; }
; #define INP(i) ((const float*)(const GASP float*)kargs()[(i)])
; __device__ __forceinline__ void tr_item(const float* W, int ldw, int k0, int n0, bf16* WT, int ldk, int drow0, int lane) {
;     const int n4 = (lane & 15) * 4, kg = lane >> 4; f32x4 v[2][8];
; #pragma unroll
;     for (int kh = 0; kh < 2; ++kh) { const float* src = W + (size_t)(k0 + kh * 32 + kg * 8) * ldw + n0 + n4;
; #pragma unroll
;         for (int i = 0; i < 8; ++i) v[kh][i] = __builtin_nontemporal_load((const f32x4*)(src + (size_t)i * ldw)); }
; #pragma unroll
;     for (int kh = 0; kh < 2; ++kh)
; #pragma unroll
;         for (int e = 0; e < 4; ++e) { u32x4 o; o.x = cvt_pk_bf16(v[kh][0][e], v[kh][1][e]); o.y = cvt_pk_bf16(v[kh][2][e], v[kh][3][e]); o.z = cvt_pk_bf16(v[kh][4][e], v[kh][5][e]); o.w = cvt_pk_bf16(v[kh][6][e], v[kh][7][e]);
;             *(u32x4*)(WT + (size_t)(drow0 + n4 + e) * ldk + k0 + kh * 32 + kg * 8) = o; }
; }
; __device__ __forceinline__ void conv_item(int it, int lane) {
;     ...
;     if (r < 2 * IT_INC) { const int idx = r / IT_INC; r -= idx * IT_INC; const int kb = r / 80, nb = r % 80;
;         tr_item(INP(I_WINC) + (size_t)idx * 2048 * 5120, 5120, 64 * kb, 64 * nb, (bf16*)(ws + WS_WINC) + (size_t)idx * 5120 * 2048, 2048, 64 * nb, lane); return; }
.LBB0_214:
	s_andn2_b64 vcc, exec, s[34:35]
	s_cbranch_vccnz .LBB0_216
	s_add_i32 s6, s33, 0xfffee600
	s_cmpk_gt_u32 s6, 0x9ff
	s_cselect_b64 s[72:73], -1, 0
	s_and_b64 s[34:35], s[72:73], exec
	s_cselect_b32 s34, 0xf600, 0
	s_add_i32 s6, s34, s6
	s_sext_i32_i16 s34, s6
	s_mulk_i32 s34, 0x6667
	s_lshr_b32 s35, s34, 31
	s_ashr_i32 s34, s34, 21
	s_add_i32 s74, s34, s35
	s_mov_b64 s[34:35], s[0:1]
	s_load_dwordx2 s[34:35], s[34:35], 0xe8
	s_mul_i32 s36, s74, 0x50
	s_sub_i32 s6, s6, s36
	s_and_b64 s[36:37], s[72:73], exec
	s_cselect_b32 s36, 0x2800000, 0
	s_sext_i32_i16 s6, s6
	s_waitcnt lgkmcnt(0)
	s_add_u32 s75, s34, s36
	s_addc_u32 s35, s35, 0
	s_lshl_b32 s34, s74, 6
	s_lshl_b32 s36, s6, 6
	s_and_b64 s[72:73], s[72:73], exec
	s_cselect_b32 s6, 0x1400000, 0
	s_add_u32 s6, s30, s6
	s_addc_u32 s74, s31, 0
	s_ashr_i32 s37, s36, 31
	s_lshl_b64 s[72:73], s[36:37], 2
	s_add_u32 s72, s75, s72
	s_addc_u32 s73, s35, s73
	v_add_u32_e32 v1, s34, v2
	v_lshl_add_u64 v[38:39], s[72:73], 0, v[4:5]
	v_mad_i64_i32 v[30:31], s[72:73], v1, s55, v[38:39]
	v_add_co_u32_e32 v10, vcc, s55, v30
	v_add_u32_e32 v1, 32, v1
	s_nop 0
	v_addc_co_u32_e32 v11, vcc, 0, v31, vcc
	v_add_co_u32_e32 v14, vcc, s47, v30
	v_mad_i64_i32 v[62:63], s[72:73], v1, s55, v[38:39]
	s_nop 0
	v_addc_co_u32_e32 v15, vcc, 0, v31, vcc
	v_add_co_u32_e32 v18, vcc, s56, v30
	global_load_dwordx4 v[6:9], v[30:31], off nt
	s_nop 0
	global_load_dwordx4 v[10:13], v[10:11], off nt
	v_addc_co_u32_e32 v19, vcc, 0, v31, vcc
	v_add_co_u32_e32 v22, vcc, s57, v30
	global_load_dwordx4 v[14:17], v[14:15], off nt
	s_nop 0
	global_load_dwordx4 v[18:21], v[18:19], off nt
	v_addc_co_u32_e32 v23, vcc, 0, v31, vcc
	v_add_co_u32_e32 v26, vcc, s58, v30
	s_ashr_i32 s35, s34, 31
	s_nop 0
	v_addc_co_u32_e32 v27, vcc, 0, v31, vcc
	v_add_co_u32_e32 v32, vcc, s59, v30
	global_load_dwordx4 v[22:25], v[22:23], off nt
	s_nop 0
	global_load_dwordx4 v[26:29], v[26:27], off nt
	v_addc_co_u32_e32 v33, vcc, 0, v31, vcc
	v_add_co_u32_e32 v34, vcc, s60, v30
	s_lshl_b64 s[34:35], s[34:35], 1
	s_nop 0
	v_addc_co_u32_e32 v35, vcc, 0, v31, vcc
	v_add_co_u32_e32 v42, vcc, s55, v62
	global_load_dwordx4 v[30:33], v[32:33], off nt
	s_nop 0
	global_load_dwordx4 v[34:37], v[34:35], off nt
	v_addc_co_u32_e32 v43, vcc, 0, v63, vcc
	v_add_co_u32_e32 v46, vcc, s47, v62
	global_load_dwordx4 v[38:41], v[62:63], off nt
	s_nop 0
	global_load_dwordx4 v[42:45], v[42:43], off nt
	v_addc_co_u32_e32 v47, vcc, 0, v63, vcc
	v_add_co_u32_e32 v50, vcc, s56, v62
	s_add_u32 s34, s6, s34
	s_nop 0
	v_addc_co_u32_e32 v51, vcc, 0, v63, vcc
	v_add_co_u32_e32 v54, vcc, s57, v62
	global_load_dwordx4 v[46:49], v[46:47], off nt
	s_nop 0
	global_load_dwordx4 v[50:53], v[50:51], off nt
	v_addc_co_u32_e32 v55, vcc, 0, v63, vcc
	v_add_co_u32_e32 v58, vcc, s58, v62
	v_or_b32_e32 v74, s36, v0
	s_nop 0
	v_addc_co_u32_e32 v59, vcc, 0, v63, vcc
	v_add_co_u32_e32 v64, vcc, s59, v62
	global_load_dwordx4 v[54:57], v[54:55], off nt
	s_nop 0
	global_load_dwordx4 v[58:61], v[58:59], off nt
	v_addc_co_u32_e32 v65, vcc, 0, v63, vcc
	v_add_co_u32_e32 v66, vcc, s60, v62
	s_addc_u32 s35, s74, s35
	s_nop 0
	v_addc_co_u32_e32 v67, vcc, 0, v63, vcc
	global_load_dwordx4 v[62:65], v[64:65], off nt
	s_nop 0
	global_load_dwordx4 v[66:69], v[66:67], off nt
	v_lshl_add_u64 v[70:71], v[2:3], 1, s[34:35]
	v_ashrrev_i32_e32 v75, 31, v74
	v_lshl_add_u64 v[76:77], v[70:71], 0, s[12:13]
	v_lshlrev_b64 v[78:79], 12, v[74:75]
	s_waitcnt vmcnt(14)
	v_cvt_pk_bf16_f32 v70, v6, v10
	v_lshl_add_u64 v[78:79], v[76:77], 0, v[78:79]
	v_or_b32_e32 v6, 1, v74
	s_waitcnt vmcnt(12)
	v_cvt_pk_bf16_f32 v71, v14, v18
	s_waitcnt vmcnt(10)
	v_cvt_pk_bf16_f32 v72, v22, v26
	s_waitcnt vmcnt(8)
	v_cvt_pk_bf16_f32 v73, v30, v34
	global_store_dwordx4 v[78:79], v[70:73], off sc1
	s_nop 1
	v_cvt_pk_bf16_f32 v70, v7, v11
	v_ashrrev_i32_e32 v7, 31, v6
	v_lshlrev_b64 v[6:7], 12, v[6:7]
	v_lshl_add_u64 v[10:11], v[76:77], 0, v[6:7]
	v_or_b32_e32 v6, 2, v74
	v_ashrrev_i32_e32 v7, 31, v6
	v_lshlrev_b64 v[6:7], 12, v[6:7]
	v_cvt_pk_bf16_f32 v71, v15, v19
	v_cvt_pk_bf16_f32 v72, v23, v27
	v_cvt_pk_bf16_f32 v73, v31, v35
	global_store_dwordx4 v[10:11], v[70:73], off sc1
	v_lshl_add_u64 v[14:15], v[76:77], 0, v[6:7]
	s_nop 0
	v_cvt_pk_bf16_f32 v70, v8, v12
	v_or_b32_e32 v12, 3, v74
	v_cvt_pk_bf16_f32 v71, v16, v20
	v_cvt_pk_bf16_f32 v72, v24, v28
	v_cvt_pk_bf16_f32 v73, v32, v36
	global_store_dwordx4 v[14:15], v[70:73], off sc1
	v_cvt_pk_bf16_f32 v6, v9, v13
	v_ashrrev_i32_e32 v13, 31, v12
	v_lshlrev_b64 v[12:13], 12, v[12:13]
	v_cvt_pk_bf16_f32 v7, v17, v21
	v_cvt_pk_bf16_f32 v8, v25, v29
	v_cvt_pk_bf16_f32 v9, v33, v37
	v_lshl_add_u64 v[12:13], v[76:77], 0, v[12:13]
	global_store_dwordx4 v[12:13], v[6:9], off sc1
	s_waitcnt vmcnt(10)
	s_nop 0
	v_cvt_pk_bf16_f32 v6, v38, v42
	s_waitcnt vmcnt(8)
	v_cvt_pk_bf16_f32 v7, v46, v50
	s_waitcnt vmcnt(6)
	v_cvt_pk_bf16_f32 v8, v54, v58
	s_waitcnt vmcnt(4)
	v_cvt_pk_bf16_f32 v9, v62, v66
	global_store_dwordx4 v[78:79], v[6:9], off offset:64 sc1
	s_nop 1
	v_cvt_pk_bf16_f32 v6, v39, v43
	v_cvt_pk_bf16_f32 v7, v47, v51
	v_cvt_pk_bf16_f32 v8, v55, v59
	v_cvt_pk_bf16_f32 v9, v63, v67
	global_store_dwordx4 v[10:11], v[6:9], off offset:64 sc1
	s_nop 1
	v_cvt_pk_bf16_f32 v6, v40, v44
	v_cvt_pk_bf16_f32 v7, v48, v52
	v_cvt_pk_bf16_f32 v8, v56, v60
	v_cvt_pk_bf16_f32 v9, v64, v68
	global_store_dwordx4 v[14:15], v[6:9], off offset:64 sc1
	s_nop 1
	v_cvt_pk_bf16_f32 v6, v41, v45
	v_cvt_pk_bf16_f32 v7, v49, v53
	v_cvt_pk_bf16_f32 v8, v57, v61
	v_cvt_pk_bf16_f32 v9, v65, v69
	global_store_dwordx4 v[12:13], v[6:9], off offset:64 sc1

; __device__ __forceinline__ unsigned cvt_pk_bf16(float lo, float hi) { unsigned r; asm volatile("v_cvt_pk_bf16_f32 %0, %1, %2" : "=v"(r) : "v"(lo), "v"(hi)); return r; }
; #define INP(i) ((const float*)(const GASP float*)kargs()[(i)])
; __device__ __forceinline__ void tr_item(const float* W, int ldw, int k0, int n0, bf16* WT, int ldk, int drow0, int lane) {
;     const int n4 = (lane & 15) * 4, kg = lane >> 4; f32x4 v[2][8];
; #pragma unroll
;     for (int kh = 0; kh < 2; ++kh) { const float* src = W + (size_t)(k0 + kh * 32 + kg * 8) * ldw + n0 + n4;
; #pragma unroll
;         for (int i = 0; i < 8; ++i) v[kh][i] = __builtin_nontemporal_load((const f32x4*)(src + (size_t)i * ldw)); }
; #pragma unroll
;     for (int kh = 0; kh < 2; ++kh)
; #pragma unroll
;         for (int e = 0; e < 4; ++e) { u32x4 o; o.x = cvt_pk_bf16(v[kh][0][e], v[kh][1][e]); o.y = cvt_pk_bf16(v[kh][2][e], v[kh][3][e]); o.z = cvt_pk_bf16(v[kh][4][e], v[kh][5][e]); o.w = cvt_pk_bf16(v[kh][6][e], v[kh][7][e]);
;             *(u32x4*)(WT + (size_t)(drow0 + n4 + e) * ldk + k0 + kh * 32 + kg * 8) = o; }
; }
; __device__ __forceinline__ void conv_item(int it, int lane) {
;     ...
;     if (r < 2 * IT_OUTAB) { const int idx = r / IT_OUTAB; r -= idx * IT_OUTAB; const int kb = r / 32, nb = r % 32;
;         tr_item(INP(I_WOUTAB) + (size_t)idx * 2048 * 2048, 2048, 64 * kb, 64 * nb, (bf16*)(ws + WS_WOUTAB) + (size_t)idx * 2048 * 2048, 2048, 64 * nb, lane); return; }
.LBB0_217:
	s_andn2_b64 vcc, exec, s[34:35]
	s_cbranch_vccnz .LBB0_219
	s_mov_b64 s[34:35], s[0:1]
	s_load_dwordx2 s[34:35], s[34:35], 0xe0
	s_add_i32 s72, s33, 0xfffeee00
	s_lshr_b32 s6, s72, 10
	s_lshl_b64 s[36:37], s[6:7], 24
	v_mov_b32_e32 v79, v5
	s_waitcnt lgkmcnt(0)
	s_add_u32 s36, s34, s36
	s_addc_u32 s37, s35, s37
	s_lshl_b32 s34, s72, 1
	s_and_b32 s72, s34, 0x7c0
	s_lshl_b32 s34, s33, 6
	s_and_b32 s73, s34, 0x7c0
	s_lshl_b64 s[34:35], s[6:7], 23
	s_add_u32 s6, s30, s34
	s_addc_u32 s74, s31, s35
	s_lshl_b32 s34, s73, 2
	v_add_u32_e32 v38, s72, v2
	s_add_u32 s34, s36, s34
	s_addc_u32 s35, s37, 0
	v_ashrrev_i32_e32 v39, 31, v38
	v_lshl_add_u64 v[40:41], s[34:35], 0, v[4:5]
	v_lshlrev_b64 v[6:7], 13, v[38:39]
	v_lshl_add_u64 v[30:31], v[40:41], 0, v[6:7]
	v_add_co_u32_e32 v10, vcc, s43, v30
	v_add_u32_e32 v38, 32, v38
	s_nop 0
	v_addc_co_u32_e32 v11, vcc, 0, v31, vcc
	v_add_co_u32_e32 v14, vcc, s44, v30
	v_ashrrev_i32_e32 v39, 31, v38
	s_nop 0
	v_addc_co_u32_e32 v15, vcc, 0, v31, vcc
	v_add_co_u32_e32 v18, vcc, s45, v30
	v_lshlrev_b64 v[38:39], 13, v[38:39]
	s_nop 0
	v_addc_co_u32_e32 v19, vcc, 0, v31, vcc
	v_add_co_u32_e32 v22, vcc, s46, v30
	v_lshl_add_u64 v[62:63], v[40:41], 0, v[38:39]
	s_nop 0
	v_addc_co_u32_e32 v23, vcc, 0, v31, vcc
	v_add_co_u32_e32 v26, vcc, s47, v30
	global_load_dwordx4 v[6:9], v[30:31], off nt
	s_nop 0
	global_load_dwordx4 v[10:13], v[10:11], off nt
	v_addc_co_u32_e32 v27, vcc, 0, v31, vcc
	v_add_co_u32_e32 v32, vcc, s48, v30
	global_load_dwordx4 v[14:17], v[14:15], off nt
	s_nop 0
	global_load_dwordx4 v[18:21], v[18:19], off nt
	v_addc_co_u32_e32 v33, vcc, 0, v31, vcc
	v_add_co_u32_e32 v34, vcc, s49, v30
	global_load_dwordx4 v[22:25], v[22:23], off nt
	s_nop 0
	global_load_dwordx4 v[26:29], v[26:27], off nt
	v_addc_co_u32_e32 v35, vcc, 0, v31, vcc
	v_add_co_u32_e32 v42, vcc, s43, v62
	global_load_dwordx4 v[30:33], v[32:33], off nt
	s_nop 0
	global_load_dwordx4 v[34:37], v[34:35], off nt
	v_addc_co_u32_e32 v43, vcc, 0, v63, vcc
	v_add_co_u32_e32 v46, vcc, s44, v62
	global_load_dwordx4 v[38:41], v[62:63], off nt
	s_nop 0
	global_load_dwordx4 v[42:45], v[42:43], off nt
	v_addc_co_u32_e32 v47, vcc, 0, v63, vcc
	v_add_co_u32_e32 v50, vcc, s45, v62
	s_lshl_b32 s34, s72, 1
	s_nop 0
	v_addc_co_u32_e32 v51, vcc, 0, v63, vcc
	v_add_co_u32_e32 v54, vcc, s46, v62
	global_load_dwordx4 v[46:49], v[46:47], off nt
	s_nop 0
	global_load_dwordx4 v[50:53], v[50:51], off nt
	v_addc_co_u32_e32 v55, vcc, 0, v63, vcc
	v_add_co_u32_e32 v58, vcc, s47, v62
	s_add_u32 s34, s6, s34
	s_nop 0
	v_addc_co_u32_e32 v59, vcc, 0, v63, vcc
	v_add_co_u32_e32 v64, vcc, s48, v62
	global_load_dwordx4 v[54:57], v[54:55], off nt
	s_nop 0
	global_load_dwordx4 v[58:61], v[58:59], off nt
	v_addc_co_u32_e32 v65, vcc, 0, v63, vcc
	v_add_co_u32_e32 v66, vcc, s49, v62
	s_addc_u32 s35, s74, 0
	s_nop 0
	v_addc_co_u32_e32 v67, vcc, 0, v63, vcc
	global_load_dwordx4 v[62:65], v[64:65], off nt
	s_nop 0
	global_load_dwordx4 v[66:69], v[66:67], off nt
	v_or_b32_e32 v1, s73, v0
	v_lshl_add_u64 v[74:75], v[2:3], 1, s[34:35]
	v_lshl_add_u64 v[76:77], v[74:75], 0, s[14:15]
	v_lshlrev_b32_e32 v78, 12, v1
	s_waitcnt vmcnt(14)
	v_cvt_pk_bf16_f32 v70, v6, v10
	v_lshl_add_u64 v[80:81], v[76:77], 0, v[78:79]
	s_waitcnt vmcnt(12)
	v_cvt_pk_bf16_f32 v71, v14, v18
	s_waitcnt vmcnt(10)
	v_cvt_pk_bf16_f32 v72, v22, v26
	s_waitcnt vmcnt(8)
	v_cvt_pk_bf16_f32 v73, v30, v34
	global_store_dwordx4 v[80:81], v[70:73], off sc1
	v_or_b32_e32 v10, 0x1000, v78
	v_or_b32_e32 v14, 0x2000, v78
	v_cvt_pk_bf16_f32 v70, v7, v11
	v_mov_b32_e32 v11, v5
	v_cvt_pk_bf16_f32 v71, v15, v19
	v_lshl_add_u64 v[6:7], v[76:77], 0, v[10:11]
	v_mov_b32_e32 v15, v5
	v_cvt_pk_bf16_f32 v72, v23, v27
	v_cvt_pk_bf16_f32 v73, v31, v35
	global_store_dwordx4 v[6:7], v[70:73], off sc1
	v_lshl_add_u64 v[6:7], v[76:77], 0, v[14:15]
	s_nop 0
	v_cvt_pk_bf16_f32 v70, v8, v12
	v_cvt_pk_bf16_f32 v71, v16, v20
	v_cvt_pk_bf16_f32 v72, v24, v28
	v_cvt_pk_bf16_f32 v73, v32, v36
	global_store_dwordx4 v[6:7], v[70:73], off sc1
	v_cvt_pk_bf16_f32 v6, v9, v13
	v_or_b32_e32 v12, 0x3000, v78
	v_mov_b32_e32 v13, v5
	v_cvt_pk_bf16_f32 v7, v17, v21
	v_lshl_add_u64 v[16:17], v[76:77], 0, v[12:13]
	v_cvt_pk_bf16_f32 v8, v25, v29
	v_cvt_pk_bf16_f32 v9, v33, v37
	global_store_dwordx4 v[16:17], v[6:9], off sc1
	v_lshl_add_u64 v[16:17], v[74:75], 0, s[16:17]
	v_lshl_add_u64 v[10:11], v[16:17], 0, v[10:11]
	s_waitcnt vmcnt(10)
	v_cvt_pk_bf16_f32 v6, v38, v42
	s_waitcnt vmcnt(8)
	v_cvt_pk_bf16_f32 v7, v46, v50
	s_waitcnt vmcnt(6)
	v_cvt_pk_bf16_f32 v8, v54, v58
	s_waitcnt vmcnt(4)
	v_cvt_pk_bf16_f32 v9, v62, v66
	global_store_dwordx4 v[80:81], v[6:9], off offset:64 sc1
	s_nop 1
	v_cvt_pk_bf16_f32 v6, v39, v43
	v_cvt_pk_bf16_f32 v7, v47, v51
	v_cvt_pk_bf16_f32 v8, v55, v59
	v_cvt_pk_bf16_f32 v9, v63, v67
	global_store_dwordx4 v[10:11], v[6:9], off sc1
	v_lshl_add_u64 v[10:11], v[16:17], 0, v[14:15]
	s_nop 0
	v_cvt_pk_bf16_f32 v6, v40, v44
	v_cvt_pk_bf16_f32 v7, v48, v52
	v_cvt_pk_bf16_f32 v8, v56, v60
	v_cvt_pk_bf16_f32 v9, v64, v68
	global_store_dwordx4 v[10:11], v[6:9], off sc1
	v_lshl_add_u64 v[10:11], v[16:17], 0, v[12:13]
	s_nop 0
	v_cvt_pk_bf16_f32 v6, v41, v45
	v_cvt_pk_bf16_f32 v7, v49, v53
	v_cvt_pk_bf16_f32 v8, v57, v61
	v_cvt_pk_bf16_f32 v9, v65, v69
	global_store_dwordx4 v[10:11], v[6:9], off sc1

; __device__ __forceinline__ unsigned cvt_pk_bf16(float lo, float hi) { unsigned r; asm volatile("v_cvt_pk_bf16_f32 %0, %1, %2" : "=v"(r) : "v"(lo), "v"(hi)); return r; }
; #define INP(i) ((const float*)(const GASP float*)kargs()[(i)])
; __device__ __forceinline__ void tr_item(const float* W, int ldw, int k0, int n0, bf16* WT, int ldk, int drow0, int lane) {
;     const int n4 = (lane & 15) * 4, kg = lane >> 4; f32x4 v[2][8];
; #pragma unroll
;     for (int kh = 0; kh < 2; ++kh) { const float* src = W + (size_t)(k0 + kh * 32 + kg * 8) * ldw + n0 + n4;
; #pragma unroll
;         for (int i = 0; i < 8; ++i) v[kh][i] = __builtin_nontemporal_load((const f32x4*)(src + (size_t)i * ldw)); }
; #pragma unroll
;     for (int kh = 0; kh < 2; ++kh)
; #pragma unroll
;         for (int e = 0; e < 4; ++e) { u32x4 o; o.x = cvt_pk_bf16(v[kh][0][e], v[kh][1][e]); o.y = cvt_pk_bf16(v[kh][2][e], v[kh][3][e]); o.z = cvt_pk_bf16(v[kh][4][e], v[kh][5][e]); o.w = cvt_pk_bf16(v[kh][6][e], v[kh][7][e]);
;             *(u32x4*)(WT + (size_t)(drow0 + n4 + e) * ldk + k0 + kh * 32 + kg * 8) = o; }
; }
; __device__ __forceinline__ void conv_item(int it, int lane) {
;     ...
;     if (r < 2 * IT_INAB) { const int idx = r / IT_INAB; r -= idx * IT_INAB; const int kb = r / 80, nb = r % 80;
;         tr_item(INP(I_WINAB) + (size_t)idx * 2048 * 5120, 5120, 64 * kb, 64 * nb, (bf16*)(ws + WS_WINAB) + (size_t)idx * 5120 * 2048, 2048, 64 * nb, lane); return; }
.LBB0_223:
	s_andn2_b64 vcc, exec, s[34:35]
	s_cbranch_vccnz .LBB0_225
	s_add_i32 s6, s33, 0xffff0400
	s_cmpk_gt_u32 s6, 0x9ff
	s_cselect_b64 s[72:73], -1, 0
	s_and_b64 s[34:35], s[72:73], exec
	s_cselect_b32 s34, 0xf600, 0
	s_add_i32 s6, s34, s6
	s_sext_i32_i16 s34, s6
	s_mulk_i32 s34, 0x6667
	s_lshr_b32 s35, s34, 31
	s_ashr_i32 s34, s34, 21
	s_add_i32 s74, s34, s35
	s_mov_b64 s[34:35], s[0:1]
	s_load_dwordx2 s[34:35], s[34:35], 0x78
	s_mul_i32 s36, s74, 0x50
	s_sub_i32 s6, s6, s36
	s_and_b64 s[36:37], s[72:73], exec
	s_cselect_b32 s36, 0x2800000, 0
	s_sext_i32_i16 s6, s6
	s_waitcnt lgkmcnt(0)
	s_add_u32 s75, s34, s36
	s_addc_u32 s35, s35, 0
	s_lshl_b32 s34, s74, 6
	s_lshl_b32 s36, s6, 6
	s_and_b64 s[72:73], s[72:73], exec
	s_cselect_b32 s6, 0x1400000, 0
	s_add_u32 s6, s30, s6
	s_addc_u32 s74, s31, 0
	s_ashr_i32 s37, s36, 31
	s_lshl_b64 s[72:73], s[36:37], 2
	s_add_u32 s72, s75, s72
	s_addc_u32 s73, s35, s73
	v_add_u32_e32 v1, s34, v2
	v_lshl_add_u64 v[38:39], s[72:73], 0, v[4:5]
	v_mad_i64_i32 v[30:31], s[72:73], v1, s55, v[38:39]
	v_add_co_u32_e32 v10, vcc, s55, v30
	v_add_u32_e32 v1, 32, v1
	s_nop 0
	v_addc_co_u32_e32 v11, vcc, 0, v31, vcc
	v_add_co_u32_e32 v14, vcc, s47, v30
	v_mad_i64_i32 v[62:63], s[72:73], v1, s55, v[38:39]
	s_nop 0
	v_addc_co_u32_e32 v15, vcc, 0, v31, vcc
	v_add_co_u32_e32 v18, vcc, s56, v30
	global_load_dwordx4 v[6:9], v[30:31], off nt
	s_nop 0
	global_load_dwordx4 v[10:13], v[10:11], off nt
	v_addc_co_u32_e32 v19, vcc, 0, v31, vcc
	v_add_co_u32_e32 v22, vcc, s57, v30
	global_load_dwordx4 v[14:17], v[14:15], off nt
	s_nop 0
	global_load_dwordx4 v[18:21], v[18:19], off nt
	v_addc_co_u32_e32 v23, vcc, 0, v31, vcc
	v_add_co_u32_e32 v26, vcc, s58, v30
	s_ashr_i32 s35, s34, 31
	s_nop 0
	v_addc_co_u32_e32 v27, vcc, 0, v31, vcc
	v_add_co_u32_e32 v32, vcc, s59, v30
	global_load_dwordx4 v[22:25], v[22:23], off nt
	s_nop 0
	global_load_dwordx4 v[26:29], v[26:27], off nt
	v_addc_co_u32_e32 v33, vcc, 0, v31, vcc
	v_add_co_u32_e32 v34, vcc, s60, v30
	s_lshl_b64 s[34:35], s[34:35], 1
	s_nop 0
	v_addc_co_u32_e32 v35, vcc, 0, v31, vcc
	v_add_co_u32_e32 v42, vcc, s55, v62
	global_load_dwordx4 v[30:33], v[32:33], off nt
	s_nop 0
	global_load_dwordx4 v[34:37], v[34:35], off nt
	v_addc_co_u32_e32 v43, vcc, 0, v63, vcc
	v_add_co_u32_e32 v46, vcc, s47, v62
	global_load_dwordx4 v[38:41], v[62:63], off nt
	s_nop 0
	global_load_dwordx4 v[42:45], v[42:43], off nt
	v_addc_co_u32_e32 v47, vcc, 0, v63, vcc
	v_add_co_u32_e32 v50, vcc, s56, v62
	s_add_u32 s34, s6, s34
	s_nop 0
	v_addc_co_u32_e32 v51, vcc, 0, v63, vcc
	v_add_co_u32_e32 v54, vcc, s57, v62
	global_load_dwordx4 v[46:49], v[46:47], off nt
	s_nop 0
	global_load_dwordx4 v[50:53], v[50:51], off nt
	v_addc_co_u32_e32 v55, vcc, 0, v63, vcc
	v_add_co_u32_e32 v58, vcc, s58, v62
	v_or_b32_e32 v74, s36, v0
	s_nop 0
	v_addc_co_u32_e32 v59, vcc, 0, v63, vcc
	v_add_co_u32_e32 v64, vcc, s59, v62
	global_load_dwordx4 v[54:57], v[54:55], off nt
	s_nop 0
	global_load_dwordx4 v[58:61], v[58:59], off nt
	v_addc_co_u32_e32 v65, vcc, 0, v63, vcc
	v_add_co_u32_e32 v66, vcc, s60, v62
	s_addc_u32 s35, s74, s35
	s_nop 0
	v_addc_co_u32_e32 v67, vcc, 0, v63, vcc
	global_load_dwordx4 v[62:65], v[64:65], off nt
	s_nop 0
	global_load_dwordx4 v[66:69], v[66:67], off nt
	v_lshl_add_u64 v[70:71], v[2:3], 1, s[34:35]
	v_ashrrev_i32_e32 v75, 31, v74
	v_lshl_add_u64 v[76:77], v[70:71], 0, s[22:23]
	v_lshlrev_b64 v[78:79], 12, v[74:75]
	s_waitcnt vmcnt(14)
	v_cvt_pk_bf16_f32 v70, v6, v10
	v_lshl_add_u64 v[78:79], v[76:77], 0, v[78:79]
	v_or_b32_e32 v6, 1, v74
	s_waitcnt vmcnt(12)
	v_cvt_pk_bf16_f32 v71, v14, v18
	s_waitcnt vmcnt(10)
	v_cvt_pk_bf16_f32 v72, v22, v26
	s_waitcnt vmcnt(8)
	v_cvt_pk_bf16_f32 v73, v30, v34
	global_store_dwordx4 v[78:79], v[70:73], off sc1
	s_nop 1
	v_cvt_pk_bf16_f32 v70, v7, v11
	v_ashrrev_i32_e32 v7, 31, v6
	v_lshlrev_b64 v[6:7], 12, v[6:7]
	v_lshl_add_u64 v[10:11], v[76:77], 0, v[6:7]
	v_or_b32_e32 v6, 2, v74
	v_ashrrev_i32_e32 v7, 31, v6
	v_lshlrev_b64 v[6:7], 12, v[6:7]
	v_cvt_pk_bf16_f32 v71, v15, v19
	v_cvt_pk_bf16_f32 v72, v23, v27
	v_cvt_pk_bf16_f32 v73, v31, v35
	global_store_dwordx4 v[10:11], v[70:73], off sc1
	v_lshl_add_u64 v[14:15], v[76:77], 0, v[6:7]
	s_nop 0
	v_cvt_pk_bf16_f32 v70, v8, v12
	v_or_b32_e32 v12, 3, v74
	v_cvt_pk_bf16_f32 v71, v16, v20
	v_cvt_pk_bf16_f32 v72, v24, v28
	v_cvt_pk_bf16_f32 v73, v32, v36
	global_store_dwordx4 v[14:15], v[70:73], off sc1
	v_cvt_pk_bf16_f32 v6, v9, v13
	v_ashrrev_i32_e32 v13, 31, v12
	v_lshlrev_b64 v[12:13], 12, v[12:13]
	v_cvt_pk_bf16_f32 v7, v17, v21
	v_cvt_pk_bf16_f32 v8, v25, v29
	v_cvt_pk_bf16_f32 v9, v33, v37
	v_lshl_add_u64 v[12:13], v[76:77], 0, v[12:13]
	global_store_dwordx4 v[12:13], v[6:9], off sc1
	s_waitcnt vmcnt(10)
	s_nop 0
	v_cvt_pk_bf16_f32 v6, v38, v42
	s_waitcnt vmcnt(8)
	v_cvt_pk_bf16_f32 v7, v46, v50
	s_waitcnt vmcnt(6)
	v_cvt_pk_bf16_f32 v8, v54, v58
	s_waitcnt vmcnt(4)
	v_cvt_pk_bf16_f32 v9, v62, v66
	global_store_dwordx4 v[78:79], v[6:9], off offset:64 sc1
	s_nop 1
	v_cvt_pk_bf16_f32 v6, v39, v43
	v_cvt_pk_bf16_f32 v7, v47, v51
	v_cvt_pk_bf16_f32 v8, v55, v59
	v_cvt_pk_bf16_f32 v9, v63, v67
	global_store_dwordx4 v[10:11], v[6:9], off offset:64 sc1
	s_nop 1
	v_cvt_pk_bf16_f32 v6, v40, v44
	v_cvt_pk_bf16_f32 v7, v48, v52
	v_cvt_pk_bf16_f32 v8, v56, v60
	v_cvt_pk_bf16_f32 v9, v64, v68
	global_store_dwordx4 v[14:15], v[6:9], off offset:64 sc1
	s_nop 1
	v_cvt_pk_bf16_f32 v6, v41, v45
	v_cvt_pk_bf16_f32 v7, v49, v53
	v_cvt_pk_bf16_f32 v8, v57, v61
	v_cvt_pk_bf16_f32 v9, v65, v69
	global_store_dwordx4 v[12:13], v[6:9], off offset:64 sc1

; __device__ __forceinline__ unsigned cvt_pk_bf16(float lo, float hi) { unsigned r; asm volatile("v_cvt_pk_bf16_f32 %0, %1, %2" : "=v"(r) : "v"(lo), "v"(hi)); return r; }
; #define INP(i) ((const float*)(const GASP float*)kargs()[(i)])
; __device__ __forceinline__ void tr_item(const float* W, int ldw, int k0, int n0, bf16* WT, int ldk, int drow0, int lane) {
;     const int n4 = (lane & 15) * 4, kg = lane >> 4; f32x4 v[2][8];
; #pragma unroll
;     for (int kh = 0; kh < 2; ++kh) { const float* src = W + (size_t)(k0 + kh * 32 + kg * 8) * ldw + n0 + n4;
; #pragma unroll
;         for (int i = 0; i < 8; ++i) v[kh][i] = __builtin_nontemporal_load((const f32x4*)(src + (size_t)i * ldw)); }
; #pragma unroll
;     for (int kh = 0; kh < 2; ++kh)
; #pragma unroll
;         for (int e = 0; e < 4; ++e) { u32x4 o; o.x = cvt_pk_bf16(v[kh][0][e], v[kh][1][e]); o.y = cvt_pk_bf16(v[kh][2][e], v[kh][3][e]); o.z = cvt_pk_bf16(v[kh][4][e], v[kh][5][e]); o.w = cvt_pk_bf16(v[kh][6][e], v[kh][7][e]);
;             *(u32x4*)(WT + (size_t)(drow0 + n4 + e) * ldk + k0 + kh * 32 + kg * 8) = o; }
; }
; __device__ __forceinline__ void conv_item(int it, int lane) {
;     ...
;     if (r < 8 * IT_D) { const int idx = r / IT_D; r -= idx * IT_D; const int kb = r / 32, nb = r % 32;
;         tr_item(INP(I_WD) + (size_t)idx * 5376 * 2048, 2048, 64 * kb, 64 * nb, (bf16*)(ws + WS_WD) + (size_t)idx * 2048 * 5376, 5376, 64 * nb, lane); return; }
.LBB0_226:
	s_andn2_b64 vcc, exec, s[34:35]
	s_cbranch_vccnz .LBB0_228
	s_add_i32 s6, s33, 0xffff5800
	s_bfe_u32 s34, s6, 0x100007
	s_mulk_i32 s34, 0xc31
	s_lshr_b32 s37, s34, 16
	s_mul_i32 s34, s37, 0xf580
	s_add_i32 s6, s34, s6
	s_sext_i32_i16 s34, s6
	s_bfe_u32 s34, s34, 0x5001a
	s_add_i32 s36, s6, s34
	s_mov_b64 s[34:35], s[0:1]
	s_load_dwordx2 s[34:35], s[34:35], 0x70
	s_sext_i32_i16 s72, s36
	s_and_b32 s36, s36, 0xffe0
	s_sub_i32 s6, s6, s36
	s_mul_i32 s36, s37, 0x2a00000
	s_waitcnt lgkmcnt(0)
	s_add_u32 s74, s34, s36
	s_sext_i32_i16 s6, s6
	s_addc_u32 s35, s35, 0
	s_lshl_b32 s34, s72, 1
	s_andn2_b32 s34, s34, 63
	s_lshl_b32 s36, s6, 6
	s_mul_i32 s37, s37, 0x1500000
	s_add_u32 s6, s30, s37
	s_addc_u32 s75, s31, 0
	s_ashr_i32 s37, s36, 31
	s_lshl_b64 s[72:73], s[36:37], 2
	v_add_u32_e32 v38, s34, v2
	s_add_u32 s72, s74, s72
	s_addc_u32 s73, s35, s73
	v_ashrrev_i32_e32 v39, 31, v38
	v_lshl_add_u64 v[40:41], s[72:73], 0, v[4:5]
	v_lshlrev_b64 v[6:7], 13, v[38:39]
	v_lshl_add_u64 v[30:31], v[40:41], 0, v[6:7]
	v_add_co_u32_e32 v10, vcc, s43, v30
	v_add_u32_e32 v38, 32, v38
	s_nop 0
	v_addc_co_u32_e32 v11, vcc, 0, v31, vcc
	v_add_co_u32_e32 v14, vcc, s44, v30
	v_ashrrev_i32_e32 v39, 31, v38
	s_nop 0
	v_addc_co_u32_e32 v15, vcc, 0, v31, vcc
	v_add_co_u32_e32 v18, vcc, s45, v30
	v_lshlrev_b64 v[38:39], 13, v[38:39]
	s_nop 0
	v_addc_co_u32_e32 v19, vcc, 0, v31, vcc
	v_add_co_u32_e32 v22, vcc, s46, v30
	v_lshl_add_u64 v[62:63], v[40:41], 0, v[38:39]
	s_nop 0
	v_addc_co_u32_e32 v23, vcc, 0, v31, vcc
	v_add_co_u32_e32 v26, vcc, s47, v30
	global_load_dwordx4 v[6:9], v[30:31], off nt
	s_nop 0
	global_load_dwordx4 v[10:13], v[10:11], off nt
	v_addc_co_u32_e32 v27, vcc, 0, v31, vcc
	v_add_co_u32_e32 v32, vcc, s48, v30
	global_load_dwordx4 v[14:17], v[14:15], off nt
	s_nop 0
	global_load_dwordx4 v[18:21], v[18:19], off nt
	v_addc_co_u32_e32 v33, vcc, 0, v31, vcc
	v_add_co_u32_e32 v34, vcc, s49, v30
	global_load_dwordx4 v[22:25], v[22:23], off nt
	s_nop 0
	global_load_dwordx4 v[26:29], v[26:27], off nt
	v_addc_co_u32_e32 v35, vcc, 0, v31, vcc
	v_add_co_u32_e32 v42, vcc, s43, v62
	global_load_dwordx4 v[30:33], v[32:33], off nt
	s_nop 0
	global_load_dwordx4 v[34:37], v[34:35], off nt
	v_addc_co_u32_e32 v43, vcc, 0, v63, vcc
	v_add_co_u32_e32 v46, vcc, s44, v62
	global_load_dwordx4 v[38:41], v[62:63], off nt
	s_nop 0
	global_load_dwordx4 v[42:45], v[42:43], off nt
	v_addc_co_u32_e32 v47, vcc, 0, v63, vcc
	v_add_co_u32_e32 v50, vcc, s45, v62
	s_ashr_i32 s35, s34, 31
	s_nop 0
	v_addc_co_u32_e32 v51, vcc, 0, v63, vcc
	v_add_co_u32_e32 v54, vcc, s46, v62
	global_load_dwordx4 v[46:49], v[46:47], off nt
	s_nop 0
	global_load_dwordx4 v[50:53], v[50:51], off nt
	v_addc_co_u32_e32 v55, vcc, 0, v63, vcc
	v_add_co_u32_e32 v58, vcc, s47, v62
	s_lshl_b64 s[34:35], s[34:35], 1
	s_nop 0
	v_addc_co_u32_e32 v59, vcc, 0, v63, vcc
	v_add_co_u32_e32 v64, vcc, s48, v62
	global_load_dwordx4 v[54:57], v[54:55], off nt
	s_nop 0
	global_load_dwordx4 v[58:61], v[58:59], off nt
	v_addc_co_u32_e32 v65, vcc, 0, v63, vcc
	v_add_co_u32_e32 v66, vcc, s49, v62
	v_or_b32_e32 v1, s36, v0
	s_nop 0
	v_addc_co_u32_e32 v67, vcc, 0, v63, vcc
	global_load_dwordx4 v[62:65], v[64:65], off nt
	s_nop 0
	global_load_dwordx4 v[66:69], v[66:67], off nt
	s_add_u32 s34, s6, s34
	s_addc_u32 s35, s75, s35
	v_mul_i32_i24_e32 v76, 0x1500, v1
	v_lshl_add_u64 v[74:75], v[2:3], 1, s[34:35]
	v_ashrrev_i32_e32 v77, 31, v76
	v_lshl_add_u64 v[74:75], v[76:77], 1, v[74:75]
	v_add_co_u32_e32 v78, vcc, s62, v74
	s_waitcnt vmcnt(14)
	v_cvt_pk_bf16_f32 v70, v6, v10
	s_nop 0
	v_addc_co_u32_e32 v79, vcc, 0, v75, vcc
	v_add_co_u32_e32 v10, vcc, s63, v74
	s_waitcnt vmcnt(12)
	v_cvt_pk_bf16_f32 v71, v14, v18
	s_waitcnt vmcnt(10)
	v_cvt_pk_bf16_f32 v72, v22, v26
	s_waitcnt vmcnt(8)
	v_cvt_pk_bf16_f32 v73, v30, v34
	global_store_dwordx4 v[78:79], v[70:73], off sc1
	v_lshl_add_u64 v[76:77], v[74:75], 0, s[26:27]
	s_nop 0
	v_cvt_pk_bf16_f32 v70, v7, v11
	v_addc_co_u32_e32 v11, vcc, 0, v75, vcc
	v_add_co_u32_e32 v14, vcc, s64, v74
	v_cvt_pk_bf16_f32 v71, v15, v19
	v_cvt_pk_bf16_f32 v72, v23, v27
	v_cvt_pk_bf16_f32 v73, v31, v35
	global_store_dwordx4 v[10:11], v[70:73], off offset:2560 sc1
	s_nop 0
	v_addc_co_u32_e32 v15, vcc, 0, v75, vcc
	v_cvt_pk_bf16_f32 v70, v8, v12
	v_add_co_u32_e32 v12, vcc, s65, v74
	v_cvt_pk_bf16_f32 v71, v16, v20
	v_cvt_pk_bf16_f32 v72, v24, v28
	v_cvt_pk_bf16_f32 v73, v32, v36
	global_store_dwordx4 v[14:15], v[70:73], off offset:1024 sc1
	v_cvt_pk_bf16_f32 v6, v9, v13
	v_cvt_pk_bf16_f32 v7, v17, v21
	v_cvt_pk_bf16_f32 v8, v25, v29
	v_cvt_pk_bf16_f32 v9, v33, v37
	s_nop 0
	v_addc_co_u32_e32 v13, vcc, 0, v75, vcc
	global_store_dwordx4 v[12:13], v[6:9], off offset:3584 sc1
	s_waitcnt vmcnt(10)
	s_nop 0
	v_cvt_pk_bf16_f32 v6, v38, v42
	s_waitcnt vmcnt(8)
	v_cvt_pk_bf16_f32 v7, v46, v50
	s_waitcnt vmcnt(6)
	v_cvt_pk_bf16_f32 v8, v54, v58
	s_waitcnt vmcnt(4)
	v_cvt_pk_bf16_f32 v9, v62, v66
	global_store_dwordx4 v[76:77], v[6:9], off offset:64 sc1
	s_nop 1
	v_cvt_pk_bf16_f32 v6, v39, v43
	v_cvt_pk_bf16_f32 v7, v47, v51
	v_cvt_pk_bf16_f32 v8, v55, v59
	v_cvt_pk_bf16_f32 v9, v63, v67
	global_store_dwordx4 v[10:11], v[6:9], off offset:2624 sc1
	s_nop 1
	v_cvt_pk_bf16_f32 v6, v40, v44
	v_cvt_pk_bf16_f32 v7, v48, v52
	v_cvt_pk_bf16_f32 v8, v56, v60
	v_cvt_pk_bf16_f32 v9, v64, v68
	global_store_dwordx4 v[14:15], v[6:9], off offset:1088 sc1
	s_nop 1
	v_cvt_pk_bf16_f32 v6, v41, v45
	v_cvt_pk_bf16_f32 v7, v49, v53
	v_cvt_pk_bf16_f32 v8, v57, v61
	v_cvt_pk_bf16_f32 v9, v65, v69
	global_store_dwordx4 v[12:13], v[6:9], off offset:3648 sc1

; #define INP(i) ((const float*)(const GASP float*)kargs()[(i)])
; __device__ __forceinline__ void conv_item(int it, int lane) {
;     unsigned char* ws = WSP; int r = it;
;     if (r < 8 * IT_GU) { const int idx = r / IT_GU; r -= idx * IT_GU; const int kb = r / 168, nb = r % 168, n0 = 64 * nb;
;         const int drow = n0 < DFF ? (n0 >> 7) * 256 + (n0 & 127) : ((n0 - DFF) >> 7) * 256 + 128 + ((n0 - DFF) & 127);
;         tr_item(INP(I_WGU) + (size_t)idx * 2048 * 10752, 10752, 64 * kb, n0, (bf16*)(ws + WS_WGU) + (size_t)idx * 10752 * 2048, 2048, drow, lane); return; }
;     r -= 8 * IT_GU;
;     if (r < 8 * IT_D) { const int idx = r / IT_D; r -= idx * IT_D; const int kb = r / 32, nb = r % 32;
;         tr_item(INP(I_WD) + (size_t)idx * 5376 * 2048, 2048, 64 * kb, 64 * nb, (bf16*)(ws + WS_WD) + (size_t)idx * 2048 * 5376, 5376, 64 * nb, lane); return; }
;     r -= 8 * IT_D;
;     if (r < 2 * IT_INAB) { const int idx = r / IT_INAB; r -= idx * IT_INAB; const int kb = r / 80, nb = r % 80;
;         tr_item(INP(I_WINAB) + (size_t)idx * 2048 * 5120, 5120, 64 * kb, 64 * nb, (bf16*)(ws + WS_WINAB) + (size_t)idx * 5120 * 2048, 2048, 64 * nb, lane); return; }
;     r -= 2 * IT_INAB;
;     if (r < 2 * IT_GLU) { const int idx = r / IT_GLU; r -= idx * IT_GLU; const int kb = r / 16, nb = r % 16;
;         tr_item(INP(I_WGLU) + (size_t)idx * 1024 * 1024, 1024, 64 * kb, 64 * nb, (bf16*)(ws + WS_WGLU) + (size_t)idx * 1024 * 1024, 1024, 64 * nb, lane); return; }
;     r -= 2 * IT_GLU;
;     if (r < 2 * IT_OUTAB) { const int idx = r / IT_OUTAB; r -= idx * IT_OUTAB; const int kb = r / 32, nb = r % 32;
;         tr_item(INP(I_WOUTAB) + (size_t)idx * 2048 * 2048, 2048, 64 * kb, 64 * nb, (bf16*)(ws + WS_WOUTAB) + (size_t)idx * 2048 * 2048, 2048, 64 * nb, lane); return; }
;     r -= 2 * IT_OUTAB;
;     if (r < 2 * IT_INC) { const int idx = r / IT_INC; r -= idx * IT_INC; const int kb = r / 80, nb = r % 80;
;         tr_item(INP(I_WINC) + (size_t)idx * 2048 * 5120, 5120, 64 * kb, 64 * nb, (bf16*)(ws + WS_WINC) + (size_t)idx * 5120 * 2048, 2048, 64 * nb, lane); return; }
;     r -= 2 * IT_INC;
;     { const int idx = r / IT_OUTC; r -= idx * IT_OUTC; const int kb = r / 32, nb = r % 32;
;       tr_item(INP(I_WOUTC) + (size_t)idx * 2560 * 2048, 2048, 64 * kb, 64 * nb, (bf16*)(ws + WS_WOUTC) + (size_t)idx * 2048 * 2560, 2560, 64 * nb, lane); }
.LBB0_277:
	s_cmpk_gt_u32 s33, 0xfbff
	s_cbranch_scc0 .LBB0_295
	s_cmp_gt_u32 s33, 0x10fff
	s_cbranch_scc0 .LBB0_292
	s_cmp_gt_u32 s33, 0x111ff
	s_cbranch_scc0 .LBB0_289
	s_cmp_gt_u32 s33, 0x119ff
	s_cbranch_scc0 .LBB0_286
	s_cmp_gt_u32 s33, 0x12dff
	s_cbranch_scc0 .LBB0_283
	s_add_i32 s10, s33, 0xfffed200
	s_mul_hi_u32 s36, s10, 0xcccccccd
	s_lshr_b32 s39, s36, 10
	s_mul_i32 s36, s39, 0xfffffb00
	s_add_i32 s10, s36, s10
	s_ashr_i32 s36, s10, 31
	s_lshr_b32 s36, s36, 27
	s_add_i32 s38, s10, s36
	s_mov_b64 s[36:37], s[0:1]
	s_load_dwordx2 s[36:37], s[36:37], 0x128
	s_and_b32 s73, s38, 0x3ffffe0
	s_sub_i32 s10, s10, s73
	s_mul_i32 s74, s39, 0x1400000
	s_mul_hi_u32 s73, s39, 0x1400000
	s_waitcnt lgkmcnt(0)
	s_add_u32 s76, s36, s74
	s_addc_u32 s37, s37, s73
	s_lshl_b32 s36, s38, 1
	s_andn2_b32 s36, s36, 63
	s_lshl_b32 s38, s10, 6
	s_mul_hi_u32 s10, s39, 0xa00000
	s_mul_i32 s39, s39, 0xa00000
	s_add_u32 s73, s34, s39
	s_addc_u32 s10, s35, s10
	s_ashr_i32 s39, s38, 31
	s_lshl_b64 s[74:75], s[38:39], 2
	v_add_u32_e32 v38, s36, v2
	s_add_u32 s74, s76, s74
	s_addc_u32 s75, s37, s75
	v_ashrrev_i32_e32 v39, 31, v38
	v_lshl_add_u64 v[40:41], s[74:75], 0, v[4:5]
	v_lshlrev_b64 v[6:7], 13, v[38:39]
	v_lshl_add_u64 v[30:31], v[40:41], 0, v[6:7]
	v_add_co_u32_e32 v10, vcc, s44, v30
	v_add_u32_e32 v38, 32, v38
	s_nop 0
	v_addc_co_u32_e32 v11, vcc, 0, v31, vcc
	v_add_co_u32_e32 v14, vcc, s45, v30
	v_ashrrev_i32_e32 v39, 31, v38
	s_nop 0
	v_addc_co_u32_e32 v15, vcc, 0, v31, vcc
	v_add_co_u32_e32 v18, vcc, s46, v30
	v_lshlrev_b64 v[38:39], 13, v[38:39]
	s_nop 0
	v_addc_co_u32_e32 v19, vcc, 0, v31, vcc
	v_add_co_u32_e32 v22, vcc, s47, v30
	v_lshl_add_u64 v[62:63], v[40:41], 0, v[38:39]
	s_nop 0
	v_addc_co_u32_e32 v23, vcc, 0, v31, vcc
	v_add_co_u32_e32 v26, vcc, s48, v30
	global_load_dwordx4 v[6:9], v[30:31], off nt
	s_nop 0
	global_load_dwordx4 v[10:13], v[10:11], off nt
	v_addc_co_u32_e32 v27, vcc, 0, v31, vcc
	v_add_co_u32_e32 v32, vcc, s49, v30
	global_load_dwordx4 v[14:17], v[14:15], off nt
	s_nop 0
	global_load_dwordx4 v[18:21], v[18:19], off nt
	v_addc_co_u32_e32 v33, vcc, 0, v31, vcc
	v_add_co_u32_e32 v34, vcc, s50, v30
	global_load_dwordx4 v[22:25], v[22:23], off nt
	s_nop 0
	global_load_dwordx4 v[26:29], v[26:27], off nt
	v_addc_co_u32_e32 v35, vcc, 0, v31, vcc
	v_add_co_u32_e32 v42, vcc, s44, v62
	global_load_dwordx4 v[30:33], v[32:33], off nt
	s_nop 0
	global_load_dwordx4 v[34:37], v[34:35], off nt
	v_addc_co_u32_e32 v43, vcc, 0, v63, vcc
	v_add_co_u32_e32 v46, vcc, s45, v62
	global_load_dwordx4 v[38:41], v[62:63], off nt
	s_nop 0
	global_load_dwordx4 v[42:45], v[42:43], off nt
	v_addc_co_u32_e32 v47, vcc, 0, v63, vcc
	v_add_co_u32_e32 v50, vcc, s46, v62
	s_ashr_i32 s37, s36, 31
	s_nop 0
	v_addc_co_u32_e32 v51, vcc, 0, v63, vcc
	v_add_co_u32_e32 v54, vcc, s47, v62
	global_load_dwordx4 v[46:49], v[46:47], off nt
	s_nop 0
	global_load_dwordx4 v[50:53], v[50:51], off nt
	v_addc_co_u32_e32 v55, vcc, 0, v63, vcc
	v_add_co_u32_e32 v58, vcc, s48, v62
	s_lshl_b64 s[36:37], s[36:37], 1
	s_nop 0
	v_addc_co_u32_e32 v59, vcc, 0, v63, vcc
	v_add_co_u32_e32 v64, vcc, s49, v62
	global_load_dwordx4 v[54:57], v[54:55], off nt
	s_nop 0
	global_load_dwordx4 v[58:61], v[58:59], off nt
	v_addc_co_u32_e32 v65, vcc, 0, v63, vcc
	v_add_co_u32_e32 v66, vcc, s50, v62
	v_or_b32_e32 v1, s38, v0
	s_nop 0
	v_addc_co_u32_e32 v67, vcc, 0, v63, vcc
	global_load_dwordx4 v[62:65], v[64:65], off nt
	s_nop 0
	global_load_dwordx4 v[66:69], v[66:67], off nt
	s_add_u32 s36, s73, s36
	s_addc_u32 s37, s10, s37
	v_mul_lo_u32 v76, v1, s42
	v_lshl_add_u64 v[74:75], v[2:3], 1, s[36:37]
	v_ashrrev_i32_e32 v77, 31, v76
	v_lshl_add_u64 v[74:75], v[76:77], 1, v[74:75]
	v_add_co_u32_e32 v78, vcc, s51, v74
	s_waitcnt vmcnt(14)
	v_cvt_pk_bf16_f32 v70, v6, v10
	s_nop 0
	v_addc_co_u32_e32 v79, vcc, 0, v75, vcc
	v_add_co_u32_e32 v10, vcc, s52, v74
	s_waitcnt vmcnt(12)
	v_cvt_pk_bf16_f32 v71, v14, v18
	s_waitcnt vmcnt(10)
	v_cvt_pk_bf16_f32 v72, v22, v26
	s_waitcnt vmcnt(8)
	v_cvt_pk_bf16_f32 v73, v30, v34
	global_store_dwordx4 v[78:79], v[70:73], off sc1
	v_lshl_add_u64 v[76:77], v[74:75], 0, s[12:13]
	s_mov_b64 s[36:37], 0
	v_cvt_pk_bf16_f32 v70, v7, v11
	v_addc_co_u32_e32 v11, vcc, 0, v75, vcc
	v_add_co_u32_e32 v14, vcc, s53, v74
	v_cvt_pk_bf16_f32 v71, v15, v19
	v_cvt_pk_bf16_f32 v72, v23, v27
	v_cvt_pk_bf16_f32 v73, v31, v35
	global_store_dwordx4 v[10:11], v[70:73], off offset:1024 sc1
	s_nop 0
	v_addc_co_u32_e32 v15, vcc, 0, v75, vcc
	v_cvt_pk_bf16_f32 v70, v8, v12
	v_add_co_u32_e32 v12, vcc, s55, v74
	v_cvt_pk_bf16_f32 v71, v16, v20
	v_cvt_pk_bf16_f32 v72, v24, v28
	v_cvt_pk_bf16_f32 v73, v32, v36
	global_store_dwordx4 v[14:15], v[70:73], off offset:2048 sc1
	v_cvt_pk_bf16_f32 v6, v9, v13
	v_cvt_pk_bf16_f32 v7, v17, v21
	v_cvt_pk_bf16_f32 v8, v25, v29
	v_cvt_pk_bf16_f32 v9, v33, v37
	s_nop 0
	v_addc_co_u32_e32 v13, vcc, 0, v75, vcc
	global_store_dwordx4 v[12:13], v[6:9], off offset:3072 sc1
	s_waitcnt vmcnt(10)
	s_nop 0
	v_cvt_pk_bf16_f32 v6, v38, v42
	s_waitcnt vmcnt(8)
	v_cvt_pk_bf16_f32 v7, v46, v50
	s_waitcnt vmcnt(6)
	v_cvt_pk_bf16_f32 v8, v54, v58
	s_waitcnt vmcnt(4)
	v_cvt_pk_bf16_f32 v9, v62, v66
	global_store_dwordx4 v[76:77], v[6:9], off offset:64 sc1
	s_nop 1
	v_cvt_pk_bf16_f32 v6, v39, v43
	v_cvt_pk_bf16_f32 v7, v47, v51
	v_cvt_pk_bf16_f32 v8, v55, v59
	v_cvt_pk_bf16_f32 v9, v63, v67
	global_store_dwordx4 v[10:11], v[6:9], off offset:1088 sc1
	s_nop 1
	v_cvt_pk_bf16_f32 v6, v40, v44
	v_cvt_pk_bf16_f32 v7, v48, v52
	v_cvt_pk_bf16_f32 v8, v56, v60
	v_cvt_pk_bf16_f32 v9, v64, v68
	global_store_dwordx4 v[14:15], v[6:9], off offset:2112 sc1
	s_nop 1
	v_cvt_pk_bf16_f32 v6, v41, v45
	v_cvt_pk_bf16_f32 v7, v49, v53
	v_cvt_pk_bf16_f32 v8, v57, v61
	v_cvt_pk_bf16_f32 v9, v65, v69
	global_store_dwordx4 v[12:13], v[6:9], off offset:3136 sc1
; __device__ __forceinline__ unsigned cvt_pk_bf16(float lo, float hi) { unsigned r; asm volatile("v_cvt_pk_bf16_f32 %0, %1, %2" : "=v"(r) : "v"(lo), "v"(hi)); return r; }
; #define INP(i) ((const float*)(const GASP float*)kargs()[(i)])
; __device__ __forceinline__ void tr_item(const float* W, int ldw, int k0, int n0, bf16* WT, int ldk, int drow0, int lane) {
;     const int n4 = (lane & 15) * 4, kg = lane >> 4; f32x4 v[2][8];
; #pragma unroll
;     for (int kh = 0; kh < 2; ++kh) { const float* src = W + (size_t)(k0 + kh * 32 + kg * 8) * ldw + n0 + n4;
; #pragma unroll
;         for (int i = 0; i < 8; ++i) v[kh][i] = __builtin_nontemporal_load((const f32x4*)(src + (size_t)i * ldw)); }
; #pragma unroll
;     for (int kh = 0; kh < 2; ++kh)
; #pragma unroll
;         for (int e = 0; e < 4; ++e) { u32x4 o; o.x = cvt_pk_bf16(v[kh][0][e], v[kh][1][e]); o.y = cvt_pk_bf16(v[kh][2][e], v[kh][3][e]); o.z = cvt_pk_bf16(v[kh][4][e], v[kh][5][e]); o.w = cvt_pk_bf16(v[kh][6][e], v[kh][7][e]);
;             *(u32x4*)(WT + (size_t)(drow0 + n4 + e) * ldk + k0 + kh * 32 + kg * 8) = o; }
; }
; __device__ __forceinline__ void conv_item(int it, int lane) {
;     ...
;     if (r < 2 * IT_INC) { const int idx = r / IT_INC; r -= idx * IT_INC; const int kb = r / 80, nb = r % 80;
;         tr_item(INP(I_WINC) + (size_t)idx * 2048 * 5120, 5120, 64 * kb, 64 * nb, (bf16*)(ws + WS_WINC) + (size_t)idx * 5120 * 2048, 2048, 64 * nb, lane); return; }
.LBB0_283:
	s_andn2_b64 vcc, exec, s[36:37]
	s_cbranch_vccnz .LBB0_285
	s_add_i32 s10, s33, 0xfffee600
	s_cmpk_gt_u32 s10, 0x9ff
	s_cselect_b64 s[74:75], -1, 0
	s_and_b64 s[36:37], s[74:75], exec
	s_cselect_b32 s36, 0xf600, 0
	s_add_i32 s10, s36, s10
	s_sext_i32_i16 s36, s10
	s_mulk_i32 s36, 0x6667
	s_lshr_b32 s37, s36, 31
	s_ashr_i32 s36, s36, 21
	s_add_i32 s73, s36, s37
	s_mov_b64 s[36:37], s[0:1]
	s_load_dwordx2 s[36:37], s[36:37], 0xe8
	s_mul_i32 s38, s73, 0x50
	s_sub_i32 s10, s10, s38
	s_and_b64 s[38:39], s[74:75], exec
	s_cselect_b32 s38, 0x2800000, 0
	s_sext_i32_i16 s10, s10
	s_waitcnt lgkmcnt(0)
	s_add_u32 s76, s36, s38
	s_addc_u32 s37, s37, 0
	s_lshl_b32 s36, s73, 6
	s_lshl_b32 s38, s10, 6
	s_and_b64 s[74:75], s[74:75], exec
	s_cselect_b32 s10, 0x1400000, 0
	s_add_u32 s10, s34, s10
	s_addc_u32 s73, s35, 0
	s_ashr_i32 s39, s38, 31
	s_lshl_b64 s[74:75], s[38:39], 2
	s_add_u32 s74, s76, s74
	s_addc_u32 s75, s37, s75
	v_add_u32_e32 v1, s36, v2
	v_lshl_add_u64 v[38:39], s[74:75], 0, v[4:5]
	v_mad_i64_i32 v[30:31], s[74:75], v1, s56, v[38:39]
	v_add_co_u32_e32 v10, vcc, s56, v30
	v_add_u32_e32 v1, 32, v1
	s_nop 0
	v_addc_co_u32_e32 v11, vcc, 0, v31, vcc
	v_add_co_u32_e32 v14, vcc, s48, v30
	v_mad_i64_i32 v[62:63], s[74:75], v1, s56, v[38:39]
	s_nop 0
	v_addc_co_u32_e32 v15, vcc, 0, v31, vcc
	v_add_co_u32_e32 v18, vcc, s57, v30
	global_load_dwordx4 v[6:9], v[30:31], off nt
	s_nop 0
	global_load_dwordx4 v[10:13], v[10:11], off nt
	v_addc_co_u32_e32 v19, vcc, 0, v31, vcc
	v_add_co_u32_e32 v22, vcc, s58, v30
	global_load_dwordx4 v[14:17], v[14:15], off nt
	s_nop 0
	global_load_dwordx4 v[18:21], v[18:19], off nt
	v_addc_co_u32_e32 v23, vcc, 0, v31, vcc
	v_add_co_u32_e32 v26, vcc, s59, v30
	s_ashr_i32 s37, s36, 31
	s_nop 0
	v_addc_co_u32_e32 v27, vcc, 0, v31, vcc
	v_add_co_u32_e32 v32, vcc, s60, v30
	global_load_dwordx4 v[22:25], v[22:23], off nt
	s_nop 0
	global_load_dwordx4 v[26:29], v[26:27], off nt
	v_addc_co_u32_e32 v33, vcc, 0, v31, vcc
	v_add_co_u32_e32 v34, vcc, s61, v30
	s_lshl_b64 s[36:37], s[36:37], 1
	s_nop 0
	v_addc_co_u32_e32 v35, vcc, 0, v31, vcc
	v_add_co_u32_e32 v42, vcc, s56, v62
	global_load_dwordx4 v[30:33], v[32:33], off nt
	s_nop 0
	global_load_dwordx4 v[34:37], v[34:35], off nt
	v_addc_co_u32_e32 v43, vcc, 0, v63, vcc
	v_add_co_u32_e32 v46, vcc, s48, v62
	global_load_dwordx4 v[38:41], v[62:63], off nt
	s_nop 0
	global_load_dwordx4 v[42:45], v[42:43], off nt
	v_addc_co_u32_e32 v47, vcc, 0, v63, vcc
	v_add_co_u32_e32 v50, vcc, s57, v62
	s_add_u32 s36, s10, s36
	s_nop 0
	v_addc_co_u32_e32 v51, vcc, 0, v63, vcc
	v_add_co_u32_e32 v54, vcc, s58, v62
	global_load_dwordx4 v[46:49], v[46:47], off nt
	s_nop 0
	global_load_dwordx4 v[50:53], v[50:51], off nt
	v_addc_co_u32_e32 v55, vcc, 0, v63, vcc
	v_add_co_u32_e32 v58, vcc, s59, v62
	v_or_b32_e32 v74, s38, v0
	s_nop 0
	v_addc_co_u32_e32 v59, vcc, 0, v63, vcc
	v_add_co_u32_e32 v64, vcc, s60, v62
	global_load_dwordx4 v[54:57], v[54:55], off nt
	s_nop 0
	global_load_dwordx4 v[58:61], v[58:59], off nt
	v_addc_co_u32_e32 v65, vcc, 0, v63, vcc
	v_add_co_u32_e32 v66, vcc, s61, v62
	s_addc_u32 s37, s73, s37
	s_nop 0
	v_addc_co_u32_e32 v67, vcc, 0, v63, vcc
	global_load_dwordx4 v[62:65], v[64:65], off nt
	s_nop 0
	global_load_dwordx4 v[66:69], v[66:67], off nt
	v_lshl_add_u64 v[70:71], v[2:3], 1, s[36:37]
	v_ashrrev_i32_e32 v75, 31, v74
	v_lshl_add_u64 v[76:77], v[70:71], 0, s[14:15]
	v_lshlrev_b64 v[78:79], 12, v[74:75]
	s_waitcnt vmcnt(14)
	v_cvt_pk_bf16_f32 v70, v6, v10
	v_lshl_add_u64 v[78:79], v[76:77], 0, v[78:79]
	v_or_b32_e32 v6, 1, v74
	s_waitcnt vmcnt(12)
	v_cvt_pk_bf16_f32 v71, v14, v18
	s_waitcnt vmcnt(10)
	v_cvt_pk_bf16_f32 v72, v22, v26
	s_waitcnt vmcnt(8)
	v_cvt_pk_bf16_f32 v73, v30, v34
	global_store_dwordx4 v[78:79], v[70:73], off sc1
	s_nop 1
	v_cvt_pk_bf16_f32 v70, v7, v11
	v_ashrrev_i32_e32 v7, 31, v6
	v_lshlrev_b64 v[6:7], 12, v[6:7]
	v_lshl_add_u64 v[10:11], v[76:77], 0, v[6:7]
	v_or_b32_e32 v6, 2, v74
	v_ashrrev_i32_e32 v7, 31, v6
	v_lshlrev_b64 v[6:7], 12, v[6:7]
	v_cvt_pk_bf16_f32 v71, v15, v19
	v_cvt_pk_bf16_f32 v72, v23, v27
	v_cvt_pk_bf16_f32 v73, v31, v35
	global_store_dwordx4 v[10:11], v[70:73], off sc1
	v_lshl_add_u64 v[14:15], v[76:77], 0, v[6:7]
	s_nop 0
	v_cvt_pk_bf16_f32 v70, v8, v12
	v_or_b32_e32 v12, 3, v74
	v_cvt_pk_bf16_f32 v71, v16, v20
	v_cvt_pk_bf16_f32 v72, v24, v28
	v_cvt_pk_bf16_f32 v73, v32, v36
	global_store_dwordx4 v[14:15], v[70:73], off sc1
	v_cvt_pk_bf16_f32 v6, v9, v13
	v_ashrrev_i32_e32 v13, 31, v12
	v_lshlrev_b64 v[12:13], 12, v[12:13]
	v_cvt_pk_bf16_f32 v7, v17, v21
	v_cvt_pk_bf16_f32 v8, v25, v29
	v_cvt_pk_bf16_f32 v9, v33, v37
	v_lshl_add_u64 v[12:13], v[76:77], 0, v[12:13]
	global_store_dwordx4 v[12:13], v[6:9], off sc1
	s_waitcnt vmcnt(10)
	s_nop 0
	v_cvt_pk_bf16_f32 v6, v38, v42
	s_waitcnt vmcnt(8)
	v_cvt_pk_bf16_f32 v7, v46, v50
	s_waitcnt vmcnt(6)
	v_cvt_pk_bf16_f32 v8, v54, v58
	s_waitcnt vmcnt(4)
	v_cvt_pk_bf16_f32 v9, v62, v66
	global_store_dwordx4 v[78:79], v[6:9], off offset:64 sc1
	s_nop 1
	v_cvt_pk_bf16_f32 v6, v39, v43
	v_cvt_pk_bf16_f32 v7, v47, v51
	v_cvt_pk_bf16_f32 v8, v55, v59
	v_cvt_pk_bf16_f32 v9, v63, v67
	global_store_dwordx4 v[10:11], v[6:9], off offset:64 sc1
	s_nop 1
	v_cvt_pk_bf16_f32 v6, v40, v44
	v_cvt_pk_bf16_f32 v7, v48, v52
	v_cvt_pk_bf16_f32 v8, v56, v60
	v_cvt_pk_bf16_f32 v9, v64, v68
	global_store_dwordx4 v[14:15], v[6:9], off offset:64 sc1
	s_nop 1
	v_cvt_pk_bf16_f32 v6, v41, v45
	v_cvt_pk_bf16_f32 v7, v49, v53
	v_cvt_pk_bf16_f32 v8, v57, v61
	v_cvt_pk_bf16_f32 v9, v65, v69
	global_store_dwordx4 v[12:13], v[6:9], off offset:64 sc1

; __device__ __forceinline__ unsigned cvt_pk_bf16(float lo, float hi) { unsigned r; asm volatile("v_cvt_pk_bf16_f32 %0, %1, %2" : "=v"(r) : "v"(lo), "v"(hi)); return r; }
; #define INP(i) ((const float*)(const GASP float*)kargs()[(i)])
; __device__ __forceinline__ void tr_item(const float* W, int ldw, int k0, int n0, bf16* WT, int ldk, int drow0, int lane) {
;     const int n4 = (lane & 15) * 4, kg = lane >> 4; f32x4 v[2][8];
; #pragma unroll
;     for (int kh = 0; kh < 2; ++kh) { const float* src = W + (size_t)(k0 + kh * 32 + kg * 8) * ldw + n0 + n4;
; #pragma unroll
;         for (int i = 0; i < 8; ++i) v[kh][i] = __builtin_nontemporal_load((const f32x4*)(src + (size_t)i * ldw)); }
; #pragma unroll
;     for (int kh = 0; kh < 2; ++kh)
; #pragma unroll
;         for (int e = 0; e < 4; ++e) { u32x4 o; o.x = cvt_pk_bf16(v[kh][0][e], v[kh][1][e]); o.y = cvt_pk_bf16(v[kh][2][e], v[kh][3][e]); o.z = cvt_pk_bf16(v[kh][4][e], v[kh][5][e]); o.w = cvt_pk_bf16(v[kh][6][e], v[kh][7][e]);
;             *(u32x4*)(WT + (size_t)(drow0 + n4 + e) * ldk + k0 + kh * 32 + kg * 8) = o; }
; }
; __device__ __forceinline__ void conv_item(int it, int lane) {
;     ...
;     if (r < 2 * IT_OUTAB) { const int idx = r / IT_OUTAB; r -= idx * IT_OUTAB; const int kb = r / 32, nb = r % 32;
;         tr_item(INP(I_WOUTAB) + (size_t)idx * 2048 * 2048, 2048, 64 * kb, 64 * nb, (bf16*)(ws + WS_WOUTAB) + (size_t)idx * 2048 * 2048, 2048, 64 * nb, lane); return; }
.LBB0_286:
	s_andn2_b64 vcc, exec, s[36:37]
	s_cbranch_vccnz .LBB0_288
	s_mov_b64 s[36:37], s[0:1]
	s_load_dwordx2 s[36:37], s[36:37], 0xe0
	s_add_i32 s73, s33, 0xfffeee00
	s_lshr_b32 s10, s73, 10
	s_lshl_b64 s[38:39], s[10:11], 24
	v_mov_b32_e32 v79, v5
	s_waitcnt lgkmcnt(0)
	s_add_u32 s38, s36, s38
	s_addc_u32 s39, s37, s39
	s_lshl_b32 s36, s73, 1
	s_and_b32 s73, s36, 0x7c0
	s_lshl_b32 s36, s33, 6
	s_and_b32 s74, s36, 0x7c0
	s_lshl_b64 s[36:37], s[10:11], 23
	s_add_u32 s10, s34, s36
	s_addc_u32 s75, s35, s37
	s_lshl_b32 s36, s74, 2
	v_add_u32_e32 v38, s73, v2
	s_add_u32 s36, s38, s36
	s_addc_u32 s37, s39, 0
	v_ashrrev_i32_e32 v39, 31, v38
	v_lshl_add_u64 v[40:41], s[36:37], 0, v[4:5]
	v_lshlrev_b64 v[6:7], 13, v[38:39]
	v_lshl_add_u64 v[30:31], v[40:41], 0, v[6:7]
	v_add_co_u32_e32 v10, vcc, s44, v30
	v_add_u32_e32 v38, 32, v38
	s_nop 0
	v_addc_co_u32_e32 v11, vcc, 0, v31, vcc
	v_add_co_u32_e32 v14, vcc, s45, v30
	v_ashrrev_i32_e32 v39, 31, v38
	s_nop 0
	v_addc_co_u32_e32 v15, vcc, 0, v31, vcc
	v_add_co_u32_e32 v18, vcc, s46, v30
	v_lshlrev_b64 v[38:39], 13, v[38:39]
	s_nop 0
	v_addc_co_u32_e32 v19, vcc, 0, v31, vcc
	v_add_co_u32_e32 v22, vcc, s47, v30
	v_lshl_add_u64 v[62:63], v[40:41], 0, v[38:39]
	s_nop 0
	v_addc_co_u32_e32 v23, vcc, 0, v31, vcc
	v_add_co_u32_e32 v26, vcc, s48, v30
	global_load_dwordx4 v[6:9], v[30:31], off nt
	s_nop 0
	global_load_dwordx4 v[10:13], v[10:11], off nt
	v_addc_co_u32_e32 v27, vcc, 0, v31, vcc
	v_add_co_u32_e32 v32, vcc, s49, v30
	global_load_dwordx4 v[14:17], v[14:15], off nt
	s_nop 0
	global_load_dwordx4 v[18:21], v[18:19], off nt
	v_addc_co_u32_e32 v33, vcc, 0, v31, vcc
	v_add_co_u32_e32 v34, vcc, s50, v30
	global_load_dwordx4 v[22:25], v[22:23], off nt
	s_nop 0
	global_load_dwordx4 v[26:29], v[26:27], off nt
	v_addc_co_u32_e32 v35, vcc, 0, v31, vcc
	v_add_co_u32_e32 v42, vcc, s44, v62
	global_load_dwordx4 v[30:33], v[32:33], off nt
	s_nop 0
	global_load_dwordx4 v[34:37], v[34:35], off nt
	v_addc_co_u32_e32 v43, vcc, 0, v63, vcc
	v_add_co_u32_e32 v46, vcc, s45, v62
	global_load_dwordx4 v[38:41], v[62:63], off nt
	s_nop 0
	global_load_dwordx4 v[42:45], v[42:43], off nt
	v_addc_co_u32_e32 v47, vcc, 0, v63, vcc
	v_add_co_u32_e32 v50, vcc, s46, v62
	s_lshl_b32 s36, s73, 1
	s_nop 0
	v_addc_co_u32_e32 v51, vcc, 0, v63, vcc
	v_add_co_u32_e32 v54, vcc, s47, v62
	global_load_dwordx4 v[46:49], v[46:47], off nt
	s_nop 0
	global_load_dwordx4 v[50:53], v[50:51], off nt
	v_addc_co_u32_e32 v55, vcc, 0, v63, vcc
	v_add_co_u32_e32 v58, vcc, s48, v62
	s_add_u32 s36, s10, s36
	s_nop 0
	v_addc_co_u32_e32 v59, vcc, 0, v63, vcc
	v_add_co_u32_e32 v64, vcc, s49, v62
	global_load_dwordx4 v[54:57], v[54:55], off nt
	s_nop 0
	global_load_dwordx4 v[58:61], v[58:59], off nt
	v_addc_co_u32_e32 v65, vcc, 0, v63, vcc
	v_add_co_u32_e32 v66, vcc, s50, v62
	s_addc_u32 s37, s75, 0
	s_nop 0
	v_addc_co_u32_e32 v67, vcc, 0, v63, vcc
	global_load_dwordx4 v[62:65], v[64:65], off nt
	s_nop 0
	global_load_dwordx4 v[66:69], v[66:67], off nt
	v_or_b32_e32 v1, s74, v0
	v_lshl_add_u64 v[74:75], v[2:3], 1, s[36:37]
	v_lshl_add_u64 v[76:77], v[74:75], 0, s[16:17]
	v_lshlrev_b32_e32 v78, 12, v1
	s_waitcnt vmcnt(14)
	v_cvt_pk_bf16_f32 v70, v6, v10
	v_lshl_add_u64 v[80:81], v[76:77], 0, v[78:79]
	s_waitcnt vmcnt(12)
	v_cvt_pk_bf16_f32 v71, v14, v18
	s_waitcnt vmcnt(10)
	v_cvt_pk_bf16_f32 v72, v22, v26
	s_waitcnt vmcnt(8)
	v_cvt_pk_bf16_f32 v73, v30, v34
	global_store_dwordx4 v[80:81], v[70:73], off sc1
	v_or_b32_e32 v10, 0x1000, v78
	v_or_b32_e32 v14, 0x2000, v78
	v_cvt_pk_bf16_f32 v70, v7, v11
	v_mov_b32_e32 v11, v5
	v_cvt_pk_bf16_f32 v71, v15, v19
	v_lshl_add_u64 v[6:7], v[76:77], 0, v[10:11]
	v_mov_b32_e32 v15, v5
	v_cvt_pk_bf16_f32 v72, v23, v27
	v_cvt_pk_bf16_f32 v73, v31, v35
	global_store_dwordx4 v[6:7], v[70:73], off sc1
	v_lshl_add_u64 v[6:7], v[76:77], 0, v[14:15]
	s_nop 0
	v_cvt_pk_bf16_f32 v70, v8, v12
	v_cvt_pk_bf16_f32 v71, v16, v20
	v_cvt_pk_bf16_f32 v72, v24, v28
	v_cvt_pk_bf16_f32 v73, v32, v36
	global_store_dwordx4 v[6:7], v[70:73], off sc1
	v_cvt_pk_bf16_f32 v6, v9, v13
	v_or_b32_e32 v12, 0x3000, v78
	v_mov_b32_e32 v13, v5
	v_cvt_pk_bf16_f32 v7, v17, v21
	v_lshl_add_u64 v[16:17], v[76:77], 0, v[12:13]
	v_cvt_pk_bf16_f32 v8, v25, v29
	v_cvt_pk_bf16_f32 v9, v33, v37
	global_store_dwordx4 v[16:17], v[6:9], off sc1
	v_lshl_add_u64 v[16:17], v[74:75], 0, s[18:19]
	v_lshl_add_u64 v[10:11], v[16:17], 0, v[10:11]
	s_waitcnt vmcnt(10)
	v_cvt_pk_bf16_f32 v6, v38, v42
	s_waitcnt vmcnt(8)
	v_cvt_pk_bf16_f32 v7, v46, v50
	s_waitcnt vmcnt(6)
	v_cvt_pk_bf16_f32 v8, v54, v58
	s_waitcnt vmcnt(4)
	v_cvt_pk_bf16_f32 v9, v62, v66
	global_store_dwordx4 v[80:81], v[6:9], off offset:64 sc1
	s_nop 1
	v_cvt_pk_bf16_f32 v6, v39, v43
	v_cvt_pk_bf16_f32 v7, v47, v51
	v_cvt_pk_bf16_f32 v8, v55, v59
	v_cvt_pk_bf16_f32 v9, v63, v67
	global_store_dwordx4 v[10:11], v[6:9], off sc1
	v_lshl_add_u64 v[10:11], v[16:17], 0, v[14:15]
	s_nop 0
	v_cvt_pk_bf16_f32 v6, v40, v44
	v_cvt_pk_bf16_f32 v7, v48, v52
	v_cvt_pk_bf16_f32 v8, v56, v60
	v_cvt_pk_bf16_f32 v9, v64, v68
	global_store_dwordx4 v[10:11], v[6:9], off sc1
	v_lshl_add_u64 v[10:11], v[16:17], 0, v[12:13]
	s_nop 0
	v_cvt_pk_bf16_f32 v6, v41, v45
	v_cvt_pk_bf16_f32 v7, v49, v53
	v_cvt_pk_bf16_f32 v8, v57, v61
	v_cvt_pk_bf16_f32 v9, v65, v69
	global_store_dwordx4 v[10:11], v[6:9], off sc1

; __device__ __forceinline__ unsigned cvt_pk_bf16(float lo, float hi) { unsigned r; asm volatile("v_cvt_pk_bf16_f32 %0, %1, %2" : "=v"(r) : "v"(lo), "v"(hi)); return r; }
; #define INP(i) ((const float*)(const GASP float*)kargs()[(i)])
; __device__ __forceinline__ void tr_item(const float* W, int ldw, int k0, int n0, bf16* WT, int ldk, int drow0, int lane) {
;     const int n4 = (lane & 15) * 4, kg = lane >> 4; f32x4 v[2][8];
; #pragma unroll
;     for (int kh = 0; kh < 2; ++kh) { const float* src = W + (size_t)(k0 + kh * 32 + kg * 8) * ldw + n0 + n4;
; #pragma unroll
;         for (int i = 0; i < 8; ++i) v[kh][i] = __builtin_nontemporal_load((const f32x4*)(src + (size_t)i * ldw)); }
; #pragma unroll
;     for (int kh = 0; kh < 2; ++kh)
; #pragma unroll
;         for (int e = 0; e < 4; ++e) { u32x4 o; o.x = cvt_pk_bf16(v[kh][0][e], v[kh][1][e]); o.y = cvt_pk_bf16(v[kh][2][e], v[kh][3][e]); o.z = cvt_pk_bf16(v[kh][4][e], v[kh][5][e]); o.w = cvt_pk_bf16(v[kh][6][e], v[kh][7][e]);
;             *(u32x4*)(WT + (size_t)(drow0 + n4 + e) * ldk + k0 + kh * 32 + kg * 8) = o; }
; }
; __device__ __forceinline__ void conv_item(int it, int lane) {
;     ...
;     if (r < 2 * IT_INAB) { const int idx = r / IT_INAB; r -= idx * IT_INAB; const int kb = r / 80, nb = r % 80;
;         tr_item(INP(I_WINAB) + (size_t)idx * 2048 * 5120, 5120, 64 * kb, 64 * nb, (bf16*)(ws + WS_WINAB) + (size_t)idx * 5120 * 2048, 2048, 64 * nb, lane); return; }
.LBB0_292:
	s_andn2_b64 vcc, exec, s[36:37]
	s_cbranch_vccnz .LBB0_294
	s_add_i32 s10, s33, 0xffff0400
	s_cmpk_gt_u32 s10, 0x9ff
	s_cselect_b64 s[74:75], -1, 0
	s_and_b64 s[36:37], s[74:75], exec
	s_cselect_b32 s36, 0xf600, 0
	s_add_i32 s10, s36, s10
	s_sext_i32_i16 s36, s10
	s_mulk_i32 s36, 0x6667
	s_lshr_b32 s37, s36, 31
	s_ashr_i32 s36, s36, 21
	s_add_i32 s73, s36, s37
	s_mov_b64 s[36:37], s[0:1]
	s_load_dwordx2 s[36:37], s[36:37], 0x78
	s_mul_i32 s38, s73, 0x50
	s_sub_i32 s10, s10, s38
	s_and_b64 s[38:39], s[74:75], exec
	s_cselect_b32 s38, 0x2800000, 0
	s_sext_i32_i16 s10, s10
	s_waitcnt lgkmcnt(0)
	s_add_u32 s76, s36, s38
	s_addc_u32 s37, s37, 0
	s_lshl_b32 s36, s73, 6
	s_lshl_b32 s38, s10, 6
	s_and_b64 s[74:75], s[74:75], exec
	s_cselect_b32 s10, 0x1400000, 0
	s_add_u32 s10, s34, s10
	s_addc_u32 s73, s35, 0
	s_ashr_i32 s39, s38, 31
	s_lshl_b64 s[74:75], s[38:39], 2
	s_add_u32 s74, s76, s74
	s_addc_u32 s75, s37, s75
	v_add_u32_e32 v1, s36, v2
	v_lshl_add_u64 v[38:39], s[74:75], 0, v[4:5]
	v_mad_i64_i32 v[30:31], s[74:75], v1, s56, v[38:39]
	v_add_co_u32_e32 v10, vcc, s56, v30
	v_add_u32_e32 v1, 32, v1
	s_nop 0
	v_addc_co_u32_e32 v11, vcc, 0, v31, vcc
	v_add_co_u32_e32 v14, vcc, s48, v30
	v_mad_i64_i32 v[62:63], s[74:75], v1, s56, v[38:39]
	s_nop 0
	v_addc_co_u32_e32 v15, vcc, 0, v31, vcc
	v_add_co_u32_e32 v18, vcc, s57, v30
	global_load_dwordx4 v[6:9], v[30:31], off nt
	s_nop 0
	global_load_dwordx4 v[10:13], v[10:11], off nt
	v_addc_co_u32_e32 v19, vcc, 0, v31, vcc
	v_add_co_u32_e32 v22, vcc, s58, v30
	global_load_dwordx4 v[14:17], v[14:15], off nt
	s_nop 0
	global_load_dwordx4 v[18:21], v[18:19], off nt
	v_addc_co_u32_e32 v23, vcc, 0, v31, vcc
	v_add_co_u32_e32 v26, vcc, s59, v30
	s_ashr_i32 s37, s36, 31
	s_nop 0
	v_addc_co_u32_e32 v27, vcc, 0, v31, vcc
	v_add_co_u32_e32 v32, vcc, s60, v30
	global_load_dwordx4 v[22:25], v[22:23], off nt
	s_nop 0
	global_load_dwordx4 v[26:29], v[26:27], off nt
	v_addc_co_u32_e32 v33, vcc, 0, v31, vcc
	v_add_co_u32_e32 v34, vcc, s61, v30
	s_lshl_b64 s[36:37], s[36:37], 1
	s_nop 0
	v_addc_co_u32_e32 v35, vcc, 0, v31, vcc
	v_add_co_u32_e32 v42, vcc, s56, v62
	global_load_dwordx4 v[30:33], v[32:33], off nt
	s_nop 0
	global_load_dwordx4 v[34:37], v[34:35], off nt
	v_addc_co_u32_e32 v43, vcc, 0, v63, vcc
	v_add_co_u32_e32 v46, vcc, s48, v62
	global_load_dwordx4 v[38:41], v[62:63], off nt
	s_nop 0
	global_load_dwordx4 v[42:45], v[42:43], off nt
	v_addc_co_u32_e32 v47, vcc, 0, v63, vcc
	v_add_co_u32_e32 v50, vcc, s57, v62
	s_add_u32 s36, s10, s36
	s_nop 0
	v_addc_co_u32_e32 v51, vcc, 0, v63, vcc
	v_add_co_u32_e32 v54, vcc, s58, v62
	global_load_dwordx4 v[46:49], v[46:47], off nt
	s_nop 0
	global_load_dwordx4 v[50:53], v[50:51], off nt
	v_addc_co_u32_e32 v55, vcc, 0, v63, vcc
	v_add_co_u32_e32 v58, vcc, s59, v62
	v_or_b32_e32 v74, s38, v0
	s_nop 0
	v_addc_co_u32_e32 v59, vcc, 0, v63, vcc
	v_add_co_u32_e32 v64, vcc, s60, v62
	global_load_dwordx4 v[54:57], v[54:55], off nt
	s_nop 0
	global_load_dwordx4 v[58:61], v[58:59], off nt
	v_addc_co_u32_e32 v65, vcc, 0, v63, vcc
	v_add_co_u32_e32 v66, vcc, s61, v62
	s_addc_u32 s37, s73, s37
	s_nop 0
	v_addc_co_u32_e32 v67, vcc, 0, v63, vcc
	global_load_dwordx4 v[62:65], v[64:65], off nt
	s_nop 0
	global_load_dwordx4 v[66:69], v[66:67], off nt
	v_lshl_add_u64 v[70:71], v[2:3], 1, s[36:37]
	v_ashrrev_i32_e32 v75, 31, v74
	v_lshl_add_u64 v[76:77], v[70:71], 0, s[26:27]
	v_lshlrev_b64 v[78:79], 12, v[74:75]
	s_waitcnt vmcnt(14)
	v_cvt_pk_bf16_f32 v70, v6, v10
	v_lshl_add_u64 v[78:79], v[76:77], 0, v[78:79]
	v_or_b32_e32 v6, 1, v74
	s_waitcnt vmcnt(12)
	v_cvt_pk_bf16_f32 v71, v14, v18
	s_waitcnt vmcnt(10)
	v_cvt_pk_bf16_f32 v72, v22, v26
	s_waitcnt vmcnt(8)
	v_cvt_pk_bf16_f32 v73, v30, v34
	global_store_dwordx4 v[78:79], v[70:73], off sc1
	s_nop 1
	v_cvt_pk_bf16_f32 v70, v7, v11
	v_ashrrev_i32_e32 v7, 31, v6
	v_lshlrev_b64 v[6:7], 12, v[6:7]
	v_lshl_add_u64 v[10:11], v[76:77], 0, v[6:7]
	v_or_b32_e32 v6, 2, v74
	v_ashrrev_i32_e32 v7, 31, v6
	v_lshlrev_b64 v[6:7], 12, v[6:7]
	v_cvt_pk_bf16_f32 v71, v15, v19
	v_cvt_pk_bf16_f32 v72, v23, v27
	v_cvt_pk_bf16_f32 v73, v31, v35
	global_store_dwordx4 v[10:11], v[70:73], off sc1
	v_lshl_add_u64 v[14:15], v[76:77], 0, v[6:7]
	s_nop 0
	v_cvt_pk_bf16_f32 v70, v8, v12
	v_or_b32_e32 v12, 3, v74
	v_cvt_pk_bf16_f32 v71, v16, v20
	v_cvt_pk_bf16_f32 v72, v24, v28
	v_cvt_pk_bf16_f32 v73, v32, v36
	global_store_dwordx4 v[14:15], v[70:73], off sc1
	v_cvt_pk_bf16_f32 v6, v9, v13
	v_ashrrev_i32_e32 v13, 31, v12
	v_lshlrev_b64 v[12:13], 12, v[12:13]
	v_cvt_pk_bf16_f32 v7, v17, v21
	v_cvt_pk_bf16_f32 v8, v25, v29
	v_cvt_pk_bf16_f32 v9, v33, v37
	v_lshl_add_u64 v[12:13], v[76:77], 0, v[12:13]
	global_store_dwordx4 v[12:13], v[6:9], off sc1
	s_waitcnt vmcnt(10)
	s_nop 0
	v_cvt_pk_bf16_f32 v6, v38, v42
	s_waitcnt vmcnt(8)
	v_cvt_pk_bf16_f32 v7, v46, v50
	s_waitcnt vmcnt(6)
	v_cvt_pk_bf16_f32 v8, v54, v58
	s_waitcnt vmcnt(4)
	v_cvt_pk_bf16_f32 v9, v62, v66
	global_store_dwordx4 v[78:79], v[6:9], off offset:64 sc1
	s_nop 1
	v_cvt_pk_bf16_f32 v6, v39, v43
	v_cvt_pk_bf16_f32 v7, v47, v51
	v_cvt_pk_bf16_f32 v8, v55, v59
	v_cvt_pk_bf16_f32 v9, v63, v67
	global_store_dwordx4 v[10:11], v[6:9], off offset:64 sc1
	s_nop 1
	v_cvt_pk_bf16_f32 v6, v40, v44
	v_cvt_pk_bf16_f32 v7, v48, v52
	v_cvt_pk_bf16_f32 v8, v56, v60
	v_cvt_pk_bf16_f32 v9, v64, v68
	global_store_dwordx4 v[14:15], v[6:9], off offset:64 sc1
	s_nop 1
	v_cvt_pk_bf16_f32 v6, v41, v45
	v_cvt_pk_bf16_f32 v7, v49, v53
	v_cvt_pk_bf16_f32 v8, v57, v61
	v_cvt_pk_bf16_f32 v9, v65, v69
	global_store_dwordx4 v[12:13], v[6:9], off offset:64 sc1

; __device__ __forceinline__ unsigned cvt_pk_bf16(float lo, float hi) { unsigned r; asm volatile("v_cvt_pk_bf16_f32 %0, %1, %2" : "=v"(r) : "v"(lo), "v"(hi)); return r; }
; #define INP(i) ((const float*)(const GASP float*)kargs()[(i)])
; __device__ __forceinline__ void tr_item(const float* W, int ldw, int k0, int n0, bf16* WT, int ldk, int drow0, int lane) {
;     const int n4 = (lane & 15) * 4, kg = lane >> 4; f32x4 v[2][8];
; #pragma unroll
;     for (int kh = 0; kh < 2; ++kh) { const float* src = W + (size_t)(k0 + kh * 32 + kg * 8) * ldw + n0 + n4;
; #pragma unroll
;         for (int i = 0; i < 8; ++i) v[kh][i] = __builtin_nontemporal_load((const f32x4*)(src + (size_t)i * ldw)); }
; #pragma unroll
;     for (int kh = 0; kh < 2; ++kh)
; #pragma unroll
;         for (int e = 0; e < 4; ++e) { u32x4 o; o.x = cvt_pk_bf16(v[kh][0][e], v[kh][1][e]); o.y = cvt_pk_bf16(v[kh][2][e], v[kh][3][e]); o.z = cvt_pk_bf16(v[kh][4][e], v[kh][5][e]); o.w = cvt_pk_bf16(v[kh][6][e], v[kh][7][e]);
;             *(u32x4*)(WT + (size_t)(drow0 + n4 + e) * ldk + k0 + kh * 32 + kg * 8) = o; }
; }
; __device__ __forceinline__ void conv_item(int it, int lane) {
;     ...
;     if (r < 8 * IT_D) { const int idx = r / IT_D; r -= idx * IT_D; const int kb = r / 32, nb = r % 32;
;         tr_item(INP(I_WD) + (size_t)idx * 5376 * 2048, 2048, 64 * kb, 64 * nb, (bf16*)(ws + WS_WD) + (size_t)idx * 2048 * 5376, 5376, 64 * nb, lane); return; }
.LBB0_295:
	s_andn2_b64 vcc, exec, s[36:37]
	s_cbranch_vccnz .LBB0_297
	s_add_i32 s10, s33, 0xffff5800
	s_bfe_u32 s36, s10, 0x100007
	s_mulk_i32 s36, 0xc31
	s_lshr_b32 s39, s36, 16
	s_mul_i32 s36, s39, 0xf580
	s_add_i32 s10, s36, s10
	s_sext_i32_i16 s36, s10
	s_bfe_u32 s36, s36, 0x5001a
	s_add_i32 s38, s10, s36
	s_mov_b64 s[36:37], s[0:1]
	s_load_dwordx2 s[36:37], s[36:37], 0x70
	s_sext_i32_i16 s73, s38
	s_and_b32 s38, s38, 0xffe0
	s_sub_i32 s10, s10, s38
	s_mul_i32 s38, s39, 0x2a00000
	s_waitcnt lgkmcnt(0)
	s_add_u32 s76, s36, s38
	s_sext_i32_i16 s10, s10
	s_addc_u32 s37, s37, 0
	s_lshl_b32 s36, s73, 1
	s_andn2_b32 s36, s36, 63
	s_lshl_b32 s38, s10, 6
	s_mul_i32 s39, s39, 0x1500000
	s_add_u32 s10, s34, s39
	s_addc_u32 s73, s35, 0
	s_ashr_i32 s39, s38, 31
	s_lshl_b64 s[74:75], s[38:39], 2
	v_add_u32_e32 v38, s36, v2
	s_add_u32 s74, s76, s74
	s_addc_u32 s75, s37, s75
	v_ashrrev_i32_e32 v39, 31, v38
	v_lshl_add_u64 v[40:41], s[74:75], 0, v[4:5]
	v_lshlrev_b64 v[6:7], 13, v[38:39]
	v_lshl_add_u64 v[30:31], v[40:41], 0, v[6:7]
	v_add_co_u32_e32 v10, vcc, s44, v30
	v_add_u32_e32 v38, 32, v38
	s_nop 0
	v_addc_co_u32_e32 v11, vcc, 0, v31, vcc
	v_add_co_u32_e32 v14, vcc, s45, v30
	v_ashrrev_i32_e32 v39, 31, v38
	s_nop 0
	v_addc_co_u32_e32 v15, vcc, 0, v31, vcc
	v_add_co_u32_e32 v18, vcc, s46, v30
	v_lshlrev_b64 v[38:39], 13, v[38:39]
	s_nop 0
	v_addc_co_u32_e32 v19, vcc, 0, v31, vcc
	v_add_co_u32_e32 v22, vcc, s47, v30
	v_lshl_add_u64 v[62:63], v[40:41], 0, v[38:39]
	s_nop 0
	v_addc_co_u32_e32 v23, vcc, 0, v31, vcc
	v_add_co_u32_e32 v26, vcc, s48, v30
	global_load_dwordx4 v[6:9], v[30:31], off nt
	s_nop 0
	global_load_dwordx4 v[10:13], v[10:11], off nt
	v_addc_co_u32_e32 v27, vcc, 0, v31, vcc
	v_add_co_u32_e32 v32, vcc, s49, v30
	global_load_dwordx4 v[14:17], v[14:15], off nt
	s_nop 0
	global_load_dwordx4 v[18:21], v[18:19], off nt
	v_addc_co_u32_e32 v33, vcc, 0, v31, vcc
	v_add_co_u32_e32 v34, vcc, s50, v30
	global_load_dwordx4 v[22:25], v[22:23], off nt
	s_nop 0
	global_load_dwordx4 v[26:29], v[26:27], off nt
	v_addc_co_u32_e32 v35, vcc, 0, v31, vcc
	v_add_co_u32_e32 v42, vcc, s44, v62
	global_load_dwordx4 v[30:33], v[32:33], off nt
	s_nop 0
	global_load_dwordx4 v[34:37], v[34:35], off nt
	v_addc_co_u32_e32 v43, vcc, 0, v63, vcc
	v_add_co_u32_e32 v46, vcc, s45, v62
	global_load_dwordx4 v[38:41], v[62:63], off nt
	s_nop 0
	global_load_dwordx4 v[42:45], v[42:43], off nt
	v_addc_co_u32_e32 v47, vcc, 0, v63, vcc
	v_add_co_u32_e32 v50, vcc, s46, v62
	s_ashr_i32 s37, s36, 31
	s_nop 0
	v_addc_co_u32_e32 v51, vcc, 0, v63, vcc
	v_add_co_u32_e32 v54, vcc, s47, v62
	global_load_dwordx4 v[46:49], v[46:47], off nt
	s_nop 0
	global_load_dwordx4 v[50:53], v[50:51], off nt
	v_addc_co_u32_e32 v55, vcc, 0, v63, vcc
	v_add_co_u32_e32 v58, vcc, s48, v62
	s_lshl_b64 s[36:37], s[36:37], 1
	s_nop 0
	v_addc_co_u32_e32 v59, vcc, 0, v63, vcc
	v_add_co_u32_e32 v64, vcc, s49, v62
	global_load_dwordx4 v[54:57], v[54:55], off nt
	s_nop 0
	global_load_dwordx4 v[58:61], v[58:59], off nt
	v_addc_co_u32_e32 v65, vcc, 0, v63, vcc
	v_add_co_u32_e32 v66, vcc, s50, v62
	v_or_b32_e32 v1, s38, v0
	s_nop 0
	v_addc_co_u32_e32 v67, vcc, 0, v63, vcc
	global_load_dwordx4 v[62:65], v[64:65], off nt
	s_nop 0
	global_load_dwordx4 v[66:69], v[66:67], off nt
	s_add_u32 s36, s10, s36
	s_addc_u32 s37, s73, s37
	v_mul_i32_i24_e32 v76, 0x1500, v1
	v_lshl_add_u64 v[74:75], v[2:3], 1, s[36:37]
	v_ashrrev_i32_e32 v77, 31, v76
	v_lshl_add_u64 v[74:75], v[76:77], 1, v[74:75]
	v_add_co_u32_e32 v78, vcc, s63, v74
	s_waitcnt vmcnt(14)
	v_cvt_pk_bf16_f32 v70, v6, v10
	s_nop 0
	v_addc_co_u32_e32 v79, vcc, 0, v75, vcc
	v_add_co_u32_e32 v10, vcc, s64, v74
	s_waitcnt vmcnt(12)
	v_cvt_pk_bf16_f32 v71, v14, v18
	s_waitcnt vmcnt(10)
	v_cvt_pk_bf16_f32 v72, v22, v26
	s_waitcnt vmcnt(8)
	v_cvt_pk_bf16_f32 v73, v30, v34
	global_store_dwordx4 v[78:79], v[70:73], off sc1
	v_lshl_add_u64 v[76:77], v[74:75], 0, s[28:29]
	s_nop 0
	v_cvt_pk_bf16_f32 v70, v7, v11
	v_addc_co_u32_e32 v11, vcc, 0, v75, vcc
	v_add_co_u32_e32 v14, vcc, s65, v74
	v_cvt_pk_bf16_f32 v71, v15, v19
	v_cvt_pk_bf16_f32 v72, v23, v27
	v_cvt_pk_bf16_f32 v73, v31, v35
	global_store_dwordx4 v[10:11], v[70:73], off offset:2560 sc1
	s_nop 0
	v_addc_co_u32_e32 v15, vcc, 0, v75, vcc
	v_cvt_pk_bf16_f32 v70, v8, v12
	v_add_co_u32_e32 v12, vcc, s66, v74
	v_cvt_pk_bf16_f32 v71, v16, v20
	v_cvt_pk_bf16_f32 v72, v24, v28
	v_cvt_pk_bf16_f32 v73, v32, v36
	global_store_dwordx4 v[14:15], v[70:73], off offset:1024 sc1
	v_cvt_pk_bf16_f32 v6, v9, v13
	v_cvt_pk_bf16_f32 v7, v17, v21
	v_cvt_pk_bf16_f32 v8, v25, v29
	v_cvt_pk_bf16_f32 v9, v33, v37
	s_nop 0
	v_addc_co_u32_e32 v13, vcc, 0, v75, vcc
	global_store_dwordx4 v[12:13], v[6:9], off offset:3584 sc1
	s_waitcnt vmcnt(10)
	s_nop 0
	v_cvt_pk_bf16_f32 v6, v38, v42
	s_waitcnt vmcnt(8)
	v_cvt_pk_bf16_f32 v7, v46, v50
	s_waitcnt vmcnt(6)
	v_cvt_pk_bf16_f32 v8, v54, v58
	s_waitcnt vmcnt(4)
	v_cvt_pk_bf16_f32 v9, v62, v66
	global_store_dwordx4 v[76:77], v[6:9], off offset:64 sc1
	s_nop 1
	v_cvt_pk_bf16_f32 v6, v39, v43
	v_cvt_pk_bf16_f32 v7, v47, v51
	v_cvt_pk_bf16_f32 v8, v55, v59
	v_cvt_pk_bf16_f32 v9, v63, v67
	global_store_dwordx4 v[10:11], v[6:9], off offset:2624 sc1
	s_nop 1
	v_cvt_pk_bf16_f32 v6, v40, v44
	v_cvt_pk_bf16_f32 v7, v48, v52
	v_cvt_pk_bf16_f32 v8, v56, v60
	v_cvt_pk_bf16_f32 v9, v64, v68
	global_store_dwordx4 v[14:15], v[6:9], off offset:1088 sc1
	s_nop 1
	v_cvt_pk_bf16_f32 v6, v41, v45
	v_cvt_pk_bf16_f32 v7, v49, v53
	v_cvt_pk_bf16_f32 v8, v57, v61
	v_cvt_pk_bf16_f32 v9, v65, v69
	global_store_dwordx4 v[12:13], v[6:9], off offset:3648 sc1

; #define INP(i) ((const float*)(const GASP float*)kargs()[(i)])
; __device__ __forceinline__ void conv_item(int it, int lane) {
;     unsigned char* ws = WSP; int r = it;
;     if (r < 8 * IT_GU) { const int idx = r / IT_GU; r -= idx * IT_GU; const int kb = r / 168, nb = r % 168, n0 = 64 * nb;
;         const int drow = n0 < DFF ? (n0 >> 7) * 256 + (n0 & 127) : ((n0 - DFF) >> 7) * 256 + 128 + ((n0 - DFF) & 127);
;         tr_item(INP(I_WGU) + (size_t)idx * 2048 * 10752, 10752, 64 * kb, n0, (bf16*)(ws + WS_WGU) + (size_t)idx * 10752 * 2048, 2048, drow, lane); return; }
;     r -= 8 * IT_GU;
;     if (r < 8 * IT_D) { const int idx = r / IT_D; r -= idx * IT_D; const int kb = r / 32, nb = r % 32;
;         tr_item(INP(I_WD) + (size_t)idx * 5376 * 2048, 2048, 64 * kb, 64 * nb, (bf16*)(ws + WS_WD) + (size_t)idx * 2048 * 5376, 5376, 64 * nb, lane); return; }
;     r -= 8 * IT_D;
;     if (r < 2 * IT_INAB) { const int idx = r / IT_INAB; r -= idx * IT_INAB; const int kb = r / 80, nb = r % 80;
;         tr_item(INP(I_WINAB) + (size_t)idx * 2048 * 5120, 5120, 64 * kb, 64 * nb, (bf16*)(ws + WS_WINAB) + (size_t)idx * 5120 * 2048, 2048, 64 * nb, lane); return; }
;     r -= 2 * IT_INAB;
;     if (r < 2 * IT_GLU) { const int idx = r / IT_GLU; r -= idx * IT_GLU; const int kb = r / 16, nb = r % 16;
;         tr_item(INP(I_WGLU) + (size_t)idx * 1024 * 1024, 1024, 64 * kb, 64 * nb, (bf16*)(ws + WS_WGLU) + (size_t)idx * 1024 * 1024, 1024, 64 * nb, lane); return; }
;     r -= 2 * IT_GLU;
;     if (r < 2 * IT_OUTAB) { const int idx = r / IT_OUTAB; r -= idx * IT_OUTAB; const int kb = r / 32, nb = r % 32;
;         tr_item(INP(I_WOUTAB) + (size_t)idx * 2048 * 2048, 2048, 64 * kb, 64 * nb, (bf16*)(ws + WS_WOUTAB) + (size_t)idx * 2048 * 2048, 2048, 64 * nb, lane); return; }
;     r -= 2 * IT_OUTAB;
;     if (r < 2 * IT_INC) { const int idx = r / IT_INC; r -= idx * IT_INC; const int kb = r / 80, nb = r % 80;
;         tr_item(INP(I_WINC) + (size_t)idx * 2048 * 5120, 5120, 64 * kb, 64 * nb, (bf16*)(ws + WS_WINC) + (size_t)idx * 5120 * 2048, 2048, 64 * nb, lane); return; }
;     r -= 2 * IT_INC;
;     { const int idx = r / IT_OUTC; r -= idx * IT_OUTC; const int kb = r / 32, nb = r % 32;
;       tr_item(INP(I_WOUTC) + (size_t)idx * 2560 * 2048, 2048, 64 * kb, 64 * nb, (bf16*)(ws + WS_WOUTC) + (size_t)idx * 2048 * 2560, 2560, 64 * nb, lane); }
.LBB0_562:
	s_mov_b64 s[2:3], s[0:1]
	s_load_dwordx2 s[2:3], s[2:3], 0x138
	s_add_i32 s6, s12, s21
	s_mov_b64 s[22:23], -1
	s_cmp_gt_i32 s6, 0xa7ff
	s_cbranch_scc0 .LBB0_584
	s_cmpk_gt_u32 s6, 0xfbff
	s_cbranch_scc0 .LBB0_581
	s_cmp_gt_u32 s6, 0x10fff
	s_cbranch_scc0 .LBB0_578
	s_cmp_gt_u32 s6, 0x111ff
	s_cbranch_scc0 .LBB0_575
	s_cmp_gt_u32 s6, 0x119ff
	s_cbranch_scc0 .LBB0_572
	s_cmp_gt_u32 s6, 0x12dff
	s_cbranch_scc0 .LBB0_569
	s_add_i32 s11, s6, 0xfffed200
	s_mul_hi_u32 s12, s11, 0xcccccccd
	s_lshr_b32 s12, s12, 10
	s_mul_i32 s19, s12, 0xfffffb00
	s_mov_b64 s[20:21], s[0:1]
	s_add_i32 s11, s19, s11
	s_ashr_i32 s19, s11, 31
	s_load_dwordx2 s[20:21], s[20:21], 0x128
	s_lshr_b32 s19, s19, 27
	s_add_i32 s19, s11, s19
	s_and_b32 s22, s19, 0x3ffffe0
	s_sub_i32 s11, s11, s22
	s_mul_i32 s23, s12, 0x1400000
	s_mul_hi_u32 s22, s12, 0x1400000
	s_waitcnt lgkmcnt(0)
	s_add_u32 s23, s20, s23
	s_addc_u32 s28, s21, s22
	s_lshl_b32 s19, s19, 1
	s_and_b32 s22, s19, 0xffffffc0
	s_lshl_b32 s26, s11, 6
	s_mul_hi_u32 s11, s12, 0xa00000
	s_mul_i32 s12, s12, 0xa00000
	s_add_u32 s12, s2, s12
	s_addc_u32 s11, s3, s11
	s_ashr_i32 s27, s26, 31
	s_lshl_b64 s[20:21], s[26:27], 2
	v_add_u32_e32 v32, s22, v66
	s_add_u32 s20, s23, s20
	s_addc_u32 s21, s28, s21
	v_lshlrev_b32_e32 v172, 2, v64
	v_ashrrev_i32_e32 v33, 31, v32
	v_lshl_add_u64 v[34:35], s[20:21], 0, v[172:173]
	v_lshlrev_b64 v[0:1], 13, v[32:33]
	v_lshl_add_u64 v[24:25], v[34:35], 0, v[0:1]
	v_add_co_u32_e32 v4, vcc, s89, v24
	s_movk_i32 s20, 0x4000
	s_nop 0
	v_addc_co_u32_e32 v5, vcc, 0, v25, vcc
	v_add_co_u32_e32 v8, vcc, s20, v24
	s_movk_i32 s19, 0x6000
	s_nop 0
	v_addc_co_u32_e32 v9, vcc, 0, v25, vcc
	v_add_co_u32_e32 v12, vcc, s19, v24
	s_mov_b32 s21, 0x8000
	s_nop 0
	v_addc_co_u32_e32 v13, vcc, 0, v25, vcc
	v_add_co_u32_e32 v16, vcc, s21, v24
	v_add_u32_e32 v32, 32, v32
	s_nop 0
	v_addc_co_u32_e32 v17, vcc, 0, v25, vcc
	v_add_co_u32_e32 v20, vcc, s33, v24
	s_mov_b32 s23, 0xe000
	s_nop 0
	v_addc_co_u32_e32 v21, vcc, 0, v25, vcc
	v_add_co_u32_e32 v26, vcc, s38, v24
	v_ashrrev_i32_e32 v33, 31, v32
	s_nop 0
	v_addc_co_u32_e32 v27, vcc, 0, v25, vcc
	v_add_co_u32_e32 v28, vcc, s23, v24
	v_lshlrev_b64 v[32:33], 13, v[32:33]
	s_nop 0
	v_addc_co_u32_e32 v29, vcc, 0, v25, vcc
	v_lshl_add_u64 v[56:57], v[34:35], 0, v[32:33]
	v_add_co_u32_e32 v36, vcc, s89, v56
	global_load_dwordx4 v[0:3], v[24:25], off nt
	s_nop 0
	global_load_dwordx4 v[4:7], v[4:5], off nt
	v_addc_co_u32_e32 v37, vcc, 0, v57, vcc
	v_add_co_u32_e32 v40, vcc, s20, v56
	global_load_dwordx4 v[8:11], v[8:9], off nt
	s_nop 0
	global_load_dwordx4 v[12:15], v[12:13], off nt
	v_addc_co_u32_e32 v41, vcc, 0, v57, vcc
	v_add_co_u32_e32 v44, vcc, s19, v56
	global_load_dwordx4 v[16:19], v[16:17], off nt
	s_nop 0
	global_load_dwordx4 v[20:23], v[20:21], off nt
	v_addc_co_u32_e32 v45, vcc, 0, v57, vcc
	v_add_co_u32_e32 v48, vcc, s21, v56
	global_load_dwordx4 v[24:27], v[26:27], off nt
	s_nop 0
	global_load_dwordx4 v[28:31], v[28:29], off nt
	v_addc_co_u32_e32 v49, vcc, 0, v57, vcc
	v_add_co_u32_e32 v52, vcc, s33, v56
	global_load_dwordx4 v[32:35], v[56:57], off nt
	s_nop 0
	global_load_dwordx4 v[36:39], v[36:37], off nt
	v_addc_co_u32_e32 v53, vcc, 0, v57, vcc
	v_add_co_u32_e32 v58, vcc, s38, v56
	global_load_dwordx4 v[40:43], v[40:41], off nt
	s_nop 0
	global_load_dwordx4 v[44:47], v[44:45], off nt
	v_addc_co_u32_e32 v59, vcc, 0, v57, vcc
	v_add_co_u32_e32 v60, vcc, s23, v56
	global_load_dwordx4 v[48:51], v[48:49], off nt
	s_nop 0
	global_load_dwordx4 v[52:55], v[52:53], off nt
	v_addc_co_u32_e32 v61, vcc, 0, v57, vcc
	global_load_dwordx4 v[56:59], v[58:59], off nt
	s_nop 0
	global_load_dwordx4 v[60:63], v[60:61], off nt
	s_ashr_i32 s23, s22, 31
	s_lshl_b64 s[20:21], s[22:23], 1
	s_add_u32 s20, s12, s20
	v_or_b32_e32 v65, s26, v64
	s_addc_u32 s21, s11, s21
	s_movk_i32 s11, 0xa00
	v_mul_lo_u32 v74, v65, s11
	v_lshl_add_u64 v[72:73], v[66:67], 1, s[20:21]
	v_ashrrev_i32_e32 v75, 31, v74
	v_lshl_add_u64 v[72:73], v[74:75], 1, v[72:73]
	s_mov_b32 s11, 0x25d00000
	v_add_co_u32_e32 v76, vcc, s11, v72
	s_mov_b32 s11, 0x25d01000
	s_nop 0
	v_addc_co_u32_e32 v77, vcc, 0, v73, vcc
	s_waitcnt vmcnt(0)
	v_cvt_pk_bf16_f32 v68, v0, v4
	v_add_co_u32_e32 v4, vcc, s11, v72
	v_cvt_pk_bf16_f32 v69, v8, v12
	v_cvt_pk_bf16_f32 v70, v16, v20
	v_cvt_pk_bf16_f32 v71, v24, v28
	global_store_dwordx4 v[76:77], v[68:71], off sc1
	s_mov_b32 s11, 0x25d02000
	s_mov_b64 s[20:21], 0x25d00000
	v_cvt_pk_bf16_f32 v68, v1, v5
	v_addc_co_u32_e32 v5, vcc, 0, v73, vcc
	v_add_co_u32_e32 v8, vcc, s11, v72
	v_cvt_pk_bf16_f32 v69, v9, v13
	s_mov_b32 s11, 0x25d03000
	s_nop 0
	v_addc_co_u32_e32 v9, vcc, 0, v73, vcc
	v_cvt_pk_bf16_f32 v70, v17, v21
	v_cvt_pk_bf16_f32 v71, v25, v29
	global_store_dwordx4 v[4:5], v[68:71], off offset:1024 sc1
	v_lshl_add_u64 v[74:75], v[72:73], 0, s[20:21]
	s_mov_b64 s[22:23], 0
	v_cvt_pk_bf16_f32 v68, v2, v6
	v_add_co_u32_e32 v6, vcc, s11, v72
	v_cvt_pk_bf16_f32 v69, v10, v14
	v_cvt_pk_bf16_f32 v70, v18, v22
	v_cvt_pk_bf16_f32 v71, v26, v30
	global_store_dwordx4 v[8:9], v[68:71], off offset:2048 sc1
	v_cvt_pk_bf16_f32 v0, v3, v7
	v_cvt_pk_bf16_f32 v1, v11, v15
	v_cvt_pk_bf16_f32 v2, v19, v23
	v_cvt_pk_bf16_f32 v3, v27, v31
	s_nop 0
	v_addc_co_u32_e32 v7, vcc, 0, v73, vcc
	global_store_dwordx4 v[6:7], v[0:3], off offset:3072 sc1
	s_nop 1
	v_cvt_pk_bf16_f32 v0, v32, v36
	v_cvt_pk_bf16_f32 v1, v40, v44
	v_cvt_pk_bf16_f32 v2, v48, v52
	v_cvt_pk_bf16_f32 v3, v56, v60
	global_store_dwordx4 v[74:75], v[0:3], off offset:64 sc1
	s_nop 1
	v_cvt_pk_bf16_f32 v0, v33, v37
	v_cvt_pk_bf16_f32 v1, v41, v45
	v_cvt_pk_bf16_f32 v2, v49, v53
	v_cvt_pk_bf16_f32 v3, v57, v61
	global_store_dwordx4 v[4:5], v[0:3], off offset:1088 sc1
	s_nop 1
	v_cvt_pk_bf16_f32 v0, v34, v38
	v_cvt_pk_bf16_f32 v1, v42, v46
	v_cvt_pk_bf16_f32 v2, v50, v54
	v_cvt_pk_bf16_f32 v3, v58, v62
	global_store_dwordx4 v[8:9], v[0:3], off offset:2112 sc1
	s_nop 1
	v_cvt_pk_bf16_f32 v0, v35, v39
	v_cvt_pk_bf16_f32 v1, v43, v47
	v_cvt_pk_bf16_f32 v2, v51, v55
	v_cvt_pk_bf16_f32 v3, v59, v63
	global_store_dwordx4 v[6:7], v[0:3], off offset:3136 sc1
; __device__ __forceinline__ unsigned cvt_pk_bf16(float lo, float hi) { unsigned r; asm volatile("v_cvt_pk_bf16_f32 %0, %1, %2" : "=v"(r) : "v"(lo), "v"(hi)); return r; }
; #define INP(i) ((const float*)(const GASP float*)kargs()[(i)])
; __device__ __forceinline__ void tr_item(const float* W, int ldw, int k0, int n0, bf16* WT, int ldk, int drow0, int lane) {
;     const int n4 = (lane & 15) * 4, kg = lane >> 4; f32x4 v[2][8];
; #pragma unroll
;     for (int kh = 0; kh < 2; ++kh) { const float* src = W + (size_t)(k0 + kh * 32 + kg * 8) * ldw + n0 + n4;
; #pragma unroll
;         for (int i = 0; i < 8; ++i) v[kh][i] = __builtin_nontemporal_load((const f32x4*)(src + (size_t)i * ldw)); }
; #pragma unroll
;     for (int kh = 0; kh < 2; ++kh)
; #pragma unroll
;         for (int e = 0; e < 4; ++e) { u32x4 o; o.x = cvt_pk_bf16(v[kh][0][e], v[kh][1][e]); o.y = cvt_pk_bf16(v[kh][2][e], v[kh][3][e]); o.z = cvt_pk_bf16(v[kh][4][e], v[kh][5][e]); o.w = cvt_pk_bf16(v[kh][6][e], v[kh][7][e]);
;             *(u32x4*)(WT + (size_t)(drow0 + n4 + e) * ldk + k0 + kh * 32 + kg * 8) = o; }
; }
; __device__ __forceinline__ void conv_item(int it, int lane) {
;     ...
;     if (r < 2 * IT_INC) { const int idx = r / IT_INC; r -= idx * IT_INC; const int kb = r / 80, nb = r % 80;
;         tr_item(INP(I_WINC) + (size_t)idx * 2048 * 5120, 5120, 64 * kb, 64 * nb, (bf16*)(ws + WS_WINC) + (size_t)idx * 5120 * 2048, 2048, 64 * nb, lane); return; }
.LBB0_569:
	s_andn2_b64 vcc, exec, s[22:23]
	s_cbranch_vccnz .LBB0_571
	s_add_i32 s11, s6, 0xfffee600
	s_cmpk_gt_u32 s11, 0x9ff
	s_cselect_b64 s[20:21], -1, 0
	s_and_b64 s[22:23], s[20:21], exec
	s_cselect_b32 s12, 0xf600, 0
	s_add_i32 s12, s12, s11
	s_sext_i32_i16 s11, s12
	s_mulk_i32 s11, 0x6667
	s_mov_b64 s[22:23], s[0:1]
	s_lshr_b32 s19, s11, 31
	s_ashr_i32 s11, s11, 21
	s_add_i32 s11, s11, s19
	s_load_dwordx2 s[22:23], s[22:23], 0xe8
	s_mul_i32 s19, s11, 0x50
	s_sub_i32 s12, s12, s19
	s_and_b64 s[26:27], s[20:21], exec
	s_cselect_b32 s19, 0x2800000, 0
	s_sext_i32_i16 s12, s12
	s_waitcnt lgkmcnt(0)
	s_add_u32 s19, s22, s19
	s_addc_u32 s23, s23, 0
	s_lshl_b32 s22, s11, 6
	s_lshl_b32 s26, s12, 6
	s_and_b64 s[20:21], s[20:21], exec
	s_cselect_b32 s11, 0x1400000, 0
	s_add_u32 s11, s2, s11
	s_addc_u32 s12, s3, 0
	s_ashr_i32 s27, s26, 31
	s_lshl_b64 s[20:21], s[26:27], 2
	s_add_u32 s20, s19, s20
	s_addc_u32 s21, s23, s21
	v_lshlrev_b32_e32 v172, 2, v64
	v_add_u32_e32 v34, s22, v66
	v_lshl_add_u64 v[32:33], s[20:21], 0, v[172:173]
	s_movk_i32 s27, 0x5000
	v_mad_i64_i32 v[24:25], s[20:21], v34, s27, v[32:33]
	v_add_co_u32_e32 v4, vcc, s27, v24
	s_mov_b32 s19, 0x14000
	s_nop 0
	v_addc_co_u32_e32 v5, vcc, 0, v25, vcc
	v_add_co_u32_e32 v8, vcc, s33, v24
	s_mov_b32 s28, 0x19000
	s_nop 0
	v_addc_co_u32_e32 v9, vcc, 0, v25, vcc
	v_add_co_u32_e32 v12, vcc, s76, v24
	s_mov_b32 s23, 0x1e000
	s_nop 0
	v_addc_co_u32_e32 v13, vcc, 0, v25, vcc
	v_add_co_u32_e32 v16, vcc, s19, v24
	v_add_u32_e32 v34, 32, v34
	s_nop 0
	v_addc_co_u32_e32 v17, vcc, 0, v25, vcc
	v_add_co_u32_e32 v20, vcc, s28, v24
	v_mad_i64_i32 v[56:57], s[20:21], v34, s27, v[32:33]
	s_nop 0
	v_addc_co_u32_e32 v21, vcc, 0, v25, vcc
	v_add_co_u32_e32 v26, vcc, s23, v24
	global_load_dwordx4 v[0:3], v[24:25], off nt
	s_nop 0
	global_load_dwordx4 v[4:7], v[4:5], off nt
	v_addc_co_u32_e32 v27, vcc, 0, v25, vcc
	v_add_co_u32_e32 v28, vcc, s77, v24
	global_load_dwordx4 v[8:11], v[8:9], off nt
	s_nop 0
	global_load_dwordx4 v[12:15], v[12:13], off nt
	v_addc_co_u32_e32 v29, vcc, 0, v25, vcc
	v_add_co_u32_e32 v36, vcc, s27, v56
	global_load_dwordx4 v[16:19], v[16:17], off nt
	s_nop 0
	global_load_dwordx4 v[20:23], v[20:21], off nt
	v_addc_co_u32_e32 v37, vcc, 0, v57, vcc
	v_add_co_u32_e32 v40, vcc, s33, v56
	global_load_dwordx4 v[24:27], v[26:27], off nt
	s_nop 0
	global_load_dwordx4 v[28:31], v[28:29], off nt
	v_addc_co_u32_e32 v41, vcc, 0, v57, vcc
	v_add_co_u32_e32 v44, vcc, s76, v56
	global_load_dwordx4 v[32:35], v[56:57], off nt
	s_nop 0
	global_load_dwordx4 v[36:39], v[36:37], off nt
	v_addc_co_u32_e32 v45, vcc, 0, v57, vcc
	v_add_co_u32_e32 v48, vcc, s19, v56
	global_load_dwordx4 v[40:43], v[40:41], off nt
	s_nop 0
	global_load_dwordx4 v[44:47], v[44:45], off nt
	v_addc_co_u32_e32 v49, vcc, 0, v57, vcc
	v_add_co_u32_e32 v52, vcc, s28, v56
	v_or_b32_e32 v72, s26, v64
	s_nop 0
	v_addc_co_u32_e32 v53, vcc, 0, v57, vcc
	v_add_co_u32_e32 v58, vcc, s23, v56
	global_load_dwordx4 v[48:51], v[48:49], off nt
	s_nop 0
	global_load_dwordx4 v[52:55], v[52:53], off nt
	v_addc_co_u32_e32 v59, vcc, 0, v57, vcc
	v_add_co_u32_e32 v60, vcc, s77, v56
	s_ashr_i32 s23, s22, 31
	s_nop 0
	v_addc_co_u32_e32 v61, vcc, 0, v57, vcc
	global_load_dwordx4 v[56:59], v[58:59], off nt
	s_nop 0
	global_load_dwordx4 v[60:63], v[60:61], off nt
	s_lshl_b64 s[20:21], s[22:23], 1
	s_add_u32 s20, s11, s20
	s_addc_u32 s21, s12, s21
	v_lshl_add_u64 v[68:69], v[66:67], 1, s[20:21]
	s_mov_b64 s[20:21], 0x23500000
	v_ashrrev_i32_e32 v73, 31, v72
	v_lshl_add_u64 v[74:75], v[68:69], 0, s[20:21]
	v_lshlrev_b64 v[76:77], 12, v[72:73]
	s_waitcnt vmcnt(0)
	v_cvt_pk_bf16_f32 v68, v0, v4
	v_lshl_add_u64 v[76:77], v[74:75], 0, v[76:77]
	v_or_b32_e32 v0, 1, v72
	v_cvt_pk_bf16_f32 v69, v8, v12
	v_cvt_pk_bf16_f32 v70, v16, v20
	v_cvt_pk_bf16_f32 v71, v24, v28
	global_store_dwordx4 v[76:77], v[68:71], off sc1
	s_nop 1
	v_cvt_pk_bf16_f32 v68, v1, v5
	v_ashrrev_i32_e32 v1, 31, v0
	v_lshlrev_b64 v[0:1], 12, v[0:1]
	v_lshl_add_u64 v[4:5], v[74:75], 0, v[0:1]
	v_or_b32_e32 v0, 2, v72
	v_ashrrev_i32_e32 v1, 31, v0
	v_lshlrev_b64 v[0:1], 12, v[0:1]
	v_cvt_pk_bf16_f32 v69, v9, v13
	v_cvt_pk_bf16_f32 v70, v17, v21
	v_cvt_pk_bf16_f32 v71, v25, v29
	global_store_dwordx4 v[4:5], v[68:71], off sc1
	v_lshl_add_u64 v[8:9], v[74:75], 0, v[0:1]
	s_nop 0
	v_cvt_pk_bf16_f32 v68, v2, v6
	v_or_b32_e32 v6, 3, v72
	v_cvt_pk_bf16_f32 v69, v10, v14
	v_cvt_pk_bf16_f32 v70, v18, v22
	v_cvt_pk_bf16_f32 v71, v26, v30
	global_store_dwordx4 v[8:9], v[68:71], off sc1
	v_cvt_pk_bf16_f32 v0, v3, v7
	v_ashrrev_i32_e32 v7, 31, v6
	v_lshlrev_b64 v[6:7], 12, v[6:7]
	v_cvt_pk_bf16_f32 v1, v11, v15
	v_cvt_pk_bf16_f32 v2, v19, v23
	v_cvt_pk_bf16_f32 v3, v27, v31
	v_lshl_add_u64 v[6:7], v[74:75], 0, v[6:7]
	global_store_dwordx4 v[6:7], v[0:3], off sc1
	s_nop 1
	v_cvt_pk_bf16_f32 v0, v32, v36
	v_cvt_pk_bf16_f32 v1, v40, v44
	v_cvt_pk_bf16_f32 v2, v48, v52
	v_cvt_pk_bf16_f32 v3, v56, v60
	global_store_dwordx4 v[76:77], v[0:3], off offset:64 sc1
	s_nop 1
	v_cvt_pk_bf16_f32 v0, v33, v37
	v_cvt_pk_bf16_f32 v1, v41, v45
	v_cvt_pk_bf16_f32 v2, v49, v53
	v_cvt_pk_bf16_f32 v3, v57, v61
	global_store_dwordx4 v[4:5], v[0:3], off offset:64 sc1
	s_nop 1
	v_cvt_pk_bf16_f32 v0, v34, v38
	v_cvt_pk_bf16_f32 v1, v42, v46
	v_cvt_pk_bf16_f32 v2, v50, v54
	v_cvt_pk_bf16_f32 v3, v58, v62
	global_store_dwordx4 v[8:9], v[0:3], off offset:64 sc1
	s_nop 1
	v_cvt_pk_bf16_f32 v0, v35, v39
	v_cvt_pk_bf16_f32 v1, v43, v47
	v_cvt_pk_bf16_f32 v2, v51, v55
	v_cvt_pk_bf16_f32 v3, v59, v63
	global_store_dwordx4 v[6:7], v[0:3], off offset:64 sc1

; __device__ __forceinline__ unsigned cvt_pk_bf16(float lo, float hi) { unsigned r; asm volatile("v_cvt_pk_bf16_f32 %0, %1, %2" : "=v"(r) : "v"(lo), "v"(hi)); return r; }
; #define INP(i) ((const float*)(const GASP float*)kargs()[(i)])
; __device__ __forceinline__ void tr_item(const float* W, int ldw, int k0, int n0, bf16* WT, int ldk, int drow0, int lane) {
;     const int n4 = (lane & 15) * 4, kg = lane >> 4; f32x4 v[2][8];
; #pragma unroll
;     for (int kh = 0; kh < 2; ++kh) { const float* src = W + (size_t)(k0 + kh * 32 + kg * 8) * ldw + n0 + n4;
; #pragma unroll
;         for (int i = 0; i < 8; ++i) v[kh][i] = __builtin_nontemporal_load((const f32x4*)(src + (size_t)i * ldw)); }
; #pragma unroll
;     for (int kh = 0; kh < 2; ++kh)
; #pragma unroll
;         for (int e = 0; e < 4; ++e) { u32x4 o; o.x = cvt_pk_bf16(v[kh][0][e], v[kh][1][e]); o.y = cvt_pk_bf16(v[kh][2][e], v[kh][3][e]); o.z = cvt_pk_bf16(v[kh][4][e], v[kh][5][e]); o.w = cvt_pk_bf16(v[kh][6][e], v[kh][7][e]);
;             *(u32x4*)(WT + (size_t)(drow0 + n4 + e) * ldk + k0 + kh * 32 + kg * 8) = o; }
; }
; __device__ __forceinline__ void conv_item(int it, int lane) {
;     ...
;     if (r < 2 * IT_OUTAB) { const int idx = r / IT_OUTAB; r -= idx * IT_OUTAB; const int kb = r / 32, nb = r % 32;
;         tr_item(INP(I_WOUTAB) + (size_t)idx * 2048 * 2048, 2048, 64 * kb, 64 * nb, (bf16*)(ws + WS_WOUTAB) + (size_t)idx * 2048 * 2048, 2048, 64 * nb, lane); return; }
.LBB0_572:
	s_andn2_b64 vcc, exec, s[22:23]
	s_cbranch_vccnz .LBB0_574
	s_mov_b64 s[20:21], s[0:1]
	s_load_dwordx2 s[20:21], s[20:21], 0xe0
	s_add_i32 s11, s6, 0xfffeee00
	s_lshr_b32 s38, s11, 10
	s_lshl_b64 s[22:23], s[38:39], 24
	v_lshlrev_b32_e32 v172, 2, v64
	s_waitcnt lgkmcnt(0)
	s_add_u32 s12, s20, s22
	s_addc_u32 s19, s21, s23
	s_lshl_b32 s11, s11, 1
	s_lshl_b32 s20, s6, 6
	s_and_b32 s11, s11, 0x7c0
	s_and_b32 s22, s20, 0x7c0
	s_lshl_b64 s[20:21], s[38:39], 23
	s_add_u32 s23, s2, s20
	s_addc_u32 s26, s3, s21
	s_lshl_b32 s20, s22, 2
	v_add_u32_e32 v32, s11, v66
	s_add_u32 s20, s12, s20
	s_addc_u32 s21, s19, 0
	v_ashrrev_i32_e32 v33, 31, v32
	v_lshl_add_u64 v[34:35], s[20:21], 0, v[172:173]
	v_lshlrev_b64 v[0:1], 13, v[32:33]
	v_lshl_add_u64 v[24:25], v[34:35], 0, v[0:1]
	v_add_co_u32_e32 v4, vcc, s89, v24
	s_movk_i32 s19, 0x4000
	s_nop 0
	v_addc_co_u32_e32 v5, vcc, 0, v25, vcc
	v_add_co_u32_e32 v8, vcc, s19, v24
	s_movk_i32 s12, 0x6000
	s_nop 0
	v_addc_co_u32_e32 v9, vcc, 0, v25, vcc
	v_add_co_u32_e32 v12, vcc, s12, v24
	s_mov_b32 s20, 0x8000
	s_nop 0
	v_addc_co_u32_e32 v13, vcc, 0, v25, vcc
	v_add_co_u32_e32 v16, vcc, s20, v24
	s_mov_b32 s38, 0xc000
	s_nop 0
	v_addc_co_u32_e32 v17, vcc, 0, v25, vcc
	v_add_co_u32_e32 v20, vcc, s33, v24
	v_add_u32_e32 v32, 32, v32
	s_nop 0
	v_addc_co_u32_e32 v21, vcc, 0, v25, vcc
	v_add_co_u32_e32 v26, vcc, s38, v24
	s_mov_b32 s21, 0xe000
	s_nop 0
	v_addc_co_u32_e32 v27, vcc, 0, v25, vcc
	v_ashrrev_i32_e32 v33, 31, v32
	v_add_co_u32_e32 v28, vcc, s21, v24
	v_lshlrev_b64 v[32:33], 13, v[32:33]
	s_nop 0
	v_addc_co_u32_e32 v29, vcc, 0, v25, vcc
	v_lshl_add_u64 v[56:57], v[34:35], 0, v[32:33]
	v_add_co_u32_e32 v36, vcc, s89, v56
	global_load_dwordx4 v[0:3], v[24:25], off nt
	s_nop 0
	global_load_dwordx4 v[4:7], v[4:5], off nt
	v_addc_co_u32_e32 v37, vcc, 0, v57, vcc
	v_add_co_u32_e32 v40, vcc, s19, v56
	global_load_dwordx4 v[8:11], v[8:9], off nt
	s_nop 0
	global_load_dwordx4 v[12:15], v[12:13], off nt
	v_addc_co_u32_e32 v41, vcc, 0, v57, vcc
	v_add_co_u32_e32 v44, vcc, s12, v56
	global_load_dwordx4 v[16:19], v[16:17], off nt
	s_nop 0
	global_load_dwordx4 v[20:23], v[20:21], off nt
	v_addc_co_u32_e32 v45, vcc, 0, v57, vcc
	v_add_co_u32_e32 v48, vcc, s20, v56
	global_load_dwordx4 v[24:27], v[26:27], off nt
	s_nop 0
	global_load_dwordx4 v[28:31], v[28:29], off nt
	v_addc_co_u32_e32 v49, vcc, 0, v57, vcc
	v_add_co_u32_e32 v52, vcc, s33, v56
	global_load_dwordx4 v[32:35], v[56:57], off nt
	s_nop 0
	global_load_dwordx4 v[36:39], v[36:37], off nt
	v_addc_co_u32_e32 v53, vcc, 0, v57, vcc
	v_add_co_u32_e32 v58, vcc, s38, v56
	global_load_dwordx4 v[40:43], v[40:41], off nt
	s_nop 0
	global_load_dwordx4 v[44:47], v[44:45], off nt
	v_addc_co_u32_e32 v59, vcc, 0, v57, vcc
	v_add_co_u32_e32 v60, vcc, s21, v56
	global_load_dwordx4 v[48:51], v[48:49], off nt
	s_nop 0
	global_load_dwordx4 v[52:55], v[52:53], off nt
	v_addc_co_u32_e32 v61, vcc, 0, v57, vcc
	global_load_dwordx4 v[56:59], v[58:59], off nt
	s_nop 0
	global_load_dwordx4 v[60:63], v[60:61], off nt
	s_lshl_b32 s11, s11, 1
	s_add_u32 s20, s23, s11
	s_addc_u32 s21, s26, 0
	v_or_b32_e32 v65, s22, v64
	v_lshl_add_u64 v[72:73], v[66:67], 1, s[20:21]
	s_mov_b64 s[20:21], 0x22500000
	v_lshl_add_u64 v[74:75], v[72:73], 0, s[20:21]
	v_lshlrev_b32_e32 v172, 12, v65
	s_waitcnt vmcnt(0)
	v_cvt_pk_bf16_f32 v68, v0, v4
	v_lshl_add_u64 v[76:77], v[74:75], 0, v[172:173]
	v_cvt_pk_bf16_f32 v69, v8, v12
	v_cvt_pk_bf16_f32 v70, v16, v20
	v_cvt_pk_bf16_f32 v71, v24, v28
	global_store_dwordx4 v[76:77], v[68:71], off sc1
	v_or_b32_e32 v4, 0x1000, v172
	v_or_b32_e32 v8, 0x2000, v172
	v_cvt_pk_bf16_f32 v68, v1, v5
	v_mov_b32_e32 v5, v173
	v_cvt_pk_bf16_f32 v69, v9, v13
	v_lshl_add_u64 v[0:1], v[74:75], 0, v[4:5]
	v_mov_b32_e32 v9, v173
	v_cvt_pk_bf16_f32 v70, v17, v21
	v_cvt_pk_bf16_f32 v71, v25, v29
	global_store_dwordx4 v[0:1], v[68:71], off sc1
	v_lshl_add_u64 v[0:1], v[74:75], 0, v[8:9]
	v_or_b32_e32 v172, 0x3000, v172
	v_cvt_pk_bf16_f32 v68, v2, v6
	v_cvt_pk_bf16_f32 v69, v10, v14
	v_cvt_pk_bf16_f32 v70, v18, v22
	v_cvt_pk_bf16_f32 v71, v26, v30
	global_store_dwordx4 v[0:1], v[68:71], off sc1
	v_cvt_pk_bf16_f32 v0, v3, v7
	v_lshl_add_u64 v[6:7], v[74:75], 0, v[172:173]
	s_mov_b64 s[20:21], 0x22500040
	v_cvt_pk_bf16_f32 v1, v11, v15
	v_cvt_pk_bf16_f32 v2, v19, v23
	v_cvt_pk_bf16_f32 v3, v27, v31
	global_store_dwordx4 v[6:7], v[0:3], off sc1
	v_lshl_add_u64 v[6:7], v[72:73], 0, s[20:21]
	v_lshl_add_u64 v[4:5], v[6:7], 0, v[4:5]
	v_cvt_pk_bf16_f32 v0, v32, v36
	v_cvt_pk_bf16_f32 v1, v40, v44
	v_cvt_pk_bf16_f32 v2, v48, v52
	v_cvt_pk_bf16_f32 v3, v56, v60
	global_store_dwordx4 v[76:77], v[0:3], off offset:64 sc1
	s_nop 1
	v_cvt_pk_bf16_f32 v0, v33, v37
	v_cvt_pk_bf16_f32 v1, v41, v45
	v_cvt_pk_bf16_f32 v2, v49, v53
	v_cvt_pk_bf16_f32 v3, v57, v61
	global_store_dwordx4 v[4:5], v[0:3], off sc1
	v_lshl_add_u64 v[4:5], v[6:7], 0, v[8:9]
	s_nop 0
	v_cvt_pk_bf16_f32 v0, v34, v38
	v_cvt_pk_bf16_f32 v1, v42, v46
	v_cvt_pk_bf16_f32 v2, v50, v54
	v_cvt_pk_bf16_f32 v3, v58, v62
	global_store_dwordx4 v[4:5], v[0:3], off sc1
	v_lshl_add_u64 v[4:5], v[6:7], 0, v[172:173]
	s_nop 0
	v_cvt_pk_bf16_f32 v0, v35, v39
	v_cvt_pk_bf16_f32 v1, v43, v47
	v_cvt_pk_bf16_f32 v2, v51, v55
	v_cvt_pk_bf16_f32 v3, v59, v63
	global_store_dwordx4 v[4:5], v[0:3], off sc1

; __device__ __forceinline__ unsigned cvt_pk_bf16(float lo, float hi) { unsigned r; asm volatile("v_cvt_pk_bf16_f32 %0, %1, %2" : "=v"(r) : "v"(lo), "v"(hi)); return r; }
; #define INP(i) ((const float*)(const GASP float*)kargs()[(i)])
; __device__ __forceinline__ void tr_item(const float* W, int ldw, int k0, int n0, bf16* WT, int ldk, int drow0, int lane) {
;     const int n4 = (lane & 15) * 4, kg = lane >> 4; f32x4 v[2][8];
; #pragma unroll
;     for (int kh = 0; kh < 2; ++kh) { const float* src = W + (size_t)(k0 + kh * 32 + kg * 8) * ldw + n0 + n4;
; #pragma unroll
;         for (int i = 0; i < 8; ++i) v[kh][i] = __builtin_nontemporal_load((const f32x4*)(src + (size_t)i * ldw)); }
; #pragma unroll
;     for (int kh = 0; kh < 2; ++kh)
; #pragma unroll
;         for (int e = 0; e < 4; ++e) { u32x4 o; o.x = cvt_pk_bf16(v[kh][0][e], v[kh][1][e]); o.y = cvt_pk_bf16(v[kh][2][e], v[kh][3][e]); o.z = cvt_pk_bf16(v[kh][4][e], v[kh][5][e]); o.w = cvt_pk_bf16(v[kh][6][e], v[kh][7][e]);
;             *(u32x4*)(WT + (size_t)(drow0 + n4 + e) * ldk + k0 + kh * 32 + kg * 8) = o; }
; }
; __device__ __forceinline__ void conv_item(int it, int lane) {
;     ...
;     if (r < 2 * IT_INAB) { const int idx = r / IT_INAB; r -= idx * IT_INAB; const int kb = r / 80, nb = r % 80;
;         tr_item(INP(I_WINAB) + (size_t)idx * 2048 * 5120, 5120, 64 * kb, 64 * nb, (bf16*)(ws + WS_WINAB) + (size_t)idx * 5120 * 2048, 2048, 64 * nb, lane); return; }
.LBB0_578:
	s_andn2_b64 vcc, exec, s[22:23]
	s_cbranch_vccnz .LBB0_580
	s_add_i32 s11, s6, 0xffff0400
	s_cmpk_gt_u32 s11, 0x9ff
	s_cselect_b64 s[20:21], -1, 0
	s_and_b64 s[22:23], s[20:21], exec
	s_cselect_b32 s12, 0xf600, 0
	s_add_i32 s12, s12, s11
	s_sext_i32_i16 s11, s12
	s_mulk_i32 s11, 0x6667
	s_mov_b64 s[22:23], s[0:1]
	s_lshr_b32 s19, s11, 31
	s_ashr_i32 s11, s11, 21
	s_add_i32 s11, s11, s19
	s_load_dwordx2 s[22:23], s[22:23], 0x78
	s_mul_i32 s19, s11, 0x50
	s_sub_i32 s12, s12, s19
	s_and_b64 s[26:27], s[20:21], exec
	s_cselect_b32 s19, 0x2800000, 0
	s_sext_i32_i16 s12, s12
	s_waitcnt lgkmcnt(0)
	s_add_u32 s19, s22, s19
	s_addc_u32 s23, s23, 0
	s_lshl_b32 s22, s11, 6
	s_lshl_b32 s26, s12, 6
	s_and_b64 s[20:21], s[20:21], exec
	s_cselect_b32 s11, 0x1400000, 0
	s_add_u32 s11, s2, s11
	s_addc_u32 s12, s3, 0
	s_ashr_i32 s27, s26, 31
	s_lshl_b64 s[20:21], s[26:27], 2
	s_add_u32 s20, s19, s20
	s_addc_u32 s21, s23, s21
	v_lshlrev_b32_e32 v172, 2, v64
	v_add_u32_e32 v34, s22, v66
	v_lshl_add_u64 v[32:33], s[20:21], 0, v[172:173]
	s_movk_i32 s27, 0x5000
	v_mad_i64_i32 v[24:25], s[20:21], v34, s27, v[32:33]
	v_add_co_u32_e32 v4, vcc, s27, v24
	s_mov_b32 s19, 0x14000
	s_nop 0
	v_addc_co_u32_e32 v5, vcc, 0, v25, vcc
	v_add_co_u32_e32 v8, vcc, s33, v24
	s_mov_b32 s28, 0x19000
	s_nop 0
	v_addc_co_u32_e32 v9, vcc, 0, v25, vcc
	v_add_co_u32_e32 v12, vcc, s76, v24
	s_mov_b32 s23, 0x1e000
	s_nop 0
	v_addc_co_u32_e32 v13, vcc, 0, v25, vcc
	v_add_co_u32_e32 v16, vcc, s19, v24
	v_add_u32_e32 v34, 32, v34
	s_nop 0
	v_addc_co_u32_e32 v17, vcc, 0, v25, vcc
	v_add_co_u32_e32 v20, vcc, s28, v24
	v_mad_i64_i32 v[56:57], s[20:21], v34, s27, v[32:33]
	s_nop 0
	v_addc_co_u32_e32 v21, vcc, 0, v25, vcc
	v_add_co_u32_e32 v26, vcc, s23, v24
	global_load_dwordx4 v[0:3], v[24:25], off nt
	s_nop 0
	global_load_dwordx4 v[4:7], v[4:5], off nt
	v_addc_co_u32_e32 v27, vcc, 0, v25, vcc
	v_add_co_u32_e32 v28, vcc, s77, v24
	global_load_dwordx4 v[8:11], v[8:9], off nt
	s_nop 0
	global_load_dwordx4 v[12:15], v[12:13], off nt
	v_addc_co_u32_e32 v29, vcc, 0, v25, vcc
	v_add_co_u32_e32 v36, vcc, s27, v56
	global_load_dwordx4 v[16:19], v[16:17], off nt
	s_nop 0
	global_load_dwordx4 v[20:23], v[20:21], off nt
	v_addc_co_u32_e32 v37, vcc, 0, v57, vcc
	v_add_co_u32_e32 v40, vcc, s33, v56
	global_load_dwordx4 v[24:27], v[26:27], off nt
	s_nop 0
	global_load_dwordx4 v[28:31], v[28:29], off nt
	v_addc_co_u32_e32 v41, vcc, 0, v57, vcc
	v_add_co_u32_e32 v44, vcc, s76, v56
	global_load_dwordx4 v[32:35], v[56:57], off nt
	s_nop 0
	global_load_dwordx4 v[36:39], v[36:37], off nt
	v_addc_co_u32_e32 v45, vcc, 0, v57, vcc
	v_add_co_u32_e32 v48, vcc, s19, v56
	global_load_dwordx4 v[40:43], v[40:41], off nt
	s_nop 0
	global_load_dwordx4 v[44:47], v[44:45], off nt
	v_addc_co_u32_e32 v49, vcc, 0, v57, vcc
	v_add_co_u32_e32 v52, vcc, s28, v56
	v_or_b32_e32 v72, s26, v64
	s_nop 0
	v_addc_co_u32_e32 v53, vcc, 0, v57, vcc
	v_add_co_u32_e32 v58, vcc, s23, v56
	global_load_dwordx4 v[48:51], v[48:49], off nt
	s_nop 0
	global_load_dwordx4 v[52:55], v[52:53], off nt
	v_addc_co_u32_e32 v59, vcc, 0, v57, vcc
	v_add_co_u32_e32 v60, vcc, s77, v56
	s_ashr_i32 s23, s22, 31
	s_nop 0
	v_addc_co_u32_e32 v61, vcc, 0, v57, vcc
	global_load_dwordx4 v[56:59], v[58:59], off nt
	s_nop 0
	global_load_dwordx4 v[60:63], v[60:61], off nt
	s_lshl_b64 s[20:21], s[22:23], 1
	s_add_u32 s20, s11, s20
	s_addc_u32 s21, s12, s21
	v_lshl_add_u64 v[68:69], v[66:67], 1, s[20:21]
	s_mov_b64 s[20:21], 0x1f900000
	v_ashrrev_i32_e32 v73, 31, v72
	v_lshl_add_u64 v[74:75], v[68:69], 0, s[20:21]
	v_lshlrev_b64 v[76:77], 12, v[72:73]
	s_waitcnt vmcnt(0)
	v_cvt_pk_bf16_f32 v68, v0, v4
	v_lshl_add_u64 v[76:77], v[74:75], 0, v[76:77]
	v_or_b32_e32 v0, 1, v72
	v_cvt_pk_bf16_f32 v69, v8, v12
	v_cvt_pk_bf16_f32 v70, v16, v20
	v_cvt_pk_bf16_f32 v71, v24, v28
	global_store_dwordx4 v[76:77], v[68:71], off sc1
	s_nop 1
	v_cvt_pk_bf16_f32 v68, v1, v5
	v_ashrrev_i32_e32 v1, 31, v0
	v_lshlrev_b64 v[0:1], 12, v[0:1]
	v_lshl_add_u64 v[4:5], v[74:75], 0, v[0:1]
	v_or_b32_e32 v0, 2, v72
	v_ashrrev_i32_e32 v1, 31, v0
	v_lshlrev_b64 v[0:1], 12, v[0:1]
	v_cvt_pk_bf16_f32 v69, v9, v13
	v_cvt_pk_bf16_f32 v70, v17, v21
	v_cvt_pk_bf16_f32 v71, v25, v29
	global_store_dwordx4 v[4:5], v[68:71], off sc1
	v_lshl_add_u64 v[8:9], v[74:75], 0, v[0:1]
	s_nop 0
	v_cvt_pk_bf16_f32 v68, v2, v6
	v_or_b32_e32 v6, 3, v72
	v_cvt_pk_bf16_f32 v69, v10, v14
	v_cvt_pk_bf16_f32 v70, v18, v22
	v_cvt_pk_bf16_f32 v71, v26, v30
	global_store_dwordx4 v[8:9], v[68:71], off sc1
	v_cvt_pk_bf16_f32 v0, v3, v7
	v_ashrrev_i32_e32 v7, 31, v6
	v_lshlrev_b64 v[6:7], 12, v[6:7]
	v_cvt_pk_bf16_f32 v1, v11, v15
	v_cvt_pk_bf16_f32 v2, v19, v23
	v_cvt_pk_bf16_f32 v3, v27, v31
	v_lshl_add_u64 v[6:7], v[74:75], 0, v[6:7]
	global_store_dwordx4 v[6:7], v[0:3], off sc1
	s_nop 1
	v_cvt_pk_bf16_f32 v0, v32, v36
	v_cvt_pk_bf16_f32 v1, v40, v44
	v_cvt_pk_bf16_f32 v2, v48, v52
	v_cvt_pk_bf16_f32 v3, v56, v60
	global_store_dwordx4 v[76:77], v[0:3], off offset:64 sc1
	s_nop 1
	v_cvt_pk_bf16_f32 v0, v33, v37
	v_cvt_pk_bf16_f32 v1, v41, v45
	v_cvt_pk_bf16_f32 v2, v49, v53
	v_cvt_pk_bf16_f32 v3, v57, v61
	global_store_dwordx4 v[4:5], v[0:3], off offset:64 sc1
	s_nop 1
	v_cvt_pk_bf16_f32 v0, v34, v38
	v_cvt_pk_bf16_f32 v1, v42, v46
	v_cvt_pk_bf16_f32 v2, v50, v54
	v_cvt_pk_bf16_f32 v3, v58, v62
	global_store_dwordx4 v[8:9], v[0:3], off offset:64 sc1
	s_nop 1
	v_cvt_pk_bf16_f32 v0, v35, v39
	v_cvt_pk_bf16_f32 v1, v43, v47
	v_cvt_pk_bf16_f32 v2, v51, v55
	v_cvt_pk_bf16_f32 v3, v59, v63
	global_store_dwordx4 v[6:7], v[0:3], off offset:64 sc1

; __device__ __forceinline__ unsigned cvt_pk_bf16(float lo, float hi) { unsigned r; asm volatile("v_cvt_pk_bf16_f32 %0, %1, %2" : "=v"(r) : "v"(lo), "v"(hi)); return r; }
; #define INP(i) ((const float*)(const GASP float*)kargs()[(i)])
; __device__ __forceinline__ void tr_item(const float* W, int ldw, int k0, int n0, bf16* WT, int ldk, int drow0, int lane) {
;     const int n4 = (lane & 15) * 4, kg = lane >> 4; f32x4 v[2][8];
; #pragma unroll
;     for (int kh = 0; kh < 2; ++kh) { const float* src = W + (size_t)(k0 + kh * 32 + kg * 8) * ldw + n0 + n4;
; #pragma unroll
;         for (int i = 0; i < 8; ++i) v[kh][i] = __builtin_nontemporal_load((const f32x4*)(src + (size_t)i * ldw)); }
; #pragma unroll
;     for (int kh = 0; kh < 2; ++kh)
; #pragma unroll
;         for (int e = 0; e < 4; ++e) { u32x4 o; o.x = cvt_pk_bf16(v[kh][0][e], v[kh][1][e]); o.y = cvt_pk_bf16(v[kh][2][e], v[kh][3][e]); o.z = cvt_pk_bf16(v[kh][4][e], v[kh][5][e]); o.w = cvt_pk_bf16(v[kh][6][e], v[kh][7][e]);
;             *(u32x4*)(WT + (size_t)(drow0 + n4 + e) * ldk + k0 + kh * 32 + kg * 8) = o; }
; }
; __device__ __forceinline__ void conv_item(int it, int lane) {
;     ...
;     if (r < 8 * IT_D) { const int idx = r / IT_D; r -= idx * IT_D; const int kb = r / 32, nb = r % 32;
;         tr_item(INP(I_WD) + (size_t)idx * 5376 * 2048, 2048, 64 * kb, 64 * nb, (bf16*)(ws + WS_WD) + (size_t)idx * 2048 * 5376, 5376, 64 * nb, lane); return; }
.LBB0_581:
	s_andn2_b64 vcc, exec, s[22:23]
	s_cbranch_vccnz .LBB0_583
	s_add_i32 s11, s6, 0xffff5800
	s_bfe_u32 s12, s11, 0x100007
	s_mulk_i32 s12, 0xc31
	s_lshr_b32 s12, s12, 16
	s_mul_i32 s19, s12, 0xf580
	s_mov_b64 s[20:21], s[0:1]
	s_add_i32 s11, s19, s11
	s_sext_i32_i16 s19, s11
	s_load_dwordx2 s[20:21], s[20:21], 0x70
	s_bfe_u32 s19, s19, 0x5001a
	s_add_i32 s19, s11, s19
	s_sext_i32_i16 s22, s19
	s_and_b32 s19, s19, 0xffe0
	s_sub_i32 s11, s11, s19
	s_mul_i32 s19, s12, 0x2a00000
	s_waitcnt lgkmcnt(0)
	s_add_u32 s19, s20, s19
	s_sext_i32_i16 s11, s11
	s_addc_u32 s23, s21, 0
	s_lshl_b32 s20, s22, 1
	s_and_b32 s22, s20, 0xffffffc0
	s_lshl_b32 s26, s11, 6
	s_mul_i32 s12, s12, 0x1500000
	s_add_u32 s11, s2, s12
	s_addc_u32 s12, s3, 0
	s_ashr_i32 s27, s26, 31
	s_lshl_b64 s[20:21], s[26:27], 2
	v_add_u32_e32 v32, s22, v66
	s_add_u32 s20, s19, s20
	s_addc_u32 s21, s23, s21
	v_lshlrev_b32_e32 v172, 2, v64
	v_ashrrev_i32_e32 v33, 31, v32
	v_lshl_add_u64 v[34:35], s[20:21], 0, v[172:173]
	v_lshlrev_b64 v[0:1], 13, v[32:33]
	v_lshl_add_u64 v[24:25], v[34:35], 0, v[0:1]
	v_add_co_u32_e32 v4, vcc, s89, v24
	s_movk_i32 s20, 0x4000
	s_nop 0
	v_addc_co_u32_e32 v5, vcc, 0, v25, vcc
	v_add_co_u32_e32 v8, vcc, s20, v24
	s_movk_i32 s19, 0x6000
	s_nop 0
	v_addc_co_u32_e32 v9, vcc, 0, v25, vcc
	v_add_co_u32_e32 v12, vcc, s19, v24
	s_mov_b32 s21, 0x8000
	s_nop 0
	v_addc_co_u32_e32 v13, vcc, 0, v25, vcc
	v_add_co_u32_e32 v16, vcc, s21, v24
	v_add_u32_e32 v32, 32, v32
	s_nop 0
	v_addc_co_u32_e32 v17, vcc, 0, v25, vcc
	v_add_co_u32_e32 v20, vcc, s33, v24
	s_mov_b32 s23, 0xe000
	s_nop 0
	v_addc_co_u32_e32 v21, vcc, 0, v25, vcc
	v_add_co_u32_e32 v26, vcc, s38, v24
	v_ashrrev_i32_e32 v33, 31, v32
	s_nop 0
	v_addc_co_u32_e32 v27, vcc, 0, v25, vcc
	v_add_co_u32_e32 v28, vcc, s23, v24
	v_lshlrev_b64 v[32:33], 13, v[32:33]
	s_nop 0
	v_addc_co_u32_e32 v29, vcc, 0, v25, vcc
	v_lshl_add_u64 v[56:57], v[34:35], 0, v[32:33]
	v_add_co_u32_e32 v36, vcc, s89, v56
	global_load_dwordx4 v[0:3], v[24:25], off nt
	s_nop 0
	global_load_dwordx4 v[4:7], v[4:5], off nt
	v_addc_co_u32_e32 v37, vcc, 0, v57, vcc
	v_add_co_u32_e32 v40, vcc, s20, v56
	global_load_dwordx4 v[8:11], v[8:9], off nt
	s_nop 0
	global_load_dwordx4 v[12:15], v[12:13], off nt
	v_addc_co_u32_e32 v41, vcc, 0, v57, vcc
	v_add_co_u32_e32 v44, vcc, s19, v56
	global_load_dwordx4 v[16:19], v[16:17], off nt
	s_nop 0
	global_load_dwordx4 v[20:23], v[20:21], off nt
	v_addc_co_u32_e32 v45, vcc, 0, v57, vcc
	v_add_co_u32_e32 v48, vcc, s21, v56
	global_load_dwordx4 v[24:27], v[26:27], off nt
	s_nop 0
	global_load_dwordx4 v[28:31], v[28:29], off nt
	v_addc_co_u32_e32 v49, vcc, 0, v57, vcc
	v_add_co_u32_e32 v52, vcc, s33, v56
	global_load_dwordx4 v[32:35], v[56:57], off nt
	s_nop 0
	global_load_dwordx4 v[36:39], v[36:37], off nt
	v_addc_co_u32_e32 v53, vcc, 0, v57, vcc
	v_add_co_u32_e32 v58, vcc, s38, v56
	global_load_dwordx4 v[40:43], v[40:41], off nt
	s_nop 0
	global_load_dwordx4 v[44:47], v[44:45], off nt
	v_addc_co_u32_e32 v59, vcc, 0, v57, vcc
	v_add_co_u32_e32 v60, vcc, s23, v56
	global_load_dwordx4 v[48:51], v[48:49], off nt
	s_nop 0
	global_load_dwordx4 v[52:55], v[52:53], off nt
	v_addc_co_u32_e32 v61, vcc, 0, v57, vcc
	global_load_dwordx4 v[56:59], v[58:59], off nt
	s_nop 0
	global_load_dwordx4 v[60:63], v[60:61], off nt
	s_ashr_i32 s23, s22, 31
	s_lshl_b64 s[20:21], s[22:23], 1
	v_or_b32_e32 v65, s26, v64
	s_add_u32 s20, s11, s20
	s_addc_u32 s21, s12, s21
	v_mul_i32_i24_e32 v74, 0x1500, v65
	v_lshl_add_u64 v[72:73], v[66:67], 1, s[20:21]
	v_ashrrev_i32_e32 v75, 31, v74
	v_lshl_add_u64 v[72:73], v[74:75], 1, v[72:73]
	s_mov_b32 s11, 0x15100000
	v_add_co_u32_e32 v76, vcc, s11, v72
	s_mov_b32 s11, 0x15102000
	s_nop 0
	v_addc_co_u32_e32 v77, vcc, 0, v73, vcc
	s_waitcnt vmcnt(0)
	v_cvt_pk_bf16_f32 v68, v0, v4
	v_add_co_u32_e32 v4, vcc, s11, v72
	v_cvt_pk_bf16_f32 v69, v8, v12
	v_cvt_pk_bf16_f32 v70, v16, v20
	v_cvt_pk_bf16_f32 v71, v24, v28
	global_store_dwordx4 v[76:77], v[68:71], off sc1
	s_mov_b32 s11, 0x15105000
	s_mov_b64 s[20:21], 0x15100000
	v_cvt_pk_bf16_f32 v68, v1, v5
	v_addc_co_u32_e32 v5, vcc, 0, v73, vcc
	v_add_co_u32_e32 v8, vcc, s11, v72
	v_cvt_pk_bf16_f32 v69, v9, v13
	s_mov_b32 s11, 0x15107000
	s_nop 0
	v_addc_co_u32_e32 v9, vcc, 0, v73, vcc
	v_cvt_pk_bf16_f32 v70, v17, v21
	v_cvt_pk_bf16_f32 v71, v25, v29
	global_store_dwordx4 v[4:5], v[68:71], off offset:2560 sc1
	v_lshl_add_u64 v[74:75], v[72:73], 0, s[20:21]
	s_nop 0
	v_cvt_pk_bf16_f32 v68, v2, v6
	v_add_co_u32_e32 v6, vcc, s11, v72
	v_cvt_pk_bf16_f32 v69, v10, v14
	v_cvt_pk_bf16_f32 v70, v18, v22
	v_cvt_pk_bf16_f32 v71, v26, v30
	global_store_dwordx4 v[8:9], v[68:71], off offset:1024 sc1
	v_cvt_pk_bf16_f32 v0, v3, v7
	v_cvt_pk_bf16_f32 v1, v11, v15
	v_cvt_pk_bf16_f32 v2, v19, v23
	v_cvt_pk_bf16_f32 v3, v27, v31
	s_nop 0
	v_addc_co_u32_e32 v7, vcc, 0, v73, vcc
	global_store_dwordx4 v[6:7], v[0:3], off offset:3584 sc1
	s_nop 1
	v_cvt_pk_bf16_f32 v0, v32, v36
	v_cvt_pk_bf16_f32 v1, v40, v44
	v_cvt_pk_bf16_f32 v2, v48, v52
	v_cvt_pk_bf16_f32 v3, v56, v60
	global_store_dwordx4 v[74:75], v[0:3], off offset:64 sc1
	s_nop 1
	v_cvt_pk_bf16_f32 v0, v33, v37
	v_cvt_pk_bf16_f32 v1, v41, v45
	v_cvt_pk_bf16_f32 v2, v49, v53
	v_cvt_pk_bf16_f32 v3, v57, v61
	global_store_dwordx4 v[4:5], v[0:3], off offset:2624 sc1
	s_nop 1
	v_cvt_pk_bf16_f32 v0, v34, v38
	v_cvt_pk_bf16_f32 v1, v42, v46
	v_cvt_pk_bf16_f32 v2, v50, v54
	v_cvt_pk_bf16_f32 v3, v58, v62
	global_store_dwordx4 v[8:9], v[0:3], off offset:1088 sc1
	s_nop 1
	v_cvt_pk_bf16_f32 v0, v35, v39
	v_cvt_pk_bf16_f32 v1, v43, v47
	v_cvt_pk_bf16_f32 v2, v51, v55
	v_cvt_pk_bf16_f32 v3, v59, v63
	global_store_dwordx4 v[6:7], v[0:3], off offset:3648 sc1

; #define INP(i) ((const float*)(const GASP float*)kargs()[(i)])
; __device__ __forceinline__ void conv_item(int it, int lane) {
;     unsigned char* ws = WSP; int r = it;
;     if (r < 8 * IT_GU) { const int idx = r / IT_GU; r -= idx * IT_GU; const int kb = r / 168, nb = r % 168, n0 = 64 * nb;
;         const int drow = n0 < DFF ? (n0 >> 7) * 256 + (n0 & 127) : ((n0 - DFF) >> 7) * 256 + 128 + ((n0 - DFF) & 127);
;         tr_item(INP(I_WGU) + (size_t)idx * 2048 * 10752, 10752, 64 * kb, n0, (bf16*)(ws + WS_WGU) + (size_t)idx * 10752 * 2048, 2048, drow, lane); return; }
;     r -= 8 * IT_GU;
;     if (r < 8 * IT_D) { const int idx = r / IT_D; r -= idx * IT_D; const int kb = r / 32, nb = r % 32;
;         tr_item(INP(I_WD) + (size_t)idx * 5376 * 2048, 2048, 64 * kb, 64 * nb, (bf16*)(ws + WS_WD) + (size_t)idx * 2048 * 5376, 5376, 64 * nb, lane); return; }
;     r -= 8 * IT_D;
;     if (r < 2 * IT_INAB) { const int idx = r / IT_INAB; r -= idx * IT_INAB; const int kb = r / 80, nb = r % 80;
;         tr_item(INP(I_WINAB) + (size_t)idx * 2048 * 5120, 5120, 64 * kb, 64 * nb, (bf16*)(ws + WS_WINAB) + (size_t)idx * 5120 * 2048, 2048, 64 * nb, lane); return; }
;     r -= 2 * IT_INAB;
;     if (r < 2 * IT_GLU) { const int idx = r / IT_GLU; r -= idx * IT_GLU; const int kb = r / 16, nb = r % 16;
;         tr_item(INP(I_WGLU) + (size_t)idx * 1024 * 1024, 1024, 64 * kb, 64 * nb, (bf16*)(ws + WS_WGLU) + (size_t)idx * 1024 * 1024, 1024, 64 * nb, lane); return; }
;     r -= 2 * IT_GLU;
;     if (r < 2 * IT_OUTAB) { const int idx = r / IT_OUTAB; r -= idx * IT_OUTAB; const int kb = r / 32, nb = r % 32;
;         tr_item(INP(I_WOUTAB) + (size_t)idx * 2048 * 2048, 2048, 64 * kb, 64 * nb, (bf16*)(ws + WS_WOUTAB) + (size_t)idx * 2048 * 2048, 2048, 64 * nb, lane); return; }
;     r -= 2 * IT_OUTAB;
;     if (r < 2 * IT_INC) { const int idx = r / IT_INC; r -= idx * IT_INC; const int kb = r / 80, nb = r % 80;
;         tr_item(INP(I_WINC) + (size_t)idx * 2048 * 5120, 5120, 64 * kb, 64 * nb, (bf16*)(ws + WS_WINC) + (size_t)idx * 5120 * 2048, 2048, 64 * nb, lane); return; }
;     r -= 2 * IT_INC;
;     { const int idx = r / IT_OUTC; r -= idx * IT_OUTC; const int kb = r / 32, nb = r % 32;
;       tr_item(INP(I_WOUTC) + (size_t)idx * 2560 * 2048, 2048, 64 * kb, 64 * nb, (bf16*)(ws + WS_WOUTC) + (size_t)idx * 2048 * 2560, 2560, 64 * nb, lane); }
.LBB0_1345:
	s_add_i32 s6, s12, s16
	s_mov_b64 s[12:13], s[0:1]
	s_load_dwordx2 s[26:27], s[12:13], 0x138
	v_lshlrev_b32_e32 v0, 2, v174
	s_waitcnt vmcnt(0)
	v_and_b32_e32 v72, 60, v0
	v_ashrrev_i32_e32 v0, 1, v174
	v_and_b32_e32 v64, -8, v0
	v_ashrrev_i32_e32 v65, 31, v64
	s_mov_b64 s[22:23], -1
	s_cmp_gt_i32 s6, 0xa7ff
	s_cbranch_scc0 .LBB0_1367
	s_cmpk_gt_u32 s6, 0xfbff
	s_cbranch_scc0 .LBB0_1364
	s_cmp_gt_u32 s6, 0x10fff
	s_cbranch_scc0 .LBB0_1361
	s_cmp_gt_u32 s6, 0x111ff
	s_cbranch_scc0 .LBB0_1358
	s_cmp_gt_u32 s6, 0x119ff
	s_cbranch_scc0 .LBB0_1355
	s_cmp_gt_u32 s6, 0x12dff
	s_cbranch_scc0 .LBB0_1352
	s_add_i32 s11, s6, 0xfffed200
	s_mul_hi_u32 s12, s11, 0xcccccccd
	s_lshr_b32 s15, s12, 10
	s_mul_i32 s12, s15, 0xfffffb00
	s_add_i32 s11, s12, s11
	s_ashr_i32 s12, s11, 31
	s_lshr_b32 s12, s12, 27
	s_add_i32 s16, s11, s12
	s_mov_b64 s[12:13], s[0:1]
	s_load_dwordx2 s[12:13], s[12:13], 0x128
	s_and_b32 s17, s16, 0x3ffffe0
	s_sub_i32 s11, s11, s17
	s_mul_i32 s18, s15, 0x1400000
	s_mul_hi_u32 s17, s15, 0x1400000
	s_waitcnt lgkmcnt(0)
	s_add_u32 s18, s12, s18
	s_addc_u32 s17, s13, s17
	s_lshl_b32 s12, s16, 1
	s_and_b32 s22, s12, 0xffffffc0
	s_lshl_b32 s28, s11, 6
	s_mul_hi_u32 s11, s15, 0xa00000
	s_mul_i32 s15, s15, 0xa00000
	s_add_u32 s15, s26, s15
	s_addc_u32 s11, s27, s11
	s_ashr_i32 s29, s28, 31
	s_lshl_b64 s[12:13], s[28:29], 2
	v_add_u32_e32 v32, s22, v64
	s_add_u32 s12, s18, s12
	s_addc_u32 s13, s17, s13
	v_lshlrev_b32_e32 v172, 2, v72
	v_ashrrev_i32_e32 v33, 31, v32
	v_lshl_add_u64 v[34:35], s[12:13], 0, v[172:173]
	v_lshlrev_b64 v[0:1], 13, v[32:33]
	v_lshl_add_u64 v[24:25], v[34:35], 0, v[0:1]
	v_add_co_u32_e32 v4, vcc, s89, v24
	s_movk_i32 s13, 0x4000
	s_nop 0
	v_addc_co_u32_e32 v5, vcc, 0, v25, vcc
	v_add_co_u32_e32 v8, vcc, s13, v24
	s_movk_i32 s12, 0x6000
	s_nop 0
	v_addc_co_u32_e32 v9, vcc, 0, v25, vcc
	v_add_co_u32_e32 v12, vcc, s12, v24
	s_mov_b32 s16, 0x8000
	s_nop 0
	v_addc_co_u32_e32 v13, vcc, 0, v25, vcc
	v_add_co_u32_e32 v16, vcc, s16, v24
	v_add_u32_e32 v32, 32, v32
	s_nop 0
	v_addc_co_u32_e32 v17, vcc, 0, v25, vcc
	v_add_co_u32_e32 v20, vcc, s33, v24
	s_mov_b32 s17, 0xe000
	s_nop 0
	v_addc_co_u32_e32 v21, vcc, 0, v25, vcc
	v_add_co_u32_e32 v26, vcc, s38, v24
	v_ashrrev_i32_e32 v33, 31, v32
	s_nop 0
	v_addc_co_u32_e32 v27, vcc, 0, v25, vcc
	v_add_co_u32_e32 v28, vcc, s17, v24
	v_lshlrev_b64 v[32:33], 13, v[32:33]
	s_nop 0
	v_addc_co_u32_e32 v29, vcc, 0, v25, vcc
	v_lshl_add_u64 v[56:57], v[34:35], 0, v[32:33]
	v_add_co_u32_e32 v36, vcc, s89, v56
	global_load_dwordx4 v[0:3], v[24:25], off nt
	s_nop 0
	global_load_dwordx4 v[4:7], v[4:5], off nt
	v_addc_co_u32_e32 v37, vcc, 0, v57, vcc
	v_add_co_u32_e32 v40, vcc, s13, v56
	global_load_dwordx4 v[8:11], v[8:9], off nt
	s_nop 0
	global_load_dwordx4 v[12:15], v[12:13], off nt
	v_addc_co_u32_e32 v41, vcc, 0, v57, vcc
	v_add_co_u32_e32 v44, vcc, s12, v56
	global_load_dwordx4 v[16:19], v[16:17], off nt
	s_nop 0
	global_load_dwordx4 v[20:23], v[20:21], off nt
	v_addc_co_u32_e32 v45, vcc, 0, v57, vcc
	v_add_co_u32_e32 v48, vcc, s16, v56
	global_load_dwordx4 v[24:27], v[26:27], off nt
	s_nop 0
	global_load_dwordx4 v[28:31], v[28:29], off nt
	v_addc_co_u32_e32 v49, vcc, 0, v57, vcc
	v_add_co_u32_e32 v52, vcc, s33, v56
	global_load_dwordx4 v[32:35], v[56:57], off nt
	s_nop 0
	global_load_dwordx4 v[36:39], v[36:37], off nt
	v_addc_co_u32_e32 v53, vcc, 0, v57, vcc
	v_add_co_u32_e32 v58, vcc, s38, v56
	global_load_dwordx4 v[40:43], v[40:41], off nt
	s_nop 0
	global_load_dwordx4 v[44:47], v[44:45], off nt
	v_addc_co_u32_e32 v59, vcc, 0, v57, vcc
	v_add_co_u32_e32 v60, vcc, s17, v56
	global_load_dwordx4 v[48:51], v[48:49], off nt
	s_nop 0
	global_load_dwordx4 v[52:55], v[52:53], off nt
	v_addc_co_u32_e32 v61, vcc, 0, v57, vcc
	global_load_dwordx4 v[56:59], v[58:59], off nt
	s_nop 0
	global_load_dwordx4 v[60:63], v[60:61], off nt
	s_ashr_i32 s23, s22, 31
	s_lshl_b64 s[12:13], s[22:23], 1
	s_add_u32 s12, s15, s12
	v_or_b32_e32 v73, s28, v72
	s_addc_u32 s13, s11, s13
	s_movk_i32 s11, 0xa00
	v_mul_lo_u32 v74, v73, s11
	v_lshl_add_u64 v[70:71], v[64:65], 1, s[12:13]
	v_ashrrev_i32_e32 v75, 31, v74
	v_lshl_add_u64 v[70:71], v[74:75], 1, v[70:71]
	s_mov_b32 s11, 0x25d00000
	v_add_co_u32_e32 v76, vcc, s11, v70
	s_mov_b32 s11, 0x25d01000
	s_nop 0
	v_addc_co_u32_e32 v77, vcc, 0, v71, vcc
	s_waitcnt vmcnt(14)
	v_cvt_pk_bf16_f32 v66, v0, v4
	v_add_co_u32_e32 v4, vcc, s11, v70
	s_waitcnt vmcnt(12)
	v_cvt_pk_bf16_f32 v67, v8, v12
	s_waitcnt vmcnt(10)
	v_cvt_pk_bf16_f32 v68, v16, v20
	s_waitcnt vmcnt(8)
	v_cvt_pk_bf16_f32 v69, v24, v28
	global_store_dwordx4 v[76:77], v[66:69], off sc1
	s_mov_b32 s11, 0x25d02000
	s_mov_b64 s[12:13], 0x25d00000
	v_cvt_pk_bf16_f32 v66, v1, v5
	v_addc_co_u32_e32 v5, vcc, 0, v71, vcc
	v_add_co_u32_e32 v8, vcc, s11, v70
	v_cvt_pk_bf16_f32 v67, v9, v13
	s_mov_b32 s11, 0x25d03000
	s_nop 0
	v_addc_co_u32_e32 v9, vcc, 0, v71, vcc
	v_cvt_pk_bf16_f32 v68, v17, v21
	v_cvt_pk_bf16_f32 v69, v25, v29
	global_store_dwordx4 v[4:5], v[66:69], off offset:1024 sc1
	v_lshl_add_u64 v[74:75], v[70:71], 0, s[12:13]
	s_mov_b64 s[22:23], 0
	v_cvt_pk_bf16_f32 v66, v2, v6
	v_add_co_u32_e32 v6, vcc, s11, v70
	v_cvt_pk_bf16_f32 v67, v10, v14
	v_cvt_pk_bf16_f32 v68, v18, v22
	v_cvt_pk_bf16_f32 v69, v26, v30
	global_store_dwordx4 v[8:9], v[66:69], off offset:2048 sc1
	v_cvt_pk_bf16_f32 v0, v3, v7
	v_cvt_pk_bf16_f32 v1, v11, v15
	v_cvt_pk_bf16_f32 v2, v19, v23
	v_cvt_pk_bf16_f32 v3, v27, v31
	s_nop 0
	v_addc_co_u32_e32 v7, vcc, 0, v71, vcc
	global_store_dwordx4 v[6:7], v[0:3], off offset:3072 sc1
	s_waitcnt vmcnt(10)
	s_nop 0
	v_cvt_pk_bf16_f32 v0, v32, v36
	s_waitcnt vmcnt(8)
	v_cvt_pk_bf16_f32 v1, v40, v44
	s_waitcnt vmcnt(6)
	v_cvt_pk_bf16_f32 v2, v48, v52
	s_waitcnt vmcnt(4)
	v_cvt_pk_bf16_f32 v3, v56, v60
	global_store_dwordx4 v[74:75], v[0:3], off offset:64 sc1
	s_nop 1
	v_cvt_pk_bf16_f32 v0, v33, v37
	v_cvt_pk_bf16_f32 v1, v41, v45
	v_cvt_pk_bf16_f32 v2, v49, v53
	v_cvt_pk_bf16_f32 v3, v57, v61
	global_store_dwordx4 v[4:5], v[0:3], off offset:1088 sc1
	s_nop 1
	v_cvt_pk_bf16_f32 v0, v34, v38
	v_cvt_pk_bf16_f32 v1, v42, v46
	v_cvt_pk_bf16_f32 v2, v50, v54
	v_cvt_pk_bf16_f32 v3, v58, v62
	global_store_dwordx4 v[8:9], v[0:3], off offset:2112 sc1
	s_nop 1
	v_cvt_pk_bf16_f32 v0, v35, v39
	v_cvt_pk_bf16_f32 v1, v43, v47
	v_cvt_pk_bf16_f32 v2, v51, v55
	v_cvt_pk_bf16_f32 v3, v59, v63
	global_store_dwordx4 v[6:7], v[0:3], off offset:3136 sc1
; __device__ __forceinline__ unsigned cvt_pk_bf16(float lo, float hi) { unsigned r; asm volatile("v_cvt_pk_bf16_f32 %0, %1, %2" : "=v"(r) : "v"(lo), "v"(hi)); return r; }
; #define INP(i) ((const float*)(const GASP float*)kargs()[(i)])
; __device__ __forceinline__ void tr_item(const float* W, int ldw, int k0, int n0, bf16* WT, int ldk, int drow0, int lane) {
;     const int n4 = (lane & 15) * 4, kg = lane >> 4; f32x4 v[2][8];
; #pragma unroll
;     for (int kh = 0; kh < 2; ++kh) { const float* src = W + (size_t)(k0 + kh * 32 + kg * 8) * ldw + n0 + n4;
; #pragma unroll
;         for (int i = 0; i < 8; ++i) v[kh][i] = __builtin_nontemporal_load((const f32x4*)(src + (size_t)i * ldw)); }
; #pragma unroll
;     for (int kh = 0; kh < 2; ++kh)
; #pragma unroll
;         for (int e = 0; e < 4; ++e) { u32x4 o; o.x = cvt_pk_bf16(v[kh][0][e], v[kh][1][e]); o.y = cvt_pk_bf16(v[kh][2][e], v[kh][3][e]); o.z = cvt_pk_bf16(v[kh][4][e], v[kh][5][e]); o.w = cvt_pk_bf16(v[kh][6][e], v[kh][7][e]);
;             *(u32x4*)(WT + (size_t)(drow0 + n4 + e) * ldk + k0 + kh * 32 + kg * 8) = o; }
; }
; __device__ __forceinline__ void conv_item(int it, int lane) {
;     ...
;     if (r < 2 * IT_INC) { const int idx = r / IT_INC; r -= idx * IT_INC; const int kb = r / 80, nb = r % 80;
;         tr_item(INP(I_WINC) + (size_t)idx * 2048 * 5120, 5120, 64 * kb, 64 * nb, (bf16*)(ws + WS_WINC) + (size_t)idx * 5120 * 2048, 2048, 64 * nb, lane); return; }
.LBB0_1352:
	s_andn2_b64 vcc, exec, s[22:23]
	s_cbranch_vccnz .LBB0_1354
	s_add_i32 s11, s6, 0xfffee600
	s_cmpk_gt_u32 s11, 0x9ff
	s_cselect_b64 s[12:13], -1, 0
	s_and_b64 s[16:17], s[12:13], exec
	s_cselect_b32 s15, 0xf600, 0
	s_add_i32 s15, s15, s11
	s_sext_i32_i16 s11, s15
	s_mulk_i32 s11, 0x6667
	s_lshr_b32 s16, s11, 31
	s_ashr_i32 s11, s11, 21
	s_add_i32 s11, s11, s16
	s_mov_b64 s[16:17], s[0:1]
	s_load_dwordx2 s[16:17], s[16:17], 0xe8
	s_mul_i32 s18, s11, 0x50
	s_sub_i32 s15, s15, s18
	s_and_b64 s[18:19], s[12:13], exec
	s_cselect_b32 s18, 0x2800000, 0
	s_sext_i32_i16 s15, s15
	s_waitcnt lgkmcnt(0)
	s_add_u32 s16, s16, s18
	s_addc_u32 s17, s17, 0
	s_lshl_b32 s22, s11, 6
	s_lshl_b32 s28, s15, 6
	s_and_b64 s[12:13], s[12:13], exec
	s_cselect_b32 s11, 0x1400000, 0
	s_add_u32 s11, s26, s11
	s_addc_u32 s15, s27, 0
	s_ashr_i32 s29, s28, 31
	s_lshl_b64 s[12:13], s[28:29], 2
	s_add_u32 s12, s16, s12
	s_addc_u32 s13, s17, s13
	v_lshlrev_b32_e32 v172, 2, v72
	v_add_u32_e32 v34, s22, v64
	v_lshl_add_u64 v[32:33], s[12:13], 0, v[172:173]
	s_movk_i32 s18, 0x5000
	v_mad_i64_i32 v[24:25], s[12:13], v34, s18, v[32:33]
	v_add_co_u32_e32 v4, vcc, s18, v24
	s_mov_b32 s16, 0x14000
	s_nop 0
	v_addc_co_u32_e32 v5, vcc, 0, v25, vcc
	v_add_co_u32_e32 v8, vcc, s33, v24
	s_mov_b32 s19, 0x19000
	s_nop 0
	v_addc_co_u32_e32 v9, vcc, 0, v25, vcc
	v_add_co_u32_e32 v12, vcc, s76, v24
	s_mov_b32 s17, 0x1e000
	s_nop 0
	v_addc_co_u32_e32 v13, vcc, 0, v25, vcc
	v_add_co_u32_e32 v16, vcc, s16, v24
	v_add_u32_e32 v34, 32, v34
	s_nop 0
	v_addc_co_u32_e32 v17, vcc, 0, v25, vcc
	v_add_co_u32_e32 v20, vcc, s19, v24
	v_mad_i64_i32 v[56:57], s[12:13], v34, s18, v[32:33]
	s_nop 0
	v_addc_co_u32_e32 v21, vcc, 0, v25, vcc
	v_add_co_u32_e32 v26, vcc, s17, v24
	global_load_dwordx4 v[0:3], v[24:25], off nt
	s_nop 0
	global_load_dwordx4 v[4:7], v[4:5], off nt
	v_addc_co_u32_e32 v27, vcc, 0, v25, vcc
	v_add_co_u32_e32 v28, vcc, s77, v24
	global_load_dwordx4 v[8:11], v[8:9], off nt
	s_nop 0
	global_load_dwordx4 v[12:15], v[12:13], off nt
	v_addc_co_u32_e32 v29, vcc, 0, v25, vcc
	v_add_co_u32_e32 v36, vcc, s18, v56
	global_load_dwordx4 v[16:19], v[16:17], off nt
	s_nop 0
	global_load_dwordx4 v[20:23], v[20:21], off nt
	v_addc_co_u32_e32 v37, vcc, 0, v57, vcc
	v_add_co_u32_e32 v40, vcc, s33, v56
	global_load_dwordx4 v[24:27], v[26:27], off nt
	s_nop 0
	global_load_dwordx4 v[28:31], v[28:29], off nt
	v_addc_co_u32_e32 v41, vcc, 0, v57, vcc
	v_add_co_u32_e32 v44, vcc, s76, v56
	global_load_dwordx4 v[32:35], v[56:57], off nt
	s_nop 0
	global_load_dwordx4 v[36:39], v[36:37], off nt
	v_addc_co_u32_e32 v45, vcc, 0, v57, vcc
	v_add_co_u32_e32 v48, vcc, s16, v56
	global_load_dwordx4 v[40:43], v[40:41], off nt
	s_nop 0
	global_load_dwordx4 v[44:47], v[44:45], off nt
	v_addc_co_u32_e32 v49, vcc, 0, v57, vcc
	v_add_co_u32_e32 v52, vcc, s19, v56
	s_ashr_i32 s23, s22, 31
	s_nop 0
	v_addc_co_u32_e32 v53, vcc, 0, v57, vcc
	v_add_co_u32_e32 v58, vcc, s17, v56
	global_load_dwordx4 v[48:51], v[48:49], off nt
	s_nop 0
	global_load_dwordx4 v[52:55], v[52:53], off nt
	v_addc_co_u32_e32 v59, vcc, 0, v57, vcc
	v_add_co_u32_e32 v60, vcc, s77, v56
	s_lshl_b64 s[12:13], s[22:23], 1
	s_nop 0
	v_addc_co_u32_e32 v61, vcc, 0, v57, vcc
	global_load_dwordx4 v[56:59], v[58:59], off nt
	s_nop 0
	global_load_dwordx4 v[60:63], v[60:61], off nt
	s_add_u32 s12, s11, s12
	v_or_b32_e32 v70, s28, v72
	s_addc_u32 s13, s15, s13
	v_lshl_add_u64 v[66:67], v[64:65], 1, s[12:13]
	s_mov_b64 s[12:13], 0x23500000
	v_ashrrev_i32_e32 v71, 31, v70
	v_lshl_add_u64 v[74:75], v[66:67], 0, s[12:13]
	v_lshlrev_b64 v[76:77], 12, v[70:71]
	s_waitcnt vmcnt(14)
	v_cvt_pk_bf16_f32 v66, v0, v4
	v_lshl_add_u64 v[76:77], v[74:75], 0, v[76:77]
	v_or_b32_e32 v0, 1, v70
	s_waitcnt vmcnt(12)
	v_cvt_pk_bf16_f32 v67, v8, v12
	s_waitcnt vmcnt(10)
	v_cvt_pk_bf16_f32 v68, v16, v20
	s_waitcnt vmcnt(8)
	v_cvt_pk_bf16_f32 v69, v24, v28
	global_store_dwordx4 v[76:77], v[66:69], off sc1
	s_nop 1
	v_cvt_pk_bf16_f32 v66, v1, v5
	v_ashrrev_i32_e32 v1, 31, v0
	v_lshlrev_b64 v[0:1], 12, v[0:1]
	v_lshl_add_u64 v[4:5], v[74:75], 0, v[0:1]
	v_or_b32_e32 v0, 2, v70
	v_ashrrev_i32_e32 v1, 31, v0
	v_lshlrev_b64 v[0:1], 12, v[0:1]
	v_cvt_pk_bf16_f32 v67, v9, v13
	v_cvt_pk_bf16_f32 v68, v17, v21
	v_cvt_pk_bf16_f32 v69, v25, v29
	global_store_dwordx4 v[4:5], v[66:69], off sc1
	v_lshl_add_u64 v[8:9], v[74:75], 0, v[0:1]
	s_nop 0
	v_cvt_pk_bf16_f32 v66, v2, v6
	v_or_b32_e32 v6, 3, v70
	v_cvt_pk_bf16_f32 v67, v10, v14
	v_cvt_pk_bf16_f32 v68, v18, v22
	v_cvt_pk_bf16_f32 v69, v26, v30
	global_store_dwordx4 v[8:9], v[66:69], off sc1
	v_cvt_pk_bf16_f32 v0, v3, v7
	v_ashrrev_i32_e32 v7, 31, v6
	v_lshlrev_b64 v[6:7], 12, v[6:7]
	v_cvt_pk_bf16_f32 v1, v11, v15
	v_cvt_pk_bf16_f32 v2, v19, v23
	v_cvt_pk_bf16_f32 v3, v27, v31
	v_lshl_add_u64 v[6:7], v[74:75], 0, v[6:7]
	global_store_dwordx4 v[6:7], v[0:3], off sc1
	s_waitcnt vmcnt(10)
	s_nop 0
	v_cvt_pk_bf16_f32 v0, v32, v36
	s_waitcnt vmcnt(8)
	v_cvt_pk_bf16_f32 v1, v40, v44
	s_waitcnt vmcnt(6)
	v_cvt_pk_bf16_f32 v2, v48, v52
	s_waitcnt vmcnt(4)
	v_cvt_pk_bf16_f32 v3, v56, v60
	global_store_dwordx4 v[76:77], v[0:3], off offset:64 sc1
	s_nop 1
	v_cvt_pk_bf16_f32 v0, v33, v37
	v_cvt_pk_bf16_f32 v1, v41, v45
	v_cvt_pk_bf16_f32 v2, v49, v53
	v_cvt_pk_bf16_f32 v3, v57, v61
	global_store_dwordx4 v[4:5], v[0:3], off offset:64 sc1
	s_nop 1
	v_cvt_pk_bf16_f32 v0, v34, v38
	v_cvt_pk_bf16_f32 v1, v42, v46
	v_cvt_pk_bf16_f32 v2, v50, v54
	v_cvt_pk_bf16_f32 v3, v58, v62
	global_store_dwordx4 v[8:9], v[0:3], off offset:64 sc1
	s_nop 1
	v_cvt_pk_bf16_f32 v0, v35, v39
	v_cvt_pk_bf16_f32 v1, v43, v47
	v_cvt_pk_bf16_f32 v2, v51, v55
	v_cvt_pk_bf16_f32 v3, v59, v63
	global_store_dwordx4 v[6:7], v[0:3], off offset:64 sc1

; __device__ __forceinline__ unsigned cvt_pk_bf16(float lo, float hi) { unsigned r; asm volatile("v_cvt_pk_bf16_f32 %0, %1, %2" : "=v"(r) : "v"(lo), "v"(hi)); return r; }
; #define INP(i) ((const float*)(const GASP float*)kargs()[(i)])
; __device__ __forceinline__ void tr_item(const float* W, int ldw, int k0, int n0, bf16* WT, int ldk, int drow0, int lane) {
;     const int n4 = (lane & 15) * 4, kg = lane >> 4; f32x4 v[2][8];
; #pragma unroll
;     for (int kh = 0; kh < 2; ++kh) { const float* src = W + (size_t)(k0 + kh * 32 + kg * 8) * ldw + n0 + n4;
; #pragma unroll
;         for (int i = 0; i < 8; ++i) v[kh][i] = __builtin_nontemporal_load((const f32x4*)(src + (size_t)i * ldw)); }
; #pragma unroll
;     for (int kh = 0; kh < 2; ++kh)
; #pragma unroll
;         for (int e = 0; e < 4; ++e) { u32x4 o; o.x = cvt_pk_bf16(v[kh][0][e], v[kh][1][e]); o.y = cvt_pk_bf16(v[kh][2][e], v[kh][3][e]); o.z = cvt_pk_bf16(v[kh][4][e], v[kh][5][e]); o.w = cvt_pk_bf16(v[kh][6][e], v[kh][7][e]);
;             *(u32x4*)(WT + (size_t)(drow0 + n4 + e) * ldk + k0 + kh * 32 + kg * 8) = o; }
; }
; __device__ __forceinline__ void conv_item(int it, int lane) {
;     ...
;     if (r < 2 * IT_OUTAB) { const int idx = r / IT_OUTAB; r -= idx * IT_OUTAB; const int kb = r / 32, nb = r % 32;
;         tr_item(INP(I_WOUTAB) + (size_t)idx * 2048 * 2048, 2048, 64 * kb, 64 * nb, (bf16*)(ws + WS_WOUTAB) + (size_t)idx * 2048 * 2048, 2048, 64 * nb, lane); return; }
.LBB0_1355:
	s_andn2_b64 vcc, exec, s[22:23]
	s_cbranch_vccnz .LBB0_1357
	s_mov_b64 s[12:13], s[0:1]
	s_load_dwordx2 s[12:13], s[12:13], 0xe0
	s_add_i32 s11, s6, 0xfffeee00
	s_lshr_b32 s38, s11, 10
	s_lshl_b64 s[16:17], s[38:39], 24
	v_lshlrev_b32_e32 v172, 2, v72
	s_waitcnt lgkmcnt(0)
	s_add_u32 s15, s12, s16
	s_addc_u32 s16, s13, s17
	s_lshl_b32 s11, s11, 1
	s_lshl_b32 s12, s6, 6
	s_and_b32 s11, s11, 0x7c0
	s_and_b32 s17, s12, 0x7c0
	s_lshl_b64 s[12:13], s[38:39], 23
	s_add_u32 s18, s26, s12
	s_addc_u32 s19, s27, s13
	s_lshl_b32 s12, s17, 2
	v_add_u32_e32 v32, s11, v64
	s_add_u32 s12, s15, s12
	s_addc_u32 s13, s16, 0
	v_ashrrev_i32_e32 v33, 31, v32
	v_lshl_add_u64 v[34:35], s[12:13], 0, v[172:173]
	v_lshlrev_b64 v[0:1], 13, v[32:33]
	v_lshl_add_u64 v[24:25], v[34:35], 0, v[0:1]
	v_add_co_u32_e32 v4, vcc, s89, v24
	s_movk_i32 s13, 0x4000
	s_nop 0
	v_addc_co_u32_e32 v5, vcc, 0, v25, vcc
	v_add_co_u32_e32 v8, vcc, s13, v24
	s_movk_i32 s12, 0x6000
	s_nop 0
	v_addc_co_u32_e32 v9, vcc, 0, v25, vcc
	v_add_co_u32_e32 v12, vcc, s12, v24
	s_mov_b32 s15, 0x8000
	s_nop 0
	v_addc_co_u32_e32 v13, vcc, 0, v25, vcc
	v_add_co_u32_e32 v16, vcc, s15, v24
	s_mov_b32 s38, 0xc000
	s_nop 0
	v_addc_co_u32_e32 v17, vcc, 0, v25, vcc
	v_add_co_u32_e32 v20, vcc, s33, v24
	v_add_u32_e32 v32, 32, v32
	s_nop 0
	v_addc_co_u32_e32 v21, vcc, 0, v25, vcc
	v_add_co_u32_e32 v26, vcc, s38, v24
	s_mov_b32 s16, 0xe000
	s_nop 0
	v_addc_co_u32_e32 v27, vcc, 0, v25, vcc
	v_ashrrev_i32_e32 v33, 31, v32
	v_add_co_u32_e32 v28, vcc, s16, v24
	v_lshlrev_b64 v[32:33], 13, v[32:33]
	s_nop 0
	v_addc_co_u32_e32 v29, vcc, 0, v25, vcc
	v_lshl_add_u64 v[56:57], v[34:35], 0, v[32:33]
	v_add_co_u32_e32 v36, vcc, s89, v56
	global_load_dwordx4 v[0:3], v[24:25], off nt
	s_nop 0
	global_load_dwordx4 v[4:7], v[4:5], off nt
	v_addc_co_u32_e32 v37, vcc, 0, v57, vcc
	v_add_co_u32_e32 v40, vcc, s13, v56
	global_load_dwordx4 v[8:11], v[8:9], off nt
	s_nop 0
	global_load_dwordx4 v[12:15], v[12:13], off nt
	v_addc_co_u32_e32 v41, vcc, 0, v57, vcc
	v_add_co_u32_e32 v44, vcc, s12, v56
	global_load_dwordx4 v[16:19], v[16:17], off nt
	s_nop 0
	global_load_dwordx4 v[20:23], v[20:21], off nt
	v_addc_co_u32_e32 v45, vcc, 0, v57, vcc
	v_add_co_u32_e32 v48, vcc, s15, v56
	global_load_dwordx4 v[24:27], v[26:27], off nt
	s_nop 0
	global_load_dwordx4 v[28:31], v[28:29], off nt
	v_addc_co_u32_e32 v49, vcc, 0, v57, vcc
	v_add_co_u32_e32 v52, vcc, s33, v56
	global_load_dwordx4 v[32:35], v[56:57], off nt
	s_nop 0
	global_load_dwordx4 v[36:39], v[36:37], off nt
	v_addc_co_u32_e32 v53, vcc, 0, v57, vcc
	v_add_co_u32_e32 v58, vcc, s38, v56
	global_load_dwordx4 v[40:43], v[40:41], off nt
	s_nop 0
	global_load_dwordx4 v[44:47], v[44:45], off nt
	v_addc_co_u32_e32 v59, vcc, 0, v57, vcc
	v_add_co_u32_e32 v60, vcc, s16, v56
	global_load_dwordx4 v[48:51], v[48:49], off nt
	s_nop 0
	global_load_dwordx4 v[52:55], v[52:53], off nt
	v_addc_co_u32_e32 v61, vcc, 0, v57, vcc
	global_load_dwordx4 v[56:59], v[58:59], off nt
	s_nop 0
	global_load_dwordx4 v[60:63], v[60:61], off nt
	s_lshl_b32 s11, s11, 1
	s_add_u32 s12, s18, s11
	s_addc_u32 s13, s19, 0
	v_or_b32_e32 v73, s17, v72
	v_lshl_add_u64 v[70:71], v[64:65], 1, s[12:13]
	s_mov_b64 s[12:13], 0x22500000
	v_lshl_add_u64 v[74:75], v[70:71], 0, s[12:13]
	v_lshlrev_b32_e32 v172, 12, v73
	s_waitcnt vmcnt(14)
	v_cvt_pk_bf16_f32 v66, v0, v4
	v_lshl_add_u64 v[76:77], v[74:75], 0, v[172:173]
	s_waitcnt vmcnt(12)
	v_cvt_pk_bf16_f32 v67, v8, v12
	s_waitcnt vmcnt(10)
	v_cvt_pk_bf16_f32 v68, v16, v20
	s_waitcnt vmcnt(8)
	v_cvt_pk_bf16_f32 v69, v24, v28
	global_store_dwordx4 v[76:77], v[66:69], off sc1
	v_or_b32_e32 v4, 0x1000, v172
	v_or_b32_e32 v8, 0x2000, v172
	v_cvt_pk_bf16_f32 v66, v1, v5
	v_mov_b32_e32 v5, v173
	v_cvt_pk_bf16_f32 v67, v9, v13
	v_lshl_add_u64 v[0:1], v[74:75], 0, v[4:5]
	v_mov_b32_e32 v9, v173
	v_cvt_pk_bf16_f32 v68, v17, v21
	v_cvt_pk_bf16_f32 v69, v25, v29
	global_store_dwordx4 v[0:1], v[66:69], off sc1
	v_lshl_add_u64 v[0:1], v[74:75], 0, v[8:9]
	v_or_b32_e32 v172, 0x3000, v172
	v_cvt_pk_bf16_f32 v66, v2, v6
	v_cvt_pk_bf16_f32 v67, v10, v14
	v_cvt_pk_bf16_f32 v68, v18, v22
	v_cvt_pk_bf16_f32 v69, v26, v30
	global_store_dwordx4 v[0:1], v[66:69], off sc1
	v_cvt_pk_bf16_f32 v0, v3, v7
	v_lshl_add_u64 v[6:7], v[74:75], 0, v[172:173]
	s_mov_b64 s[12:13], 0x22500040
	v_cvt_pk_bf16_f32 v1, v11, v15
	v_cvt_pk_bf16_f32 v2, v19, v23
	v_cvt_pk_bf16_f32 v3, v27, v31
	global_store_dwordx4 v[6:7], v[0:3], off sc1
	v_lshl_add_u64 v[6:7], v[70:71], 0, s[12:13]
	v_lshl_add_u64 v[4:5], v[6:7], 0, v[4:5]
	s_waitcnt vmcnt(10)
	v_cvt_pk_bf16_f32 v0, v32, v36
	s_waitcnt vmcnt(8)
	v_cvt_pk_bf16_f32 v1, v40, v44
	s_waitcnt vmcnt(6)
	v_cvt_pk_bf16_f32 v2, v48, v52
	s_waitcnt vmcnt(4)
	v_cvt_pk_bf16_f32 v3, v56, v60
	global_store_dwordx4 v[76:77], v[0:3], off offset:64 sc1
	s_nop 1
	v_cvt_pk_bf16_f32 v0, v33, v37
	v_cvt_pk_bf16_f32 v1, v41, v45
	v_cvt_pk_bf16_f32 v2, v49, v53
	v_cvt_pk_bf16_f32 v3, v57, v61
	global_store_dwordx4 v[4:5], v[0:3], off sc1
	v_lshl_add_u64 v[4:5], v[6:7], 0, v[8:9]
	s_nop 0
	v_cvt_pk_bf16_f32 v0, v34, v38
	v_cvt_pk_bf16_f32 v1, v42, v46
	v_cvt_pk_bf16_f32 v2, v50, v54
	v_cvt_pk_bf16_f32 v3, v58, v62
	global_store_dwordx4 v[4:5], v[0:3], off sc1
	v_lshl_add_u64 v[4:5], v[6:7], 0, v[172:173]
	s_nop 0
	v_cvt_pk_bf16_f32 v0, v35, v39
	v_cvt_pk_bf16_f32 v1, v43, v47
	v_cvt_pk_bf16_f32 v2, v51, v55
	v_cvt_pk_bf16_f32 v3, v59, v63
	global_store_dwordx4 v[4:5], v[0:3], off sc1

; __device__ __forceinline__ unsigned cvt_pk_bf16(float lo, float hi) { unsigned r; asm volatile("v_cvt_pk_bf16_f32 %0, %1, %2" : "=v"(r) : "v"(lo), "v"(hi)); return r; }
; #define INP(i) ((const float*)(const GASP float*)kargs()[(i)])
; __device__ __forceinline__ void tr_item(const float* W, int ldw, int k0, int n0, bf16* WT, int ldk, int drow0, int lane) {
;     const int n4 = (lane & 15) * 4, kg = lane >> 4; f32x4 v[2][8];
; #pragma unroll
;     for (int kh = 0; kh < 2; ++kh) { const float* src = W + (size_t)(k0 + kh * 32 + kg * 8) * ldw + n0 + n4;
; #pragma unroll
;         for (int i = 0; i < 8; ++i) v[kh][i] = __builtin_nontemporal_load((const f32x4*)(src + (size_t)i * ldw)); }
; #pragma unroll
;     for (int kh = 0; kh < 2; ++kh)
; #pragma unroll
;         for (int e = 0; e < 4; ++e) { u32x4 o; o.x = cvt_pk_bf16(v[kh][0][e], v[kh][1][e]); o.y = cvt_pk_bf16(v[kh][2][e], v[kh][3][e]); o.z = cvt_pk_bf16(v[kh][4][e], v[kh][5][e]); o.w = cvt_pk_bf16(v[kh][6][e], v[kh][7][e]);
;             *(u32x4*)(WT + (size_t)(drow0 + n4 + e) * ldk + k0 + kh * 32 + kg * 8) = o; }
; }
; __device__ __forceinline__ void conv_item(int it, int lane) {
;     ...
;     if (r < 2 * IT_INAB) { const int idx = r / IT_INAB; r -= idx * IT_INAB; const int kb = r / 80, nb = r % 80;
;         tr_item(INP(I_WINAB) + (size_t)idx * 2048 * 5120, 5120, 64 * kb, 64 * nb, (bf16*)(ws + WS_WINAB) + (size_t)idx * 5120 * 2048, 2048, 64 * nb, lane); return; }
.LBB0_1361:
	s_andn2_b64 vcc, exec, s[22:23]
	s_cbranch_vccnz .LBB0_1363
	s_add_i32 s11, s6, 0xffff0400
	s_cmpk_gt_u32 s11, 0x9ff
	s_cselect_b64 s[12:13], -1, 0
	s_and_b64 s[16:17], s[12:13], exec
	s_cselect_b32 s15, 0xf600, 0
	s_add_i32 s15, s15, s11
	s_sext_i32_i16 s11, s15
	s_mulk_i32 s11, 0x6667
	s_lshr_b32 s16, s11, 31
	s_ashr_i32 s11, s11, 21
	s_add_i32 s11, s11, s16
	s_mov_b64 s[16:17], s[0:1]
	s_load_dwordx2 s[16:17], s[16:17], 0x78
	s_mul_i32 s18, s11, 0x50
	s_sub_i32 s15, s15, s18
	s_and_b64 s[18:19], s[12:13], exec
	s_cselect_b32 s18, 0x2800000, 0
	s_sext_i32_i16 s15, s15
	s_waitcnt lgkmcnt(0)
	s_add_u32 s16, s16, s18
	s_addc_u32 s17, s17, 0
	s_lshl_b32 s22, s11, 6
	s_lshl_b32 s28, s15, 6
	s_and_b64 s[12:13], s[12:13], exec
	s_cselect_b32 s11, 0x1400000, 0
	s_add_u32 s11, s26, s11
	s_addc_u32 s15, s27, 0
	s_ashr_i32 s29, s28, 31
	s_lshl_b64 s[12:13], s[28:29], 2
	s_add_u32 s12, s16, s12
	s_addc_u32 s13, s17, s13
	v_lshlrev_b32_e32 v172, 2, v72
	v_add_u32_e32 v34, s22, v64
	v_lshl_add_u64 v[32:33], s[12:13], 0, v[172:173]
	s_movk_i32 s18, 0x5000
	v_mad_i64_i32 v[24:25], s[12:13], v34, s18, v[32:33]
	v_add_co_u32_e32 v4, vcc, s18, v24
	s_mov_b32 s16, 0x14000
	s_nop 0
	v_addc_co_u32_e32 v5, vcc, 0, v25, vcc
	v_add_co_u32_e32 v8, vcc, s33, v24
	s_mov_b32 s19, 0x19000
	s_nop 0
	v_addc_co_u32_e32 v9, vcc, 0, v25, vcc
	v_add_co_u32_e32 v12, vcc, s76, v24
	s_mov_b32 s17, 0x1e000
	s_nop 0
	v_addc_co_u32_e32 v13, vcc, 0, v25, vcc
	v_add_co_u32_e32 v16, vcc, s16, v24
	v_add_u32_e32 v34, 32, v34
	s_nop 0
	v_addc_co_u32_e32 v17, vcc, 0, v25, vcc
	v_add_co_u32_e32 v20, vcc, s19, v24
	v_mad_i64_i32 v[56:57], s[12:13], v34, s18, v[32:33]
	s_nop 0
	v_addc_co_u32_e32 v21, vcc, 0, v25, vcc
	v_add_co_u32_e32 v26, vcc, s17, v24
	global_load_dwordx4 v[0:3], v[24:25], off nt
	s_nop 0
	global_load_dwordx4 v[4:7], v[4:5], off nt
	v_addc_co_u32_e32 v27, vcc, 0, v25, vcc
	v_add_co_u32_e32 v28, vcc, s77, v24
	global_load_dwordx4 v[8:11], v[8:9], off nt
	s_nop 0
	global_load_dwordx4 v[12:15], v[12:13], off nt
	v_addc_co_u32_e32 v29, vcc, 0, v25, vcc
	v_add_co_u32_e32 v36, vcc, s18, v56
	global_load_dwordx4 v[16:19], v[16:17], off nt
	s_nop 0
	global_load_dwordx4 v[20:23], v[20:21], off nt
	v_addc_co_u32_e32 v37, vcc, 0, v57, vcc
	v_add_co_u32_e32 v40, vcc, s33, v56
	global_load_dwordx4 v[24:27], v[26:27], off nt
	s_nop 0
	global_load_dwordx4 v[28:31], v[28:29], off nt
	v_addc_co_u32_e32 v41, vcc, 0, v57, vcc
	v_add_co_u32_e32 v44, vcc, s76, v56
	global_load_dwordx4 v[32:35], v[56:57], off nt
	s_nop 0
	global_load_dwordx4 v[36:39], v[36:37], off nt
	v_addc_co_u32_e32 v45, vcc, 0, v57, vcc
	v_add_co_u32_e32 v48, vcc, s16, v56
	global_load_dwordx4 v[40:43], v[40:41], off nt
	s_nop 0
	global_load_dwordx4 v[44:47], v[44:45], off nt
	v_addc_co_u32_e32 v49, vcc, 0, v57, vcc
	v_add_co_u32_e32 v52, vcc, s19, v56
	s_ashr_i32 s23, s22, 31
	s_nop 0
	v_addc_co_u32_e32 v53, vcc, 0, v57, vcc
	v_add_co_u32_e32 v58, vcc, s17, v56
	global_load_dwordx4 v[48:51], v[48:49], off nt
	s_nop 0
	global_load_dwordx4 v[52:55], v[52:53], off nt
	v_addc_co_u32_e32 v59, vcc, 0, v57, vcc
	v_add_co_u32_e32 v60, vcc, s77, v56
	s_lshl_b64 s[12:13], s[22:23], 1
	s_nop 0
	v_addc_co_u32_e32 v61, vcc, 0, v57, vcc
	global_load_dwordx4 v[56:59], v[58:59], off nt
	s_nop 0
	global_load_dwordx4 v[60:63], v[60:61], off nt
	s_add_u32 s12, s11, s12
	v_or_b32_e32 v70, s28, v72
	s_addc_u32 s13, s15, s13
	v_lshl_add_u64 v[66:67], v[64:65], 1, s[12:13]
	s_mov_b64 s[12:13], 0x1f900000
	v_ashrrev_i32_e32 v71, 31, v70
	v_lshl_add_u64 v[74:75], v[66:67], 0, s[12:13]
	v_lshlrev_b64 v[76:77], 12, v[70:71]
	s_waitcnt vmcnt(14)
	v_cvt_pk_bf16_f32 v66, v0, v4
	v_lshl_add_u64 v[76:77], v[74:75], 0, v[76:77]
	v_or_b32_e32 v0, 1, v70
	s_waitcnt vmcnt(12)
	v_cvt_pk_bf16_f32 v67, v8, v12
	s_waitcnt vmcnt(10)
	v_cvt_pk_bf16_f32 v68, v16, v20
	s_waitcnt vmcnt(8)
	v_cvt_pk_bf16_f32 v69, v24, v28
	global_store_dwordx4 v[76:77], v[66:69], off sc1
	s_nop 1
	v_cvt_pk_bf16_f32 v66, v1, v5
	v_ashrrev_i32_e32 v1, 31, v0
	v_lshlrev_b64 v[0:1], 12, v[0:1]
	v_lshl_add_u64 v[4:5], v[74:75], 0, v[0:1]
	v_or_b32_e32 v0, 2, v70
	v_ashrrev_i32_e32 v1, 31, v0
	v_lshlrev_b64 v[0:1], 12, v[0:1]
	v_cvt_pk_bf16_f32 v67, v9, v13
	v_cvt_pk_bf16_f32 v68, v17, v21
	v_cvt_pk_bf16_f32 v69, v25, v29
	global_store_dwordx4 v[4:5], v[66:69], off sc1
	v_lshl_add_u64 v[8:9], v[74:75], 0, v[0:1]
	s_nop 0
	v_cvt_pk_bf16_f32 v66, v2, v6
	v_or_b32_e32 v6, 3, v70
	v_cvt_pk_bf16_f32 v67, v10, v14
	v_cvt_pk_bf16_f32 v68, v18, v22
	v_cvt_pk_bf16_f32 v69, v26, v30
	global_store_dwordx4 v[8:9], v[66:69], off sc1
	v_cvt_pk_bf16_f32 v0, v3, v7
	v_ashrrev_i32_e32 v7, 31, v6
	v_lshlrev_b64 v[6:7], 12, v[6:7]
	v_cvt_pk_bf16_f32 v1, v11, v15
	v_cvt_pk_bf16_f32 v2, v19, v23
	v_cvt_pk_bf16_f32 v3, v27, v31
	v_lshl_add_u64 v[6:7], v[74:75], 0, v[6:7]
	global_store_dwordx4 v[6:7], v[0:3], off sc1
	s_waitcnt vmcnt(10)
	s_nop 0
	v_cvt_pk_bf16_f32 v0, v32, v36
	s_waitcnt vmcnt(8)
	v_cvt_pk_bf16_f32 v1, v40, v44
	s_waitcnt vmcnt(6)
	v_cvt_pk_bf16_f32 v2, v48, v52
	s_waitcnt vmcnt(4)
	v_cvt_pk_bf16_f32 v3, v56, v60
	global_store_dwordx4 v[76:77], v[0:3], off offset:64 sc1
	s_nop 1
	v_cvt_pk_bf16_f32 v0, v33, v37
	v_cvt_pk_bf16_f32 v1, v41, v45
	v_cvt_pk_bf16_f32 v2, v49, v53
	v_cvt_pk_bf16_f32 v3, v57, v61
	global_store_dwordx4 v[4:5], v[0:3], off offset:64 sc1
	s_nop 1
	v_cvt_pk_bf16_f32 v0, v34, v38
	v_cvt_pk_bf16_f32 v1, v42, v46
	v_cvt_pk_bf16_f32 v2, v50, v54
	v_cvt_pk_bf16_f32 v3, v58, v62
	global_store_dwordx4 v[8:9], v[0:3], off offset:64 sc1
	s_nop 1
	v_cvt_pk_bf16_f32 v0, v35, v39
	v_cvt_pk_bf16_f32 v1, v43, v47
	v_cvt_pk_bf16_f32 v2, v51, v55
	v_cvt_pk_bf16_f32 v3, v59, v63
	global_store_dwordx4 v[6:7], v[0:3], off offset:64 sc1

; __device__ __forceinline__ unsigned cvt_pk_bf16(float lo, float hi) { unsigned r; asm volatile("v_cvt_pk_bf16_f32 %0, %1, %2" : "=v"(r) : "v"(lo), "v"(hi)); return r; }
; #define INP(i) ((const float*)(const GASP float*)kargs()[(i)])
; __device__ __forceinline__ void tr_item(const float* W, int ldw, int k0, int n0, bf16* WT, int ldk, int drow0, int lane) {
;     const int n4 = (lane & 15) * 4, kg = lane >> 4; f32x4 v[2][8];
; #pragma unroll
;     for (int kh = 0; kh < 2; ++kh) { const float* src = W + (size_t)(k0 + kh * 32 + kg * 8) * ldw + n0 + n4;
; #pragma unroll
;         for (int i = 0; i < 8; ++i) v[kh][i] = __builtin_nontemporal_load((const f32x4*)(src + (size_t)i * ldw)); }
; #pragma unroll
;     for (int kh = 0; kh < 2; ++kh)
; #pragma unroll
;         for (int e = 0; e < 4; ++e) { u32x4 o; o.x = cvt_pk_bf16(v[kh][0][e], v[kh][1][e]); o.y = cvt_pk_bf16(v[kh][2][e], v[kh][3][e]); o.z = cvt_pk_bf16(v[kh][4][e], v[kh][5][e]); o.w = cvt_pk_bf16(v[kh][6][e], v[kh][7][e]);
;             *(u32x4*)(WT + (size_t)(drow0 + n4 + e) * ldk + k0 + kh * 32 + kg * 8) = o; }
; }
; __device__ __forceinline__ void conv_item(int it, int lane) {
;     ...
;     if (r < 8 * IT_D) { const int idx = r / IT_D; r -= idx * IT_D; const int kb = r / 32, nb = r % 32;
;         tr_item(INP(I_WD) + (size_t)idx * 5376 * 2048, 2048, 64 * kb, 64 * nb, (bf16*)(ws + WS_WD) + (size_t)idx * 2048 * 5376, 5376, 64 * nb, lane); return; }
.LBB0_1364:
	s_andn2_b64 vcc, exec, s[22:23]
	s_cbranch_vccnz .LBB0_1366
	s_add_i32 s11, s6, 0xffff5800
	s_bfe_u32 s12, s11, 0x100007
	s_mulk_i32 s12, 0xc31
	s_lshr_b32 s15, s12, 16
	s_mul_i32 s12, s15, 0xf580
	s_add_i32 s11, s12, s11
	s_sext_i32_i16 s12, s11
	s_bfe_u32 s12, s12, 0x5001a
	s_add_i32 s16, s11, s12
	s_mov_b64 s[12:13], s[0:1]
	s_load_dwordx2 s[12:13], s[12:13], 0x70
	s_sext_i32_i16 s17, s16
	s_and_b32 s16, s16, 0xffe0
	s_sub_i32 s11, s11, s16
	s_mul_i32 s16, s15, 0x2a00000
	s_waitcnt lgkmcnt(0)
	s_add_u32 s16, s12, s16
	s_sext_i32_i16 s11, s11
	s_addc_u32 s18, s13, 0
	s_lshl_b32 s12, s17, 1
	s_and_b32 s22, s12, 0xffffffc0
	s_lshl_b32 s28, s11, 6
	s_mul_i32 s15, s15, 0x1500000
	s_add_u32 s11, s26, s15
	s_addc_u32 s15, s27, 0
	s_ashr_i32 s29, s28, 31
	s_lshl_b64 s[12:13], s[28:29], 2
	v_add_u32_e32 v32, s22, v64
	s_add_u32 s12, s16, s12
	s_addc_u32 s13, s18, s13
	v_lshlrev_b32_e32 v172, 2, v72
	v_ashrrev_i32_e32 v33, 31, v32
	v_lshl_add_u64 v[34:35], s[12:13], 0, v[172:173]
	v_lshlrev_b64 v[0:1], 13, v[32:33]
	v_lshl_add_u64 v[24:25], v[34:35], 0, v[0:1]
	v_add_co_u32_e32 v4, vcc, s89, v24
	s_movk_i32 s13, 0x4000
	s_nop 0
	v_addc_co_u32_e32 v5, vcc, 0, v25, vcc
	v_add_co_u32_e32 v8, vcc, s13, v24
	s_movk_i32 s12, 0x6000
	s_nop 0
	v_addc_co_u32_e32 v9, vcc, 0, v25, vcc
	v_add_co_u32_e32 v12, vcc, s12, v24
	s_mov_b32 s16, 0x8000
	s_nop 0
	v_addc_co_u32_e32 v13, vcc, 0, v25, vcc
	v_add_co_u32_e32 v16, vcc, s16, v24
	v_add_u32_e32 v32, 32, v32
	s_nop 0
	v_addc_co_u32_e32 v17, vcc, 0, v25, vcc
	v_add_co_u32_e32 v20, vcc, s33, v24
	s_mov_b32 s17, 0xe000
	s_nop 0
	v_addc_co_u32_e32 v21, vcc, 0, v25, vcc
	v_add_co_u32_e32 v26, vcc, s38, v24
	v_ashrrev_i32_e32 v33, 31, v32
	s_nop 0
	v_addc_co_u32_e32 v27, vcc, 0, v25, vcc
	v_add_co_u32_e32 v28, vcc, s17, v24
	v_lshlrev_b64 v[32:33], 13, v[32:33]
	s_nop 0
	v_addc_co_u32_e32 v29, vcc, 0, v25, vcc
	v_lshl_add_u64 v[56:57], v[34:35], 0, v[32:33]
	v_add_co_u32_e32 v36, vcc, s89, v56
	global_load_dwordx4 v[0:3], v[24:25], off nt
	s_nop 0
	global_load_dwordx4 v[4:7], v[4:5], off nt
	v_addc_co_u32_e32 v37, vcc, 0, v57, vcc
	v_add_co_u32_e32 v40, vcc, s13, v56
	global_load_dwordx4 v[8:11], v[8:9], off nt
	s_nop 0
	global_load_dwordx4 v[12:15], v[12:13], off nt
	v_addc_co_u32_e32 v41, vcc, 0, v57, vcc
	v_add_co_u32_e32 v44, vcc, s12, v56
	global_load_dwordx4 v[16:19], v[16:17], off nt
	s_nop 0
	global_load_dwordx4 v[20:23], v[20:21], off nt
	v_addc_co_u32_e32 v45, vcc, 0, v57, vcc
	v_add_co_u32_e32 v48, vcc, s16, v56
	global_load_dwordx4 v[24:27], v[26:27], off nt
	s_nop 0
	global_load_dwordx4 v[28:31], v[28:29], off nt
	v_addc_co_u32_e32 v49, vcc, 0, v57, vcc
	v_add_co_u32_e32 v52, vcc, s33, v56
	global_load_dwordx4 v[32:35], v[56:57], off nt
	s_nop 0
	global_load_dwordx4 v[36:39], v[36:37], off nt
	v_addc_co_u32_e32 v53, vcc, 0, v57, vcc
	v_add_co_u32_e32 v58, vcc, s38, v56
	global_load_dwordx4 v[40:43], v[40:41], off nt
	s_nop 0
	global_load_dwordx4 v[44:47], v[44:45], off nt
	v_addc_co_u32_e32 v59, vcc, 0, v57, vcc
	v_add_co_u32_e32 v60, vcc, s17, v56
	global_load_dwordx4 v[48:51], v[48:49], off nt
	s_nop 0
	global_load_dwordx4 v[52:55], v[52:53], off nt
	v_addc_co_u32_e32 v61, vcc, 0, v57, vcc
	global_load_dwordx4 v[56:59], v[58:59], off nt
	s_nop 0
	global_load_dwordx4 v[60:63], v[60:61], off nt
	s_ashr_i32 s23, s22, 31
	s_lshl_b64 s[12:13], s[22:23], 1
	v_or_b32_e32 v73, s28, v72
	s_add_u32 s12, s11, s12
	s_addc_u32 s13, s15, s13
	v_mul_i32_i24_e32 v74, 0x1500, v73
	v_lshl_add_u64 v[70:71], v[64:65], 1, s[12:13]
	v_ashrrev_i32_e32 v75, 31, v74
	v_lshl_add_u64 v[70:71], v[74:75], 1, v[70:71]
	s_mov_b32 s11, 0x15100000
	v_add_co_u32_e32 v76, vcc, s11, v70
	s_mov_b32 s11, 0x15102000
	s_nop 0
	v_addc_co_u32_e32 v77, vcc, 0, v71, vcc
	s_waitcnt vmcnt(14)
	v_cvt_pk_bf16_f32 v66, v0, v4
	v_add_co_u32_e32 v4, vcc, s11, v70
	s_waitcnt vmcnt(12)
	v_cvt_pk_bf16_f32 v67, v8, v12
	s_waitcnt vmcnt(10)
	v_cvt_pk_bf16_f32 v68, v16, v20
	s_waitcnt vmcnt(8)
	v_cvt_pk_bf16_f32 v69, v24, v28
	global_store_dwordx4 v[76:77], v[66:69], off sc1
	s_mov_b32 s11, 0x15105000
	s_mov_b64 s[12:13], 0x15100000
	v_cvt_pk_bf16_f32 v66, v1, v5
	v_addc_co_u32_e32 v5, vcc, 0, v71, vcc
	v_add_co_u32_e32 v8, vcc, s11, v70
	v_cvt_pk_bf16_f32 v67, v9, v13
	s_mov_b32 s11, 0x15107000
	s_nop 0
	v_addc_co_u32_e32 v9, vcc, 0, v71, vcc
	v_cvt_pk_bf16_f32 v68, v17, v21
	v_cvt_pk_bf16_f32 v69, v25, v29
	global_store_dwordx4 v[4:5], v[66:69], off offset:2560 sc1
	v_lshl_add_u64 v[74:75], v[70:71], 0, s[12:13]
	s_nop 0
	v_cvt_pk_bf16_f32 v66, v2, v6
	v_add_co_u32_e32 v6, vcc, s11, v70
	v_cvt_pk_bf16_f32 v67, v10, v14
	v_cvt_pk_bf16_f32 v68, v18, v22
	v_cvt_pk_bf16_f32 v69, v26, v30
	global_store_dwordx4 v[8:9], v[66:69], off offset:1024 sc1
	v_cvt_pk_bf16_f32 v0, v3, v7
	v_cvt_pk_bf16_f32 v1, v11, v15
	v_cvt_pk_bf16_f32 v2, v19, v23
	v_cvt_pk_bf16_f32 v3, v27, v31
	s_nop 0
	v_addc_co_u32_e32 v7, vcc, 0, v71, vcc
	global_store_dwordx4 v[6:7], v[0:3], off offset:3584 sc1
	s_waitcnt vmcnt(10)
	s_nop 0
	v_cvt_pk_bf16_f32 v0, v32, v36
	s_waitcnt vmcnt(8)
	v_cvt_pk_bf16_f32 v1, v40, v44
	s_waitcnt vmcnt(6)
	v_cvt_pk_bf16_f32 v2, v48, v52
	s_waitcnt vmcnt(4)
	v_cvt_pk_bf16_f32 v3, v56, v60
	global_store_dwordx4 v[74:75], v[0:3], off offset:64 sc1
	s_nop 1
	v_cvt_pk_bf16_f32 v0, v33, v37
	v_cvt_pk_bf16_f32 v1, v41, v45
	v_cvt_pk_bf16_f32 v2, v49, v53
	v_cvt_pk_bf16_f32 v3, v57, v61
	global_store_dwordx4 v[4:5], v[0:3], off offset:2624 sc1
	s_nop 1
	v_cvt_pk_bf16_f32 v0, v34, v38
	v_cvt_pk_bf16_f32 v1, v42, v46
	v_cvt_pk_bf16_f32 v2, v50, v54
	v_cvt_pk_bf16_f32 v3, v58, v62
	global_store_dwordx4 v[8:9], v[0:3], off offset:1088 sc1
	s_nop 1
	v_cvt_pk_bf16_f32 v0, v35, v39
	v_cvt_pk_bf16_f32 v1, v43, v47
	v_cvt_pk_bf16_f32 v2, v51, v55
	v_cvt_pk_bf16_f32 v3, v59, v63
	global_store_dwordx4 v[6:7], v[0:3], off offset:3648 sc1

; #define INP(i) ((const float*)(const GASP float*)kargs()[(i)])
; __device__ __forceinline__ void conv_item(int it, int lane) {
;     unsigned char* ws = WSP; int r = it;
;     if (r < 8 * IT_GU) { const int idx = r / IT_GU; r -= idx * IT_GU; const int kb = r / 168, nb = r % 168, n0 = 64 * nb;
;         const int drow = n0 < DFF ? (n0 >> 7) * 256 + (n0 & 127) : ((n0 - DFF) >> 7) * 256 + 128 + ((n0 - DFF) & 127);
;         tr_item(INP(I_WGU) + (size_t)idx * 2048 * 10752, 10752, 64 * kb, n0, (bf16*)(ws + WS_WGU) + (size_t)idx * 10752 * 2048, 2048, drow, lane); return; }
;     r -= 8 * IT_GU;
;     if (r < 8 * IT_D) { const int idx = r / IT_D; r -= idx * IT_D; const int kb = r / 32, nb = r % 32;
;         tr_item(INP(I_WD) + (size_t)idx * 5376 * 2048, 2048, 64 * kb, 64 * nb, (bf16*)(ws + WS_WD) + (size_t)idx * 2048 * 5376, 5376, 64 * nb, lane); return; }
;     r -= 8 * IT_D;
;     if (r < 2 * IT_INAB) { const int idx = r / IT_INAB; r -= idx * IT_INAB; const int kb = r / 80, nb = r % 80;
;         tr_item(INP(I_WINAB) + (size_t)idx * 2048 * 5120, 5120, 64 * kb, 64 * nb, (bf16*)(ws + WS_WINAB) + (size_t)idx * 5120 * 2048, 2048, 64 * nb, lane); return; }
;     r -= 2 * IT_INAB;
;     if (r < 2 * IT_GLU) { const int idx = r / IT_GLU; r -= idx * IT_GLU; const int kb = r / 16, nb = r % 16;
;         tr_item(INP(I_WGLU) + (size_t)idx * 1024 * 1024, 1024, 64 * kb, 64 * nb, (bf16*)(ws + WS_WGLU) + (size_t)idx * 1024 * 1024, 1024, 64 * nb, lane); return; }
;     r -= 2 * IT_GLU;
;     if (r < 2 * IT_OUTAB) { const int idx = r / IT_OUTAB; r -= idx * IT_OUTAB; const int kb = r / 32, nb = r % 32;
;         tr_item(INP(I_WOUTAB) + (size_t)idx * 2048 * 2048, 2048, 64 * kb, 64 * nb, (bf16*)(ws + WS_WOUTAB) + (size_t)idx * 2048 * 2048, 2048, 64 * nb, lane); return; }
;     r -= 2 * IT_OUTAB;
;     if (r < 2 * IT_INC) { const int idx = r / IT_INC; r -= idx * IT_INC; const int kb = r / 80, nb = r % 80;
;         tr_item(INP(I_WINC) + (size_t)idx * 2048 * 5120, 5120, 64 * kb, 64 * nb, (bf16*)(ws + WS_WINC) + (size_t)idx * 5120 * 2048, 2048, 64 * nb, lane); return; }
;     r -= 2 * IT_INC;
;     { const int idx = r / IT_OUTC; r -= idx * IT_OUTC; const int kb = r / 32, nb = r % 32;
;       tr_item(INP(I_WOUTC) + (size_t)idx * 2560 * 2048, 2048, 64 * kb, 64 * nb, (bf16*)(ws + WS_WOUTC) + (size_t)idx * 2048 * 2560, 2560, 64 * nb, lane); }
.LBB0_1497:
	s_mov_b64 s[2:3], s[0:1]
	s_load_dwordx2 s[2:3], s[2:3], 0x138
	s_add_i32 s6, s12, s21
	s_mov_b64 s[22:23], -1
	s_cmp_gt_i32 s6, 0xa7ff
	s_cbranch_scc0 .LBB0_1519
	s_cmpk_gt_u32 s6, 0xfbff
	s_cbranch_scc0 .LBB0_1516
	s_cmp_gt_u32 s6, 0x10fff
	s_cbranch_scc0 .LBB0_1513
	s_cmp_gt_u32 s6, 0x111ff
	s_cbranch_scc0 .LBB0_1510
	s_cmp_gt_u32 s6, 0x119ff
	s_cbranch_scc0 .LBB0_1507
	s_cmp_gt_u32 s6, 0x12dff
	s_cbranch_scc0 .LBB0_1504
	s_add_i32 s11, s6, 0xfffed200
	s_mul_hi_u32 s12, s11, 0xcccccccd
	s_lshr_b32 s12, s12, 10
	s_mul_i32 s19, s12, 0xfffffb00
	s_mov_b64 s[20:21], s[0:1]
	s_add_i32 s11, s19, s11
	s_ashr_i32 s19, s11, 31
	s_load_dwordx2 s[20:21], s[20:21], 0x128
	s_lshr_b32 s19, s19, 27
	s_add_i32 s19, s11, s19
	s_and_b32 s22, s19, 0x3ffffe0
	s_sub_i32 s11, s11, s22
	s_mul_i32 s23, s12, 0x1400000
	s_mul_hi_u32 s22, s12, 0x1400000
	s_waitcnt lgkmcnt(0)
	s_add_u32 s23, s20, s23
	s_addc_u32 s28, s21, s22
	s_lshl_b32 s19, s19, 1
	s_and_b32 s22, s19, 0xffffffc0
	s_lshl_b32 s26, s11, 6
	s_mul_hi_u32 s11, s12, 0xa00000
	s_mul_i32 s12, s12, 0xa00000
	s_add_u32 s12, s2, s12
	s_addc_u32 s11, s3, s11
	s_ashr_i32 s27, s26, 31
	s_lshl_b64 s[20:21], s[26:27], 2
	v_add_u32_e32 v32, s22, v66
	s_add_u32 s20, s23, s20
	s_addc_u32 s21, s28, s21
	v_lshlrev_b32_e32 v172, 2, v64
	v_ashrrev_i32_e32 v33, 31, v32
	v_lshl_add_u64 v[34:35], s[20:21], 0, v[172:173]
	v_lshlrev_b64 v[0:1], 13, v[32:33]
	v_lshl_add_u64 v[24:25], v[34:35], 0, v[0:1]
	v_add_co_u32_e32 v4, vcc, s89, v24
	s_movk_i32 s20, 0x4000
	s_nop 0
	v_addc_co_u32_e32 v5, vcc, 0, v25, vcc
	v_add_co_u32_e32 v8, vcc, s20, v24
	s_movk_i32 s19, 0x6000
	s_nop 0
	v_addc_co_u32_e32 v9, vcc, 0, v25, vcc
	v_add_co_u32_e32 v12, vcc, s19, v24
	s_mov_b32 s21, 0x8000
	s_nop 0
	v_addc_co_u32_e32 v13, vcc, 0, v25, vcc
	v_add_co_u32_e32 v16, vcc, s21, v24
	v_add_u32_e32 v32, 32, v32
	s_nop 0
	v_addc_co_u32_e32 v17, vcc, 0, v25, vcc
	v_add_co_u32_e32 v20, vcc, s33, v24
	s_mov_b32 s23, 0xe000
	s_nop 0
	v_addc_co_u32_e32 v21, vcc, 0, v25, vcc
	v_add_co_u32_e32 v26, vcc, s38, v24
	v_ashrrev_i32_e32 v33, 31, v32
	s_nop 0
	v_addc_co_u32_e32 v27, vcc, 0, v25, vcc
	v_add_co_u32_e32 v28, vcc, s23, v24
	v_lshlrev_b64 v[32:33], 13, v[32:33]
	s_nop 0
	v_addc_co_u32_e32 v29, vcc, 0, v25, vcc
	v_lshl_add_u64 v[56:57], v[34:35], 0, v[32:33]
	v_add_co_u32_e32 v36, vcc, s89, v56
	global_load_dwordx4 v[0:3], v[24:25], off nt
	s_nop 0
	global_load_dwordx4 v[4:7], v[4:5], off nt
	v_addc_co_u32_e32 v37, vcc, 0, v57, vcc
	v_add_co_u32_e32 v40, vcc, s20, v56
	global_load_dwordx4 v[8:11], v[8:9], off nt
	s_nop 0
	global_load_dwordx4 v[12:15], v[12:13], off nt
	v_addc_co_u32_e32 v41, vcc, 0, v57, vcc
	v_add_co_u32_e32 v44, vcc, s19, v56
	global_load_dwordx4 v[16:19], v[16:17], off nt
	s_nop 0
	global_load_dwordx4 v[20:23], v[20:21], off nt
	v_addc_co_u32_e32 v45, vcc, 0, v57, vcc
	v_add_co_u32_e32 v48, vcc, s21, v56
	global_load_dwordx4 v[24:27], v[26:27], off nt
	s_nop 0
	global_load_dwordx4 v[28:31], v[28:29], off nt
	v_addc_co_u32_e32 v49, vcc, 0, v57, vcc
	v_add_co_u32_e32 v52, vcc, s33, v56
	global_load_dwordx4 v[32:35], v[56:57], off nt
	s_nop 0
	global_load_dwordx4 v[36:39], v[36:37], off nt
	v_addc_co_u32_e32 v53, vcc, 0, v57, vcc
	v_add_co_u32_e32 v58, vcc, s38, v56
	global_load_dwordx4 v[40:43], v[40:41], off nt
	s_nop 0
	global_load_dwordx4 v[44:47], v[44:45], off nt
	v_addc_co_u32_e32 v59, vcc, 0, v57, vcc
	v_add_co_u32_e32 v60, vcc, s23, v56
	global_load_dwordx4 v[48:51], v[48:49], off nt
	s_nop 0
	global_load_dwordx4 v[52:55], v[52:53], off nt
	v_addc_co_u32_e32 v61, vcc, 0, v57, vcc
	global_load_dwordx4 v[56:59], v[58:59], off nt
	s_nop 0
	global_load_dwordx4 v[60:63], v[60:61], off nt
	s_ashr_i32 s23, s22, 31
	s_lshl_b64 s[20:21], s[22:23], 1
	s_add_u32 s20, s12, s20
	v_or_b32_e32 v65, s26, v64
	s_addc_u32 s21, s11, s21
	s_movk_i32 s11, 0xa00
	v_mul_lo_u32 v74, v65, s11
	v_lshl_add_u64 v[72:73], v[66:67], 1, s[20:21]
	v_ashrrev_i32_e32 v75, 31, v74
	v_lshl_add_u64 v[72:73], v[74:75], 1, v[72:73]
	s_mov_b32 s11, 0x25d00000
	v_add_co_u32_e32 v76, vcc, s11, v72
	s_mov_b32 s11, 0x25d01000
	s_nop 0
	v_addc_co_u32_e32 v77, vcc, 0, v73, vcc
	s_waitcnt vmcnt(14)
	v_cvt_pk_bf16_f32 v68, v0, v4
	v_add_co_u32_e32 v4, vcc, s11, v72
	s_waitcnt vmcnt(12)
	v_cvt_pk_bf16_f32 v69, v8, v12
	s_waitcnt vmcnt(10)
	v_cvt_pk_bf16_f32 v70, v16, v20
	s_waitcnt vmcnt(8)
	v_cvt_pk_bf16_f32 v71, v24, v28
	global_store_dwordx4 v[76:77], v[68:71], off sc1
	s_mov_b32 s11, 0x25d02000
	s_mov_b64 s[20:21], 0x25d00000
	v_cvt_pk_bf16_f32 v68, v1, v5
	v_addc_co_u32_e32 v5, vcc, 0, v73, vcc
	v_add_co_u32_e32 v8, vcc, s11, v72
	v_cvt_pk_bf16_f32 v69, v9, v13
	s_mov_b32 s11, 0x25d03000
	s_nop 0
	v_addc_co_u32_e32 v9, vcc, 0, v73, vcc
	v_cvt_pk_bf16_f32 v70, v17, v21
	v_cvt_pk_bf16_f32 v71, v25, v29
	global_store_dwordx4 v[4:5], v[68:71], off offset:1024 sc1
	v_lshl_add_u64 v[74:75], v[72:73], 0, s[20:21]
	s_mov_b64 s[22:23], 0
	v_cvt_pk_bf16_f32 v68, v2, v6
	v_add_co_u32_e32 v6, vcc, s11, v72
	v_cvt_pk_bf16_f32 v69, v10, v14
	v_cvt_pk_bf16_f32 v70, v18, v22
	v_cvt_pk_bf16_f32 v71, v26, v30
	global_store_dwordx4 v[8:9], v[68:71], off offset:2048 sc1
	v_cvt_pk_bf16_f32 v0, v3, v7
	v_cvt_pk_bf16_f32 v1, v11, v15
	v_cvt_pk_bf16_f32 v2, v19, v23
	v_cvt_pk_bf16_f32 v3, v27, v31
	s_nop 0
	v_addc_co_u32_e32 v7, vcc, 0, v73, vcc
	global_store_dwordx4 v[6:7], v[0:3], off offset:3072 sc1
	s_waitcnt vmcnt(10)
	s_nop 0
	v_cvt_pk_bf16_f32 v0, v32, v36
	s_waitcnt vmcnt(8)
	v_cvt_pk_bf16_f32 v1, v40, v44
	s_waitcnt vmcnt(6)
	v_cvt_pk_bf16_f32 v2, v48, v52
	s_waitcnt vmcnt(4)
	v_cvt_pk_bf16_f32 v3, v56, v60
	global_store_dwordx4 v[74:75], v[0:3], off offset:64 sc1
	s_nop 1
	v_cvt_pk_bf16_f32 v0, v33, v37
	v_cvt_pk_bf16_f32 v1, v41, v45
	v_cvt_pk_bf16_f32 v2, v49, v53
	v_cvt_pk_bf16_f32 v3, v57, v61
	global_store_dwordx4 v[4:5], v[0:3], off offset:1088 sc1
	s_nop 1
	v_cvt_pk_bf16_f32 v0, v34, v38
	v_cvt_pk_bf16_f32 v1, v42, v46
	v_cvt_pk_bf16_f32 v2, v50, v54
	v_cvt_pk_bf16_f32 v3, v58, v62
	global_store_dwordx4 v[8:9], v[0:3], off offset:2112 sc1
	s_nop 1
	v_cvt_pk_bf16_f32 v0, v35, v39
	v_cvt_pk_bf16_f32 v1, v43, v47
	v_cvt_pk_bf16_f32 v2, v51, v55
	v_cvt_pk_bf16_f32 v3, v59, v63
	global_store_dwordx4 v[6:7], v[0:3], off offset:3136 sc1
; __device__ __forceinline__ unsigned cvt_pk_bf16(float lo, float hi) { unsigned r; asm volatile("v_cvt_pk_bf16_f32 %0, %1, %2" : "=v"(r) : "v"(lo), "v"(hi)); return r; }
; #define INP(i) ((const float*)(const GASP float*)kargs()[(i)])
; __device__ __forceinline__ void tr_item(const float* W, int ldw, int k0, int n0, bf16* WT, int ldk, int drow0, int lane) {
;     const int n4 = (lane & 15) * 4, kg = lane >> 4; f32x4 v[2][8];
; #pragma unroll
;     for (int kh = 0; kh < 2; ++kh) { const float* src = W + (size_t)(k0 + kh * 32 + kg * 8) * ldw + n0 + n4;
; #pragma unroll
;         for (int i = 0; i < 8; ++i) v[kh][i] = __builtin_nontemporal_load((const f32x4*)(src + (size_t)i * ldw)); }
; #pragma unroll
;     for (int kh = 0; kh < 2; ++kh)
; #pragma unroll
;         for (int e = 0; e < 4; ++e) { u32x4 o; o.x = cvt_pk_bf16(v[kh][0][e], v[kh][1][e]); o.y = cvt_pk_bf16(v[kh][2][e], v[kh][3][e]); o.z = cvt_pk_bf16(v[kh][4][e], v[kh][5][e]); o.w = cvt_pk_bf16(v[kh][6][e], v[kh][7][e]);
;             *(u32x4*)(WT + (size_t)(drow0 + n4 + e) * ldk + k0 + kh * 32 + kg * 8) = o; }
; }
; __device__ __forceinline__ void conv_item(int it, int lane) {
;     ...
;     if (r < 2 * IT_INC) { const int idx = r / IT_INC; r -= idx * IT_INC; const int kb = r / 80, nb = r % 80;
;         tr_item(INP(I_WINC) + (size_t)idx * 2048 * 5120, 5120, 64 * kb, 64 * nb, (bf16*)(ws + WS_WINC) + (size_t)idx * 5120 * 2048, 2048, 64 * nb, lane); return; }
.LBB0_1504:
	s_andn2_b64 vcc, exec, s[22:23]
	s_cbranch_vccnz .LBB0_1506
	s_add_i32 s11, s6, 0xfffee600
	s_cmpk_gt_u32 s11, 0x9ff
	s_cselect_b64 s[20:21], -1, 0
	s_and_b64 s[22:23], s[20:21], exec
	s_cselect_b32 s12, 0xf600, 0
	s_add_i32 s12, s12, s11
	s_sext_i32_i16 s11, s12
	s_mulk_i32 s11, 0x6667
	s_mov_b64 s[22:23], s[0:1]
	s_lshr_b32 s19, s11, 31
	s_ashr_i32 s11, s11, 21
	s_add_i32 s11, s11, s19
	s_load_dwordx2 s[22:23], s[22:23], 0xe8
	s_mul_i32 s19, s11, 0x50
	s_sub_i32 s12, s12, s19
	s_and_b64 s[26:27], s[20:21], exec
	s_cselect_b32 s19, 0x2800000, 0
	s_sext_i32_i16 s12, s12
	s_waitcnt lgkmcnt(0)
	s_add_u32 s19, s22, s19
	s_addc_u32 s23, s23, 0
	s_lshl_b32 s22, s11, 6
	s_lshl_b32 s26, s12, 6
	s_and_b64 s[20:21], s[20:21], exec
	s_cselect_b32 s11, 0x1400000, 0
	s_add_u32 s11, s2, s11
	s_addc_u32 s12, s3, 0
	s_ashr_i32 s27, s26, 31
	s_lshl_b64 s[20:21], s[26:27], 2
	s_add_u32 s20, s19, s20
	s_addc_u32 s21, s23, s21
	v_lshlrev_b32_e32 v172, 2, v64
	v_add_u32_e32 v34, s22, v66
	v_lshl_add_u64 v[32:33], s[20:21], 0, v[172:173]
	s_movk_i32 s27, 0x5000
	v_mad_i64_i32 v[24:25], s[20:21], v34, s27, v[32:33]
	v_add_co_u32_e32 v4, vcc, s27, v24
	s_mov_b32 s19, 0x14000
	s_nop 0
	v_addc_co_u32_e32 v5, vcc, 0, v25, vcc
	v_add_co_u32_e32 v8, vcc, s33, v24
	s_mov_b32 s28, 0x19000
	s_nop 0
	v_addc_co_u32_e32 v9, vcc, 0, v25, vcc
	v_add_co_u32_e32 v12, vcc, s76, v24
	s_mov_b32 s23, 0x1e000
	s_nop 0
	v_addc_co_u32_e32 v13, vcc, 0, v25, vcc
	v_add_co_u32_e32 v16, vcc, s19, v24
	v_add_u32_e32 v34, 32, v34
	s_nop 0
	v_addc_co_u32_e32 v17, vcc, 0, v25, vcc
	v_add_co_u32_e32 v20, vcc, s28, v24
	v_mad_i64_i32 v[56:57], s[20:21], v34, s27, v[32:33]
	s_nop 0
	v_addc_co_u32_e32 v21, vcc, 0, v25, vcc
	v_add_co_u32_e32 v26, vcc, s23, v24
	global_load_dwordx4 v[0:3], v[24:25], off nt
	s_nop 0
	global_load_dwordx4 v[4:7], v[4:5], off nt
	v_addc_co_u32_e32 v27, vcc, 0, v25, vcc
	v_add_co_u32_e32 v28, vcc, s77, v24
	global_load_dwordx4 v[8:11], v[8:9], off nt
	s_nop 0
	global_load_dwordx4 v[12:15], v[12:13], off nt
	v_addc_co_u32_e32 v29, vcc, 0, v25, vcc
	v_add_co_u32_e32 v36, vcc, s27, v56
	global_load_dwordx4 v[16:19], v[16:17], off nt
	s_nop 0
	global_load_dwordx4 v[20:23], v[20:21], off nt
	v_addc_co_u32_e32 v37, vcc, 0, v57, vcc
	v_add_co_u32_e32 v40, vcc, s33, v56
	global_load_dwordx4 v[24:27], v[26:27], off nt
	s_nop 0
	global_load_dwordx4 v[28:31], v[28:29], off nt
	v_addc_co_u32_e32 v41, vcc, 0, v57, vcc
	v_add_co_u32_e32 v44, vcc, s76, v56
	global_load_dwordx4 v[32:35], v[56:57], off nt
	s_nop 0
	global_load_dwordx4 v[36:39], v[36:37], off nt
	v_addc_co_u32_e32 v45, vcc, 0, v57, vcc
	v_add_co_u32_e32 v48, vcc, s19, v56
	global_load_dwordx4 v[40:43], v[40:41], off nt
	s_nop 0
	global_load_dwordx4 v[44:47], v[44:45], off nt
	v_addc_co_u32_e32 v49, vcc, 0, v57, vcc
	v_add_co_u32_e32 v52, vcc, s28, v56
	v_or_b32_e32 v72, s26, v64
	s_nop 0
	v_addc_co_u32_e32 v53, vcc, 0, v57, vcc
	v_add_co_u32_e32 v58, vcc, s23, v56
	global_load_dwordx4 v[48:51], v[48:49], off nt
	s_nop 0
	global_load_dwordx4 v[52:55], v[52:53], off nt
	v_addc_co_u32_e32 v59, vcc, 0, v57, vcc
	v_add_co_u32_e32 v60, vcc, s77, v56
	s_ashr_i32 s23, s22, 31
	s_nop 0
	v_addc_co_u32_e32 v61, vcc, 0, v57, vcc
	global_load_dwordx4 v[56:59], v[58:59], off nt
	s_nop 0
	global_load_dwordx4 v[60:63], v[60:61], off nt
	s_lshl_b64 s[20:21], s[22:23], 1
	s_add_u32 s20, s11, s20
	s_addc_u32 s21, s12, s21
	v_lshl_add_u64 v[68:69], v[66:67], 1, s[20:21]
	s_mov_b64 s[20:21], 0x23500000
	v_ashrrev_i32_e32 v73, 31, v72
	v_lshl_add_u64 v[74:75], v[68:69], 0, s[20:21]
	v_lshlrev_b64 v[76:77], 12, v[72:73]
	s_waitcnt vmcnt(14)
	v_cvt_pk_bf16_f32 v68, v0, v4
	v_lshl_add_u64 v[76:77], v[74:75], 0, v[76:77]
	v_or_b32_e32 v0, 1, v72
	s_waitcnt vmcnt(12)
	v_cvt_pk_bf16_f32 v69, v8, v12
	s_waitcnt vmcnt(10)
	v_cvt_pk_bf16_f32 v70, v16, v20
	s_waitcnt vmcnt(8)
	v_cvt_pk_bf16_f32 v71, v24, v28
	global_store_dwordx4 v[76:77], v[68:71], off sc1
	s_nop 1
	v_cvt_pk_bf16_f32 v68, v1, v5
	v_ashrrev_i32_e32 v1, 31, v0
	v_lshlrev_b64 v[0:1], 12, v[0:1]
	v_lshl_add_u64 v[4:5], v[74:75], 0, v[0:1]
	v_or_b32_e32 v0, 2, v72
	v_ashrrev_i32_e32 v1, 31, v0
	v_lshlrev_b64 v[0:1], 12, v[0:1]
	v_cvt_pk_bf16_f32 v69, v9, v13
	v_cvt_pk_bf16_f32 v70, v17, v21
	v_cvt_pk_bf16_f32 v71, v25, v29
	global_store_dwordx4 v[4:5], v[68:71], off sc1
	v_lshl_add_u64 v[8:9], v[74:75], 0, v[0:1]
	s_nop 0
	v_cvt_pk_bf16_f32 v68, v2, v6
	v_or_b32_e32 v6, 3, v72
	v_cvt_pk_bf16_f32 v69, v10, v14
	v_cvt_pk_bf16_f32 v70, v18, v22
	v_cvt_pk_bf16_f32 v71, v26, v30
	global_store_dwordx4 v[8:9], v[68:71], off sc1
	v_cvt_pk_bf16_f32 v0, v3, v7
	v_ashrrev_i32_e32 v7, 31, v6
	v_lshlrev_b64 v[6:7], 12, v[6:7]
	v_cvt_pk_bf16_f32 v1, v11, v15
	v_cvt_pk_bf16_f32 v2, v19, v23
	v_cvt_pk_bf16_f32 v3, v27, v31
	v_lshl_add_u64 v[6:7], v[74:75], 0, v[6:7]
	global_store_dwordx4 v[6:7], v[0:3], off sc1
	s_waitcnt vmcnt(10)
	s_nop 0
	v_cvt_pk_bf16_f32 v0, v32, v36
	s_waitcnt vmcnt(8)
	v_cvt_pk_bf16_f32 v1, v40, v44
	s_waitcnt vmcnt(6)
	v_cvt_pk_bf16_f32 v2, v48, v52
	s_waitcnt vmcnt(4)
	v_cvt_pk_bf16_f32 v3, v56, v60
	global_store_dwordx4 v[76:77], v[0:3], off offset:64 sc1
	s_nop 1
	v_cvt_pk_bf16_f32 v0, v33, v37
	v_cvt_pk_bf16_f32 v1, v41, v45
	v_cvt_pk_bf16_f32 v2, v49, v53
	v_cvt_pk_bf16_f32 v3, v57, v61
	global_store_dwordx4 v[4:5], v[0:3], off offset:64 sc1
	s_nop 1
	v_cvt_pk_bf16_f32 v0, v34, v38
	v_cvt_pk_bf16_f32 v1, v42, v46
	v_cvt_pk_bf16_f32 v2, v50, v54
	v_cvt_pk_bf16_f32 v3, v58, v62
	global_store_dwordx4 v[8:9], v[0:3], off offset:64 sc1
	s_nop 1
	v_cvt_pk_bf16_f32 v0, v35, v39
	v_cvt_pk_bf16_f32 v1, v43, v47
	v_cvt_pk_bf16_f32 v2, v51, v55
	v_cvt_pk_bf16_f32 v3, v59, v63
	global_store_dwordx4 v[6:7], v[0:3], off offset:64 sc1

; __device__ __forceinline__ unsigned cvt_pk_bf16(float lo, float hi) { unsigned r; asm volatile("v_cvt_pk_bf16_f32 %0, %1, %2" : "=v"(r) : "v"(lo), "v"(hi)); return r; }
; #define INP(i) ((const float*)(const GASP float*)kargs()[(i)])
; __device__ __forceinline__ void tr_item(const float* W, int ldw, int k0, int n0, bf16* WT, int ldk, int drow0, int lane) {
;     const int n4 = (lane & 15) * 4, kg = lane >> 4; f32x4 v[2][8];
; #pragma unroll
;     for (int kh = 0; kh < 2; ++kh) { const float* src = W + (size_t)(k0 + kh * 32 + kg * 8) * ldw + n0 + n4;
; #pragma unroll
;         for (int i = 0; i < 8; ++i) v[kh][i] = __builtin_nontemporal_load((const f32x4*)(src + (size_t)i * ldw)); }
; #pragma unroll
;     for (int kh = 0; kh < 2; ++kh)
; #pragma unroll
;         for (int e = 0; e < 4; ++e) { u32x4 o; o.x = cvt_pk_bf16(v[kh][0][e], v[kh][1][e]); o.y = cvt_pk_bf16(v[kh][2][e], v[kh][3][e]); o.z = cvt_pk_bf16(v[kh][4][e], v[kh][5][e]); o.w = cvt_pk_bf16(v[kh][6][e], v[kh][7][e]);
;             *(u32x4*)(WT + (size_t)(drow0 + n4 + e) * ldk + k0 + kh * 32 + kg * 8) = o; }
; }
; __device__ __forceinline__ void conv_item(int it, int lane) {
;     ...
;     if (r < 2 * IT_OUTAB) { const int idx = r / IT_OUTAB; r -= idx * IT_OUTAB; const int kb = r / 32, nb = r % 32;
;         tr_item(INP(I_WOUTAB) + (size_t)idx * 2048 * 2048, 2048, 64 * kb, 64 * nb, (bf16*)(ws + WS_WOUTAB) + (size_t)idx * 2048 * 2048, 2048, 64 * nb, lane); return; }
.LBB0_1507:
	s_andn2_b64 vcc, exec, s[22:23]
	s_cbranch_vccnz .LBB0_1509
	s_mov_b64 s[20:21], s[0:1]
	s_load_dwordx2 s[20:21], s[20:21], 0xe0
	s_add_i32 s11, s6, 0xfffeee00
	s_lshr_b32 s38, s11, 10
	s_lshl_b64 s[22:23], s[38:39], 24
	v_lshlrev_b32_e32 v172, 2, v64
	s_waitcnt lgkmcnt(0)
	s_add_u32 s12, s20, s22
	s_addc_u32 s19, s21, s23
	s_lshl_b32 s11, s11, 1
	s_lshl_b32 s20, s6, 6
	s_and_b32 s11, s11, 0x7c0
	s_and_b32 s22, s20, 0x7c0
	s_lshl_b64 s[20:21], s[38:39], 23
	s_add_u32 s23, s2, s20
	s_addc_u32 s26, s3, s21
	s_lshl_b32 s20, s22, 2
	v_add_u32_e32 v32, s11, v66
	s_add_u32 s20, s12, s20
	s_addc_u32 s21, s19, 0
	v_ashrrev_i32_e32 v33, 31, v32
	v_lshl_add_u64 v[34:35], s[20:21], 0, v[172:173]
	v_lshlrev_b64 v[0:1], 13, v[32:33]
	v_lshl_add_u64 v[24:25], v[34:35], 0, v[0:1]
	v_add_co_u32_e32 v4, vcc, s89, v24
	s_movk_i32 s19, 0x4000
	s_nop 0
	v_addc_co_u32_e32 v5, vcc, 0, v25, vcc
	v_add_co_u32_e32 v8, vcc, s19, v24
	s_movk_i32 s12, 0x6000
	s_nop 0
	v_addc_co_u32_e32 v9, vcc, 0, v25, vcc
	v_add_co_u32_e32 v12, vcc, s12, v24
	s_mov_b32 s20, 0x8000
	s_nop 0
	v_addc_co_u32_e32 v13, vcc, 0, v25, vcc
	v_add_co_u32_e32 v16, vcc, s20, v24
	s_mov_b32 s38, 0xc000
	s_nop 0
	v_addc_co_u32_e32 v17, vcc, 0, v25, vcc
	v_add_co_u32_e32 v20, vcc, s33, v24
	v_add_u32_e32 v32, 32, v32
	s_nop 0
	v_addc_co_u32_e32 v21, vcc, 0, v25, vcc
	v_add_co_u32_e32 v26, vcc, s38, v24
	s_mov_b32 s21, 0xe000
	s_nop 0
	v_addc_co_u32_e32 v27, vcc, 0, v25, vcc
	v_ashrrev_i32_e32 v33, 31, v32
	v_add_co_u32_e32 v28, vcc, s21, v24
	v_lshlrev_b64 v[32:33], 13, v[32:33]
	s_nop 0
	v_addc_co_u32_e32 v29, vcc, 0, v25, vcc
	v_lshl_add_u64 v[56:57], v[34:35], 0, v[32:33]
	v_add_co_u32_e32 v36, vcc, s89, v56
	global_load_dwordx4 v[0:3], v[24:25], off nt
	s_nop 0
	global_load_dwordx4 v[4:7], v[4:5], off nt
	v_addc_co_u32_e32 v37, vcc, 0, v57, vcc
	v_add_co_u32_e32 v40, vcc, s19, v56
	global_load_dwordx4 v[8:11], v[8:9], off nt
	s_nop 0
	global_load_dwordx4 v[12:15], v[12:13], off nt
	v_addc_co_u32_e32 v41, vcc, 0, v57, vcc
	v_add_co_u32_e32 v44, vcc, s12, v56
	global_load_dwordx4 v[16:19], v[16:17], off nt
	s_nop 0
	global_load_dwordx4 v[20:23], v[20:21], off nt
	v_addc_co_u32_e32 v45, vcc, 0, v57, vcc
	v_add_co_u32_e32 v48, vcc, s20, v56
	global_load_dwordx4 v[24:27], v[26:27], off nt
	s_nop 0
	global_load_dwordx4 v[28:31], v[28:29], off nt
	v_addc_co_u32_e32 v49, vcc, 0, v57, vcc
	v_add_co_u32_e32 v52, vcc, s33, v56
	global_load_dwordx4 v[32:35], v[56:57], off nt
	s_nop 0
	global_load_dwordx4 v[36:39], v[36:37], off nt
	v_addc_co_u32_e32 v53, vcc, 0, v57, vcc
	v_add_co_u32_e32 v58, vcc, s38, v56
	global_load_dwordx4 v[40:43], v[40:41], off nt
	s_nop 0
	global_load_dwordx4 v[44:47], v[44:45], off nt
	v_addc_co_u32_e32 v59, vcc, 0, v57, vcc
	v_add_co_u32_e32 v60, vcc, s21, v56
	global_load_dwordx4 v[48:51], v[48:49], off nt
	s_nop 0
	global_load_dwordx4 v[52:55], v[52:53], off nt
	v_addc_co_u32_e32 v61, vcc, 0, v57, vcc
	global_load_dwordx4 v[56:59], v[58:59], off nt
	s_nop 0
	global_load_dwordx4 v[60:63], v[60:61], off nt
	s_lshl_b32 s11, s11, 1
	s_add_u32 s20, s23, s11
	s_addc_u32 s21, s26, 0
	v_or_b32_e32 v65, s22, v64
	v_lshl_add_u64 v[72:73], v[66:67], 1, s[20:21]
	s_mov_b64 s[20:21], 0x22500000
	v_lshl_add_u64 v[74:75], v[72:73], 0, s[20:21]
	v_lshlrev_b32_e32 v172, 12, v65
	s_waitcnt vmcnt(14)
	v_cvt_pk_bf16_f32 v68, v0, v4
	v_lshl_add_u64 v[76:77], v[74:75], 0, v[172:173]
	s_waitcnt vmcnt(12)
	v_cvt_pk_bf16_f32 v69, v8, v12
	s_waitcnt vmcnt(10)
	v_cvt_pk_bf16_f32 v70, v16, v20
	s_waitcnt vmcnt(8)
	v_cvt_pk_bf16_f32 v71, v24, v28
	global_store_dwordx4 v[76:77], v[68:71], off sc1
	v_or_b32_e32 v4, 0x1000, v172
	v_or_b32_e32 v8, 0x2000, v172
	v_cvt_pk_bf16_f32 v68, v1, v5
	v_mov_b32_e32 v5, v173
	v_cvt_pk_bf16_f32 v69, v9, v13
	v_lshl_add_u64 v[0:1], v[74:75], 0, v[4:5]
	v_mov_b32_e32 v9, v173
	v_cvt_pk_bf16_f32 v70, v17, v21
	v_cvt_pk_bf16_f32 v71, v25, v29
	global_store_dwordx4 v[0:1], v[68:71], off sc1
	v_lshl_add_u64 v[0:1], v[74:75], 0, v[8:9]
	v_or_b32_e32 v172, 0x3000, v172
	v_cvt_pk_bf16_f32 v68, v2, v6
	v_cvt_pk_bf16_f32 v69, v10, v14
	v_cvt_pk_bf16_f32 v70, v18, v22
	v_cvt_pk_bf16_f32 v71, v26, v30
	global_store_dwordx4 v[0:1], v[68:71], off sc1
	v_cvt_pk_bf16_f32 v0, v3, v7
	v_lshl_add_u64 v[6:7], v[74:75], 0, v[172:173]
	s_mov_b64 s[20:21], 0x22500040
	v_cvt_pk_bf16_f32 v1, v11, v15
	v_cvt_pk_bf16_f32 v2, v19, v23
	v_cvt_pk_bf16_f32 v3, v27, v31
	global_store_dwordx4 v[6:7], v[0:3], off sc1
	v_lshl_add_u64 v[6:7], v[72:73], 0, s[20:21]
	v_lshl_add_u64 v[4:5], v[6:7], 0, v[4:5]
	s_waitcnt vmcnt(10)
	v_cvt_pk_bf16_f32 v0, v32, v36
	s_waitcnt vmcnt(8)
	v_cvt_pk_bf16_f32 v1, v40, v44
	s_waitcnt vmcnt(6)
	v_cvt_pk_bf16_f32 v2, v48, v52
	s_waitcnt vmcnt(4)
	v_cvt_pk_bf16_f32 v3, v56, v60
	global_store_dwordx4 v[76:77], v[0:3], off offset:64 sc1
	s_nop 1
	v_cvt_pk_bf16_f32 v0, v33, v37
	v_cvt_pk_bf16_f32 v1, v41, v45
	v_cvt_pk_bf16_f32 v2, v49, v53
	v_cvt_pk_bf16_f32 v3, v57, v61
	global_store_dwordx4 v[4:5], v[0:3], off sc1
	v_lshl_add_u64 v[4:5], v[6:7], 0, v[8:9]
	s_nop 0
	v_cvt_pk_bf16_f32 v0, v34, v38
	v_cvt_pk_bf16_f32 v1, v42, v46
	v_cvt_pk_bf16_f32 v2, v50, v54
	v_cvt_pk_bf16_f32 v3, v58, v62
	global_store_dwordx4 v[4:5], v[0:3], off sc1
	v_lshl_add_u64 v[4:5], v[6:7], 0, v[172:173]
	s_nop 0
	v_cvt_pk_bf16_f32 v0, v35, v39
	v_cvt_pk_bf16_f32 v1, v43, v47
	v_cvt_pk_bf16_f32 v2, v51, v55
	v_cvt_pk_bf16_f32 v3, v59, v63
	global_store_dwordx4 v[4:5], v[0:3], off sc1

; __device__ __forceinline__ unsigned cvt_pk_bf16(float lo, float hi) { unsigned r; asm volatile("v_cvt_pk_bf16_f32 %0, %1, %2" : "=v"(r) : "v"(lo), "v"(hi)); return r; }
; #define INP(i) ((const float*)(const GASP float*)kargs()[(i)])
; __device__ __forceinline__ void tr_item(const float* W, int ldw, int k0, int n0, bf16* WT, int ldk, int drow0, int lane) {
;     const int n4 = (lane & 15) * 4, kg = lane >> 4; f32x4 v[2][8];
; #pragma unroll
;     for (int kh = 0; kh < 2; ++kh) { const float* src = W + (size_t)(k0 + kh * 32 + kg * 8) * ldw + n0 + n4;
; #pragma unroll
;         for (int i = 0; i < 8; ++i) v[kh][i] = __builtin_nontemporal_load((const f32x4*)(src + (size_t)i * ldw)); }
; #pragma unroll
;     for (int kh = 0; kh < 2; ++kh)
; #pragma unroll
;         for (int e = 0; e < 4; ++e) { u32x4 o; o.x = cvt_pk_bf16(v[kh][0][e], v[kh][1][e]); o.y = cvt_pk_bf16(v[kh][2][e], v[kh][3][e]); o.z = cvt_pk_bf16(v[kh][4][e], v[kh][5][e]); o.w = cvt_pk_bf16(v[kh][6][e], v[kh][7][e]);
;             *(u32x4*)(WT + (size_t)(drow0 + n4 + e) * ldk + k0 + kh * 32 + kg * 8) = o; }
; }
; __device__ __forceinline__ void conv_item(int it, int lane) {
;     ...
;     if (r < 2 * IT_INAB) { const int idx = r / IT_INAB; r -= idx * IT_INAB; const int kb = r / 80, nb = r % 80;
;         tr_item(INP(I_WINAB) + (size_t)idx * 2048 * 5120, 5120, 64 * kb, 64 * nb, (bf16*)(ws + WS_WINAB) + (size_t)idx * 5120 * 2048, 2048, 64 * nb, lane); return; }
.LBB0_1513:
	s_andn2_b64 vcc, exec, s[22:23]
	s_cbranch_vccnz .LBB0_1515
	s_add_i32 s11, s6, 0xffff0400
	s_cmpk_gt_u32 s11, 0x9ff
	s_cselect_b64 s[20:21], -1, 0
	s_and_b64 s[22:23], s[20:21], exec
	s_cselect_b32 s12, 0xf600, 0
	s_add_i32 s12, s12, s11
	s_sext_i32_i16 s11, s12
	s_mulk_i32 s11, 0x6667
	s_mov_b64 s[22:23], s[0:1]
	s_lshr_b32 s19, s11, 31
	s_ashr_i32 s11, s11, 21
	s_add_i32 s11, s11, s19
	s_load_dwordx2 s[22:23], s[22:23], 0x78
	s_mul_i32 s19, s11, 0x50
	s_sub_i32 s12, s12, s19
	s_and_b64 s[26:27], s[20:21], exec
	s_cselect_b32 s19, 0x2800000, 0
	s_sext_i32_i16 s12, s12
	s_waitcnt lgkmcnt(0)
	s_add_u32 s19, s22, s19
	s_addc_u32 s23, s23, 0
	s_lshl_b32 s22, s11, 6
	s_lshl_b32 s26, s12, 6
	s_and_b64 s[20:21], s[20:21], exec
	s_cselect_b32 s11, 0x1400000, 0
	s_add_u32 s11, s2, s11
	s_addc_u32 s12, s3, 0
	s_ashr_i32 s27, s26, 31
	s_lshl_b64 s[20:21], s[26:27], 2
	s_add_u32 s20, s19, s20
	s_addc_u32 s21, s23, s21
	v_lshlrev_b32_e32 v172, 2, v64
	v_add_u32_e32 v34, s22, v66
	v_lshl_add_u64 v[32:33], s[20:21], 0, v[172:173]
	s_movk_i32 s27, 0x5000
	v_mad_i64_i32 v[24:25], s[20:21], v34, s27, v[32:33]
	v_add_co_u32_e32 v4, vcc, s27, v24
	s_mov_b32 s19, 0x14000
	s_nop 0
	v_addc_co_u32_e32 v5, vcc, 0, v25, vcc
	v_add_co_u32_e32 v8, vcc, s33, v24
	s_mov_b32 s28, 0x19000
	s_nop 0
	v_addc_co_u32_e32 v9, vcc, 0, v25, vcc
	v_add_co_u32_e32 v12, vcc, s76, v24
	s_mov_b32 s23, 0x1e000
	s_nop 0
	v_addc_co_u32_e32 v13, vcc, 0, v25, vcc
	v_add_co_u32_e32 v16, vcc, s19, v24
	v_add_u32_e32 v34, 32, v34
	s_nop 0
	v_addc_co_u32_e32 v17, vcc, 0, v25, vcc
	v_add_co_u32_e32 v20, vcc, s28, v24
	v_mad_i64_i32 v[56:57], s[20:21], v34, s27, v[32:33]
	s_nop 0
	v_addc_co_u32_e32 v21, vcc, 0, v25, vcc
	v_add_co_u32_e32 v26, vcc, s23, v24
	global_load_dwordx4 v[0:3], v[24:25], off nt
	s_nop 0
	global_load_dwordx4 v[4:7], v[4:5], off nt
	v_addc_co_u32_e32 v27, vcc, 0, v25, vcc
	v_add_co_u32_e32 v28, vcc, s77, v24
	global_load_dwordx4 v[8:11], v[8:9], off nt
	s_nop 0
	global_load_dwordx4 v[12:15], v[12:13], off nt
	v_addc_co_u32_e32 v29, vcc, 0, v25, vcc
	v_add_co_u32_e32 v36, vcc, s27, v56
	global_load_dwordx4 v[16:19], v[16:17], off nt
	s_nop 0
	global_load_dwordx4 v[20:23], v[20:21], off nt
	v_addc_co_u32_e32 v37, vcc, 0, v57, vcc
	v_add_co_u32_e32 v40, vcc, s33, v56
	global_load_dwordx4 v[24:27], v[26:27], off nt
	s_nop 0
	global_load_dwordx4 v[28:31], v[28:29], off nt
	v_addc_co_u32_e32 v41, vcc, 0, v57, vcc
	v_add_co_u32_e32 v44, vcc, s76, v56
	global_load_dwordx4 v[32:35], v[56:57], off nt
	s_nop 0
	global_load_dwordx4 v[36:39], v[36:37], off nt
	v_addc_co_u32_e32 v45, vcc, 0, v57, vcc
	v_add_co_u32_e32 v48, vcc, s19, v56
	global_load_dwordx4 v[40:43], v[40:41], off nt
	s_nop 0
	global_load_dwordx4 v[44:47], v[44:45], off nt
	v_addc_co_u32_e32 v49, vcc, 0, v57, vcc
	v_add_co_u32_e32 v52, vcc, s28, v56
	v_or_b32_e32 v72, s26, v64
	s_nop 0
	v_addc_co_u32_e32 v53, vcc, 0, v57, vcc
	v_add_co_u32_e32 v58, vcc, s23, v56
	global_load_dwordx4 v[48:51], v[48:49], off nt
	s_nop 0
	global_load_dwordx4 v[52:55], v[52:53], off nt
	v_addc_co_u32_e32 v59, vcc, 0, v57, vcc
	v_add_co_u32_e32 v60, vcc, s77, v56
	s_ashr_i32 s23, s22, 31
	s_nop 0
	v_addc_co_u32_e32 v61, vcc, 0, v57, vcc
	global_load_dwordx4 v[56:59], v[58:59], off nt
	s_nop 0
	global_load_dwordx4 v[60:63], v[60:61], off nt
	s_lshl_b64 s[20:21], s[22:23], 1
	s_add_u32 s20, s11, s20
	s_addc_u32 s21, s12, s21
	v_lshl_add_u64 v[68:69], v[66:67], 1, s[20:21]
	s_mov_b64 s[20:21], 0x1f900000
	v_ashrrev_i32_e32 v73, 31, v72
	v_lshl_add_u64 v[74:75], v[68:69], 0, s[20:21]
	v_lshlrev_b64 v[76:77], 12, v[72:73]
	s_waitcnt vmcnt(14)
	v_cvt_pk_bf16_f32 v68, v0, v4
	v_lshl_add_u64 v[76:77], v[74:75], 0, v[76:77]
	v_or_b32_e32 v0, 1, v72
	s_waitcnt vmcnt(12)
	v_cvt_pk_bf16_f32 v69, v8, v12
	s_waitcnt vmcnt(10)
	v_cvt_pk_bf16_f32 v70, v16, v20
	s_waitcnt vmcnt(8)
	v_cvt_pk_bf16_f32 v71, v24, v28
	global_store_dwordx4 v[76:77], v[68:71], off sc1
	s_nop 1
	v_cvt_pk_bf16_f32 v68, v1, v5
	v_ashrrev_i32_e32 v1, 31, v0
	v_lshlrev_b64 v[0:1], 12, v[0:1]
	v_lshl_add_u64 v[4:5], v[74:75], 0, v[0:1]
	v_or_b32_e32 v0, 2, v72
	v_ashrrev_i32_e32 v1, 31, v0
	v_lshlrev_b64 v[0:1], 12, v[0:1]
	v_cvt_pk_bf16_f32 v69, v9, v13
	v_cvt_pk_bf16_f32 v70, v17, v21
	v_cvt_pk_bf16_f32 v71, v25, v29
	global_store_dwordx4 v[4:5], v[68:71], off sc1
	v_lshl_add_u64 v[8:9], v[74:75], 0, v[0:1]
	s_nop 0
	v_cvt_pk_bf16_f32 v68, v2, v6
	v_or_b32_e32 v6, 3, v72
	v_cvt_pk_bf16_f32 v69, v10, v14
	v_cvt_pk_bf16_f32 v70, v18, v22
	v_cvt_pk_bf16_f32 v71, v26, v30
	global_store_dwordx4 v[8:9], v[68:71], off sc1
	v_cvt_pk_bf16_f32 v0, v3, v7
	v_ashrrev_i32_e32 v7, 31, v6
	v_lshlrev_b64 v[6:7], 12, v[6:7]
	v_cvt_pk_bf16_f32 v1, v11, v15
	v_cvt_pk_bf16_f32 v2, v19, v23
	v_cvt_pk_bf16_f32 v3, v27, v31
	v_lshl_add_u64 v[6:7], v[74:75], 0, v[6:7]
	global_store_dwordx4 v[6:7], v[0:3], off sc1
	s_waitcnt vmcnt(10)
	s_nop 0
	v_cvt_pk_bf16_f32 v0, v32, v36
	s_waitcnt vmcnt(8)
	v_cvt_pk_bf16_f32 v1, v40, v44
	s_waitcnt vmcnt(6)
	v_cvt_pk_bf16_f32 v2, v48, v52
	s_waitcnt vmcnt(4)
	v_cvt_pk_bf16_f32 v3, v56, v60
	global_store_dwordx4 v[76:77], v[0:3], off offset:64 sc1
	s_nop 1
	v_cvt_pk_bf16_f32 v0, v33, v37
	v_cvt_pk_bf16_f32 v1, v41, v45
	v_cvt_pk_bf16_f32 v2, v49, v53
	v_cvt_pk_bf16_f32 v3, v57, v61
	global_store_dwordx4 v[4:5], v[0:3], off offset:64 sc1
	s_nop 1
	v_cvt_pk_bf16_f32 v0, v34, v38
	v_cvt_pk_bf16_f32 v1, v42, v46
	v_cvt_pk_bf16_f32 v2, v50, v54
	v_cvt_pk_bf16_f32 v3, v58, v62
	global_store_dwordx4 v[8:9], v[0:3], off offset:64 sc1
	s_nop 1
	v_cvt_pk_bf16_f32 v0, v35, v39
	v_cvt_pk_bf16_f32 v1, v43, v47
	v_cvt_pk_bf16_f32 v2, v51, v55
	v_cvt_pk_bf16_f32 v3, v59, v63
	global_store_dwordx4 v[6:7], v[0:3], off offset:64 sc1

; __device__ __forceinline__ unsigned cvt_pk_bf16(float lo, float hi) { unsigned r; asm volatile("v_cvt_pk_bf16_f32 %0, %1, %2" : "=v"(r) : "v"(lo), "v"(hi)); return r; }
; #define INP(i) ((const float*)(const GASP float*)kargs()[(i)])
; __device__ __forceinline__ void tr_item(const float* W, int ldw, int k0, int n0, bf16* WT, int ldk, int drow0, int lane) {
;     const int n4 = (lane & 15) * 4, kg = lane >> 4; f32x4 v[2][8];
; #pragma unroll
;     for (int kh = 0; kh < 2; ++kh) { const float* src = W + (size_t)(k0 + kh * 32 + kg * 8) * ldw + n0 + n4;
; #pragma unroll
;         for (int i = 0; i < 8; ++i) v[kh][i] = __builtin_nontemporal_load((const f32x4*)(src + (size_t)i * ldw)); }
; #pragma unroll
;     for (int kh = 0; kh < 2; ++kh)
; #pragma unroll
;         for (int e = 0; e < 4; ++e) { u32x4 o; o.x = cvt_pk_bf16(v[kh][0][e], v[kh][1][e]); o.y = cvt_pk_bf16(v[kh][2][e], v[kh][3][e]); o.z = cvt_pk_bf16(v[kh][4][e], v[kh][5][e]); o.w = cvt_pk_bf16(v[kh][6][e], v[kh][7][e]);
;             *(u32x4*)(WT + (size_t)(drow0 + n4 + e) * ldk + k0 + kh * 32 + kg * 8) = o; }
; }
; __device__ __forceinline__ void conv_item(int it, int lane) {
;     ...
;     if (r < 8 * IT_D) { const int idx = r / IT_D; r -= idx * IT_D; const int kb = r / 32, nb = r % 32;
;         tr_item(INP(I_WD) + (size_t)idx * 5376 * 2048, 2048, 64 * kb, 64 * nb, (bf16*)(ws + WS_WD) + (size_t)idx * 2048 * 5376, 5376, 64 * nb, lane); return; }
.LBB0_1516:
	s_andn2_b64 vcc, exec, s[22:23]
	s_cbranch_vccnz .LBB0_1518
	s_add_i32 s11, s6, 0xffff5800
	s_bfe_u32 s12, s11, 0x100007
	s_mulk_i32 s12, 0xc31
	s_lshr_b32 s12, s12, 16
	s_mul_i32 s19, s12, 0xf580
	s_mov_b64 s[20:21], s[0:1]
	s_add_i32 s11, s19, s11
	s_sext_i32_i16 s19, s11
	s_load_dwordx2 s[20:21], s[20:21], 0x70
	s_bfe_u32 s19, s19, 0x5001a
	s_add_i32 s19, s11, s19
	s_sext_i32_i16 s22, s19
	s_and_b32 s19, s19, 0xffe0
	s_sub_i32 s11, s11, s19
	s_mul_i32 s19, s12, 0x2a00000
	s_waitcnt lgkmcnt(0)
	s_add_u32 s19, s20, s19
	s_sext_i32_i16 s11, s11
	s_addc_u32 s23, s21, 0
	s_lshl_b32 s20, s22, 1
	s_and_b32 s22, s20, 0xffffffc0
	s_lshl_b32 s26, s11, 6
	s_mul_i32 s12, s12, 0x1500000
	s_add_u32 s11, s2, s12
	s_addc_u32 s12, s3, 0
	s_ashr_i32 s27, s26, 31
	s_lshl_b64 s[20:21], s[26:27], 2
	v_add_u32_e32 v32, s22, v66
	s_add_u32 s20, s19, s20
	s_addc_u32 s21, s23, s21
	v_lshlrev_b32_e32 v172, 2, v64
	v_ashrrev_i32_e32 v33, 31, v32
	v_lshl_add_u64 v[34:35], s[20:21], 0, v[172:173]
	v_lshlrev_b64 v[0:1], 13, v[32:33]
	v_lshl_add_u64 v[24:25], v[34:35], 0, v[0:1]
	v_add_co_u32_e32 v4, vcc, s89, v24
	s_movk_i32 s20, 0x4000
	s_nop 0
	v_addc_co_u32_e32 v5, vcc, 0, v25, vcc
	v_add_co_u32_e32 v8, vcc, s20, v24
	s_movk_i32 s19, 0x6000
	s_nop 0
	v_addc_co_u32_e32 v9, vcc, 0, v25, vcc
	v_add_co_u32_e32 v12, vcc, s19, v24
	s_mov_b32 s21, 0x8000
	s_nop 0
	v_addc_co_u32_e32 v13, vcc, 0, v25, vcc
	v_add_co_u32_e32 v16, vcc, s21, v24
	v_add_u32_e32 v32, 32, v32
	s_nop 0
	v_addc_co_u32_e32 v17, vcc, 0, v25, vcc
	v_add_co_u32_e32 v20, vcc, s33, v24
	s_mov_b32 s23, 0xe000
	s_nop 0
	v_addc_co_u32_e32 v21, vcc, 0, v25, vcc
	v_add_co_u32_e32 v26, vcc, s38, v24
	v_ashrrev_i32_e32 v33, 31, v32
	s_nop 0
	v_addc_co_u32_e32 v27, vcc, 0, v25, vcc
	v_add_co_u32_e32 v28, vcc, s23, v24
	v_lshlrev_b64 v[32:33], 13, v[32:33]
	s_nop 0
	v_addc_co_u32_e32 v29, vcc, 0, v25, vcc
	v_lshl_add_u64 v[56:57], v[34:35], 0, v[32:33]
	v_add_co_u32_e32 v36, vcc, s89, v56
	global_load_dwordx4 v[0:3], v[24:25], off nt
	s_nop 0
	global_load_dwordx4 v[4:7], v[4:5], off nt
	v_addc_co_u32_e32 v37, vcc, 0, v57, vcc
	v_add_co_u32_e32 v40, vcc, s20, v56
	global_load_dwordx4 v[8:11], v[8:9], off nt
	s_nop 0
	global_load_dwordx4 v[12:15], v[12:13], off nt
	v_addc_co_u32_e32 v41, vcc, 0, v57, vcc
	v_add_co_u32_e32 v44, vcc, s19, v56
	global_load_dwordx4 v[16:19], v[16:17], off nt
	s_nop 0
	global_load_dwordx4 v[20:23], v[20:21], off nt
	v_addc_co_u32_e32 v45, vcc, 0, v57, vcc
	v_add_co_u32_e32 v48, vcc, s21, v56
	global_load_dwordx4 v[24:27], v[26:27], off nt
	s_nop 0
	global_load_dwordx4 v[28:31], v[28:29], off nt
	v_addc_co_u32_e32 v49, vcc, 0, v57, vcc
	v_add_co_u32_e32 v52, vcc, s33, v56
	global_load_dwordx4 v[32:35], v[56:57], off nt
	s_nop 0
	global_load_dwordx4 v[36:39], v[36:37], off nt
	v_addc_co_u32_e32 v53, vcc, 0, v57, vcc
	v_add_co_u32_e32 v58, vcc, s38, v56
	global_load_dwordx4 v[40:43], v[40:41], off nt
	s_nop 0
	global_load_dwordx4 v[44:47], v[44:45], off nt
	v_addc_co_u32_e32 v59, vcc, 0, v57, vcc
	v_add_co_u32_e32 v60, vcc, s23, v56
	global_load_dwordx4 v[48:51], v[48:49], off nt
	s_nop 0
	global_load_dwordx4 v[52:55], v[52:53], off nt
	v_addc_co_u32_e32 v61, vcc, 0, v57, vcc
	global_load_dwordx4 v[56:59], v[58:59], off nt
	s_nop 0
	global_load_dwordx4 v[60:63], v[60:61], off nt
	s_ashr_i32 s23, s22, 31
	s_lshl_b64 s[20:21], s[22:23], 1
	v_or_b32_e32 v65, s26, v64
	s_add_u32 s20, s11, s20
	s_addc_u32 s21, s12, s21
	v_mul_i32_i24_e32 v74, 0x1500, v65
	v_lshl_add_u64 v[72:73], v[66:67], 1, s[20:21]
	v_ashrrev_i32_e32 v75, 31, v74
	v_lshl_add_u64 v[72:73], v[74:75], 1, v[72:73]
	s_mov_b32 s11, 0x15100000
	v_add_co_u32_e32 v76, vcc, s11, v72
	s_mov_b32 s11, 0x15102000
	s_nop 0
	v_addc_co_u32_e32 v77, vcc, 0, v73, vcc
	s_waitcnt vmcnt(14)
	v_cvt_pk_bf16_f32 v68, v0, v4
	v_add_co_u32_e32 v4, vcc, s11, v72
	s_waitcnt vmcnt(12)
	v_cvt_pk_bf16_f32 v69, v8, v12
	s_waitcnt vmcnt(10)
	v_cvt_pk_bf16_f32 v70, v16, v20
	s_waitcnt vmcnt(8)
	v_cvt_pk_bf16_f32 v71, v24, v28
	global_store_dwordx4 v[76:77], v[68:71], off sc1
	s_mov_b32 s11, 0x15105000
	s_mov_b64 s[20:21], 0x15100000
	v_cvt_pk_bf16_f32 v68, v1, v5
	v_addc_co_u32_e32 v5, vcc, 0, v73, vcc
	v_add_co_u32_e32 v8, vcc, s11, v72
	v_cvt_pk_bf16_f32 v69, v9, v13
	s_mov_b32 s11, 0x15107000
	s_nop 0
	v_addc_co_u32_e32 v9, vcc, 0, v73, vcc
	v_cvt_pk_bf16_f32 v70, v17, v21
	v_cvt_pk_bf16_f32 v71, v25, v29
	global_store_dwordx4 v[4:5], v[68:71], off offset:2560 sc1
	v_lshl_add_u64 v[74:75], v[72:73], 0, s[20:21]
	s_nop 0
	v_cvt_pk_bf16_f32 v68, v2, v6
	v_add_co_u32_e32 v6, vcc, s11, v72
	v_cvt_pk_bf16_f32 v69, v10, v14
	v_cvt_pk_bf16_f32 v70, v18, v22
	v_cvt_pk_bf16_f32 v71, v26, v30
	global_store_dwordx4 v[8:9], v[68:71], off offset:1024 sc1
	v_cvt_pk_bf16_f32 v0, v3, v7
	v_cvt_pk_bf16_f32 v1, v11, v15
	v_cvt_pk_bf16_f32 v2, v19, v23
	v_cvt_pk_bf16_f32 v3, v27, v31
	s_nop 0
	v_addc_co_u32_e32 v7, vcc, 0, v73, vcc
	global_store_dwordx4 v[6:7], v[0:3], off offset:3584 sc1
	s_waitcnt vmcnt(10)
	s_nop 0
	v_cvt_pk_bf16_f32 v0, v32, v36
	s_waitcnt vmcnt(8)
	v_cvt_pk_bf16_f32 v1, v40, v44
	s_waitcnt vmcnt(6)
	v_cvt_pk_bf16_f32 v2, v48, v52
	s_waitcnt vmcnt(4)
	v_cvt_pk_bf16_f32 v3, v56, v60
	global_store_dwordx4 v[74:75], v[0:3], off offset:64 sc1
	s_nop 1
	v_cvt_pk_bf16_f32 v0, v33, v37
	v_cvt_pk_bf16_f32 v1, v41, v45
	v_cvt_pk_bf16_f32 v2, v49, v53
	v_cvt_pk_bf16_f32 v3, v57, v61
	global_store_dwordx4 v[4:5], v[0:3], off offset:2624 sc1
	s_nop 1
	v_cvt_pk_bf16_f32 v0, v34, v38
	v_cvt_pk_bf16_f32 v1, v42, v46
	v_cvt_pk_bf16_f32 v2, v50, v54
	v_cvt_pk_bf16_f32 v3, v58, v62
	global_store_dwordx4 v[8:9], v[0:3], off offset:1088 sc1
	s_nop 1
	v_cvt_pk_bf16_f32 v0, v35, v39
	v_cvt_pk_bf16_f32 v1, v43, v47
	v_cvt_pk_bf16_f32 v2, v51, v55
	v_cvt_pk_bf16_f32 v3, v59, v63
	global_store_dwordx4 v[6:7], v[0:3], off offset:3648 sc1

; __device__ __forceinline__ void tr_item(const float* W, int ldw, int k0, int n0, bf16* WT, int ldk, int drow0, int lane) {
;     const int n4 = (lane & 15) * 4, kg = lane >> 4; f32x4 v[2][8];
; #pragma unroll
;     for (int kh = 0; kh < 2; ++kh) { const float* src = W + (size_t)(k0 + kh * 32 + kg * 8) * ldw + n0 + n4;
; #pragma unroll
;         for (int i = 0; i < 8; ++i) v[kh][i] = __builtin_nontemporal_load((const f32x4*)(src + (size_t)i * ldw)); }
; #pragma unroll
;     for (int kh = 0; kh < 2; ++kh)
; #pragma unroll
;         for (int e = 0; e < 4; ++e) { u32x4 o; o.x = cvt_pk_bf16(v[kh][0][e], v[kh][1][e]); o.y = cvt_pk_bf16(v[kh][2][e], v[kh][3][e]); o.z = cvt_pk_bf16(v[kh][4][e], v[kh][5][e]); o.w = cvt_pk_bf16(v[kh][6][e], v[kh][7][e]);
;             *(u32x4*)(WT + (size_t)(drow0 + n4 + e) * ldk + k0 + kh * 32 + kg * 8) = o; }
; }
; __device__ __forceinline__ void conv_item(int it, int lane) {
;     unsigned char* ws = WSP; int r = it;
;     if (r < 8 * IT_GU) { const int idx = r / IT_GU; r -= idx * IT_GU; const int kb = r / 168, nb = r % 168, n0 = 64 * nb;
;         const int drow = n0 < DFF ? (n0 >> 7) * 256 + (n0 & 127) : ((n0 - DFF) >> 7) * 256 + 128 + ((n0 - DFF) & 127);
;         tr_item(INP(I_WGU) + (size_t)idx * 2048 * 10752, 10752, 64 * kb, n0, (bf16*)(ws + WS_WGU) + (size_t)idx * 10752 * 2048, 2048, drow, lane); return; }
;     r -= 8 * IT_GU;
;     if (r < 8 * IT_D) { const int idx = r / IT_D; r -= idx * IT_D; const int kb = r / 32, nb = r % 32;
;         tr_item(INP(I_WD) + (size_t)idx * 5376 * 2048, 2048, 64 * kb, 64 * nb, (bf16*)(ws + WS_WD) + (size_t)idx * 2048 * 5376, 5376, 64 * nb, lane); return; }
;     r -= 8 * IT_D;
;     if (r < 2 * IT_INAB) { const int idx = r / IT_INAB; r -= idx * IT_INAB; const int kb = r / 80, nb = r % 80;
;         tr_item(INP(I_WINAB) + (size_t)idx * 2048 * 5120, 5120, 64 * kb, 64 * nb, (bf16*)(ws + WS_WINAB) + (size_t)idx * 5120 * 2048, 2048, 64 * nb, lane); return; }
;     r -= 2 * IT_INAB;
;     if (r < 2 * IT_GLU) { const int idx = r / IT_GLU; r -= idx * IT_GLU; const int kb = r / 16, nb = r % 16;
;         tr_item(INP(I_WGLU) + (size_t)idx * 1024 * 1024, 1024, 64 * kb, 64 * nb, (bf16*)(ws + WS_WGLU) + (size_t)idx * 1024 * 1024, 1024, 64 * nb, lane); return; }
;     r -= 2 * IT_GLU;
;     if (r < 2 * IT_OUTAB) { const int idx = r / IT_OUTAB; r -= idx * IT_OUTAB; const int kb = r / 32, nb = r % 32;
.LBB0_1918:
	s_mov_b64 s[20:21], s[0:1]
	s_load_dwordx2 s[36:37], s[20:21], 0x138
	s_add_i32 s6, s12, s28
	s_mov_b64 s[22:23], -1
	s_cmp_gt_i32 s6, 0xa7ff
	s_cbranch_scc0 .LBB0_1940
	s_cmpk_gt_u32 s6, 0xfbff
	s_cbranch_scc0 .LBB0_1937
	s_cmp_gt_u32 s6, 0x10fff
	s_cbranch_scc0 .LBB0_1934
	s_cmp_gt_u32 s6, 0x111ff
	s_cbranch_scc0 .LBB0_1931
	s_cmp_gt_u32 s6, 0x119ff
	s_cbranch_scc0 .LBB0_1928
	s_cmp_gt_u32 s6, 0x12dff
	s_cbranch_scc0 .LBB0_1925
	s_add_i32 s11, s6, 0xfffed200
	s_mul_hi_u32 s12, s11, 0xcccccccd
	s_lshr_b32 s12, s12, 10
	s_mul_i32 s20, s12, 0xfffffb00
	s_add_i32 s11, s20, s11
	s_ashr_i32 s20, s11, 31
	s_lshr_b32 s20, s20, 27
	s_add_i32 s22, s11, s20
	s_mov_b64 s[20:21], s[0:1]
	s_load_dwordx2 s[20:21], s[20:21], 0x128
	s_and_b32 s23, s22, 0x3ffffe0
	s_sub_i32 s11, s11, s23
	s_mul_i32 s28, s12, 0x1400000
	s_mul_hi_u32 s23, s12, 0x1400000
	s_waitcnt lgkmcnt(0)
	s_add_u32 s28, s20, s28
	s_addc_u32 s23, s21, s23
	s_lshl_b32 s20, s22, 1
	s_and_b32 s22, s20, 0xffffffc0
	s_lshl_b32 s40, s11, 6
	s_mul_hi_u32 s11, s12, 0xa00000
	s_mul_i32 s12, s12, 0xa00000
	s_add_u32 s12, s36, s12
	s_addc_u32 s11, s37, s11
	s_ashr_i32 s41, s40, 31
	s_lshl_b64 s[20:21], s[40:41], 2
	v_add_u32_e32 v32, s22, v66
	s_add_u32 s20, s28, s20
	s_addc_u32 s21, s23, s21
	v_lshlrev_b32_e32 v172, 2, v64
	v_ashrrev_i32_e32 v33, 31, v32
	v_lshl_add_u64 v[34:35], s[20:21], 0, v[172:173]
	v_lshlrev_b64 v[0:1], 13, v[32:33]
	v_lshl_add_u64 v[24:25], v[34:35], 0, v[0:1]
	v_add_co_u32_e32 v4, vcc, s89, v24
	s_movk_i32 s21, 0x4000
	s_nop 0
	v_addc_co_u32_e32 v5, vcc, 0, v25, vcc
	v_add_co_u32_e32 v8, vcc, s21, v24
	s_movk_i32 s20, 0x6000
	s_nop 0
	v_addc_co_u32_e32 v9, vcc, 0, v25, vcc
	v_add_co_u32_e32 v12, vcc, s20, v24
	s_mov_b32 s23, 0x8000
	s_nop 0
	v_addc_co_u32_e32 v13, vcc, 0, v25, vcc
	v_add_co_u32_e32 v16, vcc, s23, v24
	v_add_u32_e32 v32, 32, v32
	s_nop 0
	v_addc_co_u32_e32 v17, vcc, 0, v25, vcc
	v_add_co_u32_e32 v20, vcc, s33, v24
	s_mov_b32 s28, 0xe000
	s_nop 0
	v_addc_co_u32_e32 v21, vcc, 0, v25, vcc
	v_add_co_u32_e32 v26, vcc, s38, v24
	v_ashrrev_i32_e32 v33, 31, v32
	s_nop 0
	v_addc_co_u32_e32 v27, vcc, 0, v25, vcc
	v_add_co_u32_e32 v28, vcc, s28, v24
	v_lshlrev_b64 v[32:33], 13, v[32:33]
	s_nop 0
	v_addc_co_u32_e32 v29, vcc, 0, v25, vcc
	v_lshl_add_u64 v[56:57], v[34:35], 0, v[32:33]
	v_add_co_u32_e32 v36, vcc, s89, v56
	global_load_dwordx4 v[0:3], v[24:25], off nt
	s_nop 0
	global_load_dwordx4 v[4:7], v[4:5], off nt
	v_addc_co_u32_e32 v37, vcc, 0, v57, vcc
	v_add_co_u32_e32 v40, vcc, s21, v56
	global_load_dwordx4 v[8:11], v[8:9], off nt
	s_nop 0
	global_load_dwordx4 v[12:15], v[12:13], off nt
	v_addc_co_u32_e32 v41, vcc, 0, v57, vcc
	v_add_co_u32_e32 v44, vcc, s20, v56
	global_load_dwordx4 v[16:19], v[16:17], off nt
	s_nop 0
	global_load_dwordx4 v[20:23], v[20:21], off nt
	v_addc_co_u32_e32 v45, vcc, 0, v57, vcc
	v_add_co_u32_e32 v48, vcc, s23, v56
	global_load_dwordx4 v[24:27], v[26:27], off nt
	s_nop 0
	global_load_dwordx4 v[28:31], v[28:29], off nt
	v_addc_co_u32_e32 v49, vcc, 0, v57, vcc
	v_add_co_u32_e32 v52, vcc, s33, v56
	global_load_dwordx4 v[32:35], v[56:57], off nt
	s_nop 0
	global_load_dwordx4 v[36:39], v[36:37], off nt
	v_addc_co_u32_e32 v53, vcc, 0, v57, vcc
	v_add_co_u32_e32 v58, vcc, s38, v56
	global_load_dwordx4 v[40:43], v[40:41], off nt
	s_nop 0
	global_load_dwordx4 v[44:47], v[44:45], off nt
	v_addc_co_u32_e32 v59, vcc, 0, v57, vcc
	v_add_co_u32_e32 v60, vcc, s28, v56
	global_load_dwordx4 v[48:51], v[48:49], off nt
	s_nop 0
	global_load_dwordx4 v[52:55], v[52:53], off nt
	v_addc_co_u32_e32 v61, vcc, 0, v57, vcc
	global_load_dwordx4 v[56:59], v[58:59], off nt
	s_nop 0
	global_load_dwordx4 v[60:63], v[60:61], off nt
	s_ashr_i32 s23, s22, 31
	s_lshl_b64 s[20:21], s[22:23], 1
	s_add_u32 s20, s12, s20
	v_or_b32_e32 v74, s40, v64
	s_addc_u32 s21, s11, s21
	s_movk_i32 s11, 0xa00
	v_mul_lo_u32 v74, v74, s11
	v_lshl_add_u64 v[72:73], v[66:67], 1, s[20:21]
	v_ashrrev_i32_e32 v75, 31, v74
	v_lshl_add_u64 v[72:73], v[74:75], 1, v[72:73]
	s_mov_b32 s11, 0x25d00000
	v_add_co_u32_e32 v76, vcc, s11, v72
	s_mov_b32 s11, 0x25d01000
	s_nop 0
	v_addc_co_u32_e32 v77, vcc, 0, v73, vcc
	s_waitcnt vmcnt(14)
	v_cvt_pk_bf16_f32 v68, v0, v4
	v_add_co_u32_e32 v4, vcc, s11, v72
	s_waitcnt vmcnt(12)
	v_cvt_pk_bf16_f32 v69, v8, v12
	s_waitcnt vmcnt(10)
	v_cvt_pk_bf16_f32 v70, v16, v20
	s_waitcnt vmcnt(8)
	v_cvt_pk_bf16_f32 v71, v24, v28
	global_store_dwordx4 v[76:77], v[68:71], off sc1
	s_mov_b32 s11, 0x25d02000
	s_mov_b64 s[20:21], 0x25d00000
	v_cvt_pk_bf16_f32 v68, v1, v5
	v_addc_co_u32_e32 v5, vcc, 0, v73, vcc
	v_add_co_u32_e32 v8, vcc, s11, v72
	v_cvt_pk_bf16_f32 v69, v9, v13
	s_mov_b32 s11, 0x25d03000
	s_nop 0
	v_addc_co_u32_e32 v9, vcc, 0, v73, vcc
	v_cvt_pk_bf16_f32 v70, v17, v21
	v_cvt_pk_bf16_f32 v71, v25, v29
	global_store_dwordx4 v[4:5], v[68:71], off offset:1024 sc1
	v_lshl_add_u64 v[74:75], v[72:73], 0, s[20:21]
	s_mov_b64 s[22:23], 0
	v_cvt_pk_bf16_f32 v68, v2, v6
	v_add_co_u32_e32 v6, vcc, s11, v72
	v_cvt_pk_bf16_f32 v69, v10, v14
	v_cvt_pk_bf16_f32 v70, v18, v22
	v_cvt_pk_bf16_f32 v71, v26, v30
	global_store_dwordx4 v[8:9], v[68:71], off offset:2048 sc1
	v_cvt_pk_bf16_f32 v0, v3, v7
	v_cvt_pk_bf16_f32 v1, v11, v15
	v_cvt_pk_bf16_f32 v2, v19, v23
	v_cvt_pk_bf16_f32 v3, v27, v31
	s_nop 0
	v_addc_co_u32_e32 v7, vcc, 0, v73, vcc
	global_store_dwordx4 v[6:7], v[0:3], off offset:3072 sc1
	s_waitcnt vmcnt(10)
	s_nop 0
	v_cvt_pk_bf16_f32 v0, v32, v36
	s_waitcnt vmcnt(8)
	v_cvt_pk_bf16_f32 v1, v40, v44
	s_waitcnt vmcnt(6)
	v_cvt_pk_bf16_f32 v2, v48, v52
	s_waitcnt vmcnt(4)
	v_cvt_pk_bf16_f32 v3, v56, v60
	global_store_dwordx4 v[74:75], v[0:3], off offset:64 sc1
	s_nop 1
	v_cvt_pk_bf16_f32 v0, v33, v37
	v_cvt_pk_bf16_f32 v1, v41, v45
	v_cvt_pk_bf16_f32 v2, v49, v53
	v_cvt_pk_bf16_f32 v3, v57, v61
	global_store_dwordx4 v[4:5], v[0:3], off offset:1088 sc1
	s_nop 1
	v_cvt_pk_bf16_f32 v0, v34, v38
	v_cvt_pk_bf16_f32 v1, v42, v46
	v_cvt_pk_bf16_f32 v2, v50, v54
	v_cvt_pk_bf16_f32 v3, v58, v62
	global_store_dwordx4 v[8:9], v[0:3], off offset:2112 sc1
	s_nop 1
	v_cvt_pk_bf16_f32 v0, v35, v39
	v_cvt_pk_bf16_f32 v1, v43, v47
	v_cvt_pk_bf16_f32 v2, v51, v55
	v_cvt_pk_bf16_f32 v3, v59, v63
	global_store_dwordx4 v[6:7], v[0:3], off offset:3136 sc1
; __device__ __forceinline__ unsigned cvt_pk_bf16(float lo, float hi) { unsigned r; asm volatile("v_cvt_pk_bf16_f32 %0, %1, %2" : "=v"(r) : "v"(lo), "v"(hi)); return r; }
; #define INP(i) ((const float*)(const GASP float*)kargs()[(i)])
; __device__ __forceinline__ void tr_item(const float* W, int ldw, int k0, int n0, bf16* WT, int ldk, int drow0, int lane) {
;     const int n4 = (lane & 15) * 4, kg = lane >> 4; f32x4 v[2][8];
; #pragma unroll
;     for (int kh = 0; kh < 2; ++kh) { const float* src = W + (size_t)(k0 + kh * 32 + kg * 8) * ldw + n0 + n4;
; #pragma unroll
;         for (int i = 0; i < 8; ++i) v[kh][i] = __builtin_nontemporal_load((const f32x4*)(src + (size_t)i * ldw)); }
; #pragma unroll
;     for (int kh = 0; kh < 2; ++kh)
; #pragma unroll
;         for (int e = 0; e < 4; ++e) { u32x4 o; o.x = cvt_pk_bf16(v[kh][0][e], v[kh][1][e]); o.y = cvt_pk_bf16(v[kh][2][e], v[kh][3][e]); o.z = cvt_pk_bf16(v[kh][4][e], v[kh][5][e]); o.w = cvt_pk_bf16(v[kh][6][e], v[kh][7][e]);
;             *(u32x4*)(WT + (size_t)(drow0 + n4 + e) * ldk + k0 + kh * 32 + kg * 8) = o; }
; }
; __device__ __forceinline__ void conv_item(int it, int lane) {
;     ...
;     if (r < 2 * IT_INC) { const int idx = r / IT_INC; r -= idx * IT_INC; const int kb = r / 80, nb = r % 80;
;         tr_item(INP(I_WINC) + (size_t)idx * 2048 * 5120, 5120, 64 * kb, 64 * nb, (bf16*)(ws + WS_WINC) + (size_t)idx * 5120 * 2048, 2048, 64 * nb, lane); return; }
.LBB0_1925:
	s_andn2_b64 vcc, exec, s[22:23]
	s_cbranch_vccnz .LBB0_1927
	s_add_i32 s11, s6, 0xfffee600
	s_cmpk_gt_u32 s11, 0x9ff
	s_cselect_b64 s[20:21], -1, 0
	s_and_b64 s[22:23], s[20:21], exec
	s_cselect_b32 s12, 0xf600, 0
	s_add_i32 s12, s12, s11
	s_sext_i32_i16 s11, s12
	s_mulk_i32 s11, 0x6667
	s_lshr_b32 s22, s11, 31
	s_ashr_i32 s11, s11, 21
	s_add_i32 s11, s11, s22
	s_mov_b64 s[22:23], s[0:1]
	s_load_dwordx2 s[22:23], s[22:23], 0xe8
	s_mul_i32 s28, s11, 0x50
	s_sub_i32 s12, s12, s28
	s_and_b64 s[28:29], s[20:21], exec
	s_cselect_b32 s28, 0x2800000, 0
	s_sext_i32_i16 s12, s12
	s_waitcnt lgkmcnt(0)
	s_add_u32 s28, s22, s28
	s_addc_u32 s23, s23, 0
	s_lshl_b32 s22, s11, 6
	s_lshl_b32 s40, s12, 6
	s_and_b64 s[20:21], s[20:21], exec
	s_cselect_b32 s11, 0x1400000, 0
	s_add_u32 s11, s36, s11
	s_addc_u32 s12, s37, 0
	s_ashr_i32 s41, s40, 31
	s_lshl_b64 s[20:21], s[40:41], 2
	s_add_u32 s20, s28, s20
	s_addc_u32 s21, s23, s21
	v_lshlrev_b32_e32 v172, 2, v64
	v_add_u32_e32 v34, s22, v66
	v_lshl_add_u64 v[32:33], s[20:21], 0, v[172:173]
	s_movk_i32 s29, 0x5000
	v_mad_i64_i32 v[24:25], s[20:21], v34, s29, v[32:33]
	v_add_co_u32_e32 v4, vcc, s29, v24
	s_mov_b32 s23, 0x14000
	s_nop 0
	v_addc_co_u32_e32 v5, vcc, 0, v25, vcc
	v_add_co_u32_e32 v8, vcc, s33, v24
	s_mov_b32 s30, 0x19000
	s_nop 0
	v_addc_co_u32_e32 v9, vcc, 0, v25, vcc
	v_add_co_u32_e32 v12, vcc, s76, v24
	s_mov_b32 s28, 0x1e000
	s_nop 0
	v_addc_co_u32_e32 v13, vcc, 0, v25, vcc
	v_add_co_u32_e32 v16, vcc, s23, v24
	v_add_u32_e32 v34, 32, v34
	s_nop 0
	v_addc_co_u32_e32 v17, vcc, 0, v25, vcc
	v_add_co_u32_e32 v20, vcc, s30, v24
	v_mad_i64_i32 v[56:57], s[20:21], v34, s29, v[32:33]
	s_nop 0
	v_addc_co_u32_e32 v21, vcc, 0, v25, vcc
	v_add_co_u32_e32 v26, vcc, s28, v24
	global_load_dwordx4 v[0:3], v[24:25], off nt
	s_nop 0
	global_load_dwordx4 v[4:7], v[4:5], off nt
	v_addc_co_u32_e32 v27, vcc, 0, v25, vcc
	v_add_co_u32_e32 v28, vcc, s77, v24
	global_load_dwordx4 v[8:11], v[8:9], off nt
	s_nop 0
	global_load_dwordx4 v[12:15], v[12:13], off nt
	v_addc_co_u32_e32 v29, vcc, 0, v25, vcc
	v_add_co_u32_e32 v36, vcc, s29, v56
	global_load_dwordx4 v[16:19], v[16:17], off nt
	s_nop 0
	global_load_dwordx4 v[20:23], v[20:21], off nt
	v_addc_co_u32_e32 v37, vcc, 0, v57, vcc
	v_add_co_u32_e32 v40, vcc, s33, v56
	global_load_dwordx4 v[24:27], v[26:27], off nt
	s_nop 0
	global_load_dwordx4 v[28:31], v[28:29], off nt
	v_addc_co_u32_e32 v41, vcc, 0, v57, vcc
	v_add_co_u32_e32 v44, vcc, s76, v56
	global_load_dwordx4 v[32:35], v[56:57], off nt
	s_nop 0
	global_load_dwordx4 v[36:39], v[36:37], off nt
	v_addc_co_u32_e32 v45, vcc, 0, v57, vcc
	v_add_co_u32_e32 v48, vcc, s23, v56
	global_load_dwordx4 v[40:43], v[40:41], off nt
	s_nop 0
	global_load_dwordx4 v[44:47], v[44:45], off nt
	v_addc_co_u32_e32 v49, vcc, 0, v57, vcc
	v_add_co_u32_e32 v52, vcc, s30, v56
	s_ashr_i32 s23, s22, 31
	s_nop 0
	v_addc_co_u32_e32 v53, vcc, 0, v57, vcc
	v_add_co_u32_e32 v58, vcc, s28, v56
	global_load_dwordx4 v[48:51], v[48:49], off nt
	s_nop 0
	global_load_dwordx4 v[52:55], v[52:53], off nt
	v_addc_co_u32_e32 v59, vcc, 0, v57, vcc
	v_add_co_u32_e32 v60, vcc, s77, v56
	s_lshl_b64 s[20:21], s[22:23], 1
	s_nop 0
	v_addc_co_u32_e32 v61, vcc, 0, v57, vcc
	global_load_dwordx4 v[56:59], v[58:59], off nt
	s_nop 0
	global_load_dwordx4 v[60:63], v[60:61], off nt
	s_add_u32 s20, s11, s20
	v_or_b32_e32 v72, s40, v64
	s_addc_u32 s21, s12, s21
	v_lshl_add_u64 v[68:69], v[66:67], 1, s[20:21]
	s_mov_b64 s[20:21], 0x23500000
	v_ashrrev_i32_e32 v73, 31, v72
	v_lshl_add_u64 v[74:75], v[68:69], 0, s[20:21]
	v_lshlrev_b64 v[76:77], 12, v[72:73]
	s_waitcnt vmcnt(14)
	v_cvt_pk_bf16_f32 v68, v0, v4
	v_lshl_add_u64 v[76:77], v[74:75], 0, v[76:77]
	v_or_b32_e32 v0, 1, v72
	s_waitcnt vmcnt(12)
	v_cvt_pk_bf16_f32 v69, v8, v12
	s_waitcnt vmcnt(10)
	v_cvt_pk_bf16_f32 v70, v16, v20
	s_waitcnt vmcnt(8)
	v_cvt_pk_bf16_f32 v71, v24, v28
	global_store_dwordx4 v[76:77], v[68:71], off sc1
	s_nop 1
	v_cvt_pk_bf16_f32 v68, v1, v5
	v_ashrrev_i32_e32 v1, 31, v0
	v_lshlrev_b64 v[0:1], 12, v[0:1]
	v_lshl_add_u64 v[4:5], v[74:75], 0, v[0:1]
	v_or_b32_e32 v0, 2, v72
	v_ashrrev_i32_e32 v1, 31, v0
	v_lshlrev_b64 v[0:1], 12, v[0:1]
	v_cvt_pk_bf16_f32 v69, v9, v13
	v_cvt_pk_bf16_f32 v70, v17, v21
	v_cvt_pk_bf16_f32 v71, v25, v29
	global_store_dwordx4 v[4:5], v[68:71], off sc1
	v_lshl_add_u64 v[8:9], v[74:75], 0, v[0:1]
	s_nop 0
	v_cvt_pk_bf16_f32 v68, v2, v6
	v_or_b32_e32 v6, 3, v72
	v_cvt_pk_bf16_f32 v69, v10, v14
	v_cvt_pk_bf16_f32 v70, v18, v22
	v_cvt_pk_bf16_f32 v71, v26, v30
	global_store_dwordx4 v[8:9], v[68:71], off sc1
	v_cvt_pk_bf16_f32 v0, v3, v7
	v_ashrrev_i32_e32 v7, 31, v6
	v_lshlrev_b64 v[6:7], 12, v[6:7]
	v_cvt_pk_bf16_f32 v1, v11, v15
	v_cvt_pk_bf16_f32 v2, v19, v23
	v_cvt_pk_bf16_f32 v3, v27, v31
	v_lshl_add_u64 v[6:7], v[74:75], 0, v[6:7]
	global_store_dwordx4 v[6:7], v[0:3], off sc1
	s_waitcnt vmcnt(10)
	s_nop 0
	v_cvt_pk_bf16_f32 v0, v32, v36
	s_waitcnt vmcnt(8)
	v_cvt_pk_bf16_f32 v1, v40, v44
	s_waitcnt vmcnt(6)
	v_cvt_pk_bf16_f32 v2, v48, v52
	s_waitcnt vmcnt(4)
	v_cvt_pk_bf16_f32 v3, v56, v60
	global_store_dwordx4 v[76:77], v[0:3], off offset:64 sc1
	s_nop 1
	v_cvt_pk_bf16_f32 v0, v33, v37
	v_cvt_pk_bf16_f32 v1, v41, v45
	v_cvt_pk_bf16_f32 v2, v49, v53
	v_cvt_pk_bf16_f32 v3, v57, v61
	global_store_dwordx4 v[4:5], v[0:3], off offset:64 sc1
	s_nop 1
	v_cvt_pk_bf16_f32 v0, v34, v38
	v_cvt_pk_bf16_f32 v1, v42, v46
	v_cvt_pk_bf16_f32 v2, v50, v54
	v_cvt_pk_bf16_f32 v3, v58, v62
	global_store_dwordx4 v[8:9], v[0:3], off offset:64 sc1
	s_nop 1
	v_cvt_pk_bf16_f32 v0, v35, v39
	v_cvt_pk_bf16_f32 v1, v43, v47
	v_cvt_pk_bf16_f32 v2, v51, v55
	v_cvt_pk_bf16_f32 v3, v59, v63
	global_store_dwordx4 v[6:7], v[0:3], off offset:64 sc1

; __device__ __forceinline__ unsigned cvt_pk_bf16(float lo, float hi) { unsigned r; asm volatile("v_cvt_pk_bf16_f32 %0, %1, %2" : "=v"(r) : "v"(lo), "v"(hi)); return r; }
; #define INP(i) ((const float*)(const GASP float*)kargs()[(i)])
; __device__ __forceinline__ void tr_item(const float* W, int ldw, int k0, int n0, bf16* WT, int ldk, int drow0, int lane) {
;     const int n4 = (lane & 15) * 4, kg = lane >> 4; f32x4 v[2][8];
; #pragma unroll
;     for (int kh = 0; kh < 2; ++kh) { const float* src = W + (size_t)(k0 + kh * 32 + kg * 8) * ldw + n0 + n4;
; #pragma unroll
;         for (int i = 0; i < 8; ++i) v[kh][i] = __builtin_nontemporal_load((const f32x4*)(src + (size_t)i * ldw)); }
; #pragma unroll
;     for (int kh = 0; kh < 2; ++kh)
; #pragma unroll
;         for (int e = 0; e < 4; ++e) { u32x4 o; o.x = cvt_pk_bf16(v[kh][0][e], v[kh][1][e]); o.y = cvt_pk_bf16(v[kh][2][e], v[kh][3][e]); o.z = cvt_pk_bf16(v[kh][4][e], v[kh][5][e]); o.w = cvt_pk_bf16(v[kh][6][e], v[kh][7][e]);
;             *(u32x4*)(WT + (size_t)(drow0 + n4 + e) * ldk + k0 + kh * 32 + kg * 8) = o; }
; }
; __device__ __forceinline__ void conv_item(int it, int lane) {
;     ...
;     if (r < 2 * IT_OUTAB) { const int idx = r / IT_OUTAB; r -= idx * IT_OUTAB; const int kb = r / 32, nb = r % 32;
;         tr_item(INP(I_WOUTAB) + (size_t)idx * 2048 * 2048, 2048, 64 * kb, 64 * nb, (bf16*)(ws + WS_WOUTAB) + (size_t)idx * 2048 * 2048, 2048, 64 * nb, lane); return; }
.LBB0_1928:
	s_andn2_b64 vcc, exec, s[22:23]
	s_cbranch_vccnz .LBB0_1930
	s_mov_b64 s[20:21], s[0:1]
	s_load_dwordx2 s[20:21], s[20:21], 0xe0
	s_add_i32 s11, s6, 0xfffeee00
	s_lshr_b32 s38, s11, 10
	s_lshl_b64 s[22:23], s[38:39], 24
	v_lshlrev_b32_e32 v172, 2, v64
	s_waitcnt lgkmcnt(0)
	s_add_u32 s12, s20, s22
	s_addc_u32 s22, s21, s23
	s_lshl_b32 s11, s11, 1
	s_lshl_b32 s20, s6, 6
	s_and_b32 s11, s11, 0x7c0
	s_and_b32 s23, s20, 0x7c0
	s_lshl_b64 s[20:21], s[38:39], 23
	s_add_u32 s28, s36, s20
	s_addc_u32 s29, s37, s21
	s_lshl_b32 s20, s23, 2
	v_add_u32_e32 v32, s11, v66
	s_add_u32 s20, s12, s20
	s_addc_u32 s21, s22, 0
	v_ashrrev_i32_e32 v33, 31, v32
	v_lshl_add_u64 v[34:35], s[20:21], 0, v[172:173]
	v_lshlrev_b64 v[0:1], 13, v[32:33]
	v_lshl_add_u64 v[24:25], v[34:35], 0, v[0:1]
	v_add_co_u32_e32 v4, vcc, s89, v24
	s_movk_i32 s20, 0x4000
	s_nop 0
	v_addc_co_u32_e32 v5, vcc, 0, v25, vcc
	v_add_co_u32_e32 v8, vcc, s20, v24
	s_movk_i32 s12, 0x6000
	s_nop 0
	v_addc_co_u32_e32 v9, vcc, 0, v25, vcc
	v_add_co_u32_e32 v12, vcc, s12, v24
	s_mov_b32 s21, 0x8000
	s_nop 0
	v_addc_co_u32_e32 v13, vcc, 0, v25, vcc
	v_add_co_u32_e32 v16, vcc, s21, v24
	s_mov_b32 s38, 0xc000
	s_nop 0
	v_addc_co_u32_e32 v17, vcc, 0, v25, vcc
	v_add_co_u32_e32 v20, vcc, s33, v24
	v_add_u32_e32 v32, 32, v32
	s_nop 0
	v_addc_co_u32_e32 v21, vcc, 0, v25, vcc
	v_add_co_u32_e32 v26, vcc, s38, v24
	s_mov_b32 s22, 0xe000
	s_nop 0
	v_addc_co_u32_e32 v27, vcc, 0, v25, vcc
	v_ashrrev_i32_e32 v33, 31, v32
	v_add_co_u32_e32 v28, vcc, s22, v24
	v_lshlrev_b64 v[32:33], 13, v[32:33]
	s_nop 0
	v_addc_co_u32_e32 v29, vcc, 0, v25, vcc
	v_lshl_add_u64 v[56:57], v[34:35], 0, v[32:33]
	v_add_co_u32_e32 v36, vcc, s89, v56
	global_load_dwordx4 v[0:3], v[24:25], off nt
	s_nop 0
	global_load_dwordx4 v[4:7], v[4:5], off nt
	v_addc_co_u32_e32 v37, vcc, 0, v57, vcc
	v_add_co_u32_e32 v40, vcc, s20, v56
	global_load_dwordx4 v[8:11], v[8:9], off nt
	s_nop 0
	global_load_dwordx4 v[12:15], v[12:13], off nt
	v_addc_co_u32_e32 v41, vcc, 0, v57, vcc
	v_add_co_u32_e32 v44, vcc, s12, v56
	global_load_dwordx4 v[16:19], v[16:17], off nt
	s_nop 0
	global_load_dwordx4 v[20:23], v[20:21], off nt
	v_addc_co_u32_e32 v45, vcc, 0, v57, vcc
	v_add_co_u32_e32 v48, vcc, s21, v56
	global_load_dwordx4 v[24:27], v[26:27], off nt
	s_nop 0
	global_load_dwordx4 v[28:31], v[28:29], off nt
	v_addc_co_u32_e32 v49, vcc, 0, v57, vcc
	v_add_co_u32_e32 v52, vcc, s33, v56
	global_load_dwordx4 v[32:35], v[56:57], off nt
	s_nop 0
	global_load_dwordx4 v[36:39], v[36:37], off nt
	v_addc_co_u32_e32 v53, vcc, 0, v57, vcc
	v_add_co_u32_e32 v58, vcc, s38, v56
	global_load_dwordx4 v[40:43], v[40:41], off nt
	s_nop 0
	global_load_dwordx4 v[44:47], v[44:45], off nt
	v_addc_co_u32_e32 v59, vcc, 0, v57, vcc
	v_add_co_u32_e32 v60, vcc, s22, v56
	global_load_dwordx4 v[48:51], v[48:49], off nt
	s_nop 0
	global_load_dwordx4 v[52:55], v[52:53], off nt
	v_addc_co_u32_e32 v61, vcc, 0, v57, vcc
	global_load_dwordx4 v[56:59], v[58:59], off nt
	s_nop 0
	global_load_dwordx4 v[60:63], v[60:61], off nt
	s_lshl_b32 s11, s11, 1
	s_add_u32 s20, s28, s11
	s_addc_u32 s21, s29, 0
	v_or_b32_e32 v76, s23, v64
	v_lshl_add_u64 v[72:73], v[66:67], 1, s[20:21]
	s_mov_b64 s[20:21], 0x22500000
	v_lshl_add_u64 v[74:75], v[72:73], 0, s[20:21]
	v_lshlrev_b32_e32 v172, 12, v76
	s_waitcnt vmcnt(14)
	v_cvt_pk_bf16_f32 v68, v0, v4
	v_lshl_add_u64 v[76:77], v[74:75], 0, v[172:173]
	s_waitcnt vmcnt(12)
	v_cvt_pk_bf16_f32 v69, v8, v12
	s_waitcnt vmcnt(10)
	v_cvt_pk_bf16_f32 v70, v16, v20
	s_waitcnt vmcnt(8)
	v_cvt_pk_bf16_f32 v71, v24, v28
	global_store_dwordx4 v[76:77], v[68:71], off sc1
	v_or_b32_e32 v4, 0x1000, v172
	v_or_b32_e32 v8, 0x2000, v172
	v_cvt_pk_bf16_f32 v68, v1, v5
	v_mov_b32_e32 v5, v173
	v_cvt_pk_bf16_f32 v69, v9, v13
	v_lshl_add_u64 v[0:1], v[74:75], 0, v[4:5]
	v_mov_b32_e32 v9, v173
	v_cvt_pk_bf16_f32 v70, v17, v21
	v_cvt_pk_bf16_f32 v71, v25, v29
	global_store_dwordx4 v[0:1], v[68:71], off sc1
	v_lshl_add_u64 v[0:1], v[74:75], 0, v[8:9]
	v_or_b32_e32 v172, 0x3000, v172
	v_cvt_pk_bf16_f32 v68, v2, v6
	v_cvt_pk_bf16_f32 v69, v10, v14
	v_cvt_pk_bf16_f32 v70, v18, v22
	v_cvt_pk_bf16_f32 v71, v26, v30
	global_store_dwordx4 v[0:1], v[68:71], off sc1
	v_cvt_pk_bf16_f32 v0, v3, v7
	v_lshl_add_u64 v[6:7], v[74:75], 0, v[172:173]
	s_mov_b64 s[20:21], 0x22500040
	v_cvt_pk_bf16_f32 v1, v11, v15
	v_cvt_pk_bf16_f32 v2, v19, v23
	v_cvt_pk_bf16_f32 v3, v27, v31
	global_store_dwordx4 v[6:7], v[0:3], off sc1
	v_lshl_add_u64 v[6:7], v[72:73], 0, s[20:21]
	v_lshl_add_u64 v[4:5], v[6:7], 0, v[4:5]
	s_waitcnt vmcnt(10)
	v_cvt_pk_bf16_f32 v0, v32, v36
	s_waitcnt vmcnt(8)
	v_cvt_pk_bf16_f32 v1, v40, v44
	s_waitcnt vmcnt(6)
	v_cvt_pk_bf16_f32 v2, v48, v52
	s_waitcnt vmcnt(4)
	v_cvt_pk_bf16_f32 v3, v56, v60
	global_store_dwordx4 v[76:77], v[0:3], off offset:64 sc1
	s_nop 1
	v_cvt_pk_bf16_f32 v0, v33, v37
	v_cvt_pk_bf16_f32 v1, v41, v45
	v_cvt_pk_bf16_f32 v2, v49, v53
	v_cvt_pk_bf16_f32 v3, v57, v61
	global_store_dwordx4 v[4:5], v[0:3], off sc1
	v_lshl_add_u64 v[4:5], v[6:7], 0, v[8:9]
	s_nop 0
	v_cvt_pk_bf16_f32 v0, v34, v38
	v_cvt_pk_bf16_f32 v1, v42, v46
	v_cvt_pk_bf16_f32 v2, v50, v54
	v_cvt_pk_bf16_f32 v3, v58, v62
	global_store_dwordx4 v[4:5], v[0:3], off sc1
	v_lshl_add_u64 v[4:5], v[6:7], 0, v[172:173]
	s_nop 0
	v_cvt_pk_bf16_f32 v0, v35, v39
	v_cvt_pk_bf16_f32 v1, v43, v47
	v_cvt_pk_bf16_f32 v2, v51, v55
	v_cvt_pk_bf16_f32 v3, v59, v63
	global_store_dwordx4 v[4:5], v[0:3], off sc1

; __device__ __forceinline__ unsigned cvt_pk_bf16(float lo, float hi) { unsigned r; asm volatile("v_cvt_pk_bf16_f32 %0, %1, %2" : "=v"(r) : "v"(lo), "v"(hi)); return r; }
; #define INP(i) ((const float*)(const GASP float*)kargs()[(i)])
; __device__ __forceinline__ void tr_item(const float* W, int ldw, int k0, int n0, bf16* WT, int ldk, int drow0, int lane) {
;     const int n4 = (lane & 15) * 4, kg = lane >> 4; f32x4 v[2][8];
; #pragma unroll
;     for (int kh = 0; kh < 2; ++kh) { const float* src = W + (size_t)(k0 + kh * 32 + kg * 8) * ldw + n0 + n4;
; #pragma unroll
;         for (int i = 0; i < 8; ++i) v[kh][i] = __builtin_nontemporal_load((const f32x4*)(src + (size_t)i * ldw)); }
; #pragma unroll
;     for (int kh = 0; kh < 2; ++kh)
; #pragma unroll
;         for (int e = 0; e < 4; ++e) { u32x4 o; o.x = cvt_pk_bf16(v[kh][0][e], v[kh][1][e]); o.y = cvt_pk_bf16(v[kh][2][e], v[kh][3][e]); o.z = cvt_pk_bf16(v[kh][4][e], v[kh][5][e]); o.w = cvt_pk_bf16(v[kh][6][e], v[kh][7][e]);
;             *(u32x4*)(WT + (size_t)(drow0 + n4 + e) * ldk + k0 + kh * 32 + kg * 8) = o; }
; }
; __device__ __forceinline__ void conv_item(int it, int lane) {
;     ...
;     if (r < 2 * IT_INAB) { const int idx = r / IT_INAB; r -= idx * IT_INAB; const int kb = r / 80, nb = r % 80;
;         tr_item(INP(I_WINAB) + (size_t)idx * 2048 * 5120, 5120, 64 * kb, 64 * nb, (bf16*)(ws + WS_WINAB) + (size_t)idx * 5120 * 2048, 2048, 64 * nb, lane); return; }
.LBB0_1934:
	s_andn2_b64 vcc, exec, s[22:23]
	s_cbranch_vccnz .LBB0_1936
	s_add_i32 s11, s6, 0xffff0400
	s_cmpk_gt_u32 s11, 0x9ff
	s_cselect_b64 s[20:21], -1, 0
	s_and_b64 s[22:23], s[20:21], exec
	s_cselect_b32 s12, 0xf600, 0
	s_add_i32 s12, s12, s11
	s_sext_i32_i16 s11, s12
	s_mulk_i32 s11, 0x6667
	s_lshr_b32 s22, s11, 31
	s_ashr_i32 s11, s11, 21
	s_add_i32 s11, s11, s22
	s_mov_b64 s[22:23], s[0:1]
	s_load_dwordx2 s[22:23], s[22:23], 0x78
	s_mul_i32 s28, s11, 0x50
	s_sub_i32 s12, s12, s28
	s_and_b64 s[28:29], s[20:21], exec
	s_cselect_b32 s28, 0x2800000, 0
	s_sext_i32_i16 s12, s12
	s_waitcnt lgkmcnt(0)
	s_add_u32 s28, s22, s28
	s_addc_u32 s23, s23, 0
	s_lshl_b32 s22, s11, 6
	s_lshl_b32 s40, s12, 6
	s_and_b64 s[20:21], s[20:21], exec
	s_cselect_b32 s11, 0x1400000, 0
	s_add_u32 s11, s36, s11
	s_addc_u32 s12, s37, 0
	s_ashr_i32 s41, s40, 31
	s_lshl_b64 s[20:21], s[40:41], 2
	s_add_u32 s20, s28, s20
	s_addc_u32 s21, s23, s21
	v_lshlrev_b32_e32 v172, 2, v64
	v_add_u32_e32 v34, s22, v66
	v_lshl_add_u64 v[32:33], s[20:21], 0, v[172:173]
	s_movk_i32 s29, 0x5000
	v_mad_i64_i32 v[24:25], s[20:21], v34, s29, v[32:33]
	v_add_co_u32_e32 v4, vcc, s29, v24
	s_mov_b32 s23, 0x14000
	s_nop 0
	v_addc_co_u32_e32 v5, vcc, 0, v25, vcc
	v_add_co_u32_e32 v8, vcc, s33, v24
	s_mov_b32 s30, 0x19000
	s_nop 0
	v_addc_co_u32_e32 v9, vcc, 0, v25, vcc
	v_add_co_u32_e32 v12, vcc, s76, v24
	s_mov_b32 s28, 0x1e000
	s_nop 0
	v_addc_co_u32_e32 v13, vcc, 0, v25, vcc
	v_add_co_u32_e32 v16, vcc, s23, v24
	v_add_u32_e32 v34, 32, v34
	s_nop 0
	v_addc_co_u32_e32 v17, vcc, 0, v25, vcc
	v_add_co_u32_e32 v20, vcc, s30, v24
	v_mad_i64_i32 v[56:57], s[20:21], v34, s29, v[32:33]
	s_nop 0
	v_addc_co_u32_e32 v21, vcc, 0, v25, vcc
	v_add_co_u32_e32 v26, vcc, s28, v24
	global_load_dwordx4 v[0:3], v[24:25], off nt
	s_nop 0
	global_load_dwordx4 v[4:7], v[4:5], off nt
	v_addc_co_u32_e32 v27, vcc, 0, v25, vcc
	v_add_co_u32_e32 v28, vcc, s77, v24
	global_load_dwordx4 v[8:11], v[8:9], off nt
	s_nop 0
	global_load_dwordx4 v[12:15], v[12:13], off nt
	v_addc_co_u32_e32 v29, vcc, 0, v25, vcc
	v_add_co_u32_e32 v36, vcc, s29, v56
	global_load_dwordx4 v[16:19], v[16:17], off nt
	s_nop 0
	global_load_dwordx4 v[20:23], v[20:21], off nt
	v_addc_co_u32_e32 v37, vcc, 0, v57, vcc
	v_add_co_u32_e32 v40, vcc, s33, v56
	global_load_dwordx4 v[24:27], v[26:27], off nt
	s_nop 0
	global_load_dwordx4 v[28:31], v[28:29], off nt
	v_addc_co_u32_e32 v41, vcc, 0, v57, vcc
	v_add_co_u32_e32 v44, vcc, s76, v56
	global_load_dwordx4 v[32:35], v[56:57], off nt
	s_nop 0
	global_load_dwordx4 v[36:39], v[36:37], off nt
	v_addc_co_u32_e32 v45, vcc, 0, v57, vcc
	v_add_co_u32_e32 v48, vcc, s23, v56
	global_load_dwordx4 v[40:43], v[40:41], off nt
	s_nop 0
	global_load_dwordx4 v[44:47], v[44:45], off nt
	v_addc_co_u32_e32 v49, vcc, 0, v57, vcc
	v_add_co_u32_e32 v52, vcc, s30, v56
	s_ashr_i32 s23, s22, 31
	s_nop 0
	v_addc_co_u32_e32 v53, vcc, 0, v57, vcc
	v_add_co_u32_e32 v58, vcc, s28, v56
	global_load_dwordx4 v[48:51], v[48:49], off nt
	s_nop 0
	global_load_dwordx4 v[52:55], v[52:53], off nt
	v_addc_co_u32_e32 v59, vcc, 0, v57, vcc
	v_add_co_u32_e32 v60, vcc, s77, v56
	s_lshl_b64 s[20:21], s[22:23], 1
	s_nop 0
	v_addc_co_u32_e32 v61, vcc, 0, v57, vcc
	global_load_dwordx4 v[56:59], v[58:59], off nt
	s_nop 0
	global_load_dwordx4 v[60:63], v[60:61], off nt
	s_add_u32 s20, s11, s20
	v_or_b32_e32 v72, s40, v64
	s_addc_u32 s21, s12, s21
	v_lshl_add_u64 v[68:69], v[66:67], 1, s[20:21]
	s_mov_b64 s[20:21], 0x1f900000
	v_ashrrev_i32_e32 v73, 31, v72
	v_lshl_add_u64 v[74:75], v[68:69], 0, s[20:21]
	v_lshlrev_b64 v[76:77], 12, v[72:73]
	s_waitcnt vmcnt(14)
	v_cvt_pk_bf16_f32 v68, v0, v4
	v_lshl_add_u64 v[76:77], v[74:75], 0, v[76:77]
	v_or_b32_e32 v0, 1, v72
	s_waitcnt vmcnt(12)
	v_cvt_pk_bf16_f32 v69, v8, v12
	s_waitcnt vmcnt(10)
	v_cvt_pk_bf16_f32 v70, v16, v20
	s_waitcnt vmcnt(8)
	v_cvt_pk_bf16_f32 v71, v24, v28
	global_store_dwordx4 v[76:77], v[68:71], off sc1
	s_nop 1
	v_cvt_pk_bf16_f32 v68, v1, v5
	v_ashrrev_i32_e32 v1, 31, v0
	v_lshlrev_b64 v[0:1], 12, v[0:1]
	v_lshl_add_u64 v[4:5], v[74:75], 0, v[0:1]
	v_or_b32_e32 v0, 2, v72
	v_ashrrev_i32_e32 v1, 31, v0
	v_lshlrev_b64 v[0:1], 12, v[0:1]
	v_cvt_pk_bf16_f32 v69, v9, v13
	v_cvt_pk_bf16_f32 v70, v17, v21
	v_cvt_pk_bf16_f32 v71, v25, v29
	global_store_dwordx4 v[4:5], v[68:71], off sc1
	v_lshl_add_u64 v[8:9], v[74:75], 0, v[0:1]
	s_nop 0
	v_cvt_pk_bf16_f32 v68, v2, v6
	v_or_b32_e32 v6, 3, v72
	v_cvt_pk_bf16_f32 v69, v10, v14
	v_cvt_pk_bf16_f32 v70, v18, v22
	v_cvt_pk_bf16_f32 v71, v26, v30
	global_store_dwordx4 v[8:9], v[68:71], off sc1
	v_cvt_pk_bf16_f32 v0, v3, v7
	v_ashrrev_i32_e32 v7, 31, v6
	v_lshlrev_b64 v[6:7], 12, v[6:7]
	v_cvt_pk_bf16_f32 v1, v11, v15
	v_cvt_pk_bf16_f32 v2, v19, v23
	v_cvt_pk_bf16_f32 v3, v27, v31
	v_lshl_add_u64 v[6:7], v[74:75], 0, v[6:7]
	global_store_dwordx4 v[6:7], v[0:3], off sc1
	s_waitcnt vmcnt(10)
	s_nop 0
	v_cvt_pk_bf16_f32 v0, v32, v36
	s_waitcnt vmcnt(8)
	v_cvt_pk_bf16_f32 v1, v40, v44
	s_waitcnt vmcnt(6)
	v_cvt_pk_bf16_f32 v2, v48, v52
	s_waitcnt vmcnt(4)
	v_cvt_pk_bf16_f32 v3, v56, v60
	global_store_dwordx4 v[76:77], v[0:3], off offset:64 sc1
	s_nop 1
	v_cvt_pk_bf16_f32 v0, v33, v37
	v_cvt_pk_bf16_f32 v1, v41, v45
	v_cvt_pk_bf16_f32 v2, v49, v53
	v_cvt_pk_bf16_f32 v3, v57, v61
	global_store_dwordx4 v[4:5], v[0:3], off offset:64 sc1
	s_nop 1
	v_cvt_pk_bf16_f32 v0, v34, v38
	v_cvt_pk_bf16_f32 v1, v42, v46
	v_cvt_pk_bf16_f32 v2, v50, v54
	v_cvt_pk_bf16_f32 v3, v58, v62
	global_store_dwordx4 v[8:9], v[0:3], off offset:64 sc1
	s_nop 1
	v_cvt_pk_bf16_f32 v0, v35, v39
	v_cvt_pk_bf16_f32 v1, v43, v47
	v_cvt_pk_bf16_f32 v2, v51, v55
	v_cvt_pk_bf16_f32 v3, v59, v63
	global_store_dwordx4 v[6:7], v[0:3], off offset:64 sc1

; __device__ __forceinline__ unsigned cvt_pk_bf16(float lo, float hi) { unsigned r; asm volatile("v_cvt_pk_bf16_f32 %0, %1, %2" : "=v"(r) : "v"(lo), "v"(hi)); return r; }
; #define INP(i) ((const float*)(const GASP float*)kargs()[(i)])
; __device__ __forceinline__ void tr_item(const float* W, int ldw, int k0, int n0, bf16* WT, int ldk, int drow0, int lane) {
;     const int n4 = (lane & 15) * 4, kg = lane >> 4; f32x4 v[2][8];
; #pragma unroll
;     for (int kh = 0; kh < 2; ++kh) { const float* src = W + (size_t)(k0 + kh * 32 + kg * 8) * ldw + n0 + n4;
; #pragma unroll
;         for (int i = 0; i < 8; ++i) v[kh][i] = __builtin_nontemporal_load((const f32x4*)(src + (size_t)i * ldw)); }
; #pragma unroll
;     for (int kh = 0; kh < 2; ++kh)
; #pragma unroll
;         for (int e = 0; e < 4; ++e) { u32x4 o; o.x = cvt_pk_bf16(v[kh][0][e], v[kh][1][e]); o.y = cvt_pk_bf16(v[kh][2][e], v[kh][3][e]); o.z = cvt_pk_bf16(v[kh][4][e], v[kh][5][e]); o.w = cvt_pk_bf16(v[kh][6][e], v[kh][7][e]);
;             *(u32x4*)(WT + (size_t)(drow0 + n4 + e) * ldk + k0 + kh * 32 + kg * 8) = o; }
; }
; __device__ __forceinline__ void conv_item(int it, int lane) {
;     ...
;     if (r < 8 * IT_D) { const int idx = r / IT_D; r -= idx * IT_D; const int kb = r / 32, nb = r % 32;
;         tr_item(INP(I_WD) + (size_t)idx * 5376 * 2048, 2048, 64 * kb, 64 * nb, (bf16*)(ws + WS_WD) + (size_t)idx * 2048 * 5376, 5376, 64 * nb, lane); return; }
.LBB0_1937:
	s_andn2_b64 vcc, exec, s[22:23]
	s_cbranch_vccnz .LBB0_1939
	s_add_i32 s11, s6, 0xffff5800
	s_bfe_u32 s12, s11, 0x100007
	s_mulk_i32 s12, 0xc31
	s_lshr_b32 s12, s12, 16
	s_mul_i32 s20, s12, 0xf580
	s_add_i32 s11, s20, s11
	s_sext_i32_i16 s20, s11
	s_bfe_u32 s20, s20, 0x5001a
	s_add_i32 s22, s11, s20
	s_mov_b64 s[20:21], s[0:1]
	s_load_dwordx2 s[20:21], s[20:21], 0x70
	s_sext_i32_i16 s23, s22
	s_and_b32 s22, s22, 0xffe0
	s_sub_i32 s11, s11, s22
	s_mul_i32 s22, s12, 0x2a00000
	s_waitcnt lgkmcnt(0)
	s_add_u32 s28, s20, s22
	s_sext_i32_i16 s11, s11
	s_addc_u32 s29, s21, 0
	s_lshl_b32 s20, s23, 1
	s_and_b32 s22, s20, 0xffffffc0
	s_lshl_b32 s40, s11, 6
	s_mul_i32 s12, s12, 0x1500000
	s_add_u32 s11, s36, s12
	s_addc_u32 s12, s37, 0
	s_ashr_i32 s41, s40, 31
	s_lshl_b64 s[20:21], s[40:41], 2
	v_add_u32_e32 v32, s22, v66
	s_add_u32 s20, s28, s20
	s_addc_u32 s21, s29, s21
	v_lshlrev_b32_e32 v172, 2, v64
	v_ashrrev_i32_e32 v33, 31, v32
	v_lshl_add_u64 v[34:35], s[20:21], 0, v[172:173]
	v_lshlrev_b64 v[0:1], 13, v[32:33]
	v_lshl_add_u64 v[24:25], v[34:35], 0, v[0:1]
	v_add_co_u32_e32 v4, vcc, s89, v24
	s_movk_i32 s21, 0x4000
	s_nop 0
	v_addc_co_u32_e32 v5, vcc, 0, v25, vcc
	v_add_co_u32_e32 v8, vcc, s21, v24
	s_movk_i32 s20, 0x6000
	s_nop 0
	v_addc_co_u32_e32 v9, vcc, 0, v25, vcc
	v_add_co_u32_e32 v12, vcc, s20, v24
	s_mov_b32 s23, 0x8000
	s_nop 0
	v_addc_co_u32_e32 v13, vcc, 0, v25, vcc
	v_add_co_u32_e32 v16, vcc, s23, v24
	v_add_u32_e32 v32, 32, v32
	s_nop 0
	v_addc_co_u32_e32 v17, vcc, 0, v25, vcc
	v_add_co_u32_e32 v20, vcc, s33, v24
	s_mov_b32 s28, 0xe000
	s_nop 0
	v_addc_co_u32_e32 v21, vcc, 0, v25, vcc
	v_add_co_u32_e32 v26, vcc, s38, v24
	v_ashrrev_i32_e32 v33, 31, v32
	s_nop 0
	v_addc_co_u32_e32 v27, vcc, 0, v25, vcc
	v_add_co_u32_e32 v28, vcc, s28, v24
	v_lshlrev_b64 v[32:33], 13, v[32:33]
	s_nop 0
	v_addc_co_u32_e32 v29, vcc, 0, v25, vcc
	v_lshl_add_u64 v[56:57], v[34:35], 0, v[32:33]
	v_add_co_u32_e32 v36, vcc, s89, v56
	global_load_dwordx4 v[0:3], v[24:25], off nt
	s_nop 0
	global_load_dwordx4 v[4:7], v[4:5], off nt
	v_addc_co_u32_e32 v37, vcc, 0, v57, vcc
	v_add_co_u32_e32 v40, vcc, s21, v56
	global_load_dwordx4 v[8:11], v[8:9], off nt
	s_nop 0
	global_load_dwordx4 v[12:15], v[12:13], off nt
	v_addc_co_u32_e32 v41, vcc, 0, v57, vcc
	v_add_co_u32_e32 v44, vcc, s20, v56
	global_load_dwordx4 v[16:19], v[16:17], off nt
	s_nop 0
	global_load_dwordx4 v[20:23], v[20:21], off nt
	v_addc_co_u32_e32 v45, vcc, 0, v57, vcc
	v_add_co_u32_e32 v48, vcc, s23, v56
	global_load_dwordx4 v[24:27], v[26:27], off nt
	s_nop 0
	global_load_dwordx4 v[28:31], v[28:29], off nt
	v_addc_co_u32_e32 v49, vcc, 0, v57, vcc
	v_add_co_u32_e32 v52, vcc, s33, v56
	global_load_dwordx4 v[32:35], v[56:57], off nt
	s_nop 0
	global_load_dwordx4 v[36:39], v[36:37], off nt
	v_addc_co_u32_e32 v53, vcc, 0, v57, vcc
	v_add_co_u32_e32 v58, vcc, s38, v56
	global_load_dwordx4 v[40:43], v[40:41], off nt
	s_nop 0
	global_load_dwordx4 v[44:47], v[44:45], off nt
	v_addc_co_u32_e32 v59, vcc, 0, v57, vcc
	v_add_co_u32_e32 v60, vcc, s28, v56
	global_load_dwordx4 v[48:51], v[48:49], off nt
	s_nop 0
	global_load_dwordx4 v[52:55], v[52:53], off nt
	v_addc_co_u32_e32 v61, vcc, 0, v57, vcc
	global_load_dwordx4 v[56:59], v[58:59], off nt
	s_nop 0
	global_load_dwordx4 v[60:63], v[60:61], off nt
	s_ashr_i32 s23, s22, 31
	s_lshl_b64 s[20:21], s[22:23], 1
	v_or_b32_e32 v74, s40, v64
	s_add_u32 s20, s11, s20
	s_addc_u32 s21, s12, s21
	v_mul_i32_i24_e32 v74, 0x1500, v74
	v_lshl_add_u64 v[72:73], v[66:67], 1, s[20:21]
	v_ashrrev_i32_e32 v75, 31, v74
	v_lshl_add_u64 v[72:73], v[74:75], 1, v[72:73]
	s_mov_b32 s11, 0x15100000
	v_add_co_u32_e32 v76, vcc, s11, v72
	s_mov_b32 s11, 0x15102000
	s_nop 0
	v_addc_co_u32_e32 v77, vcc, 0, v73, vcc
	s_waitcnt vmcnt(14)
	v_cvt_pk_bf16_f32 v68, v0, v4
	v_add_co_u32_e32 v4, vcc, s11, v72
	s_waitcnt vmcnt(12)
	v_cvt_pk_bf16_f32 v69, v8, v12
	s_waitcnt vmcnt(10)
	v_cvt_pk_bf16_f32 v70, v16, v20
	s_waitcnt vmcnt(8)
	v_cvt_pk_bf16_f32 v71, v24, v28
	global_store_dwordx4 v[76:77], v[68:71], off sc1
	s_mov_b32 s11, 0x15105000
	s_mov_b64 s[20:21], 0x15100000
	v_cvt_pk_bf16_f32 v68, v1, v5
	v_addc_co_u32_e32 v5, vcc, 0, v73, vcc
	v_add_co_u32_e32 v8, vcc, s11, v72
	v_cvt_pk_bf16_f32 v69, v9, v13
	s_mov_b32 s11, 0x15107000
	s_nop 0
	v_addc_co_u32_e32 v9, vcc, 0, v73, vcc
	v_cvt_pk_bf16_f32 v70, v17, v21
	v_cvt_pk_bf16_f32 v71, v25, v29
	global_store_dwordx4 v[4:5], v[68:71], off offset:2560 sc1
	v_lshl_add_u64 v[74:75], v[72:73], 0, s[20:21]
	s_nop 0
	v_cvt_pk_bf16_f32 v68, v2, v6
	v_add_co_u32_e32 v6, vcc, s11, v72
	v_cvt_pk_bf16_f32 v69, v10, v14
	v_cvt_pk_bf16_f32 v70, v18, v22
	v_cvt_pk_bf16_f32 v71, v26, v30
	global_store_dwordx4 v[8:9], v[68:71], off offset:1024 sc1
	v_cvt_pk_bf16_f32 v0, v3, v7
	v_cvt_pk_bf16_f32 v1, v11, v15
	v_cvt_pk_bf16_f32 v2, v19, v23
	v_cvt_pk_bf16_f32 v3, v27, v31
	s_nop 0
	v_addc_co_u32_e32 v7, vcc, 0, v73, vcc
	global_store_dwordx4 v[6:7], v[0:3], off offset:3584 sc1
	s_waitcnt vmcnt(10)
	s_nop 0
	v_cvt_pk_bf16_f32 v0, v32, v36
	s_waitcnt vmcnt(8)
	v_cvt_pk_bf16_f32 v1, v40, v44
	s_waitcnt vmcnt(6)
	v_cvt_pk_bf16_f32 v2, v48, v52
	s_waitcnt vmcnt(4)
	v_cvt_pk_bf16_f32 v3, v56, v60
	global_store_dwordx4 v[74:75], v[0:3], off offset:64 sc1
	s_nop 1
	v_cvt_pk_bf16_f32 v0, v33, v37
	v_cvt_pk_bf16_f32 v1, v41, v45
	v_cvt_pk_bf16_f32 v2, v49, v53
	v_cvt_pk_bf16_f32 v3, v57, v61
	global_store_dwordx4 v[4:5], v[0:3], off offset:2624 sc1
	s_nop 1
	v_cvt_pk_bf16_f32 v0, v34, v38
	v_cvt_pk_bf16_f32 v1, v42, v46
	v_cvt_pk_bf16_f32 v2, v50, v54
	v_cvt_pk_bf16_f32 v3, v58, v62
	global_store_dwordx4 v[8:9], v[0:3], off offset:1088 sc1
	s_nop 1
	v_cvt_pk_bf16_f32 v0, v35, v39
	v_cvt_pk_bf16_f32 v1, v43, v47
	v_cvt_pk_bf16_f32 v2, v51, v55
	v_cvt_pk_bf16_f32 v3, v59, v63
	global_store_dwordx4 v[6:7], v[0:3], off offset:3648 sc1

; __device__ __forceinline__ void tr_item(const float* W, int ldw, int k0, int n0, bf16* WT, int ldk, int drow0, int lane) {
;     const int n4 = (lane & 15) * 4, kg = lane >> 4; f32x4 v[2][8];
; #pragma unroll
;     for (int kh = 0; kh < 2; ++kh) { const float* src = W + (size_t)(k0 + kh * 32 + kg * 8) * ldw + n0 + n4;
; #pragma unroll
;         for (int i = 0; i < 8; ++i) v[kh][i] = __builtin_nontemporal_load((const f32x4*)(src + (size_t)i * ldw)); }
; #pragma unroll
;     for (int kh = 0; kh < 2; ++kh)
; #pragma unroll
;         for (int e = 0; e < 4; ++e) { u32x4 o; o.x = cvt_pk_bf16(v[kh][0][e], v[kh][1][e]); o.y = cvt_pk_bf16(v[kh][2][e], v[kh][3][e]); o.z = cvt_pk_bf16(v[kh][4][e], v[kh][5][e]); o.w = cvt_pk_bf16(v[kh][6][e], v[kh][7][e]);
;             *(u32x4*)(WT + (size_t)(drow0 + n4 + e) * ldk + k0 + kh * 32 + kg * 8) = o; }
; }
; __device__ __forceinline__ void conv_item(int it, int lane) {
;     unsigned char* ws = WSP; int r = it;
;     if (r < 8 * IT_GU) { const int idx = r / IT_GU; r -= idx * IT_GU; const int kb = r / 168, nb = r % 168, n0 = 64 * nb;
;         const int drow = n0 < DFF ? (n0 >> 7) * 256 + (n0 & 127) : ((n0 - DFF) >> 7) * 256 + 128 + ((n0 - DFF) & 127);
;         tr_item(INP(I_WGU) + (size_t)idx * 2048 * 10752, 10752, 64 * kb, n0, (bf16*)(ws + WS_WGU) + (size_t)idx * 10752 * 2048, 2048, drow, lane); return; }
;     r -= 8 * IT_GU;
;     if (r < 8 * IT_D) { const int idx = r / IT_D; r -= idx * IT_D; const int kb = r / 32, nb = r % 32;
;         tr_item(INP(I_WD) + (size_t)idx * 5376 * 2048, 2048, 64 * kb, 64 * nb, (bf16*)(ws + WS_WD) + (size_t)idx * 2048 * 5376, 5376, 64 * nb, lane); return; }
;     r -= 8 * IT_D;
;     if (r < 2 * IT_INAB) { const int idx = r / IT_INAB; r -= idx * IT_INAB; const int kb = r / 80, nb = r % 80;
;         tr_item(INP(I_WINAB) + (size_t)idx * 2048 * 5120, 5120, 64 * kb, 64 * nb, (bf16*)(ws + WS_WINAB) + (size_t)idx * 5120 * 2048, 2048, 64 * nb, lane); return; }
;     r -= 2 * IT_INAB;
;     if (r < 2 * IT_GLU) { const int idx = r / IT_GLU; r -= idx * IT_GLU; const int kb = r / 16, nb = r % 16;
;         tr_item(INP(I_WGLU) + (size_t)idx * 1024 * 1024, 1024, 64 * kb, 64 * nb, (bf16*)(ws + WS_WGLU) + (size_t)idx * 1024 * 1024, 1024, 64 * nb, lane); return; }
;     r -= 2 * IT_GLU;
;     if (r < 2 * IT_OUTAB) { const int idx = r / IT_OUTAB; r -= idx * IT_OUTAB; const int kb = r / 32, nb = r % 32;
.LBB0_2118:
	s_add_i32 s6, s12, s16
	s_mov_b64 s[12:13], s[0:1]
	s_load_dwordx2 s[26:27], s[12:13], 0x138
	v_lshlrev_b32_e32 v0, 2, v174
	s_waitcnt vmcnt(0)
	v_and_b32_e32 v72, 60, v0
	v_ashrrev_i32_e32 v0, 1, v174
	v_and_b32_e32 v64, -8, v0
	v_ashrrev_i32_e32 v65, 31, v64
	s_mov_b64 s[22:23], -1
	s_cmp_gt_i32 s6, 0xa7ff
	s_cbranch_scc0 .LBB0_2140
	s_cmpk_gt_u32 s6, 0xfbff
	s_cbranch_scc0 .LBB0_2137
	s_cmp_gt_u32 s6, 0x10fff
	s_cbranch_scc0 .LBB0_2134
	s_cmp_gt_u32 s6, 0x111ff
	s_cbranch_scc0 .LBB0_2131
	s_cmp_gt_u32 s6, 0x119ff
	s_cbranch_scc0 .LBB0_2128
	s_cmp_gt_u32 s6, 0x12dff
	s_cbranch_scc0 .LBB0_2125
	s_add_i32 s11, s6, 0xfffed200
	s_mul_hi_u32 s12, s11, 0xcccccccd
	s_lshr_b32 s15, s12, 10
	s_mul_i32 s12, s15, 0xfffffb00
	s_add_i32 s11, s12, s11
	s_ashr_i32 s12, s11, 31
	s_lshr_b32 s12, s12, 27
	s_add_i32 s16, s11, s12
	s_mov_b64 s[12:13], s[0:1]
	s_load_dwordx2 s[12:13], s[12:13], 0x128
	s_and_b32 s17, s16, 0x3ffffe0
	s_sub_i32 s11, s11, s17
	s_mul_i32 s18, s15, 0x1400000
	s_mul_hi_u32 s17, s15, 0x1400000
	s_waitcnt lgkmcnt(0)
	s_add_u32 s18, s12, s18
	s_addc_u32 s17, s13, s17
	s_lshl_b32 s12, s16, 1
	s_and_b32 s22, s12, 0xffffffc0
	s_lshl_b32 s36, s11, 6
	s_mul_hi_u32 s11, s15, 0xa00000
	s_mul_i32 s15, s15, 0xa00000
	s_add_u32 s15, s26, s15
	s_addc_u32 s11, s27, s11
	s_ashr_i32 s37, s36, 31
	s_lshl_b64 s[12:13], s[36:37], 2
	v_add_u32_e32 v32, s22, v64
	s_add_u32 s12, s18, s12
	s_addc_u32 s13, s17, s13
	v_lshlrev_b32_e32 v172, 2, v72
	v_ashrrev_i32_e32 v33, 31, v32
	v_lshl_add_u64 v[34:35], s[12:13], 0, v[172:173]
	v_lshlrev_b64 v[0:1], 13, v[32:33]
	v_lshl_add_u64 v[24:25], v[34:35], 0, v[0:1]
	v_add_co_u32_e32 v4, vcc, s89, v24
	s_movk_i32 s13, 0x4000
	s_nop 0
	v_addc_co_u32_e32 v5, vcc, 0, v25, vcc
	v_add_co_u32_e32 v8, vcc, s13, v24
	s_movk_i32 s12, 0x6000
	s_nop 0
	v_addc_co_u32_e32 v9, vcc, 0, v25, vcc
	v_add_co_u32_e32 v12, vcc, s12, v24
	s_mov_b32 s16, 0x8000
	s_nop 0
	v_addc_co_u32_e32 v13, vcc, 0, v25, vcc
	v_add_co_u32_e32 v16, vcc, s16, v24
	v_add_u32_e32 v32, 32, v32
	s_nop 0
	v_addc_co_u32_e32 v17, vcc, 0, v25, vcc
	v_add_co_u32_e32 v20, vcc, s33, v24
	s_mov_b32 s17, 0xe000
	s_nop 0
	v_addc_co_u32_e32 v21, vcc, 0, v25, vcc
	v_add_co_u32_e32 v26, vcc, s38, v24
	v_ashrrev_i32_e32 v33, 31, v32
	s_nop 0
	v_addc_co_u32_e32 v27, vcc, 0, v25, vcc
	v_add_co_u32_e32 v28, vcc, s17, v24
	v_lshlrev_b64 v[32:33], 13, v[32:33]
	s_nop 0
	v_addc_co_u32_e32 v29, vcc, 0, v25, vcc
	v_lshl_add_u64 v[56:57], v[34:35], 0, v[32:33]
	v_add_co_u32_e32 v36, vcc, s89, v56
	global_load_dwordx4 v[0:3], v[24:25], off nt
	s_nop 0
	global_load_dwordx4 v[4:7], v[4:5], off nt
	v_addc_co_u32_e32 v37, vcc, 0, v57, vcc
	v_add_co_u32_e32 v40, vcc, s13, v56
	global_load_dwordx4 v[8:11], v[8:9], off nt
	s_nop 0
	global_load_dwordx4 v[12:15], v[12:13], off nt
	v_addc_co_u32_e32 v41, vcc, 0, v57, vcc
	v_add_co_u32_e32 v44, vcc, s12, v56
	global_load_dwordx4 v[16:19], v[16:17], off nt
	s_nop 0
	global_load_dwordx4 v[20:23], v[20:21], off nt
	v_addc_co_u32_e32 v45, vcc, 0, v57, vcc
	v_add_co_u32_e32 v48, vcc, s16, v56
	global_load_dwordx4 v[24:27], v[26:27], off nt
	s_nop 0
	global_load_dwordx4 v[28:31], v[28:29], off nt
	v_addc_co_u32_e32 v49, vcc, 0, v57, vcc
	v_add_co_u32_e32 v52, vcc, s33, v56
	global_load_dwordx4 v[32:35], v[56:57], off nt
	s_nop 0
	global_load_dwordx4 v[36:39], v[36:37], off nt
	v_addc_co_u32_e32 v53, vcc, 0, v57, vcc
	v_add_co_u32_e32 v58, vcc, s38, v56
	global_load_dwordx4 v[40:43], v[40:41], off nt
	s_nop 0
	global_load_dwordx4 v[44:47], v[44:45], off nt
	v_addc_co_u32_e32 v59, vcc, 0, v57, vcc
	v_add_co_u32_e32 v60, vcc, s17, v56
	global_load_dwordx4 v[48:51], v[48:49], off nt
	s_nop 0
	global_load_dwordx4 v[52:55], v[52:53], off nt
	v_addc_co_u32_e32 v61, vcc, 0, v57, vcc
	global_load_dwordx4 v[56:59], v[58:59], off nt
	s_nop 0
	global_load_dwordx4 v[60:63], v[60:61], off nt
	s_ashr_i32 s23, s22, 31
	s_lshl_b64 s[12:13], s[22:23], 1
	s_add_u32 s12, s15, s12
	v_or_b32_e32 v73, s36, v72
	s_addc_u32 s13, s11, s13
	s_movk_i32 s11, 0xa00
	v_mul_lo_u32 v74, v73, s11
	v_lshl_add_u64 v[70:71], v[64:65], 1, s[12:13]
	v_ashrrev_i32_e32 v75, 31, v74
	v_lshl_add_u64 v[70:71], v[74:75], 1, v[70:71]
	s_mov_b32 s11, 0x25d00000
	v_add_co_u32_e32 v76, vcc, s11, v70
	s_mov_b32 s11, 0x25d01000
	s_nop 0
	v_addc_co_u32_e32 v77, vcc, 0, v71, vcc
	s_waitcnt vmcnt(14)
	v_cvt_pk_bf16_f32 v66, v0, v4
	v_add_co_u32_e32 v4, vcc, s11, v70
	s_waitcnt vmcnt(12)
	v_cvt_pk_bf16_f32 v67, v8, v12
	s_waitcnt vmcnt(10)
	v_cvt_pk_bf16_f32 v68, v16, v20
	s_waitcnt vmcnt(8)
	v_cvt_pk_bf16_f32 v69, v24, v28
	global_store_dwordx4 v[76:77], v[66:69], off sc1
	s_mov_b32 s11, 0x25d02000
	s_mov_b64 s[12:13], 0x25d00000
	v_cvt_pk_bf16_f32 v66, v1, v5
	v_addc_co_u32_e32 v5, vcc, 0, v71, vcc
	v_add_co_u32_e32 v8, vcc, s11, v70
	v_cvt_pk_bf16_f32 v67, v9, v13
	s_mov_b32 s11, 0x25d03000
	s_nop 0
	v_addc_co_u32_e32 v9, vcc, 0, v71, vcc
	v_cvt_pk_bf16_f32 v68, v17, v21
	v_cvt_pk_bf16_f32 v69, v25, v29
	global_store_dwordx4 v[4:5], v[66:69], off offset:1024 sc1
	v_lshl_add_u64 v[74:75], v[70:71], 0, s[12:13]
	s_mov_b64 s[22:23], 0
	v_cvt_pk_bf16_f32 v66, v2, v6
	v_add_co_u32_e32 v6, vcc, s11, v70
	v_cvt_pk_bf16_f32 v67, v10, v14
	v_cvt_pk_bf16_f32 v68, v18, v22
	v_cvt_pk_bf16_f32 v69, v26, v30
	global_store_dwordx4 v[8:9], v[66:69], off offset:2048 sc1
	v_cvt_pk_bf16_f32 v0, v3, v7
	v_cvt_pk_bf16_f32 v1, v11, v15
	v_cvt_pk_bf16_f32 v2, v19, v23
	v_cvt_pk_bf16_f32 v3, v27, v31
	s_nop 0
	v_addc_co_u32_e32 v7, vcc, 0, v71, vcc
	global_store_dwordx4 v[6:7], v[0:3], off offset:3072 sc1
	s_waitcnt vmcnt(10)
	s_nop 0
	v_cvt_pk_bf16_f32 v0, v32, v36
	s_waitcnt vmcnt(8)
	v_cvt_pk_bf16_f32 v1, v40, v44
	s_waitcnt vmcnt(6)
	v_cvt_pk_bf16_f32 v2, v48, v52
	s_waitcnt vmcnt(4)
	v_cvt_pk_bf16_f32 v3, v56, v60
	global_store_dwordx4 v[74:75], v[0:3], off offset:64 sc1
	s_nop 1
	v_cvt_pk_bf16_f32 v0, v33, v37
	v_cvt_pk_bf16_f32 v1, v41, v45
	v_cvt_pk_bf16_f32 v2, v49, v53
	v_cvt_pk_bf16_f32 v3, v57, v61
	global_store_dwordx4 v[4:5], v[0:3], off offset:1088 sc1
	s_nop 1
	v_cvt_pk_bf16_f32 v0, v34, v38
	v_cvt_pk_bf16_f32 v1, v42, v46
	v_cvt_pk_bf16_f32 v2, v50, v54
	v_cvt_pk_bf16_f32 v3, v58, v62
	global_store_dwordx4 v[8:9], v[0:3], off offset:2112 sc1
	s_nop 1
	v_cvt_pk_bf16_f32 v0, v35, v39
	v_cvt_pk_bf16_f32 v1, v43, v47
	v_cvt_pk_bf16_f32 v2, v51, v55
	v_cvt_pk_bf16_f32 v3, v59, v63
	global_store_dwordx4 v[6:7], v[0:3], off offset:3136 sc1
; __device__ __forceinline__ unsigned cvt_pk_bf16(float lo, float hi) { unsigned r; asm volatile("v_cvt_pk_bf16_f32 %0, %1, %2" : "=v"(r) : "v"(lo), "v"(hi)); return r; }
; #define INP(i) ((const float*)(const GASP float*)kargs()[(i)])
; __device__ __forceinline__ void tr_item(const float* W, int ldw, int k0, int n0, bf16* WT, int ldk, int drow0, int lane) {
;     const int n4 = (lane & 15) * 4, kg = lane >> 4; f32x4 v[2][8];
; #pragma unroll
;     for (int kh = 0; kh < 2; ++kh) { const float* src = W + (size_t)(k0 + kh * 32 + kg * 8) * ldw + n0 + n4;
; #pragma unroll
;         for (int i = 0; i < 8; ++i) v[kh][i] = __builtin_nontemporal_load((const f32x4*)(src + (size_t)i * ldw)); }
; #pragma unroll
;     for (int kh = 0; kh < 2; ++kh)
; #pragma unroll
;         for (int e = 0; e < 4; ++e) { u32x4 o; o.x = cvt_pk_bf16(v[kh][0][e], v[kh][1][e]); o.y = cvt_pk_bf16(v[kh][2][e], v[kh][3][e]); o.z = cvt_pk_bf16(v[kh][4][e], v[kh][5][e]); o.w = cvt_pk_bf16(v[kh][6][e], v[kh][7][e]);
;             *(u32x4*)(WT + (size_t)(drow0 + n4 + e) * ldk + k0 + kh * 32 + kg * 8) = o; }
; }
; __device__ __forceinline__ void conv_item(int it, int lane) {
;     ...
;     if (r < 2 * IT_INC) { const int idx = r / IT_INC; r -= idx * IT_INC; const int kb = r / 80, nb = r % 80;
;         tr_item(INP(I_WINC) + (size_t)idx * 2048 * 5120, 5120, 64 * kb, 64 * nb, (bf16*)(ws + WS_WINC) + (size_t)idx * 5120 * 2048, 2048, 64 * nb, lane); return; }
.LBB0_2125:
	s_andn2_b64 vcc, exec, s[22:23]
	s_cbranch_vccnz .LBB0_2127
	s_add_i32 s11, s6, 0xfffee600
	s_cmpk_gt_u32 s11, 0x9ff
	s_cselect_b64 s[12:13], -1, 0
	s_and_b64 s[16:17], s[12:13], exec
	s_cselect_b32 s15, 0xf600, 0
	s_add_i32 s15, s15, s11
	s_sext_i32_i16 s11, s15
	s_mulk_i32 s11, 0x6667
	s_lshr_b32 s16, s11, 31
	s_ashr_i32 s11, s11, 21
	s_add_i32 s11, s11, s16
	s_mov_b64 s[16:17], s[0:1]
	s_load_dwordx2 s[16:17], s[16:17], 0xe8
	s_mul_i32 s18, s11, 0x50
	s_sub_i32 s15, s15, s18
	s_and_b64 s[18:19], s[12:13], exec
	s_cselect_b32 s18, 0x2800000, 0
	s_sext_i32_i16 s15, s15
	s_waitcnt lgkmcnt(0)
	s_add_u32 s16, s16, s18
	s_addc_u32 s17, s17, 0
	s_lshl_b32 s22, s11, 6
	s_lshl_b32 s36, s15, 6
	s_and_b64 s[12:13], s[12:13], exec
	s_cselect_b32 s11, 0x1400000, 0
	s_add_u32 s11, s26, s11
	s_addc_u32 s15, s27, 0
	s_ashr_i32 s37, s36, 31
	s_lshl_b64 s[12:13], s[36:37], 2
	s_add_u32 s12, s16, s12
	s_addc_u32 s13, s17, s13
	v_lshlrev_b32_e32 v172, 2, v72
	v_add_u32_e32 v34, s22, v64
	v_lshl_add_u64 v[32:33], s[12:13], 0, v[172:173]
	s_movk_i32 s18, 0x5000
	v_mad_i64_i32 v[24:25], s[12:13], v34, s18, v[32:33]
	v_add_co_u32_e32 v4, vcc, s18, v24
	s_mov_b32 s16, 0x14000
	s_nop 0
	v_addc_co_u32_e32 v5, vcc, 0, v25, vcc
	v_add_co_u32_e32 v8, vcc, s33, v24
	s_mov_b32 s19, 0x19000
	s_nop 0
	v_addc_co_u32_e32 v9, vcc, 0, v25, vcc
	v_add_co_u32_e32 v12, vcc, s76, v24
	s_mov_b32 s17, 0x1e000
	s_nop 0
	v_addc_co_u32_e32 v13, vcc, 0, v25, vcc
	v_add_co_u32_e32 v16, vcc, s16, v24
	v_add_u32_e32 v34, 32, v34
	s_nop 0
	v_addc_co_u32_e32 v17, vcc, 0, v25, vcc
	v_add_co_u32_e32 v20, vcc, s19, v24
	v_mad_i64_i32 v[56:57], s[12:13], v34, s18, v[32:33]
	s_nop 0
	v_addc_co_u32_e32 v21, vcc, 0, v25, vcc
	v_add_co_u32_e32 v26, vcc, s17, v24
	global_load_dwordx4 v[0:3], v[24:25], off nt
	s_nop 0
	global_load_dwordx4 v[4:7], v[4:5], off nt
	v_addc_co_u32_e32 v27, vcc, 0, v25, vcc
	v_add_co_u32_e32 v28, vcc, s77, v24
	global_load_dwordx4 v[8:11], v[8:9], off nt
	s_nop 0
	global_load_dwordx4 v[12:15], v[12:13], off nt
	v_addc_co_u32_e32 v29, vcc, 0, v25, vcc
	v_add_co_u32_e32 v36, vcc, s18, v56
	global_load_dwordx4 v[16:19], v[16:17], off nt
	s_nop 0
	global_load_dwordx4 v[20:23], v[20:21], off nt
	v_addc_co_u32_e32 v37, vcc, 0, v57, vcc
	v_add_co_u32_e32 v40, vcc, s33, v56
	global_load_dwordx4 v[24:27], v[26:27], off nt
	s_nop 0
	global_load_dwordx4 v[28:31], v[28:29], off nt
	v_addc_co_u32_e32 v41, vcc, 0, v57, vcc
	v_add_co_u32_e32 v44, vcc, s76, v56
	global_load_dwordx4 v[32:35], v[56:57], off nt
	s_nop 0
	global_load_dwordx4 v[36:39], v[36:37], off nt
	v_addc_co_u32_e32 v45, vcc, 0, v57, vcc
	v_add_co_u32_e32 v48, vcc, s16, v56
	global_load_dwordx4 v[40:43], v[40:41], off nt
	s_nop 0
	global_load_dwordx4 v[44:47], v[44:45], off nt
	v_addc_co_u32_e32 v49, vcc, 0, v57, vcc
	v_add_co_u32_e32 v52, vcc, s19, v56
	s_ashr_i32 s23, s22, 31
	s_nop 0
	v_addc_co_u32_e32 v53, vcc, 0, v57, vcc
	v_add_co_u32_e32 v58, vcc, s17, v56
	global_load_dwordx4 v[48:51], v[48:49], off nt
	s_nop 0
	global_load_dwordx4 v[52:55], v[52:53], off nt
	v_addc_co_u32_e32 v59, vcc, 0, v57, vcc
	v_add_co_u32_e32 v60, vcc, s77, v56
	s_lshl_b64 s[12:13], s[22:23], 1
	s_nop 0
	v_addc_co_u32_e32 v61, vcc, 0, v57, vcc
	global_load_dwordx4 v[56:59], v[58:59], off nt
	s_nop 0
	global_load_dwordx4 v[60:63], v[60:61], off nt
	s_add_u32 s12, s11, s12
	v_or_b32_e32 v70, s36, v72
	s_addc_u32 s13, s15, s13
	v_lshl_add_u64 v[66:67], v[64:65], 1, s[12:13]
	s_mov_b64 s[12:13], 0x23500000
	v_ashrrev_i32_e32 v71, 31, v70
	v_lshl_add_u64 v[74:75], v[66:67], 0, s[12:13]
	v_lshlrev_b64 v[76:77], 12, v[70:71]
	s_waitcnt vmcnt(14)
	v_cvt_pk_bf16_f32 v66, v0, v4
	v_lshl_add_u64 v[76:77], v[74:75], 0, v[76:77]
	v_or_b32_e32 v0, 1, v70
	s_waitcnt vmcnt(12)
	v_cvt_pk_bf16_f32 v67, v8, v12
	s_waitcnt vmcnt(10)
	v_cvt_pk_bf16_f32 v68, v16, v20
	s_waitcnt vmcnt(8)
	v_cvt_pk_bf16_f32 v69, v24, v28
	global_store_dwordx4 v[76:77], v[66:69], off sc1
	s_nop 1
	v_cvt_pk_bf16_f32 v66, v1, v5
	v_ashrrev_i32_e32 v1, 31, v0
	v_lshlrev_b64 v[0:1], 12, v[0:1]
	v_lshl_add_u64 v[4:5], v[74:75], 0, v[0:1]
	v_or_b32_e32 v0, 2, v70
	v_ashrrev_i32_e32 v1, 31, v0
	v_lshlrev_b64 v[0:1], 12, v[0:1]
	v_cvt_pk_bf16_f32 v67, v9, v13
	v_cvt_pk_bf16_f32 v68, v17, v21
	v_cvt_pk_bf16_f32 v69, v25, v29
	global_store_dwordx4 v[4:5], v[66:69], off sc1
	v_lshl_add_u64 v[8:9], v[74:75], 0, v[0:1]
	s_nop 0
	v_cvt_pk_bf16_f32 v66, v2, v6
	v_or_b32_e32 v6, 3, v70
	v_cvt_pk_bf16_f32 v67, v10, v14
	v_cvt_pk_bf16_f32 v68, v18, v22
	v_cvt_pk_bf16_f32 v69, v26, v30
	global_store_dwordx4 v[8:9], v[66:69], off sc1
	v_cvt_pk_bf16_f32 v0, v3, v7
	v_ashrrev_i32_e32 v7, 31, v6
	v_lshlrev_b64 v[6:7], 12, v[6:7]
	v_cvt_pk_bf16_f32 v1, v11, v15
	v_cvt_pk_bf16_f32 v2, v19, v23
	v_cvt_pk_bf16_f32 v3, v27, v31
	v_lshl_add_u64 v[6:7], v[74:75], 0, v[6:7]
	global_store_dwordx4 v[6:7], v[0:3], off sc1
	s_waitcnt vmcnt(10)
	s_nop 0
	v_cvt_pk_bf16_f32 v0, v32, v36
	s_waitcnt vmcnt(8)
	v_cvt_pk_bf16_f32 v1, v40, v44
	s_waitcnt vmcnt(6)
	v_cvt_pk_bf16_f32 v2, v48, v52
	s_waitcnt vmcnt(4)
	v_cvt_pk_bf16_f32 v3, v56, v60
	global_store_dwordx4 v[76:77], v[0:3], off offset:64 sc1
	s_nop 1
	v_cvt_pk_bf16_f32 v0, v33, v37
	v_cvt_pk_bf16_f32 v1, v41, v45
	v_cvt_pk_bf16_f32 v2, v49, v53
	v_cvt_pk_bf16_f32 v3, v57, v61
	global_store_dwordx4 v[4:5], v[0:3], off offset:64 sc1
	s_nop 1
	v_cvt_pk_bf16_f32 v0, v34, v38
	v_cvt_pk_bf16_f32 v1, v42, v46
	v_cvt_pk_bf16_f32 v2, v50, v54
	v_cvt_pk_bf16_f32 v3, v58, v62
	global_store_dwordx4 v[8:9], v[0:3], off offset:64 sc1
	s_nop 1
	v_cvt_pk_bf16_f32 v0, v35, v39
	v_cvt_pk_bf16_f32 v1, v43, v47
	v_cvt_pk_bf16_f32 v2, v51, v55
	v_cvt_pk_bf16_f32 v3, v59, v63
	global_store_dwordx4 v[6:7], v[0:3], off offset:64 sc1

; __device__ __forceinline__ unsigned cvt_pk_bf16(float lo, float hi) { unsigned r; asm volatile("v_cvt_pk_bf16_f32 %0, %1, %2" : "=v"(r) : "v"(lo), "v"(hi)); return r; }
; #define INP(i) ((const float*)(const GASP float*)kargs()[(i)])
; __device__ __forceinline__ void tr_item(const float* W, int ldw, int k0, int n0, bf16* WT, int ldk, int drow0, int lane) {
;     const int n4 = (lane & 15) * 4, kg = lane >> 4; f32x4 v[2][8];
; #pragma unroll
;     for (int kh = 0; kh < 2; ++kh) { const float* src = W + (size_t)(k0 + kh * 32 + kg * 8) * ldw + n0 + n4;
; #pragma unroll
;         for (int i = 0; i < 8; ++i) v[kh][i] = __builtin_nontemporal_load((const f32x4*)(src + (size_t)i * ldw)); }
; #pragma unroll
;     for (int kh = 0; kh < 2; ++kh)
; #pragma unroll
;         for (int e = 0; e < 4; ++e) { u32x4 o; o.x = cvt_pk_bf16(v[kh][0][e], v[kh][1][e]); o.y = cvt_pk_bf16(v[kh][2][e], v[kh][3][e]); o.z = cvt_pk_bf16(v[kh][4][e], v[kh][5][e]); o.w = cvt_pk_bf16(v[kh][6][e], v[kh][7][e]);
;             *(u32x4*)(WT + (size_t)(drow0 + n4 + e) * ldk + k0 + kh * 32 + kg * 8) = o; }
; }
; __device__ __forceinline__ void conv_item(int it, int lane) {
;     ...
;     if (r < 2 * IT_INAB) { const int idx = r / IT_INAB; r -= idx * IT_INAB; const int kb = r / 80, nb = r % 80;
;         tr_item(INP(I_WINAB) + (size_t)idx * 2048 * 5120, 5120, 64 * kb, 64 * nb, (bf16*)(ws + WS_WINAB) + (size_t)idx * 5120 * 2048, 2048, 64 * nb, lane); return; }
.LBB0_2134:
	s_andn2_b64 vcc, exec, s[22:23]
	s_cbranch_vccnz .LBB0_2136
	s_add_i32 s11, s6, 0xffff0400
	s_cmpk_gt_u32 s11, 0x9ff
	s_cselect_b64 s[12:13], -1, 0
	s_and_b64 s[16:17], s[12:13], exec
	s_cselect_b32 s15, 0xf600, 0
	s_add_i32 s15, s15, s11
	s_sext_i32_i16 s11, s15
	s_mulk_i32 s11, 0x6667
	s_lshr_b32 s16, s11, 31
	s_ashr_i32 s11, s11, 21
	s_add_i32 s11, s11, s16
	s_mov_b64 s[16:17], s[0:1]
	s_load_dwordx2 s[16:17], s[16:17], 0x78
	s_mul_i32 s18, s11, 0x50
	s_sub_i32 s15, s15, s18
	s_and_b64 s[18:19], s[12:13], exec
	s_cselect_b32 s18, 0x2800000, 0
	s_sext_i32_i16 s15, s15
	s_waitcnt lgkmcnt(0)
	s_add_u32 s16, s16, s18
	s_addc_u32 s17, s17, 0
	s_lshl_b32 s22, s11, 6
	s_lshl_b32 s36, s15, 6
	s_and_b64 s[12:13], s[12:13], exec
	s_cselect_b32 s11, 0x1400000, 0
	s_add_u32 s11, s26, s11
	s_addc_u32 s15, s27, 0
	s_ashr_i32 s37, s36, 31
	s_lshl_b64 s[12:13], s[36:37], 2
	s_add_u32 s12, s16, s12
	s_addc_u32 s13, s17, s13
	v_lshlrev_b32_e32 v172, 2, v72
	v_add_u32_e32 v34, s22, v64
	v_lshl_add_u64 v[32:33], s[12:13], 0, v[172:173]
	s_movk_i32 s18, 0x5000
	v_mad_i64_i32 v[24:25], s[12:13], v34, s18, v[32:33]
	v_add_co_u32_e32 v4, vcc, s18, v24
	s_mov_b32 s16, 0x14000
	s_nop 0
	v_addc_co_u32_e32 v5, vcc, 0, v25, vcc
	v_add_co_u32_e32 v8, vcc, s33, v24
	s_mov_b32 s19, 0x19000
	s_nop 0
	v_addc_co_u32_e32 v9, vcc, 0, v25, vcc
	v_add_co_u32_e32 v12, vcc, s76, v24
	s_mov_b32 s17, 0x1e000
	s_nop 0
	v_addc_co_u32_e32 v13, vcc, 0, v25, vcc
	v_add_co_u32_e32 v16, vcc, s16, v24
	v_add_u32_e32 v34, 32, v34
	s_nop 0
	v_addc_co_u32_e32 v17, vcc, 0, v25, vcc
	v_add_co_u32_e32 v20, vcc, s19, v24
	v_mad_i64_i32 v[56:57], s[12:13], v34, s18, v[32:33]
	s_nop 0
	v_addc_co_u32_e32 v21, vcc, 0, v25, vcc
	v_add_co_u32_e32 v26, vcc, s17, v24
	global_load_dwordx4 v[0:3], v[24:25], off nt
	s_nop 0
	global_load_dwordx4 v[4:7], v[4:5], off nt
	v_addc_co_u32_e32 v27, vcc, 0, v25, vcc
	v_add_co_u32_e32 v28, vcc, s77, v24
	global_load_dwordx4 v[8:11], v[8:9], off nt
	s_nop 0
	global_load_dwordx4 v[12:15], v[12:13], off nt
	v_addc_co_u32_e32 v29, vcc, 0, v25, vcc
	v_add_co_u32_e32 v36, vcc, s18, v56
	global_load_dwordx4 v[16:19], v[16:17], off nt
	s_nop 0
	global_load_dwordx4 v[20:23], v[20:21], off nt
	v_addc_co_u32_e32 v37, vcc, 0, v57, vcc
	v_add_co_u32_e32 v40, vcc, s33, v56
	global_load_dwordx4 v[24:27], v[26:27], off nt
	s_nop 0
	global_load_dwordx4 v[28:31], v[28:29], off nt
	v_addc_co_u32_e32 v41, vcc, 0, v57, vcc
	v_add_co_u32_e32 v44, vcc, s76, v56
	global_load_dwordx4 v[32:35], v[56:57], off nt
	s_nop 0
	global_load_dwordx4 v[36:39], v[36:37], off nt
	v_addc_co_u32_e32 v45, vcc, 0, v57, vcc
	v_add_co_u32_e32 v48, vcc, s16, v56
	global_load_dwordx4 v[40:43], v[40:41], off nt
	s_nop 0
	global_load_dwordx4 v[44:47], v[44:45], off nt
	v_addc_co_u32_e32 v49, vcc, 0, v57, vcc
	v_add_co_u32_e32 v52, vcc, s19, v56
	s_ashr_i32 s23, s22, 31
	s_nop 0
	v_addc_co_u32_e32 v53, vcc, 0, v57, vcc
	v_add_co_u32_e32 v58, vcc, s17, v56
	global_load_dwordx4 v[48:51], v[48:49], off nt
	s_nop 0
	global_load_dwordx4 v[52:55], v[52:53], off nt
	v_addc_co_u32_e32 v59, vcc, 0, v57, vcc
	v_add_co_u32_e32 v60, vcc, s77, v56
	s_lshl_b64 s[12:13], s[22:23], 1
	s_nop 0
	v_addc_co_u32_e32 v61, vcc, 0, v57, vcc
	global_load_dwordx4 v[56:59], v[58:59], off nt
	s_nop 0
	global_load_dwordx4 v[60:63], v[60:61], off nt
	s_add_u32 s12, s11, s12
	v_or_b32_e32 v70, s36, v72
	s_addc_u32 s13, s15, s13
	v_lshl_add_u64 v[66:67], v[64:65], 1, s[12:13]
	s_mov_b64 s[12:13], 0x1f900000
	v_ashrrev_i32_e32 v71, 31, v70
	v_lshl_add_u64 v[74:75], v[66:67], 0, s[12:13]
	v_lshlrev_b64 v[76:77], 12, v[70:71]
	s_waitcnt vmcnt(14)
	v_cvt_pk_bf16_f32 v66, v0, v4
	v_lshl_add_u64 v[76:77], v[74:75], 0, v[76:77]
	v_or_b32_e32 v0, 1, v70
	s_waitcnt vmcnt(12)
	v_cvt_pk_bf16_f32 v67, v8, v12
	s_waitcnt vmcnt(10)
	v_cvt_pk_bf16_f32 v68, v16, v20
	s_waitcnt vmcnt(8)
	v_cvt_pk_bf16_f32 v69, v24, v28
	global_store_dwordx4 v[76:77], v[66:69], off sc1
	s_nop 1
	v_cvt_pk_bf16_f32 v66, v1, v5
	v_ashrrev_i32_e32 v1, 31, v0
	v_lshlrev_b64 v[0:1], 12, v[0:1]
	v_lshl_add_u64 v[4:5], v[74:75], 0, v[0:1]
	v_or_b32_e32 v0, 2, v70
	v_ashrrev_i32_e32 v1, 31, v0
	v_lshlrev_b64 v[0:1], 12, v[0:1]
	v_cvt_pk_bf16_f32 v67, v9, v13
	v_cvt_pk_bf16_f32 v68, v17, v21
	v_cvt_pk_bf16_f32 v69, v25, v29
	global_store_dwordx4 v[4:5], v[66:69], off sc1
	v_lshl_add_u64 v[8:9], v[74:75], 0, v[0:1]
	s_nop 0
	v_cvt_pk_bf16_f32 v66, v2, v6
	v_or_b32_e32 v6, 3, v70
	v_cvt_pk_bf16_f32 v67, v10, v14
	v_cvt_pk_bf16_f32 v68, v18, v22
	v_cvt_pk_bf16_f32 v69, v26, v30
	global_store_dwordx4 v[8:9], v[66:69], off sc1
	v_cvt_pk_bf16_f32 v0, v3, v7
	v_ashrrev_i32_e32 v7, 31, v6
	v_lshlrev_b64 v[6:7], 12, v[6:7]
	v_cvt_pk_bf16_f32 v1, v11, v15
	v_cvt_pk_bf16_f32 v2, v19, v23
	v_cvt_pk_bf16_f32 v3, v27, v31
	v_lshl_add_u64 v[6:7], v[74:75], 0, v[6:7]
	global_store_dwordx4 v[6:7], v[0:3], off sc1
	s_waitcnt vmcnt(10)
	s_nop 0
	v_cvt_pk_bf16_f32 v0, v32, v36
	s_waitcnt vmcnt(8)
	v_cvt_pk_bf16_f32 v1, v40, v44
	s_waitcnt vmcnt(6)
	v_cvt_pk_bf16_f32 v2, v48, v52
	s_waitcnt vmcnt(4)
	v_cvt_pk_bf16_f32 v3, v56, v60
	global_store_dwordx4 v[76:77], v[0:3], off offset:64 sc1
	s_nop 1
	v_cvt_pk_bf16_f32 v0, v33, v37
	v_cvt_pk_bf16_f32 v1, v41, v45
	v_cvt_pk_bf16_f32 v2, v49, v53
	v_cvt_pk_bf16_f32 v3, v57, v61
	global_store_dwordx4 v[4:5], v[0:3], off offset:64 sc1
	s_nop 1
	v_cvt_pk_bf16_f32 v0, v34, v38
	v_cvt_pk_bf16_f32 v1, v42, v46
	v_cvt_pk_bf16_f32 v2, v50, v54
	v_cvt_pk_bf16_f32 v3, v58, v62
	global_store_dwordx4 v[8:9], v[0:3], off offset:64 sc1
	s_nop 1
	v_cvt_pk_bf16_f32 v0, v35, v39
	v_cvt_pk_bf16_f32 v1, v43, v47
	v_cvt_pk_bf16_f32 v2, v51, v55
	v_cvt_pk_bf16_f32 v3, v59, v63
	global_store_dwordx4 v[6:7], v[0:3], off offset:64 sc1

; __device__ __forceinline__ unsigned cvt_pk_bf16(float lo, float hi) { unsigned r; asm volatile("v_cvt_pk_bf16_f32 %0, %1, %2" : "=v"(r) : "v"(lo), "v"(hi)); return r; }
; #define INP(i) ((const float*)(const GASP float*)kargs()[(i)])
; __device__ __forceinline__ void tr_item(const float* W, int ldw, int k0, int n0, bf16* WT, int ldk, int drow0, int lane) {
;     const int n4 = (lane & 15) * 4, kg = lane >> 4; f32x4 v[2][8];
; #pragma unroll
;     for (int kh = 0; kh < 2; ++kh) { const float* src = W + (size_t)(k0 + kh * 32 + kg * 8) * ldw + n0 + n4;
; #pragma unroll
;         for (int i = 0; i < 8; ++i) v[kh][i] = __builtin_nontemporal_load((const f32x4*)(src + (size_t)i * ldw)); }
; #pragma unroll
;     for (int kh = 0; kh < 2; ++kh)
; #pragma unroll
;         for (int e = 0; e < 4; ++e) { u32x4 o; o.x = cvt_pk_bf16(v[kh][0][e], v[kh][1][e]); o.y = cvt_pk_bf16(v[kh][2][e], v[kh][3][e]); o.z = cvt_pk_bf16(v[kh][4][e], v[kh][5][e]); o.w = cvt_pk_bf16(v[kh][6][e], v[kh][7][e]);
;             *(u32x4*)(WT + (size_t)(drow0 + n4 + e) * ldk + k0 + kh * 32 + kg * 8) = o; }
; }
; __device__ __forceinline__ void conv_item(int it, int lane) {
;     ...
;     if (r < 8 * IT_D) { const int idx = r / IT_D; r -= idx * IT_D; const int kb = r / 32, nb = r % 32;
;         tr_item(INP(I_WD) + (size_t)idx * 5376 * 2048, 2048, 64 * kb, 64 * nb, (bf16*)(ws + WS_WD) + (size_t)idx * 2048 * 5376, 5376, 64 * nb, lane); return; }
.LBB0_2137:
	s_andn2_b64 vcc, exec, s[22:23]
	s_cbranch_vccnz .LBB0_2139
	s_add_i32 s11, s6, 0xffff5800
	s_bfe_u32 s12, s11, 0x100007
	s_mulk_i32 s12, 0xc31
	s_lshr_b32 s15, s12, 16
	s_mul_i32 s12, s15, 0xf580
	s_add_i32 s11, s12, s11
	s_sext_i32_i16 s12, s11
	s_bfe_u32 s12, s12, 0x5001a
	s_add_i32 s16, s11, s12
	s_mov_b64 s[12:13], s[0:1]
	s_load_dwordx2 s[12:13], s[12:13], 0x70
	s_sext_i32_i16 s17, s16
	s_and_b32 s16, s16, 0xffe0
	s_sub_i32 s11, s11, s16
	s_mul_i32 s16, s15, 0x2a00000
	s_waitcnt lgkmcnt(0)
	s_add_u32 s16, s12, s16
	s_sext_i32_i16 s11, s11
	s_addc_u32 s18, s13, 0
	s_lshl_b32 s12, s17, 1
	s_and_b32 s22, s12, 0xffffffc0
	s_lshl_b32 s36, s11, 6
	s_mul_i32 s15, s15, 0x1500000
	s_add_u32 s11, s26, s15
	s_addc_u32 s15, s27, 0
	s_ashr_i32 s37, s36, 31
	s_lshl_b64 s[12:13], s[36:37], 2
	v_add_u32_e32 v32, s22, v64
	s_add_u32 s12, s16, s12
	s_addc_u32 s13, s18, s13
	v_lshlrev_b32_e32 v172, 2, v72
	v_ashrrev_i32_e32 v33, 31, v32
	v_lshl_add_u64 v[34:35], s[12:13], 0, v[172:173]
	v_lshlrev_b64 v[0:1], 13, v[32:33]
	v_lshl_add_u64 v[24:25], v[34:35], 0, v[0:1]
	v_add_co_u32_e32 v4, vcc, s89, v24
	s_movk_i32 s13, 0x4000
	s_nop 0
	v_addc_co_u32_e32 v5, vcc, 0, v25, vcc
	v_add_co_u32_e32 v8, vcc, s13, v24
	s_movk_i32 s12, 0x6000
	s_nop 0
	v_addc_co_u32_e32 v9, vcc, 0, v25, vcc
	v_add_co_u32_e32 v12, vcc, s12, v24
	s_mov_b32 s16, 0x8000
	s_nop 0
	v_addc_co_u32_e32 v13, vcc, 0, v25, vcc
	v_add_co_u32_e32 v16, vcc, s16, v24
	v_add_u32_e32 v32, 32, v32
	s_nop 0
	v_addc_co_u32_e32 v17, vcc, 0, v25, vcc
	v_add_co_u32_e32 v20, vcc, s33, v24
	s_mov_b32 s17, 0xe000
	s_nop 0
	v_addc_co_u32_e32 v21, vcc, 0, v25, vcc
	v_add_co_u32_e32 v26, vcc, s38, v24
	v_ashrrev_i32_e32 v33, 31, v32
	s_nop 0
	v_addc_co_u32_e32 v27, vcc, 0, v25, vcc
	v_add_co_u32_e32 v28, vcc, s17, v24
	v_lshlrev_b64 v[32:33], 13, v[32:33]
	s_nop 0
	v_addc_co_u32_e32 v29, vcc, 0, v25, vcc
	v_lshl_add_u64 v[56:57], v[34:35], 0, v[32:33]
	v_add_co_u32_e32 v36, vcc, s89, v56
	global_load_dwordx4 v[0:3], v[24:25], off nt
	s_nop 0
	global_load_dwordx4 v[4:7], v[4:5], off nt
	v_addc_co_u32_e32 v37, vcc, 0, v57, vcc
	v_add_co_u32_e32 v40, vcc, s13, v56
	global_load_dwordx4 v[8:11], v[8:9], off nt
	s_nop 0
	global_load_dwordx4 v[12:15], v[12:13], off nt
	v_addc_co_u32_e32 v41, vcc, 0, v57, vcc
	v_add_co_u32_e32 v44, vcc, s12, v56
	global_load_dwordx4 v[16:19], v[16:17], off nt
	s_nop 0
	global_load_dwordx4 v[20:23], v[20:21], off nt
	v_addc_co_u32_e32 v45, vcc, 0, v57, vcc
	v_add_co_u32_e32 v48, vcc, s16, v56
	global_load_dwordx4 v[24:27], v[26:27], off nt
	s_nop 0
	global_load_dwordx4 v[28:31], v[28:29], off nt
	v_addc_co_u32_e32 v49, vcc, 0, v57, vcc
	v_add_co_u32_e32 v52, vcc, s33, v56
	global_load_dwordx4 v[32:35], v[56:57], off nt
	s_nop 0
	global_load_dwordx4 v[36:39], v[36:37], off nt
	v_addc_co_u32_e32 v53, vcc, 0, v57, vcc
	v_add_co_u32_e32 v58, vcc, s38, v56
	global_load_dwordx4 v[40:43], v[40:41], off nt
	s_nop 0
	global_load_dwordx4 v[44:47], v[44:45], off nt
	v_addc_co_u32_e32 v59, vcc, 0, v57, vcc
	v_add_co_u32_e32 v60, vcc, s17, v56
	global_load_dwordx4 v[48:51], v[48:49], off nt
	s_nop 0
	global_load_dwordx4 v[52:55], v[52:53], off nt
	v_addc_co_u32_e32 v61, vcc, 0, v57, vcc
	global_load_dwordx4 v[56:59], v[58:59], off nt
	s_nop 0
	global_load_dwordx4 v[60:63], v[60:61], off nt
	s_ashr_i32 s23, s22, 31
	s_lshl_b64 s[12:13], s[22:23], 1
	v_or_b32_e32 v73, s36, v72
	s_add_u32 s12, s11, s12
	s_addc_u32 s13, s15, s13
	v_mul_i32_i24_e32 v74, 0x1500, v73
	v_lshl_add_u64 v[70:71], v[64:65], 1, s[12:13]
	v_ashrrev_i32_e32 v75, 31, v74
	v_lshl_add_u64 v[70:71], v[74:75], 1, v[70:71]
	s_mov_b32 s11, 0x15100000
	v_add_co_u32_e32 v76, vcc, s11, v70
	s_mov_b32 s11, 0x15102000
	s_nop 0
	v_addc_co_u32_e32 v77, vcc, 0, v71, vcc
	s_waitcnt vmcnt(14)
	v_cvt_pk_bf16_f32 v66, v0, v4
	v_add_co_u32_e32 v4, vcc, s11, v70
	s_waitcnt vmcnt(12)
	v_cvt_pk_bf16_f32 v67, v8, v12
	s_waitcnt vmcnt(10)
	v_cvt_pk_bf16_f32 v68, v16, v20
	s_waitcnt vmcnt(8)
	v_cvt_pk_bf16_f32 v69, v24, v28
	global_store_dwordx4 v[76:77], v[66:69], off sc1
	s_mov_b32 s11, 0x15105000
	s_mov_b64 s[12:13], 0x15100000
	v_cvt_pk_bf16_f32 v66, v1, v5
	v_addc_co_u32_e32 v5, vcc, 0, v71, vcc
	v_add_co_u32_e32 v8, vcc, s11, v70
	v_cvt_pk_bf16_f32 v67, v9, v13
	s_mov_b32 s11, 0x15107000
	s_nop 0
	v_addc_co_u32_e32 v9, vcc, 0, v71, vcc
	v_cvt_pk_bf16_f32 v68, v17, v21
	v_cvt_pk_bf16_f32 v69, v25, v29
	global_store_dwordx4 v[4:5], v[66:69], off offset:2560 sc1
	v_lshl_add_u64 v[74:75], v[70:71], 0, s[12:13]
	s_nop 0
	v_cvt_pk_bf16_f32 v66, v2, v6
	v_add_co_u32_e32 v6, vcc, s11, v70
	v_cvt_pk_bf16_f32 v67, v10, v14
	v_cvt_pk_bf16_f32 v68, v18, v22
	v_cvt_pk_bf16_f32 v69, v26, v30
	global_store_dwordx4 v[8:9], v[66:69], off offset:1024 sc1
	v_cvt_pk_bf16_f32 v0, v3, v7
	v_cvt_pk_bf16_f32 v1, v11, v15
	v_cvt_pk_bf16_f32 v2, v19, v23
	v_cvt_pk_bf16_f32 v3, v27, v31
	s_nop 0
	v_addc_co_u32_e32 v7, vcc, 0, v71, vcc
	global_store_dwordx4 v[6:7], v[0:3], off offset:3584 sc1
	s_waitcnt vmcnt(10)
	s_nop 0
	v_cvt_pk_bf16_f32 v0, v32, v36
	s_waitcnt vmcnt(8)
	v_cvt_pk_bf16_f32 v1, v40, v44
	s_waitcnt vmcnt(6)
	v_cvt_pk_bf16_f32 v2, v48, v52
	s_waitcnt vmcnt(4)
	v_cvt_pk_bf16_f32 v3, v56, v60
	global_store_dwordx4 v[74:75], v[0:3], off offset:64 sc1
	s_nop 1
	v_cvt_pk_bf16_f32 v0, v33, v37
	v_cvt_pk_bf16_f32 v1, v41, v45
	v_cvt_pk_bf16_f32 v2, v49, v53
	v_cvt_pk_bf16_f32 v3, v57, v61
	global_store_dwordx4 v[4:5], v[0:3], off offset:2624 sc1
	s_nop 1
	v_cvt_pk_bf16_f32 v0, v34, v38
	v_cvt_pk_bf16_f32 v1, v42, v46
	v_cvt_pk_bf16_f32 v2, v50, v54
	v_cvt_pk_bf16_f32 v3, v58, v62
	global_store_dwordx4 v[8:9], v[0:3], off offset:1088 sc1
	s_nop 1
	v_cvt_pk_bf16_f32 v0, v35, v39
	v_cvt_pk_bf16_f32 v1, v43, v47
	v_cvt_pk_bf16_f32 v2, v51, v55
	v_cvt_pk_bf16_f32 v3, v59, v63
	global_store_dwordx4 v[6:7], v[0:3], off offset:3648 sc1

; __device__ __forceinline__ void tr_item(const float* W, int ldw, int k0, int n0, bf16* WT, int ldk, int drow0, int lane) {
;     const int n4 = (lane & 15) * 4, kg = lane >> 4; f32x4 v[2][8];
; #pragma unroll
;     for (int kh = 0; kh < 2; ++kh) { const float* src = W + (size_t)(k0 + kh * 32 + kg * 8) * ldw + n0 + n4;
; #pragma unroll
;         for (int i = 0; i < 8; ++i) v[kh][i] = __builtin_nontemporal_load((const f32x4*)(src + (size_t)i * ldw)); }
; #pragma unroll
;     for (int kh = 0; kh < 2; ++kh)
; #pragma unroll
;         for (int e = 0; e < 4; ++e) { u32x4 o; o.x = cvt_pk_bf16(v[kh][0][e], v[kh][1][e]); o.y = cvt_pk_bf16(v[kh][2][e], v[kh][3][e]); o.z = cvt_pk_bf16(v[kh][4][e], v[kh][5][e]); o.w = cvt_pk_bf16(v[kh][6][e], v[kh][7][e]);
;             *(u32x4*)(WT + (size_t)(drow0 + n4 + e) * ldk + k0 + kh * 32 + kg * 8) = o; }
; }
; __device__ __forceinline__ void conv_item(int it, int lane) {
;     unsigned char* ws = WSP; int r = it;
;     if (r < 8 * IT_GU) { const int idx = r / IT_GU; r -= idx * IT_GU; const int kb = r / 168, nb = r % 168, n0 = 64 * nb;
;         const int drow = n0 < DFF ? (n0 >> 7) * 256 + (n0 & 127) : ((n0 - DFF) >> 7) * 256 + 128 + ((n0 - DFF) & 127);
;         tr_item(INP(I_WGU) + (size_t)idx * 2048 * 10752, 10752, 64 * kb, n0, (bf16*)(ws + WS_WGU) + (size_t)idx * 10752 * 2048, 2048, drow, lane); return; }
;     r -= 8 * IT_GU;
;     if (r < 8 * IT_D) { const int idx = r / IT_D; r -= idx * IT_D; const int kb = r / 32, nb = r % 32;
;         tr_item(INP(I_WD) + (size_t)idx * 5376 * 2048, 2048, 64 * kb, 64 * nb, (bf16*)(ws + WS_WD) + (size_t)idx * 2048 * 5376, 5376, 64 * nb, lane); return; }
;     r -= 8 * IT_D;
;     if (r < 2 * IT_INAB) { const int idx = r / IT_INAB; r -= idx * IT_INAB; const int kb = r / 80, nb = r % 80;
;         tr_item(INP(I_WINAB) + (size_t)idx * 2048 * 5120, 5120, 64 * kb, 64 * nb, (bf16*)(ws + WS_WINAB) + (size_t)idx * 5120 * 2048, 2048, 64 * nb, lane); return; }
;     r -= 2 * IT_INAB;
;     if (r < 2 * IT_GLU) { const int idx = r / IT_GLU; r -= idx * IT_GLU; const int kb = r / 16, nb = r % 16;
;         tr_item(INP(I_WGLU) + (size_t)idx * 1024 * 1024, 1024, 64 * kb, 64 * nb, (bf16*)(ws + WS_WGLU) + (size_t)idx * 1024 * 1024, 1024, 64 * nb, lane); return; }
;     r -= 2 * IT_GLU;
;     if (r < 2 * IT_OUTAB) { const int idx = r / IT_OUTAB; r -= idx * IT_OUTAB; const int kb = r / 32, nb = r % 32;
.LBB0_2504:
	s_mov_b64 s[2:3], s[0:1]
	s_load_dwordx2 s[2:3], s[2:3], 0x138
	s_add_i32 s6, s12, s26
	s_mov_b64 s[22:23], -1
	s_cmp_gt_i32 s6, 0xa7ff
	s_cbranch_scc0 .LBB0_2526
	s_cmpk_gt_u32 s6, 0xfbff
	s_cbranch_scc0 .LBB0_2523
	s_cmp_gt_u32 s6, 0x10fff
	s_cbranch_scc0 .LBB0_2520
	s_cmp_gt_u32 s6, 0x111ff
	s_cbranch_scc0 .LBB0_2517
	s_cmp_gt_u32 s6, 0x119ff
	s_cbranch_scc0 .LBB0_2514
	s_cmp_gt_u32 s6, 0x12dff
	s_cbranch_scc0 .LBB0_2511
	s_add_i32 s11, s6, 0xfffed200
	s_mul_hi_u32 s12, s11, 0xcccccccd
	s_lshr_b32 s12, s12, 10
	s_mul_i32 s20, s12, 0xfffffb00
	s_add_i32 s11, s20, s11
	s_ashr_i32 s20, s11, 31
	s_lshr_b32 s20, s20, 27
	s_add_i32 s22, s11, s20
	s_mov_b64 s[20:21], s[0:1]
	s_load_dwordx2 s[20:21], s[20:21], 0x128
	s_and_b32 s23, s22, 0x3ffffe0
	s_sub_i32 s11, s11, s23
	s_mul_i32 s26, s12, 0x1400000
	s_mul_hi_u32 s23, s12, 0x1400000
	s_waitcnt lgkmcnt(0)
	s_add_u32 s30, s20, s26
	s_addc_u32 s23, s21, s23
	s_lshl_b32 s20, s22, 1
	s_and_b32 s22, s20, 0xffffffc0
	s_lshl_b32 s26, s11, 6
	s_mul_hi_u32 s11, s12, 0xa00000
	s_mul_i32 s12, s12, 0xa00000
	s_add_u32 s12, s2, s12
	s_addc_u32 s11, s3, s11
	s_ashr_i32 s27, s26, 31
	s_lshl_b64 s[20:21], s[26:27], 2
	v_add_u32_e32 v32, s22, v66
	s_add_u32 s20, s30, s20
	s_addc_u32 s21, s23, s21
	v_lshlrev_b32_e32 v172, 2, v64
	v_ashrrev_i32_e32 v33, 31, v32
	v_lshl_add_u64 v[34:35], s[20:21], 0, v[172:173]
	v_lshlrev_b64 v[0:1], 13, v[32:33]
	v_lshl_add_u64 v[24:25], v[34:35], 0, v[0:1]
	v_add_co_u32_e32 v4, vcc, s89, v24
	s_movk_i32 s21, 0x4000
	s_nop 0
	v_addc_co_u32_e32 v5, vcc, 0, v25, vcc
	v_add_co_u32_e32 v8, vcc, s21, v24
	s_movk_i32 s20, 0x6000
	s_nop 0
	v_addc_co_u32_e32 v9, vcc, 0, v25, vcc
	v_add_co_u32_e32 v12, vcc, s20, v24
	s_mov_b32 s23, 0x8000
	s_nop 0
	v_addc_co_u32_e32 v13, vcc, 0, v25, vcc
	v_add_co_u32_e32 v16, vcc, s23, v24
	v_add_u32_e32 v32, 32, v32
	s_nop 0
	v_addc_co_u32_e32 v17, vcc, 0, v25, vcc
	v_add_co_u32_e32 v20, vcc, s33, v24
	s_mov_b32 s27, 0xe000
	s_nop 0
	v_addc_co_u32_e32 v21, vcc, 0, v25, vcc
	v_add_co_u32_e32 v26, vcc, s38, v24
	v_ashrrev_i32_e32 v33, 31, v32
	s_nop 0
	v_addc_co_u32_e32 v27, vcc, 0, v25, vcc
	v_add_co_u32_e32 v28, vcc, s27, v24
	v_lshlrev_b64 v[32:33], 13, v[32:33]
	s_nop 0
	v_addc_co_u32_e32 v29, vcc, 0, v25, vcc
	v_lshl_add_u64 v[56:57], v[34:35], 0, v[32:33]
	v_add_co_u32_e32 v36, vcc, s89, v56
	global_load_dwordx4 v[0:3], v[24:25], off nt
	s_nop 0
	global_load_dwordx4 v[4:7], v[4:5], off nt
	v_addc_co_u32_e32 v37, vcc, 0, v57, vcc
	v_add_co_u32_e32 v40, vcc, s21, v56
	global_load_dwordx4 v[8:11], v[8:9], off nt
	s_nop 0
	global_load_dwordx4 v[12:15], v[12:13], off nt
	v_addc_co_u32_e32 v41, vcc, 0, v57, vcc
	v_add_co_u32_e32 v44, vcc, s20, v56
	global_load_dwordx4 v[16:19], v[16:17], off nt
	s_nop 0
	global_load_dwordx4 v[20:23], v[20:21], off nt
	v_addc_co_u32_e32 v45, vcc, 0, v57, vcc
	v_add_co_u32_e32 v48, vcc, s23, v56
	global_load_dwordx4 v[24:27], v[26:27], off nt
	s_nop 0
	global_load_dwordx4 v[28:31], v[28:29], off nt
	v_addc_co_u32_e32 v49, vcc, 0, v57, vcc
	v_add_co_u32_e32 v52, vcc, s33, v56
	global_load_dwordx4 v[32:35], v[56:57], off nt
	s_nop 0
	global_load_dwordx4 v[36:39], v[36:37], off nt
	v_addc_co_u32_e32 v53, vcc, 0, v57, vcc
	v_add_co_u32_e32 v58, vcc, s38, v56
	global_load_dwordx4 v[40:43], v[40:41], off nt
	s_nop 0
	global_load_dwordx4 v[44:47], v[44:45], off nt
	v_addc_co_u32_e32 v59, vcc, 0, v57, vcc
	v_add_co_u32_e32 v60, vcc, s27, v56
	global_load_dwordx4 v[48:51], v[48:49], off nt
	s_nop 0
	global_load_dwordx4 v[52:55], v[52:53], off nt
	v_addc_co_u32_e32 v61, vcc, 0, v57, vcc
	global_load_dwordx4 v[56:59], v[58:59], off nt
	s_nop 0
	global_load_dwordx4 v[60:63], v[60:61], off nt
	s_ashr_i32 s23, s22, 31
	s_lshl_b64 s[20:21], s[22:23], 1
	s_add_u32 s20, s12, s20
	v_or_b32_e32 v65, s26, v64
	s_addc_u32 s21, s11, s21
	s_movk_i32 s11, 0xa00
	v_mul_lo_u32 v74, v65, s11
	v_lshl_add_u64 v[72:73], v[66:67], 1, s[20:21]
	v_ashrrev_i32_e32 v75, 31, v74
	v_lshl_add_u64 v[72:73], v[74:75], 1, v[72:73]
	s_mov_b32 s11, 0x25d00000
	v_add_co_u32_e32 v76, vcc, s11, v72
	s_mov_b32 s11, 0x25d01000
	s_nop 0
	v_addc_co_u32_e32 v77, vcc, 0, v73, vcc
	s_waitcnt vmcnt(14)
	v_cvt_pk_bf16_f32 v68, v0, v4
	v_add_co_u32_e32 v4, vcc, s11, v72
	s_waitcnt vmcnt(12)
	v_cvt_pk_bf16_f32 v69, v8, v12
	s_waitcnt vmcnt(10)
	v_cvt_pk_bf16_f32 v70, v16, v20
	s_waitcnt vmcnt(8)
	v_cvt_pk_bf16_f32 v71, v24, v28
	global_store_dwordx4 v[76:77], v[68:71], off sc1
	s_mov_b32 s11, 0x25d02000
	s_mov_b64 s[20:21], 0x25d00000
	v_cvt_pk_bf16_f32 v68, v1, v5
	v_addc_co_u32_e32 v5, vcc, 0, v73, vcc
	v_add_co_u32_e32 v8, vcc, s11, v72
	v_cvt_pk_bf16_f32 v69, v9, v13
	s_mov_b32 s11, 0x25d03000
	s_nop 0
	v_addc_co_u32_e32 v9, vcc, 0, v73, vcc
	v_cvt_pk_bf16_f32 v70, v17, v21
	v_cvt_pk_bf16_f32 v71, v25, v29
	global_store_dwordx4 v[4:5], v[68:71], off offset:1024 sc1
	v_lshl_add_u64 v[74:75], v[72:73], 0, s[20:21]
	s_mov_b64 s[22:23], 0
	v_cvt_pk_bf16_f32 v68, v2, v6
	v_add_co_u32_e32 v6, vcc, s11, v72
	v_cvt_pk_bf16_f32 v69, v10, v14
	v_cvt_pk_bf16_f32 v70, v18, v22
	v_cvt_pk_bf16_f32 v71, v26, v30
	global_store_dwordx4 v[8:9], v[68:71], off offset:2048 sc1
	v_cvt_pk_bf16_f32 v0, v3, v7
	v_cvt_pk_bf16_f32 v1, v11, v15
	v_cvt_pk_bf16_f32 v2, v19, v23
	v_cvt_pk_bf16_f32 v3, v27, v31
	s_nop 0
	v_addc_co_u32_e32 v7, vcc, 0, v73, vcc
	global_store_dwordx4 v[6:7], v[0:3], off offset:3072 sc1
	s_waitcnt vmcnt(10)
	s_nop 0
	v_cvt_pk_bf16_f32 v0, v32, v36
	s_waitcnt vmcnt(8)
	v_cvt_pk_bf16_f32 v1, v40, v44
	s_waitcnt vmcnt(6)
	v_cvt_pk_bf16_f32 v2, v48, v52
	s_waitcnt vmcnt(4)
	v_cvt_pk_bf16_f32 v3, v56, v60
	global_store_dwordx4 v[74:75], v[0:3], off offset:64 sc1
	s_nop 1
	v_cvt_pk_bf16_f32 v0, v33, v37
	v_cvt_pk_bf16_f32 v1, v41, v45
	v_cvt_pk_bf16_f32 v2, v49, v53
	v_cvt_pk_bf16_f32 v3, v57, v61
	global_store_dwordx4 v[4:5], v[0:3], off offset:1088 sc1
	s_nop 1
	v_cvt_pk_bf16_f32 v0, v34, v38
	v_cvt_pk_bf16_f32 v1, v42, v46
	v_cvt_pk_bf16_f32 v2, v50, v54
	v_cvt_pk_bf16_f32 v3, v58, v62
	global_store_dwordx4 v[8:9], v[0:3], off offset:2112 sc1
	s_nop 1
	v_cvt_pk_bf16_f32 v0, v35, v39
	v_cvt_pk_bf16_f32 v1, v43, v47
	v_cvt_pk_bf16_f32 v2, v51, v55
	v_cvt_pk_bf16_f32 v3, v59, v63
	global_store_dwordx4 v[6:7], v[0:3], off offset:3136 sc1
; __device__ __forceinline__ unsigned cvt_pk_bf16(float lo, float hi) { unsigned r; asm volatile("v_cvt_pk_bf16_f32 %0, %1, %2" : "=v"(r) : "v"(lo), "v"(hi)); return r; }
; #define INP(i) ((const float*)(const GASP float*)kargs()[(i)])
; __device__ __forceinline__ void tr_item(const float* W, int ldw, int k0, int n0, bf16* WT, int ldk, int drow0, int lane) {
;     const int n4 = (lane & 15) * 4, kg = lane >> 4; f32x4 v[2][8];
; #pragma unroll
;     for (int kh = 0; kh < 2; ++kh) { const float* src = W + (size_t)(k0 + kh * 32 + kg * 8) * ldw + n0 + n4;
; #pragma unroll
;         for (int i = 0; i < 8; ++i) v[kh][i] = __builtin_nontemporal_load((const f32x4*)(src + (size_t)i * ldw)); }
; #pragma unroll
;     for (int kh = 0; kh < 2; ++kh)
; #pragma unroll
;         for (int e = 0; e < 4; ++e) { u32x4 o; o.x = cvt_pk_bf16(v[kh][0][e], v[kh][1][e]); o.y = cvt_pk_bf16(v[kh][2][e], v[kh][3][e]); o.z = cvt_pk_bf16(v[kh][4][e], v[kh][5][e]); o.w = cvt_pk_bf16(v[kh][6][e], v[kh][7][e]);
;             *(u32x4*)(WT + (size_t)(drow0 + n4 + e) * ldk + k0 + kh * 32 + kg * 8) = o; }
; }
; __device__ __forceinline__ void conv_item(int it, int lane) {
;     ...
;     if (r < 2 * IT_INC) { const int idx = r / IT_INC; r -= idx * IT_INC; const int kb = r / 80, nb = r % 80;
;         tr_item(INP(I_WINC) + (size_t)idx * 2048 * 5120, 5120, 64 * kb, 64 * nb, (bf16*)(ws + WS_WINC) + (size_t)idx * 5120 * 2048, 2048, 64 * nb, lane); return; }
.LBB0_2511:
	s_andn2_b64 vcc, exec, s[22:23]
	s_cbranch_vccnz .LBB0_2513
	s_add_i32 s11, s6, 0xfffee600
	s_cmpk_gt_u32 s11, 0x9ff
	s_cselect_b64 s[20:21], -1, 0
	s_and_b64 s[22:23], s[20:21], exec
	s_cselect_b32 s12, 0xf600, 0
	s_add_i32 s12, s12, s11
	s_sext_i32_i16 s11, s12
	s_mulk_i32 s11, 0x6667
	s_lshr_b32 s22, s11, 31
	s_ashr_i32 s11, s11, 21
	s_add_i32 s11, s11, s22
	s_mov_b64 s[22:23], s[0:1]
	s_load_dwordx2 s[22:23], s[22:23], 0xe8
	s_mul_i32 s26, s11, 0x50
	s_sub_i32 s12, s12, s26
	s_and_b64 s[26:27], s[20:21], exec
	s_cselect_b32 s26, 0x2800000, 0
	s_sext_i32_i16 s12, s12
	s_waitcnt lgkmcnt(0)
	s_add_u32 s30, s22, s26
	s_addc_u32 s23, s23, 0
	s_lshl_b32 s22, s11, 6
	s_lshl_b32 s26, s12, 6
	s_and_b64 s[20:21], s[20:21], exec
	s_cselect_b32 s11, 0x1400000, 0
	s_add_u32 s11, s2, s11
	s_addc_u32 s12, s3, 0
	s_ashr_i32 s27, s26, 31
	s_lshl_b64 s[20:21], s[26:27], 2
	s_add_u32 s20, s30, s20
	s_addc_u32 s21, s23, s21
	v_lshlrev_b32_e32 v172, 2, v64
	v_add_u32_e32 v34, s22, v66
	v_lshl_add_u64 v[32:33], s[20:21], 0, v[172:173]
	s_movk_i32 s30, 0x5000
	v_mad_i64_i32 v[24:25], s[20:21], v34, s30, v[32:33]
	v_add_co_u32_e32 v4, vcc, s30, v24
	s_mov_b32 s23, 0x14000
	s_nop 0
	v_addc_co_u32_e32 v5, vcc, 0, v25, vcc
	v_add_co_u32_e32 v8, vcc, s33, v24
	s_mov_b32 s31, 0x19000
	s_nop 0
	v_addc_co_u32_e32 v9, vcc, 0, v25, vcc
	v_add_co_u32_e32 v12, vcc, s76, v24
	s_mov_b32 s27, 0x1e000
	s_nop 0
	v_addc_co_u32_e32 v13, vcc, 0, v25, vcc
	v_add_co_u32_e32 v16, vcc, s23, v24
	v_add_u32_e32 v34, 32, v34
	s_nop 0
	v_addc_co_u32_e32 v17, vcc, 0, v25, vcc
	v_add_co_u32_e32 v20, vcc, s31, v24
	v_mad_i64_i32 v[56:57], s[20:21], v34, s30, v[32:33]
	s_nop 0
	v_addc_co_u32_e32 v21, vcc, 0, v25, vcc
	v_add_co_u32_e32 v26, vcc, s27, v24
	global_load_dwordx4 v[0:3], v[24:25], off nt
	s_nop 0
	global_load_dwordx4 v[4:7], v[4:5], off nt
	v_addc_co_u32_e32 v27, vcc, 0, v25, vcc
	v_add_co_u32_e32 v28, vcc, s77, v24
	global_load_dwordx4 v[8:11], v[8:9], off nt
	s_nop 0
	global_load_dwordx4 v[12:15], v[12:13], off nt
	v_addc_co_u32_e32 v29, vcc, 0, v25, vcc
	v_add_co_u32_e32 v36, vcc, s30, v56
	global_load_dwordx4 v[16:19], v[16:17], off nt
	s_nop 0
	global_load_dwordx4 v[20:23], v[20:21], off nt
	v_addc_co_u32_e32 v37, vcc, 0, v57, vcc
	v_add_co_u32_e32 v40, vcc, s33, v56
	global_load_dwordx4 v[24:27], v[26:27], off nt
	s_nop 0
	global_load_dwordx4 v[28:31], v[28:29], off nt
	v_addc_co_u32_e32 v41, vcc, 0, v57, vcc
	v_add_co_u32_e32 v44, vcc, s76, v56
	global_load_dwordx4 v[32:35], v[56:57], off nt
	s_nop 0
	global_load_dwordx4 v[36:39], v[36:37], off nt
	v_addc_co_u32_e32 v45, vcc, 0, v57, vcc
	v_add_co_u32_e32 v48, vcc, s23, v56
	global_load_dwordx4 v[40:43], v[40:41], off nt
	s_nop 0
	global_load_dwordx4 v[44:47], v[44:45], off nt
	v_addc_co_u32_e32 v49, vcc, 0, v57, vcc
	v_add_co_u32_e32 v52, vcc, s31, v56
	s_ashr_i32 s23, s22, 31
	s_nop 0
	v_addc_co_u32_e32 v53, vcc, 0, v57, vcc
	v_add_co_u32_e32 v58, vcc, s27, v56
	global_load_dwordx4 v[48:51], v[48:49], off nt
	s_nop 0
	global_load_dwordx4 v[52:55], v[52:53], off nt
	v_addc_co_u32_e32 v59, vcc, 0, v57, vcc
	v_add_co_u32_e32 v60, vcc, s77, v56
	s_lshl_b64 s[20:21], s[22:23], 1
	s_nop 0
	v_addc_co_u32_e32 v61, vcc, 0, v57, vcc
	global_load_dwordx4 v[56:59], v[58:59], off nt
	s_nop 0
	global_load_dwordx4 v[60:63], v[60:61], off nt
	s_add_u32 s20, s11, s20
	v_or_b32_e32 v72, s26, v64
	s_addc_u32 s21, s12, s21
	v_lshl_add_u64 v[68:69], v[66:67], 1, s[20:21]
	s_mov_b64 s[20:21], 0x23500000
	v_ashrrev_i32_e32 v73, 31, v72
	v_lshl_add_u64 v[74:75], v[68:69], 0, s[20:21]
	v_lshlrev_b64 v[76:77], 12, v[72:73]
	s_waitcnt vmcnt(14)
	v_cvt_pk_bf16_f32 v68, v0, v4
	v_lshl_add_u64 v[76:77], v[74:75], 0, v[76:77]
	v_or_b32_e32 v0, 1, v72
	s_waitcnt vmcnt(12)
	v_cvt_pk_bf16_f32 v69, v8, v12
	s_waitcnt vmcnt(10)
	v_cvt_pk_bf16_f32 v70, v16, v20
	s_waitcnt vmcnt(8)
	v_cvt_pk_bf16_f32 v71, v24, v28
	global_store_dwordx4 v[76:77], v[68:71], off sc1
	s_nop 1
	v_cvt_pk_bf16_f32 v68, v1, v5
	v_ashrrev_i32_e32 v1, 31, v0
	v_lshlrev_b64 v[0:1], 12, v[0:1]
	v_lshl_add_u64 v[4:5], v[74:75], 0, v[0:1]
	v_or_b32_e32 v0, 2, v72
	v_ashrrev_i32_e32 v1, 31, v0
	v_lshlrev_b64 v[0:1], 12, v[0:1]
	v_cvt_pk_bf16_f32 v69, v9, v13
	v_cvt_pk_bf16_f32 v70, v17, v21
	v_cvt_pk_bf16_f32 v71, v25, v29
	global_store_dwordx4 v[4:5], v[68:71], off sc1
	v_lshl_add_u64 v[8:9], v[74:75], 0, v[0:1]
	s_nop 0
	v_cvt_pk_bf16_f32 v68, v2, v6
	v_or_b32_e32 v6, 3, v72
	v_cvt_pk_bf16_f32 v69, v10, v14
	v_cvt_pk_bf16_f32 v70, v18, v22
	v_cvt_pk_bf16_f32 v71, v26, v30
	global_store_dwordx4 v[8:9], v[68:71], off sc1
	v_cvt_pk_bf16_f32 v0, v3, v7
	v_ashrrev_i32_e32 v7, 31, v6
	v_lshlrev_b64 v[6:7], 12, v[6:7]
	v_cvt_pk_bf16_f32 v1, v11, v15
	v_cvt_pk_bf16_f32 v2, v19, v23
	v_cvt_pk_bf16_f32 v3, v27, v31
	v_lshl_add_u64 v[6:7], v[74:75], 0, v[6:7]
	global_store_dwordx4 v[6:7], v[0:3], off sc1
	s_waitcnt vmcnt(10)
	s_nop 0
	v_cvt_pk_bf16_f32 v0, v32, v36
	s_waitcnt vmcnt(8)
	v_cvt_pk_bf16_f32 v1, v40, v44
	s_waitcnt vmcnt(6)
	v_cvt_pk_bf16_f32 v2, v48, v52
	s_waitcnt vmcnt(4)
	v_cvt_pk_bf16_f32 v3, v56, v60
	global_store_dwordx4 v[76:77], v[0:3], off offset:64 sc1
	s_nop 1
	v_cvt_pk_bf16_f32 v0, v33, v37
	v_cvt_pk_bf16_f32 v1, v41, v45
	v_cvt_pk_bf16_f32 v2, v49, v53
	v_cvt_pk_bf16_f32 v3, v57, v61
	global_store_dwordx4 v[4:5], v[0:3], off offset:64 sc1
	s_nop 1
	v_cvt_pk_bf16_f32 v0, v34, v38
	v_cvt_pk_bf16_f32 v1, v42, v46
	v_cvt_pk_bf16_f32 v2, v50, v54
	v_cvt_pk_bf16_f32 v3, v58, v62
	global_store_dwordx4 v[8:9], v[0:3], off offset:64 sc1
	s_nop 1
	v_cvt_pk_bf16_f32 v0, v35, v39
	v_cvt_pk_bf16_f32 v1, v43, v47
	v_cvt_pk_bf16_f32 v2, v51, v55
	v_cvt_pk_bf16_f32 v3, v59, v63
	global_store_dwordx4 v[6:7], v[0:3], off offset:64 sc1

; __device__ __forceinline__ unsigned cvt_pk_bf16(float lo, float hi) { unsigned r; asm volatile("v_cvt_pk_bf16_f32 %0, %1, %2" : "=v"(r) : "v"(lo), "v"(hi)); return r; }
; #define INP(i) ((const float*)(const GASP float*)kargs()[(i)])
; __device__ __forceinline__ void tr_item(const float* W, int ldw, int k0, int n0, bf16* WT, int ldk, int drow0, int lane) {
;     const int n4 = (lane & 15) * 4, kg = lane >> 4; f32x4 v[2][8];
; #pragma unroll
;     for (int kh = 0; kh < 2; ++kh) { const float* src = W + (size_t)(k0 + kh * 32 + kg * 8) * ldw + n0 + n4;
; #pragma unroll
;         for (int i = 0; i < 8; ++i) v[kh][i] = __builtin_nontemporal_load((const f32x4*)(src + (size_t)i * ldw)); }
; #pragma unroll
;     for (int kh = 0; kh < 2; ++kh)
; #pragma unroll
;         for (int e = 0; e < 4; ++e) { u32x4 o; o.x = cvt_pk_bf16(v[kh][0][e], v[kh][1][e]); o.y = cvt_pk_bf16(v[kh][2][e], v[kh][3][e]); o.z = cvt_pk_bf16(v[kh][4][e], v[kh][5][e]); o.w = cvt_pk_bf16(v[kh][6][e], v[kh][7][e]);
;             *(u32x4*)(WT + (size_t)(drow0 + n4 + e) * ldk + k0 + kh * 32 + kg * 8) = o; }
; }
; __device__ __forceinline__ void conv_item(int it, int lane) {
;     ...
;     if (r < 2 * IT_OUTAB) { const int idx = r / IT_OUTAB; r -= idx * IT_OUTAB; const int kb = r / 32, nb = r % 32;
;         tr_item(INP(I_WOUTAB) + (size_t)idx * 2048 * 2048, 2048, 64 * kb, 64 * nb, (bf16*)(ws + WS_WOUTAB) + (size_t)idx * 2048 * 2048, 2048, 64 * nb, lane); return; }
.LBB0_2514:
	s_andn2_b64 vcc, exec, s[22:23]
	s_cbranch_vccnz .LBB0_2516
	s_mov_b64 s[20:21], s[0:1]
	s_load_dwordx2 s[20:21], s[20:21], 0xe0
	s_add_i32 s11, s6, 0xfffeee00
	s_lshr_b32 s38, s11, 10
	s_lshl_b64 s[22:23], s[38:39], 24
	v_lshlrev_b32_e32 v172, 2, v64
	s_waitcnt lgkmcnt(0)
	s_add_u32 s12, s20, s22
	s_addc_u32 s22, s21, s23
	s_lshl_b32 s11, s11, 1
	s_lshl_b32 s20, s6, 6
	s_and_b32 s11, s11, 0x7c0
	s_and_b32 s23, s20, 0x7c0
	s_lshl_b64 s[20:21], s[38:39], 23
	s_add_u32 s26, s2, s20
	s_addc_u32 s27, s3, s21
	s_lshl_b32 s20, s23, 2
	v_add_u32_e32 v32, s11, v66
	s_add_u32 s20, s12, s20
	s_addc_u32 s21, s22, 0
	v_ashrrev_i32_e32 v33, 31, v32
	v_lshl_add_u64 v[34:35], s[20:21], 0, v[172:173]
	v_lshlrev_b64 v[0:1], 13, v[32:33]
	v_lshl_add_u64 v[24:25], v[34:35], 0, v[0:1]
	v_add_co_u32_e32 v4, vcc, s89, v24
	s_movk_i32 s20, 0x4000
	s_nop 0
	v_addc_co_u32_e32 v5, vcc, 0, v25, vcc
	v_add_co_u32_e32 v8, vcc, s20, v24
	s_movk_i32 s12, 0x6000
	s_nop 0
	v_addc_co_u32_e32 v9, vcc, 0, v25, vcc
	v_add_co_u32_e32 v12, vcc, s12, v24
	s_mov_b32 s21, 0x8000
	s_nop 0
	v_addc_co_u32_e32 v13, vcc, 0, v25, vcc
	v_add_co_u32_e32 v16, vcc, s21, v24
	s_mov_b32 s38, 0xc000
	s_nop 0
	v_addc_co_u32_e32 v17, vcc, 0, v25, vcc
	v_add_co_u32_e32 v20, vcc, s33, v24
	v_add_u32_e32 v32, 32, v32
	s_nop 0
	v_addc_co_u32_e32 v21, vcc, 0, v25, vcc
	v_add_co_u32_e32 v26, vcc, s38, v24
	s_mov_b32 s22, 0xe000
	s_nop 0
	v_addc_co_u32_e32 v27, vcc, 0, v25, vcc
	v_ashrrev_i32_e32 v33, 31, v32
	v_add_co_u32_e32 v28, vcc, s22, v24
	v_lshlrev_b64 v[32:33], 13, v[32:33]
	s_nop 0
	v_addc_co_u32_e32 v29, vcc, 0, v25, vcc
	v_lshl_add_u64 v[56:57], v[34:35], 0, v[32:33]
	v_add_co_u32_e32 v36, vcc, s89, v56
	global_load_dwordx4 v[0:3], v[24:25], off nt
	s_nop 0
	global_load_dwordx4 v[4:7], v[4:5], off nt
	v_addc_co_u32_e32 v37, vcc, 0, v57, vcc
	v_add_co_u32_e32 v40, vcc, s20, v56
	global_load_dwordx4 v[8:11], v[8:9], off nt
	s_nop 0
	global_load_dwordx4 v[12:15], v[12:13], off nt
	v_addc_co_u32_e32 v41, vcc, 0, v57, vcc
	v_add_co_u32_e32 v44, vcc, s12, v56
	global_load_dwordx4 v[16:19], v[16:17], off nt
	s_nop 0
	global_load_dwordx4 v[20:23], v[20:21], off nt
	v_addc_co_u32_e32 v45, vcc, 0, v57, vcc
	v_add_co_u32_e32 v48, vcc, s21, v56
	global_load_dwordx4 v[24:27], v[26:27], off nt
	s_nop 0
	global_load_dwordx4 v[28:31], v[28:29], off nt
	v_addc_co_u32_e32 v49, vcc, 0, v57, vcc
	v_add_co_u32_e32 v52, vcc, s33, v56
	global_load_dwordx4 v[32:35], v[56:57], off nt
	s_nop 0
	global_load_dwordx4 v[36:39], v[36:37], off nt
	v_addc_co_u32_e32 v53, vcc, 0, v57, vcc
	v_add_co_u32_e32 v58, vcc, s38, v56
	global_load_dwordx4 v[40:43], v[40:41], off nt
	s_nop 0
	global_load_dwordx4 v[44:47], v[44:45], off nt
	v_addc_co_u32_e32 v59, vcc, 0, v57, vcc
	v_add_co_u32_e32 v60, vcc, s22, v56
	global_load_dwordx4 v[48:51], v[48:49], off nt
	s_nop 0
	global_load_dwordx4 v[52:55], v[52:53], off nt
	v_addc_co_u32_e32 v61, vcc, 0, v57, vcc
	global_load_dwordx4 v[56:59], v[58:59], off nt
	s_nop 0
	global_load_dwordx4 v[60:63], v[60:61], off nt
	s_lshl_b32 s11, s11, 1
	s_add_u32 s20, s26, s11
	s_addc_u32 s21, s27, 0
	v_or_b32_e32 v65, s23, v64
	v_lshl_add_u64 v[72:73], v[66:67], 1, s[20:21]
	s_mov_b64 s[20:21], 0x22500000
	v_lshl_add_u64 v[74:75], v[72:73], 0, s[20:21]
	v_lshlrev_b32_e32 v172, 12, v65
	s_waitcnt vmcnt(14)
	v_cvt_pk_bf16_f32 v68, v0, v4
	v_lshl_add_u64 v[76:77], v[74:75], 0, v[172:173]
	s_waitcnt vmcnt(12)
	v_cvt_pk_bf16_f32 v69, v8, v12
	s_waitcnt vmcnt(10)
	v_cvt_pk_bf16_f32 v70, v16, v20
	s_waitcnt vmcnt(8)
	v_cvt_pk_bf16_f32 v71, v24, v28
	global_store_dwordx4 v[76:77], v[68:71], off sc1
	v_or_b32_e32 v4, 0x1000, v172
	v_or_b32_e32 v8, 0x2000, v172
	v_cvt_pk_bf16_f32 v68, v1, v5
	v_mov_b32_e32 v5, v173
	v_cvt_pk_bf16_f32 v69, v9, v13
	v_lshl_add_u64 v[0:1], v[74:75], 0, v[4:5]
	v_mov_b32_e32 v9, v173
	v_cvt_pk_bf16_f32 v70, v17, v21
	v_cvt_pk_bf16_f32 v71, v25, v29
	global_store_dwordx4 v[0:1], v[68:71], off sc1
	v_lshl_add_u64 v[0:1], v[74:75], 0, v[8:9]
	v_or_b32_e32 v172, 0x3000, v172
	v_cvt_pk_bf16_f32 v68, v2, v6
	v_cvt_pk_bf16_f32 v69, v10, v14
	v_cvt_pk_bf16_f32 v70, v18, v22
	v_cvt_pk_bf16_f32 v71, v26, v30
	global_store_dwordx4 v[0:1], v[68:71], off sc1
	v_cvt_pk_bf16_f32 v0, v3, v7
	v_lshl_add_u64 v[6:7], v[74:75], 0, v[172:173]
	s_mov_b64 s[20:21], 0x22500040
	v_cvt_pk_bf16_f32 v1, v11, v15
	v_cvt_pk_bf16_f32 v2, v19, v23
	v_cvt_pk_bf16_f32 v3, v27, v31
	global_store_dwordx4 v[6:7], v[0:3], off sc1
	v_lshl_add_u64 v[6:7], v[72:73], 0, s[20:21]
	v_lshl_add_u64 v[4:5], v[6:7], 0, v[4:5]
	s_waitcnt vmcnt(10)
	v_cvt_pk_bf16_f32 v0, v32, v36
	s_waitcnt vmcnt(8)
	v_cvt_pk_bf16_f32 v1, v40, v44
	s_waitcnt vmcnt(6)
	v_cvt_pk_bf16_f32 v2, v48, v52
	s_waitcnt vmcnt(4)
	v_cvt_pk_bf16_f32 v3, v56, v60
	global_store_dwordx4 v[76:77], v[0:3], off offset:64 sc1
	s_nop 1
	v_cvt_pk_bf16_f32 v0, v33, v37
	v_cvt_pk_bf16_f32 v1, v41, v45
	v_cvt_pk_bf16_f32 v2, v49, v53
	v_cvt_pk_bf16_f32 v3, v57, v61
	global_store_dwordx4 v[4:5], v[0:3], off sc1
	v_lshl_add_u64 v[4:5], v[6:7], 0, v[8:9]
	s_nop 0
	v_cvt_pk_bf16_f32 v0, v34, v38
	v_cvt_pk_bf16_f32 v1, v42, v46
	v_cvt_pk_bf16_f32 v2, v50, v54
	v_cvt_pk_bf16_f32 v3, v58, v62
	global_store_dwordx4 v[4:5], v[0:3], off sc1
	v_lshl_add_u64 v[4:5], v[6:7], 0, v[172:173]
	s_nop 0
	v_cvt_pk_bf16_f32 v0, v35, v39
	v_cvt_pk_bf16_f32 v1, v43, v47
	v_cvt_pk_bf16_f32 v2, v51, v55
	v_cvt_pk_bf16_f32 v3, v59, v63
	global_store_dwordx4 v[4:5], v[0:3], off sc1

; __device__ __forceinline__ unsigned cvt_pk_bf16(float lo, float hi) { unsigned r; asm volatile("v_cvt_pk_bf16_f32 %0, %1, %2" : "=v"(r) : "v"(lo), "v"(hi)); return r; }
; #define INP(i) ((const float*)(const GASP float*)kargs()[(i)])
; __device__ __forceinline__ void tr_item(const float* W, int ldw, int k0, int n0, bf16* WT, int ldk, int drow0, int lane) {
;     const int n4 = (lane & 15) * 4, kg = lane >> 4; f32x4 v[2][8];
; #pragma unroll
;     for (int kh = 0; kh < 2; ++kh) { const float* src = W + (size_t)(k0 + kh * 32 + kg * 8) * ldw + n0 + n4;
; #pragma unroll
;         for (int i = 0; i < 8; ++i) v[kh][i] = __builtin_nontemporal_load((const f32x4*)(src + (size_t)i * ldw)); }
; #pragma unroll
;     for (int kh = 0; kh < 2; ++kh)
; #pragma unroll
;         for (int e = 0; e < 4; ++e) { u32x4 o; o.x = cvt_pk_bf16(v[kh][0][e], v[kh][1][e]); o.y = cvt_pk_bf16(v[kh][2][e], v[kh][3][e]); o.z = cvt_pk_bf16(v[kh][4][e], v[kh][5][e]); o.w = cvt_pk_bf16(v[kh][6][e], v[kh][7][e]);
;             *(u32x4*)(WT + (size_t)(drow0 + n4 + e) * ldk + k0 + kh * 32 + kg * 8) = o; }
; }
; __device__ __forceinline__ void conv_item(int it, int lane) {
;     ...
;     if (r < 2 * IT_INAB) { const int idx = r / IT_INAB; r -= idx * IT_INAB; const int kb = r / 80, nb = r % 80;
;         tr_item(INP(I_WINAB) + (size_t)idx * 2048 * 5120, 5120, 64 * kb, 64 * nb, (bf16*)(ws + WS_WINAB) + (size_t)idx * 5120 * 2048, 2048, 64 * nb, lane); return; }
.LBB0_2520:
	s_andn2_b64 vcc, exec, s[22:23]
	s_cbranch_vccnz .LBB0_2522
	s_add_i32 s11, s6, 0xffff0400
	s_cmpk_gt_u32 s11, 0x9ff
	s_cselect_b64 s[20:21], -1, 0
	s_and_b64 s[22:23], s[20:21], exec
	s_cselect_b32 s12, 0xf600, 0
	s_add_i32 s12, s12, s11
	s_sext_i32_i16 s11, s12
	s_mulk_i32 s11, 0x6667
	s_lshr_b32 s22, s11, 31
	s_ashr_i32 s11, s11, 21
	s_add_i32 s11, s11, s22
	s_mov_b64 s[22:23], s[0:1]
	s_load_dwordx2 s[22:23], s[22:23], 0x78
	s_mul_i32 s26, s11, 0x50
	s_sub_i32 s12, s12, s26
	s_and_b64 s[26:27], s[20:21], exec
	s_cselect_b32 s26, 0x2800000, 0
	s_sext_i32_i16 s12, s12
	s_waitcnt lgkmcnt(0)
	s_add_u32 s30, s22, s26
	s_addc_u32 s23, s23, 0
	s_lshl_b32 s22, s11, 6
	s_lshl_b32 s26, s12, 6
	s_and_b64 s[20:21], s[20:21], exec
	s_cselect_b32 s11, 0x1400000, 0
	s_add_u32 s11, s2, s11
	s_addc_u32 s12, s3, 0
	s_ashr_i32 s27, s26, 31
	s_lshl_b64 s[20:21], s[26:27], 2
	s_add_u32 s20, s30, s20
	s_addc_u32 s21, s23, s21
	v_lshlrev_b32_e32 v172, 2, v64
	v_add_u32_e32 v34, s22, v66
	v_lshl_add_u64 v[32:33], s[20:21], 0, v[172:173]
	s_movk_i32 s30, 0x5000
	v_mad_i64_i32 v[24:25], s[20:21], v34, s30, v[32:33]
	v_add_co_u32_e32 v4, vcc, s30, v24
	s_mov_b32 s23, 0x14000
	s_nop 0
	v_addc_co_u32_e32 v5, vcc, 0, v25, vcc
	v_add_co_u32_e32 v8, vcc, s33, v24
	s_mov_b32 s31, 0x19000
	s_nop 0
	v_addc_co_u32_e32 v9, vcc, 0, v25, vcc
	v_add_co_u32_e32 v12, vcc, s76, v24
	s_mov_b32 s27, 0x1e000
	s_nop 0
	v_addc_co_u32_e32 v13, vcc, 0, v25, vcc
	v_add_co_u32_e32 v16, vcc, s23, v24
	v_add_u32_e32 v34, 32, v34
	s_nop 0
	v_addc_co_u32_e32 v17, vcc, 0, v25, vcc
	v_add_co_u32_e32 v20, vcc, s31, v24
	v_mad_i64_i32 v[56:57], s[20:21], v34, s30, v[32:33]
	s_nop 0
	v_addc_co_u32_e32 v21, vcc, 0, v25, vcc
	v_add_co_u32_e32 v26, vcc, s27, v24
	global_load_dwordx4 v[0:3], v[24:25], off nt
	s_nop 0
	global_load_dwordx4 v[4:7], v[4:5], off nt
	v_addc_co_u32_e32 v27, vcc, 0, v25, vcc
	v_add_co_u32_e32 v28, vcc, s77, v24
	global_load_dwordx4 v[8:11], v[8:9], off nt
	s_nop 0
	global_load_dwordx4 v[12:15], v[12:13], off nt
	v_addc_co_u32_e32 v29, vcc, 0, v25, vcc
	v_add_co_u32_e32 v36, vcc, s30, v56
	global_load_dwordx4 v[16:19], v[16:17], off nt
	s_nop 0
	global_load_dwordx4 v[20:23], v[20:21], off nt
	v_addc_co_u32_e32 v37, vcc, 0, v57, vcc
	v_add_co_u32_e32 v40, vcc, s33, v56
	global_load_dwordx4 v[24:27], v[26:27], off nt
	s_nop 0
	global_load_dwordx4 v[28:31], v[28:29], off nt
	v_addc_co_u32_e32 v41, vcc, 0, v57, vcc
	v_add_co_u32_e32 v44, vcc, s76, v56
	global_load_dwordx4 v[32:35], v[56:57], off nt
	s_nop 0
	global_load_dwordx4 v[36:39], v[36:37], off nt
	v_addc_co_u32_e32 v45, vcc, 0, v57, vcc
	v_add_co_u32_e32 v48, vcc, s23, v56
	global_load_dwordx4 v[40:43], v[40:41], off nt
	s_nop 0
	global_load_dwordx4 v[44:47], v[44:45], off nt
	v_addc_co_u32_e32 v49, vcc, 0, v57, vcc
	v_add_co_u32_e32 v52, vcc, s31, v56
	s_ashr_i32 s23, s22, 31
	s_nop 0
	v_addc_co_u32_e32 v53, vcc, 0, v57, vcc
	v_add_co_u32_e32 v58, vcc, s27, v56
	global_load_dwordx4 v[48:51], v[48:49], off nt
	s_nop 0
	global_load_dwordx4 v[52:55], v[52:53], off nt
	v_addc_co_u32_e32 v59, vcc, 0, v57, vcc
	v_add_co_u32_e32 v60, vcc, s77, v56
	s_lshl_b64 s[20:21], s[22:23], 1
	s_nop 0
	v_addc_co_u32_e32 v61, vcc, 0, v57, vcc
	global_load_dwordx4 v[56:59], v[58:59], off nt
	s_nop 0
	global_load_dwordx4 v[60:63], v[60:61], off nt
	s_add_u32 s20, s11, s20
	v_or_b32_e32 v72, s26, v64
	s_addc_u32 s21, s12, s21
	v_lshl_add_u64 v[68:69], v[66:67], 1, s[20:21]
	s_mov_b64 s[20:21], 0x1f900000
	v_ashrrev_i32_e32 v73, 31, v72
	v_lshl_add_u64 v[74:75], v[68:69], 0, s[20:21]
	v_lshlrev_b64 v[76:77], 12, v[72:73]
	s_waitcnt vmcnt(14)
	v_cvt_pk_bf16_f32 v68, v0, v4
	v_lshl_add_u64 v[76:77], v[74:75], 0, v[76:77]
	v_or_b32_e32 v0, 1, v72
	s_waitcnt vmcnt(12)
	v_cvt_pk_bf16_f32 v69, v8, v12
	s_waitcnt vmcnt(10)
	v_cvt_pk_bf16_f32 v70, v16, v20
	s_waitcnt vmcnt(8)
	v_cvt_pk_bf16_f32 v71, v24, v28
	global_store_dwordx4 v[76:77], v[68:71], off sc1
	s_nop 1
	v_cvt_pk_bf16_f32 v68, v1, v5
	v_ashrrev_i32_e32 v1, 31, v0
	v_lshlrev_b64 v[0:1], 12, v[0:1]
	v_lshl_add_u64 v[4:5], v[74:75], 0, v[0:1]
	v_or_b32_e32 v0, 2, v72
	v_ashrrev_i32_e32 v1, 31, v0
	v_lshlrev_b64 v[0:1], 12, v[0:1]
	v_cvt_pk_bf16_f32 v69, v9, v13
	v_cvt_pk_bf16_f32 v70, v17, v21
	v_cvt_pk_bf16_f32 v71, v25, v29
	global_store_dwordx4 v[4:5], v[68:71], off sc1
	v_lshl_add_u64 v[8:9], v[74:75], 0, v[0:1]
	s_nop 0
	v_cvt_pk_bf16_f32 v68, v2, v6
	v_or_b32_e32 v6, 3, v72
	v_cvt_pk_bf16_f32 v69, v10, v14
	v_cvt_pk_bf16_f32 v70, v18, v22
	v_cvt_pk_bf16_f32 v71, v26, v30
	global_store_dwordx4 v[8:9], v[68:71], off sc1
	v_cvt_pk_bf16_f32 v0, v3, v7
	v_ashrrev_i32_e32 v7, 31, v6
	v_lshlrev_b64 v[6:7], 12, v[6:7]
	v_cvt_pk_bf16_f32 v1, v11, v15
	v_cvt_pk_bf16_f32 v2, v19, v23
	v_cvt_pk_bf16_f32 v3, v27, v31
	v_lshl_add_u64 v[6:7], v[74:75], 0, v[6:7]
	global_store_dwordx4 v[6:7], v[0:3], off sc1
	s_waitcnt vmcnt(10)
	s_nop 0
	v_cvt_pk_bf16_f32 v0, v32, v36
	s_waitcnt vmcnt(8)
	v_cvt_pk_bf16_f32 v1, v40, v44
	s_waitcnt vmcnt(6)
	v_cvt_pk_bf16_f32 v2, v48, v52
	s_waitcnt vmcnt(4)
	v_cvt_pk_bf16_f32 v3, v56, v60
	global_store_dwordx4 v[76:77], v[0:3], off offset:64 sc1
	s_nop 1
	v_cvt_pk_bf16_f32 v0, v33, v37
	v_cvt_pk_bf16_f32 v1, v41, v45
	v_cvt_pk_bf16_f32 v2, v49, v53
	v_cvt_pk_bf16_f32 v3, v57, v61
	global_store_dwordx4 v[4:5], v[0:3], off offset:64 sc1
	s_nop 1
	v_cvt_pk_bf16_f32 v0, v34, v38
	v_cvt_pk_bf16_f32 v1, v42, v46
	v_cvt_pk_bf16_f32 v2, v50, v54
	v_cvt_pk_bf16_f32 v3, v58, v62
	global_store_dwordx4 v[8:9], v[0:3], off offset:64 sc1
	s_nop 1
	v_cvt_pk_bf16_f32 v0, v35, v39
	v_cvt_pk_bf16_f32 v1, v43, v47
	v_cvt_pk_bf16_f32 v2, v51, v55
	v_cvt_pk_bf16_f32 v3, v59, v63
	global_store_dwordx4 v[6:7], v[0:3], off offset:64 sc1

; __device__ __forceinline__ unsigned cvt_pk_bf16(float lo, float hi) { unsigned r; asm volatile("v_cvt_pk_bf16_f32 %0, %1, %2" : "=v"(r) : "v"(lo), "v"(hi)); return r; }
; #define INP(i) ((const float*)(const GASP float*)kargs()[(i)])
; __device__ __forceinline__ void tr_item(const float* W, int ldw, int k0, int n0, bf16* WT, int ldk, int drow0, int lane) {
;     const int n4 = (lane & 15) * 4, kg = lane >> 4; f32x4 v[2][8];
; #pragma unroll
;     for (int kh = 0; kh < 2; ++kh) { const float* src = W + (size_t)(k0 + kh * 32 + kg * 8) * ldw + n0 + n4;
; #pragma unroll
;         for (int i = 0; i < 8; ++i) v[kh][i] = __builtin_nontemporal_load((const f32x4*)(src + (size_t)i * ldw)); }
; #pragma unroll
;     for (int kh = 0; kh < 2; ++kh)
; #pragma unroll
;         for (int e = 0; e < 4; ++e) { u32x4 o; o.x = cvt_pk_bf16(v[kh][0][e], v[kh][1][e]); o.y = cvt_pk_bf16(v[kh][2][e], v[kh][3][e]); o.z = cvt_pk_bf16(v[kh][4][e], v[kh][5][e]); o.w = cvt_pk_bf16(v[kh][6][e], v[kh][7][e]);
;             *(u32x4*)(WT + (size_t)(drow0 + n4 + e) * ldk + k0 + kh * 32 + kg * 8) = o; }
; }
; __device__ __forceinline__ void conv_item(int it, int lane) {
;     ...
;     if (r < 8 * IT_D) { const int idx = r / IT_D; r -= idx * IT_D; const int kb = r / 32, nb = r % 32;
;         tr_item(INP(I_WD) + (size_t)idx * 5376 * 2048, 2048, 64 * kb, 64 * nb, (bf16*)(ws + WS_WD) + (size_t)idx * 2048 * 5376, 5376, 64 * nb, lane); return; }
.LBB0_2523:
	s_andn2_b64 vcc, exec, s[22:23]
	s_cbranch_vccnz .LBB0_2525
	s_add_i32 s11, s6, 0xffff5800
	s_bfe_u32 s12, s11, 0x100007
	s_mulk_i32 s12, 0xc31
	s_lshr_b32 s12, s12, 16
	s_mul_i32 s20, s12, 0xf580
	s_add_i32 s11, s20, s11
	s_sext_i32_i16 s20, s11
	s_bfe_u32 s20, s20, 0x5001a
	s_add_i32 s22, s11, s20
	s_mov_b64 s[20:21], s[0:1]
	s_load_dwordx2 s[20:21], s[20:21], 0x70
	s_sext_i32_i16 s23, s22
	s_and_b32 s22, s22, 0xffe0
	s_sub_i32 s11, s11, s22
	s_mul_i32 s22, s12, 0x2a00000
	s_waitcnt lgkmcnt(0)
	s_add_u32 s30, s20, s22
	s_sext_i32_i16 s11, s11
	s_addc_u32 s31, s21, 0
	s_lshl_b32 s20, s23, 1
	s_and_b32 s22, s20, 0xffffffc0
	s_lshl_b32 s26, s11, 6
	s_mul_i32 s12, s12, 0x1500000
	s_add_u32 s11, s2, s12
	s_addc_u32 s12, s3, 0
	s_ashr_i32 s27, s26, 31
	s_lshl_b64 s[20:21], s[26:27], 2
	v_add_u32_e32 v32, s22, v66
	s_add_u32 s20, s30, s20
	s_addc_u32 s21, s31, s21
	v_lshlrev_b32_e32 v172, 2, v64
	v_ashrrev_i32_e32 v33, 31, v32
	v_lshl_add_u64 v[34:35], s[20:21], 0, v[172:173]
	v_lshlrev_b64 v[0:1], 13, v[32:33]
	v_lshl_add_u64 v[24:25], v[34:35], 0, v[0:1]
	v_add_co_u32_e32 v4, vcc, s89, v24
	s_movk_i32 s21, 0x4000
	s_nop 0
	v_addc_co_u32_e32 v5, vcc, 0, v25, vcc
	v_add_co_u32_e32 v8, vcc, s21, v24
	s_movk_i32 s20, 0x6000
	s_nop 0
	v_addc_co_u32_e32 v9, vcc, 0, v25, vcc
	v_add_co_u32_e32 v12, vcc, s20, v24
	s_mov_b32 s23, 0x8000
	s_nop 0
	v_addc_co_u32_e32 v13, vcc, 0, v25, vcc
	v_add_co_u32_e32 v16, vcc, s23, v24
	v_add_u32_e32 v32, 32, v32
	s_nop 0
	v_addc_co_u32_e32 v17, vcc, 0, v25, vcc
	v_add_co_u32_e32 v20, vcc, s33, v24
	s_mov_b32 s27, 0xe000
	s_nop 0
	v_addc_co_u32_e32 v21, vcc, 0, v25, vcc
	v_add_co_u32_e32 v26, vcc, s38, v24
	v_ashrrev_i32_e32 v33, 31, v32
	s_nop 0
	v_addc_co_u32_e32 v27, vcc, 0, v25, vcc
	v_add_co_u32_e32 v28, vcc, s27, v24
	v_lshlrev_b64 v[32:33], 13, v[32:33]
	s_nop 0
	v_addc_co_u32_e32 v29, vcc, 0, v25, vcc
	v_lshl_add_u64 v[56:57], v[34:35], 0, v[32:33]
	v_add_co_u32_e32 v36, vcc, s89, v56
	global_load_dwordx4 v[0:3], v[24:25], off nt
	s_nop 0
	global_load_dwordx4 v[4:7], v[4:5], off nt
	v_addc_co_u32_e32 v37, vcc, 0, v57, vcc
	v_add_co_u32_e32 v40, vcc, s21, v56
	global_load_dwordx4 v[8:11], v[8:9], off nt
	s_nop 0
	global_load_dwordx4 v[12:15], v[12:13], off nt
	v_addc_co_u32_e32 v41, vcc, 0, v57, vcc
	v_add_co_u32_e32 v44, vcc, s20, v56
	global_load_dwordx4 v[16:19], v[16:17], off nt
	s_nop 0
	global_load_dwordx4 v[20:23], v[20:21], off nt
	v_addc_co_u32_e32 v45, vcc, 0, v57, vcc
	v_add_co_u32_e32 v48, vcc, s23, v56
	global_load_dwordx4 v[24:27], v[26:27], off nt
	s_nop 0
	global_load_dwordx4 v[28:31], v[28:29], off nt
	v_addc_co_u32_e32 v49, vcc, 0, v57, vcc
	v_add_co_u32_e32 v52, vcc, s33, v56
	global_load_dwordx4 v[32:35], v[56:57], off nt
	s_nop 0
	global_load_dwordx4 v[36:39], v[36:37], off nt
	v_addc_co_u32_e32 v53, vcc, 0, v57, vcc
	v_add_co_u32_e32 v58, vcc, s38, v56
	global_load_dwordx4 v[40:43], v[40:41], off nt
	s_nop 0
	global_load_dwordx4 v[44:47], v[44:45], off nt
	v_addc_co_u32_e32 v59, vcc, 0, v57, vcc
	v_add_co_u32_e32 v60, vcc, s27, v56
	global_load_dwordx4 v[48:51], v[48:49], off nt
	s_nop 0
	global_load_dwordx4 v[52:55], v[52:53], off nt
	v_addc_co_u32_e32 v61, vcc, 0, v57, vcc
	global_load_dwordx4 v[56:59], v[58:59], off nt
	s_nop 0
	global_load_dwordx4 v[60:63], v[60:61], off nt
	s_ashr_i32 s23, s22, 31
	s_lshl_b64 s[20:21], s[22:23], 1
	v_or_b32_e32 v65, s26, v64
	s_add_u32 s20, s11, s20
	s_addc_u32 s21, s12, s21
	v_mul_i32_i24_e32 v74, 0x1500, v65
	v_lshl_add_u64 v[72:73], v[66:67], 1, s[20:21]
	v_ashrrev_i32_e32 v75, 31, v74
	v_lshl_add_u64 v[72:73], v[74:75], 1, v[72:73]
	s_mov_b32 s11, 0x15100000
	v_add_co_u32_e32 v76, vcc, s11, v72
	s_mov_b32 s11, 0x15102000
	s_nop 0
	v_addc_co_u32_e32 v77, vcc, 0, v73, vcc
	s_waitcnt vmcnt(14)
	v_cvt_pk_bf16_f32 v68, v0, v4
	v_add_co_u32_e32 v4, vcc, s11, v72
	s_waitcnt vmcnt(12)
	v_cvt_pk_bf16_f32 v69, v8, v12
	s_waitcnt vmcnt(10)
	v_cvt_pk_bf16_f32 v70, v16, v20
	s_waitcnt vmcnt(8)
	v_cvt_pk_bf16_f32 v71, v24, v28
	global_store_dwordx4 v[76:77], v[68:71], off sc1
	s_mov_b32 s11, 0x15105000
	s_mov_b64 s[20:21], 0x15100000
	v_cvt_pk_bf16_f32 v68, v1, v5
	v_addc_co_u32_e32 v5, vcc, 0, v73, vcc
	v_add_co_u32_e32 v8, vcc, s11, v72
	v_cvt_pk_bf16_f32 v69, v9, v13
	s_mov_b32 s11, 0x15107000
	s_nop 0
	v_addc_co_u32_e32 v9, vcc, 0, v73, vcc
	v_cvt_pk_bf16_f32 v70, v17, v21
	v_cvt_pk_bf16_f32 v71, v25, v29
	global_store_dwordx4 v[4:5], v[68:71], off offset:2560 sc1
	v_lshl_add_u64 v[74:75], v[72:73], 0, s[20:21]
	s_nop 0
	v_cvt_pk_bf16_f32 v68, v2, v6
	v_add_co_u32_e32 v6, vcc, s11, v72
	v_cvt_pk_bf16_f32 v69, v10, v14
	v_cvt_pk_bf16_f32 v70, v18, v22
	v_cvt_pk_bf16_f32 v71, v26, v30
	global_store_dwordx4 v[8:9], v[68:71], off offset:1024 sc1
	v_cvt_pk_bf16_f32 v0, v3, v7
	v_cvt_pk_bf16_f32 v1, v11, v15
	v_cvt_pk_bf16_f32 v2, v19, v23
	v_cvt_pk_bf16_f32 v3, v27, v31
	s_nop 0
	v_addc_co_u32_e32 v7, vcc, 0, v73, vcc
	global_store_dwordx4 v[6:7], v[0:3], off offset:3584 sc1
	s_waitcnt vmcnt(10)
	s_nop 0
	v_cvt_pk_bf16_f32 v0, v32, v36
	s_waitcnt vmcnt(8)
	v_cvt_pk_bf16_f32 v1, v40, v44
	s_waitcnt vmcnt(6)
	v_cvt_pk_bf16_f32 v2, v48, v52
	s_waitcnt vmcnt(4)
	v_cvt_pk_bf16_f32 v3, v56, v60
	global_store_dwordx4 v[74:75], v[0:3], off offset:64 sc1
	s_nop 1
	v_cvt_pk_bf16_f32 v0, v33, v37
	v_cvt_pk_bf16_f32 v1, v41, v45
	v_cvt_pk_bf16_f32 v2, v49, v53
	v_cvt_pk_bf16_f32 v3, v57, v61
	global_store_dwordx4 v[4:5], v[0:3], off offset:2624 sc1
	s_nop 1
	v_cvt_pk_bf16_f32 v0, v34, v38
	v_cvt_pk_bf16_f32 v1, v42, v46
	v_cvt_pk_bf16_f32 v2, v50, v54
	v_cvt_pk_bf16_f32 v3, v58, v62
	global_store_dwordx4 v[8:9], v[0:3], off offset:1088 sc1
	s_nop 1
	v_cvt_pk_bf16_f32 v0, v35, v39
	v_cvt_pk_bf16_f32 v1, v43, v47
	v_cvt_pk_bf16_f32 v2, v51, v55
	v_cvt_pk_bf16_f32 v3, v59, v63
	global_store_dwordx4 v[6:7], v[0:3], off offset:3648 sc1
